# FFN-up conv epilogue: one wait for the conv weights per column half instead of a vmcnt(0) in every row block (which waited on the previous block's stores)
# speedup vs baseline: 1.0046x; 1.0046x over previous
.LBB0_1256:
	s_mul_hi_i32 s67, s39, 0x3e0f83e1
	s_lshr_b32 s72, s67, 31
	s_ashr_i32 s67, s67, 3
	s_add_i32 s72, s67, s72
	s_mul_i32 s67, s72, 33
	s_sub_i32 s39, s39, s67
	s_mul_i32 s67, s39, 0xfe
	v_add_u32_e32 v194, s67, v228
	s_or_b32 s67, s39, s40
	s_cmp_eq_u32 s67, 0
	s_cselect_b64 s[74:75], -1, 0
	s_cmp_eq_u32 s39, 32
	s_movk_i32 s39, 0x42
	s_cselect_b32 s39, s39, 0x100
	s_and_b64 s[74:75], s[74:75], s[8:9]
	s_ashr_i32 s73, s72, 31
	v_cndmask_b32_e64 v221, v159, 0, s[74:75]
	v_cndmask_b32_e64 v220, v158, 0, s[74:75]
	v_cndmask_b32_e64 v223, v157, 0, s[74:75]
	v_cndmask_b32_e64 v222, v156, 0, s[74:75]
	v_cndmask_b32_e64 v159, v155, 0, s[74:75]
	v_cndmask_b32_e64 v158, v154, 0, s[74:75]
	v_cndmask_b32_e64 v153, v153, 0, s[74:75]
	v_cndmask_b32_e64 v152, v152, 0, s[74:75]
	v_cmp_gt_u32_e32 vcc, s39, v224
	s_lshl_b64 s[72:73], s[72:73], 13
	v_mov_b32_dpp v173, v222 row_shr:1 row_mask:0xf bank_mask:0xf
	v_mov_b32_dpp v218, v222 row_shr:2 row_mask:0xf bank_mask:0xf
	v_mov_b32_dpp v169, v152 row_shr:1 row_mask:0xf bank_mask:0xf
	v_mov_b32_dpp v216, v152 row_shr:2 row_mask:0xf bank_mask:0xf
	v_mov_b32_dpp v208, v222 row_ror:1 row_mask:0xf bank_mask:0xf bound_ctrl:1
	v_mov_b32_dpp v200, v152 row_ror:1 row_mask:0xf bank_mask:0xf bound_ctrl:1
	v_mov_b32_dpp v210, v222 row_ror:2 row_mask:0xf bank_mask:0xf bound_ctrl:1
	v_mov_b32_dpp v204, v152 row_ror:2 row_mask:0xf bank_mask:0xf bound_ctrl:1
	v_mov_b32_dpp v175, v223 row_shr:1 row_mask:0xf bank_mask:0xf
	v_mov_b32_dpp v219, v223 row_shr:2 row_mask:0xf bank_mask:0xf
	v_mov_b32_dpp v171, v153 row_shr:1 row_mask:0xf bank_mask:0xf
	v_mov_b32_dpp v217, v153 row_shr:2 row_mask:0xf bank_mask:0xf
	v_mov_b32_dpp v209, v223 row_ror:1 row_mask:0xf bank_mask:0xf bound_ctrl:1
	v_mov_b32_dpp v201, v153 row_ror:1 row_mask:0xf bank_mask:0xf bound_ctrl:1
	v_mov_b32_dpp v211, v223 row_ror:2 row_mask:0xf bank_mask:0xf bound_ctrl:1
	v_mov_b32_dpp v205, v153 row_ror:2 row_mask:0xf bank_mask:0xf bound_ctrl:1
	v_mov_b32_dpp v165, v220 row_shr:1 row_mask:0xf bank_mask:0xf
	v_mov_b32_dpp v214, v220 row_shr:2 row_mask:0xf bank_mask:0xf
	v_mov_b32_dpp v161, v158 row_shr:1 row_mask:0xf bank_mask:0xf
	v_mov_b32_dpp v212, v158 row_shr:2 row_mask:0xf bank_mask:0xf
	v_mov_b32_dpp v202, v220 row_ror:1 row_mask:0xf bank_mask:0xf bound_ctrl:1
	v_mov_b32_dpp v154, v158 row_ror:1 row_mask:0xf bank_mask:0xf bound_ctrl:1
	v_mov_b32_dpp v206, v220 row_ror:2 row_mask:0xf bank_mask:0xf bound_ctrl:1
	v_mov_b32_dpp v156, v158 row_ror:2 row_mask:0xf bank_mask:0xf bound_ctrl:1
	v_mov_b32_dpp v167, v221 row_shr:1 row_mask:0xf bank_mask:0xf
	v_mov_b32_dpp v215, v221 row_shr:2 row_mask:0xf bank_mask:0xf
	v_mov_b32_dpp v163, v159 row_shr:1 row_mask:0xf bank_mask:0xf
	v_mov_b32_dpp v213, v159 row_shr:2 row_mask:0xf bank_mask:0xf
	v_mov_b32_dpp v203, v221 row_ror:1 row_mask:0xf bank_mask:0xf bound_ctrl:1
	v_mov_b32_dpp v155, v159 row_ror:1 row_mask:0xf bank_mask:0xf bound_ctrl:1
	v_mov_b32_dpp v207, v221 row_ror:2 row_mask:0xf bank_mask:0xf bound_ctrl:1
	v_mov_b32_dpp v157, v159 row_ror:2 row_mask:0xf bank_mask:0xf bound_ctrl:1
	s_and_b64 s[76:77], s[12:13], vcc
	v_ashrrev_i32_e32 v195, 31, v194
	s_waitcnt vmcnt(0)
	s_and_saveexec_b64 s[78:79], s[76:77]
	s_cbranch_execz .LBB0_1258
	v_mov_b32_e32 v174, v173
	v_pk_fma_f32 v[172:173], v[120:121], v[218:219], v[132:133]
	v_mov_b32_e32 v166, v165
	v_pk_fma_f32 v[172:173], v[124:125], v[174:175], v[172:173]
	v_pk_fma_f32 v[164:165], v[122:123], v[214:215], v[134:135]
	v_pk_fma_f32 v[172:173], v[222:223], v[128:129], v[172:173]
	v_pk_fma_f32 v[164:165], v[126:127], v[166:167], v[164:165]
	v_mul_f32_e32 v160, 0x3d372713, v172
	v_fma_f32 v160, v172, v160, 1.0
	v_mul_f32_e32 v162, 0x3d372713, v173
	v_mul_f32_e32 v160, v172, v160
	v_fma_f32 v162, v173, v162, 1.0
	v_mul_f32_e32 v160, 0x40135761, v160
	v_mul_f32_e32 v162, v173, v162
	v_exp_f32_e32 v160, v160
	v_mul_f32_e32 v162, 0x40135761, v162
	v_exp_f32_e32 v162, v162
	v_pk_fma_f32 v[164:165], v[220:221], v[130:131], v[164:165]
	v_add_f32_e32 v160, 1.0, v160
	v_rcp_f32_e32 v168, v160
	v_add_f32_e32 v160, 1.0, v162
	v_mov_b32_e32 v170, v169
	v_rcp_f32_e32 v169, v160
	v_mul_f32_e32 v160, 0x3d372713, v164
	v_mul_f32_e32 v162, 0x3d372713, v165
	v_fma_f32 v160, v164, v160, 1.0
	v_fma_f32 v162, v165, v162, 1.0
	v_mul_f32_e32 v160, v164, v160
	v_mul_f32_e32 v162, v165, v162
	v_mul_f32_e32 v160, 0x40135761, v160
	v_mul_f32_e32 v162, 0x40135761, v162
	v_exp_f32_e32 v160, v160
	v_exp_f32_e32 v166, v162
	v_mov_b32_e32 v162, v161
	v_pk_fma_f32 v[174:175], v[104:105], v[216:217], v[116:117]
	v_add_f32_e32 v160, 1.0, v160
	v_add_f32_e32 v161, 1.0, v166
	v_rcp_f32_e32 v160, v160
	v_rcp_f32_e32 v161, v161
	v_pk_fma_f32 v[166:167], v[106:107], v[212:213], v[118:119]
	v_pk_fma_f32 v[170:171], v[108:109], v[170:171], v[174:175]
	v_pk_fma_f32 v[162:163], v[110:111], v[162:163], v[166:167]
	v_pk_fma_f32 v[152:153], v[152:153], v[112:113], v[170:171]
	v_pk_fma_f32 v[168:169], v[172:173], v[168:169], v[172:173] neg_lo:[1,0,0] neg_hi:[1,0,0]
	v_pk_fma_f32 v[158:159], v[158:159], v[114:115], v[162:163]
	v_pk_fma_f32 v[160:161], v[164:165], v[160:161], v[164:165] neg_lo:[1,0,0] neg_hi:[1,0,0]
	v_pk_mul_f32 v[152:153], v[152:153], v[168:169]
	v_pk_mul_f32 v[158:159], v[158:159], v[160:161]
	v_cvt_pk_bf16_f32 v152, v152, v153
	v_cvt_pk_bf16_f32 v153, v158, v159
	v_lshl_add_u64 v[158:159], s[72:73], 0, v[194:195]
	v_mov_b64_e32 v[160:161], s[44:45]
	v_mad_u64_u32 v[160:161], s[80:81], v158, s1, v[160:161]
	v_mad_i32_i24 v161, v159, s1, v161
	v_lshl_add_u64 v[158:159], v[192:193], 1, v[160:161]
	global_store_dwordx2 v[158:159], v[152:153], off
.LBB0_1258:
	s_or_b64 exec, exec, s[78:79]
	v_cmp_gt_i32_e32 vcc, s39, v229
	v_add_u32_e32 v152, 16, v194
	v_mov_b32_dpp v208, v148 row_shr:1 row_mask:0xf bank_mask:0xf
	v_mov_b32_dpp v210, v148 row_shr:2 row_mask:0xf bank_mask:0xf
	v_mov_b32_dpp v200, v144 row_shr:1 row_mask:0xf bank_mask:0xf
	v_mov_b32_dpp v204, v144 row_shr:2 row_mask:0xf bank_mask:0xf
	v_mov_b32_dpp v174, v148 row_ror:1 row_mask:0xf bank_mask:0xf bound_ctrl:1
	v_mov_b32_dpp v162, v144 row_ror:1 row_mask:0xf bank_mask:0xf bound_ctrl:1
	v_mov_b32_dpp v212, v148 row_ror:2 row_mask:0xf bank_mask:0xf bound_ctrl:1
	v_mov_b32_dpp v166, v144 row_ror:2 row_mask:0xf bank_mask:0xf bound_ctrl:1
	v_mov_b32_dpp v209, v149 row_shr:1 row_mask:0xf bank_mask:0xf
	v_mov_b32_dpp v211, v149 row_shr:2 row_mask:0xf bank_mask:0xf
	v_mov_b32_dpp v201, v145 row_shr:1 row_mask:0xf bank_mask:0xf
	v_mov_b32_dpp v205, v145 row_shr:2 row_mask:0xf bank_mask:0xf
	v_mov_b32_dpp v175, v149 row_ror:1 row_mask:0xf bank_mask:0xf bound_ctrl:1
	v_mov_b32_dpp v163, v145 row_ror:1 row_mask:0xf bank_mask:0xf bound_ctrl:1
	v_mov_b32_dpp v213, v149 row_ror:2 row_mask:0xf bank_mask:0xf bound_ctrl:1
	v_mov_b32_dpp v167, v145 row_ror:2 row_mask:0xf bank_mask:0xf bound_ctrl:1
	v_mov_b32_dpp v202, v150 row_shr:1 row_mask:0xf bank_mask:0xf
	v_mov_b32_dpp v206, v150 row_shr:2 row_mask:0xf bank_mask:0xf
	v_mov_b32_dpp v154, v146 row_shr:1 row_mask:0xf bank_mask:0xf
	v_mov_b32_dpp v156, v146 row_shr:2 row_mask:0xf bank_mask:0xf
	v_mov_b32_dpp v164, v150 row_ror:1 row_mask:0xf bank_mask:0xf bound_ctrl:1
	v_mov_b32_dpp v158, v146 row_ror:1 row_mask:0xf bank_mask:0xf bound_ctrl:1
	v_mov_b32_dpp v168, v150 row_ror:2 row_mask:0xf bank_mask:0xf bound_ctrl:1
	v_mov_b32_dpp v160, v146 row_ror:2 row_mask:0xf bank_mask:0xf bound_ctrl:1
	v_mov_b32_dpp v203, v151 row_shr:1 row_mask:0xf bank_mask:0xf
	v_mov_b32_dpp v207, v151 row_shr:2 row_mask:0xf bank_mask:0xf
	v_mov_b32_dpp v155, v147 row_shr:1 row_mask:0xf bank_mask:0xf
	v_mov_b32_dpp v157, v147 row_shr:2 row_mask:0xf bank_mask:0xf
	v_mov_b32_dpp v165, v151 row_ror:1 row_mask:0xf bank_mask:0xf bound_ctrl:1
	v_mov_b32_dpp v159, v147 row_ror:1 row_mask:0xf bank_mask:0xf bound_ctrl:1
	v_mov_b32_dpp v169, v151 row_ror:2 row_mask:0xf bank_mask:0xf bound_ctrl:1
	v_mov_b32_dpp v161, v147 row_ror:2 row_mask:0xf bank_mask:0xf bound_ctrl:1
	s_and_b64 s[78:79], s[52:53], vcc
	v_ashrrev_i32_e32 v153, 31, v152
	s_and_saveexec_b64 s[80:81], s[78:79]
	s_cbranch_execz .LBB0_1260
	v_pk_fma_f32 v[170:171], v[120:121], v[210:211], v[132:133]
	v_pk_fma_f32 v[172:173], v[104:105], v[204:205], v[116:117]
	v_pk_fma_f32 v[170:171], v[124:125], v[208:209], v[170:171]
	v_pk_fma_f32 v[172:173], v[108:109], v[200:201], v[172:173]
	v_pk_fma_f32 v[148:149], v[148:149], v[128:129], v[170:171]
	v_pk_fma_f32 v[144:145], v[144:145], v[112:113], v[172:173]
	v_mul_f32_e32 v170, 0x3d372713, v148
	v_mul_f32_e32 v171, 0x3d372713, v149
	v_fma_f32 v170, v148, v170, 1.0
	v_fma_f32 v171, v149, v171, 1.0
	v_mul_f32_e32 v170, v148, v170
	v_mul_f32_e32 v171, v149, v171
	v_mul_f32_e32 v170, 0x40135761, v170
	v_mul_f32_e32 v171, 0x40135761, v171
	v_exp_f32_e32 v170, v170
	v_exp_f32_e32 v171, v171
	v_pk_fma_f32 v[156:157], v[106:107], v[156:157], v[118:119]
	v_add_f32_e32 v170, 1.0, v170
	v_add_f32_e32 v171, 1.0, v171
	v_rcp_f32_e32 v170, v170
	v_rcp_f32_e32 v171, v171
	v_pk_fma_f32 v[154:155], v[110:111], v[154:155], v[156:157]
	v_pk_fma_f32 v[148:149], v[148:149], v[170:171], v[148:149] neg_lo:[1,0,0] neg_hi:[1,0,0]
	v_pk_fma_f32 v[170:171], v[122:123], v[206:207], v[134:135]
	v_pk_mul_f32 v[144:145], v[144:145], v[148:149]
	v_pk_fma_f32 v[170:171], v[126:127], v[202:203], v[170:171]
	v_pk_fma_f32 v[146:147], v[146:147], v[114:115], v[154:155]
	v_pk_fma_f32 v[150:151], v[150:151], v[130:131], v[170:171]
	v_cvt_pk_bf16_f32 v144, v144, v145
	v_mul_f32_e32 v170, 0x3d372713, v150
	v_mul_f32_e32 v171, 0x3d372713, v151
	v_fma_f32 v170, v150, v170, 1.0
	v_fma_f32 v171, v151, v171, 1.0
	v_mul_f32_e32 v170, v150, v170
	v_mul_f32_e32 v171, v151, v171
	v_mul_f32_e32 v170, 0x40135761, v170
	v_mul_f32_e32 v171, 0x40135761, v171
	v_exp_f32_e32 v170, v170
	v_exp_f32_e32 v171, v171
	v_add_f32_e32 v148, 1.0, v170
	v_add_f32_e32 v149, 1.0, v171
	v_rcp_f32_e32 v148, v148
	v_rcp_f32_e32 v149, v149
	s_nop 0
	v_pk_fma_f32 v[148:149], v[150:151], v[148:149], v[150:151] neg_lo:[1,0,0] neg_hi:[1,0,0]
	s_nop 0
	v_pk_mul_f32 v[146:147], v[146:147], v[148:149]
	v_mov_b64_e32 v[148:149], s[44:45]
	v_cvt_pk_bf16_f32 v145, v146, v147
	v_lshl_add_u64 v[146:147], s[72:73], 0, v[152:153]
	v_mad_u64_u32 v[148:149], s[82:83], v146, s1, v[148:149]
	v_mad_i32_i24 v149, v147, s1, v149
	v_lshl_add_u64 v[146:147], v[192:193], 1, v[148:149]
	global_store_dwordx2 v[146:147], v[144:145], off
.LBB0_1260:
	s_or_b64 exec, exec, s[80:81]
	v_cmp_gt_i32_e32 vcc, s39, v230
	v_add_u32_e32 v146, 32, v194
	v_mov_b32_dpp v174, v140 row_shr:1 row_mask:0xf bank_mask:0xf
	v_mov_b32_dpp v212, v140 row_shr:2 row_mask:0xf bank_mask:0xf
	v_mov_b32_dpp v162, v136 row_shr:1 row_mask:0xf bank_mask:0xf
	v_mov_b32_dpp v166, v136 row_shr:2 row_mask:0xf bank_mask:0xf
	v_mov_b32_dpp v200, v140 row_ror:1 row_mask:0xf bank_mask:0xf bound_ctrl:1
	v_mov_b32_dpp v154, v136 row_ror:1 row_mask:0xf bank_mask:0xf bound_ctrl:1
	v_mov_b32_dpp v202, v140 row_ror:2 row_mask:0xf bank_mask:0xf bound_ctrl:1
	v_mov_b32_dpp v170, v136 row_ror:2 row_mask:0xf bank_mask:0xf bound_ctrl:1
	v_mov_b32_dpp v175, v141 row_shr:1 row_mask:0xf bank_mask:0xf
	v_mov_b32_dpp v213, v141 row_shr:2 row_mask:0xf bank_mask:0xf
	v_mov_b32_dpp v163, v137 row_shr:1 row_mask:0xf bank_mask:0xf
	v_mov_b32_dpp v167, v137 row_shr:2 row_mask:0xf bank_mask:0xf
	v_mov_b32_dpp v201, v141 row_ror:1 row_mask:0xf bank_mask:0xf bound_ctrl:1
	v_mov_b32_dpp v155, v137 row_ror:1 row_mask:0xf bank_mask:0xf bound_ctrl:1
	v_mov_b32_dpp v203, v141 row_ror:2 row_mask:0xf bank_mask:0xf bound_ctrl:1
	v_mov_b32_dpp v171, v137 row_ror:2 row_mask:0xf bank_mask:0xf bound_ctrl:1
	v_mov_b32_dpp v164, v142 row_shr:1 row_mask:0xf bank_mask:0xf
	v_mov_b32_dpp v168, v142 row_shr:2 row_mask:0xf bank_mask:0xf
	v_mov_b32_dpp v158, v138 row_shr:1 row_mask:0xf bank_mask:0xf
	v_mov_b32_dpp v160, v138 row_shr:2 row_mask:0xf bank_mask:0xf
	v_mov_b32_dpp v156, v142 row_ror:1 row_mask:0xf bank_mask:0xf bound_ctrl:1
	v_mov_b32_dpp v144, v138 row_ror:1 row_mask:0xf bank_mask:0xf bound_ctrl:1
	v_mov_b32_dpp v172, v142 row_ror:2 row_mask:0xf bank_mask:0xf bound_ctrl:1
	v_mov_b32_dpp v150, v138 row_ror:2 row_mask:0xf bank_mask:0xf bound_ctrl:1
	v_mov_b32_dpp v165, v143 row_shr:1 row_mask:0xf bank_mask:0xf
	v_mov_b32_dpp v169, v143 row_shr:2 row_mask:0xf bank_mask:0xf
	v_mov_b32_dpp v159, v139 row_shr:1 row_mask:0xf bank_mask:0xf
	v_mov_b32_dpp v161, v139 row_shr:2 row_mask:0xf bank_mask:0xf
	v_mov_b32_dpp v157, v143 row_ror:1 row_mask:0xf bank_mask:0xf bound_ctrl:1
	v_mov_b32_dpp v145, v139 row_ror:1 row_mask:0xf bank_mask:0xf bound_ctrl:1
	v_mov_b32_dpp v173, v143 row_ror:2 row_mask:0xf bank_mask:0xf bound_ctrl:1
	v_mov_b32_dpp v151, v139 row_ror:2 row_mask:0xf bank_mask:0xf bound_ctrl:1
	s_and_b64 s[80:81], s[52:53], vcc
	v_ashrrev_i32_e32 v147, 31, v146
	s_and_saveexec_b64 s[82:83], s[80:81]
	s_cbranch_execz .LBB0_1262
	v_pk_fma_f32 v[148:149], v[120:121], v[212:213], v[132:133]
	v_pk_fma_f32 v[166:167], v[104:105], v[166:167], v[116:117]
	v_pk_fma_f32 v[148:149], v[124:125], v[174:175], v[148:149]
	v_pk_fma_f32 v[162:163], v[108:109], v[162:163], v[166:167]
	v_pk_fma_f32 v[140:141], v[140:141], v[128:129], v[148:149]
	v_pk_fma_f32 v[136:137], v[136:137], v[112:113], v[162:163]
	v_mul_f32_e32 v148, 0x3d372713, v140
	v_mul_f32_e32 v149, 0x3d372713, v141
	v_fma_f32 v148, v140, v148, 1.0
	v_fma_f32 v149, v141, v149, 1.0
	v_mul_f32_e32 v148, v140, v148
	v_mul_f32_e32 v149, v141, v149
	v_mul_f32_e32 v148, 0x40135761, v148
	v_mul_f32_e32 v149, 0x40135761, v149
	v_exp_f32_e32 v148, v148
	v_exp_f32_e32 v149, v149
	v_add_f32_e32 v148, 1.0, v148
	v_add_f32_e32 v149, 1.0, v149
	v_rcp_f32_e32 v148, v148
	v_rcp_f32_e32 v149, v149
	s_nop 0
	v_pk_fma_f32 v[140:141], v[140:141], v[148:149], v[140:141] neg_lo:[1,0,0] neg_hi:[1,0,0]
	v_pk_fma_f32 v[148:149], v[122:123], v[168:169], v[134:135]
	v_pk_mul_f32 v[136:137], v[136:137], v[140:141]
	v_pk_fma_f32 v[148:149], v[126:127], v[164:165], v[148:149]
	v_cvt_pk_bf16_f32 v136, v136, v137
	v_pk_fma_f32 v[142:143], v[142:143], v[130:131], v[148:149]
	s_nop 0
	v_mul_f32_e32 v148, 0x3d372713, v142
	v_mul_f32_e32 v149, 0x3d372713, v143
	v_fma_f32 v148, v142, v148, 1.0
	v_fma_f32 v149, v143, v149, 1.0
	v_mul_f32_e32 v148, v142, v148
	v_mul_f32_e32 v149, v143, v149
	v_mul_f32_e32 v148, 0x40135761, v148
	v_mul_f32_e32 v149, 0x40135761, v149
	v_exp_f32_e32 v148, v148
	v_exp_f32_e32 v149, v149
	v_add_f32_e32 v140, 1.0, v148
	v_add_f32_e32 v141, 1.0, v149
	v_rcp_f32_e32 v140, v140
	v_rcp_f32_e32 v141, v141
	v_pk_fma_f32 v[148:149], v[106:107], v[160:161], v[118:119]
	v_pk_fma_f32 v[140:141], v[142:143], v[140:141], v[142:143] neg_lo:[1,0,0] neg_hi:[1,0,0]
	v_pk_fma_f32 v[148:149], v[110:111], v[158:159], v[148:149]
	s_nop 0
	v_pk_fma_f32 v[138:139], v[138:139], v[114:115], v[148:149]
	s_nop 0
	v_pk_mul_f32 v[138:139], v[138:139], v[140:141]
	v_mov_b64_e32 v[140:141], s[44:45]
	v_cvt_pk_bf16_f32 v137, v138, v139
	v_lshl_add_u64 v[138:139], s[72:73], 0, v[146:147]
	v_mad_u64_u32 v[140:141], s[84:85], v138, s1, v[140:141]
	v_mad_i32_i24 v141, v139, s1, v141
	v_lshl_add_u64 v[138:139], v[192:193], 1, v[140:141]
	global_store_dwordx2 v[138:139], v[136:137], off
.LBB0_1262:
	s_or_b64 exec, exec, s[82:83]
	v_cmp_gt_i32_e32 vcc, s39, v231
	v_add_u32_e32 v148, 48, v194
	v_mov_b32_dpp v200, v100 row_shr:1 row_mask:0xf bank_mask:0xf
	v_mov_b32_dpp v202, v100 row_shr:2 row_mask:0xf bank_mask:0xf
	v_mov_b32_dpp v154, v96 row_shr:1 row_mask:0xf bank_mask:0xf
	v_mov_b32_dpp v170, v96 row_shr:2 row_mask:0xf bank_mask:0xf
	v_mov_b32_dpp v201, v101 row_shr:1 row_mask:0xf bank_mask:0xf
	v_mov_b32_dpp v203, v101 row_shr:2 row_mask:0xf bank_mask:0xf
	v_mov_b32_dpp v155, v97 row_shr:1 row_mask:0xf bank_mask:0xf
	v_mov_b32_dpp v171, v97 row_shr:2 row_mask:0xf bank_mask:0xf
	v_mov_b32_dpp v156, v102 row_shr:1 row_mask:0xf bank_mask:0xf
	v_mov_b32_dpp v172, v102 row_shr:2 row_mask:0xf bank_mask:0xf
	v_mov_b32_dpp v144, v98 row_shr:1 row_mask:0xf bank_mask:0xf
	v_mov_b32_dpp v150, v98 row_shr:2 row_mask:0xf bank_mask:0xf
	v_mov_b32_dpp v157, v103 row_shr:1 row_mask:0xf bank_mask:0xf
	v_mov_b32_dpp v173, v103 row_shr:2 row_mask:0xf bank_mask:0xf
	v_mov_b32_dpp v145, v99 row_shr:1 row_mask:0xf bank_mask:0xf
	v_mov_b32_dpp v151, v99 row_shr:2 row_mask:0xf bank_mask:0xf
	s_and_b64 s[82:83], s[52:53], vcc
	v_ashrrev_i32_e32 v149, 31, v148
	s_and_saveexec_b64 s[84:85], s[82:83]
	s_cbranch_execz .LBB0_1264
	v_pk_fma_f32 v[136:137], v[120:121], v[202:203], v[132:133]
	v_pk_fma_f32 v[138:139], v[104:105], v[170:171], v[116:117]
	v_pk_fma_f32 v[136:137], v[124:125], v[200:201], v[136:137]
	v_pk_fma_f32 v[138:139], v[108:109], v[154:155], v[138:139]
	v_pk_fma_f32 v[100:101], v[100:101], v[128:129], v[136:137]
	v_pk_fma_f32 v[96:97], v[96:97], v[112:113], v[138:139]
	v_mul_f32_e32 v136, 0x3d372713, v100
	v_mul_f32_e32 v137, 0x3d372713, v101
	v_fma_f32 v136, v100, v136, 1.0
	v_fma_f32 v137, v101, v137, 1.0
	v_mul_f32_e32 v136, v100, v136
	v_mul_f32_e32 v137, v101, v137
	v_mul_f32_e32 v136, 0x40135761, v136
	v_mul_f32_e32 v137, 0x40135761, v137
	v_exp_f32_e32 v136, v136
	v_exp_f32_e32 v137, v137
	v_add_f32_e32 v136, 1.0, v136
	v_add_f32_e32 v137, 1.0, v137
	v_rcp_f32_e32 v136, v136
	v_rcp_f32_e32 v137, v137
	s_nop 0
	v_pk_fma_f32 v[100:101], v[100:101], v[136:137], v[100:101] neg_lo:[1,0,0] neg_hi:[1,0,0]
	v_pk_fma_f32 v[136:137], v[122:123], v[172:173], v[134:135]
	v_pk_mul_f32 v[96:97], v[96:97], v[100:101]
	v_pk_fma_f32 v[136:137], v[126:127], v[156:157], v[136:137]
	v_cvt_pk_bf16_f32 v96, v96, v97
	v_pk_fma_f32 v[102:103], v[102:103], v[130:131], v[136:137]
	s_nop 0
	v_mul_f32_e32 v136, 0x3d372713, v102
	v_mul_f32_e32 v137, 0x3d372713, v103
	v_fma_f32 v136, v102, v136, 1.0
	v_fma_f32 v137, v103, v137, 1.0
	v_mul_f32_e32 v136, v102, v136
	v_mul_f32_e32 v137, v103, v137
	v_mul_f32_e32 v136, 0x40135761, v136
	v_mul_f32_e32 v137, 0x40135761, v137
	v_exp_f32_e32 v136, v136
	v_exp_f32_e32 v137, v137
	v_add_f32_e32 v100, 1.0, v136
	v_add_f32_e32 v101, 1.0, v137
	v_rcp_f32_e32 v100, v100
	v_rcp_f32_e32 v101, v101
	v_pk_fma_f32 v[136:137], v[106:107], v[150:151], v[118:119]
	v_pk_fma_f32 v[100:101], v[102:103], v[100:101], v[102:103] neg_lo:[1,0,0] neg_hi:[1,0,0]
	v_pk_fma_f32 v[136:137], v[110:111], v[144:145], v[136:137]
	s_nop 0
	v_pk_fma_f32 v[98:99], v[98:99], v[114:115], v[136:137]
	s_nop 0
	v_pk_mul_f32 v[98:99], v[98:99], v[100:101]
	v_mov_b64_e32 v[100:101], s[44:45]
	v_cvt_pk_bf16_f32 v97, v98, v99
	v_lshl_add_u64 v[98:99], s[72:73], 0, v[148:149]
	v_mad_u64_u32 v[100:101], s[86:87], v98, s1, v[100:101]
	v_mad_i32_i24 v101, v99, s1, v101
	v_lshl_add_u64 v[98:99], v[192:193], 1, v[100:101]
	global_store_dwordx2 v[98:99], v[96:97], off
.LBB0_1264:
	s_or_b64 exec, exec, s[84:85]
	v_add_u32_e32 v96, 0x1100, v241
	v_add_u32_e32 v100, 0x1000, v241
	ds_read2_b64 v[136:139], v96 offset1:1
	ds_read2_b64 v[140:143], v100 offset1:1
	v_add_u32_e32 v96, 0x1110, v241
	v_add_u32_e32 v100, 0x1010, v241
	ds_read2_b64 v[96:99], v96 offset1:1
	ds_read2_b64 v[100:103], v100 offset1:1
	s_waitcnt lgkmcnt(0)
	v_cndmask_b32_e64 v172, v137, v136, s[10:11]
	v_cndmask_b32_e64 v173, v139, v138, s[10:11]
	v_cndmask_b32_e64 v174, v141, v140, s[10:11]
	v_cndmask_b32_e64 v168, v97, v96, s[10:11]
	v_cndmask_b32_e64 v169, v99, v98, s[10:11]
	v_cndmask_b32_e64 v175, v143, v142, s[10:11]
	v_cndmask_b32_e64 v170, v101, v100, s[10:11]
	v_cndmask_b32_e64 v171, v103, v102, s[10:11]
	v_add_u32_e32 v144, 0x80, v194
	v_cmp_gt_u32_e32 vcc, s39, v232
	v_mov_b32_dpp v141, v92 row_shr:1 row_mask:0xf bank_mask:0xf
	v_mov_b32_dpp v174, v92 row_shr:2 row_mask:0xf bank_mask:0xf
	v_mov_b32_dpp v137, v88 row_shr:1 row_mask:0xf bank_mask:0xf
	v_mov_b32_dpp v172, v88 row_shr:2 row_mask:0xf bank_mask:0xf
	v_mov_b32_dpp v164, v92 row_ror:1 row_mask:0xf bank_mask:0xf bound_ctrl:1
	v_mov_b32_dpp v156, v88 row_ror:1 row_mask:0xf bank_mask:0xf bound_ctrl:1
	v_mov_b32_dpp v166, v92 row_ror:2 row_mask:0xf bank_mask:0xf bound_ctrl:1
	v_mov_b32_dpp v160, v88 row_ror:2 row_mask:0xf bank_mask:0xf bound_ctrl:1
	v_mov_b32_dpp v143, v93 row_shr:1 row_mask:0xf bank_mask:0xf
	v_mov_b32_dpp v175, v93 row_shr:2 row_mask:0xf bank_mask:0xf
	v_mov_b32_dpp v139, v89 row_shr:1 row_mask:0xf bank_mask:0xf
	v_mov_b32_dpp v173, v89 row_shr:2 row_mask:0xf bank_mask:0xf
	v_mov_b32_dpp v165, v93 row_ror:1 row_mask:0xf bank_mask:0xf bound_ctrl:1
	v_mov_b32_dpp v157, v89 row_ror:1 row_mask:0xf bank_mask:0xf bound_ctrl:1
	v_mov_b32_dpp v167, v93 row_ror:2 row_mask:0xf bank_mask:0xf bound_ctrl:1
	v_mov_b32_dpp v161, v89 row_ror:2 row_mask:0xf bank_mask:0xf bound_ctrl:1
	v_mov_b32_dpp v101, v94 row_shr:1 row_mask:0xf bank_mask:0xf
	v_mov_b32_dpp v170, v94 row_shr:2 row_mask:0xf bank_mask:0xf
	v_mov_b32_dpp v97, v90 row_shr:1 row_mask:0xf bank_mask:0xf
	v_mov_b32_dpp v168, v90 row_shr:2 row_mask:0xf bank_mask:0xf
	v_mov_b32_dpp v158, v94 row_ror:1 row_mask:0xf bank_mask:0xf bound_ctrl:1
	v_mov_b32_dpp v150, v90 row_ror:1 row_mask:0xf bank_mask:0xf bound_ctrl:1
	v_mov_b32_dpp v162, v94 row_ror:2 row_mask:0xf bank_mask:0xf bound_ctrl:1
	v_mov_b32_dpp v154, v90 row_ror:2 row_mask:0xf bank_mask:0xf bound_ctrl:1
	v_mov_b32_dpp v103, v95 row_shr:1 row_mask:0xf bank_mask:0xf
	v_mov_b32_dpp v171, v95 row_shr:2 row_mask:0xf bank_mask:0xf
	v_mov_b32_dpp v99, v91 row_shr:1 row_mask:0xf bank_mask:0xf
	v_mov_b32_dpp v169, v91 row_shr:2 row_mask:0xf bank_mask:0xf
	v_mov_b32_dpp v159, v95 row_ror:1 row_mask:0xf bank_mask:0xf bound_ctrl:1
	v_mov_b32_dpp v151, v91 row_ror:1 row_mask:0xf bank_mask:0xf bound_ctrl:1
	v_mov_b32_dpp v163, v95 row_ror:2 row_mask:0xf bank_mask:0xf bound_ctrl:1
	v_mov_b32_dpp v155, v91 row_ror:2 row_mask:0xf bank_mask:0xf bound_ctrl:1
	s_and_b64 s[84:85], s[14:15], vcc
	v_ashrrev_i32_e32 v145, 31, v144
	s_and_saveexec_b64 s[86:87], s[84:85]
	s_cbranch_execz .LBB0_1266
	v_mov_b32_e32 v142, v141
	v_pk_fma_f32 v[140:141], v[120:121], v[174:175], v[132:133]
	v_mov_b32_e32 v138, v137
	v_pk_fma_f32 v[140:141], v[124:125], v[142:143], v[140:141]
	v_mov_b32_e32 v102, v101
	v_pk_fma_f32 v[92:93], v[92:93], v[128:129], v[140:141]
	v_pk_fma_f32 v[140:141], v[104:105], v[172:173], v[116:117]
	v_mul_f32_e32 v96, 0x3d372713, v92
	v_fma_f32 v96, v92, v96, 1.0
	v_mul_f32_e32 v98, 0x3d372713, v93
	v_mul_f32_e32 v96, v92, v96
	v_fma_f32 v98, v93, v98, 1.0
	v_mul_f32_e32 v96, 0x40135761, v96
	v_mul_f32_e32 v98, v93, v98
	v_exp_f32_e32 v96, v96
	v_mul_f32_e32 v98, 0x40135761, v98
	v_exp_f32_e32 v98, v98
	v_pk_fma_f32 v[138:139], v[108:109], v[138:139], v[140:141]
	v_add_f32_e32 v96, 1.0, v96
	v_rcp_f32_e32 v136, v96
	v_add_f32_e32 v96, 1.0, v98
	v_rcp_f32_e32 v137, v96
	v_pk_fma_f32 v[88:89], v[88:89], v[112:113], v[138:139]
	v_mov_b32_e32 v98, v97
	v_pk_fma_f32 v[96:97], v[106:107], v[168:169], v[118:119]
	v_pk_fma_f32 v[92:93], v[92:93], v[136:137], v[92:93] neg_lo:[1,0,0] neg_hi:[1,0,0]
	v_pk_fma_f32 v[96:97], v[110:111], v[98:99], v[96:97]
	v_pk_mul_f32 v[88:89], v[88:89], v[92:93]
	v_pk_fma_f32 v[92:93], v[122:123], v[170:171], v[134:135]
	v_pk_fma_f32 v[90:91], v[90:91], v[114:115], v[96:97]
	v_pk_fma_f32 v[92:93], v[126:127], v[102:103], v[92:93]
	v_cvt_pk_bf16_f32 v88, v88, v89
	v_pk_fma_f32 v[92:93], v[94:95], v[130:131], v[92:93]
	s_nop 0
	v_mul_f32_e32 v94, 0x3d372713, v92
	v_mul_f32_e32 v95, 0x3d372713, v93
	v_fma_f32 v94, v92, v94, 1.0
	v_fma_f32 v95, v93, v95, 1.0
	v_mul_f32_e32 v94, v92, v94
	v_mul_f32_e32 v95, v93, v95
	v_mul_f32_e32 v94, 0x40135761, v94
	v_mul_f32_e32 v95, 0x40135761, v95
	v_exp_f32_e32 v94, v94
	v_exp_f32_e32 v95, v95
	v_add_f32_e32 v94, 1.0, v94
	v_add_f32_e32 v95, 1.0, v95
	v_rcp_f32_e32 v94, v94
	v_rcp_f32_e32 v95, v95
	s_nop 0
	v_pk_fma_f32 v[92:93], v[92:93], v[94:95], v[92:93] neg_lo:[1,0,0] neg_hi:[1,0,0]
	s_nop 0
	v_pk_mul_f32 v[90:91], v[90:91], v[92:93]
	v_mov_b64_e32 v[92:93], s[44:45]
	v_cvt_pk_bf16_f32 v89, v90, v91
	v_lshl_add_u64 v[90:91], s[72:73], 0, v[144:145]
	v_mad_u64_u32 v[92:93], s[88:89], v90, s1, v[92:93]
	v_mad_i32_i24 v93, v91, s1, v93
	v_lshl_add_u64 v[90:91], v[192:193], 1, v[92:93]
	global_store_dwordx2 v[90:91], v[88:89], off
.LBB0_1266:
	s_or_b64 exec, exec, s[86:87]
	v_cmp_gt_u32_e32 vcc, s39, v233
	v_add_u32_e32 v136, 0x90, v194
	v_mov_b32_dpp v164, v84 row_shr:1 row_mask:0xf bank_mask:0xf
	v_mov_b32_dpp v166, v84 row_shr:2 row_mask:0xf bank_mask:0xf
	v_mov_b32_dpp v156, v80 row_shr:1 row_mask:0xf bank_mask:0xf
	v_mov_b32_dpp v160, v80 row_shr:2 row_mask:0xf bank_mask:0xf
	v_mov_b32_dpp v140, v84 row_ror:1 row_mask:0xf bank_mask:0xf bound_ctrl:1
	v_mov_b32_dpp v92, v80 row_ror:1 row_mask:0xf bank_mask:0xf bound_ctrl:1
	v_mov_b32_dpp v142, v84 row_ror:2 row_mask:0xf bank_mask:0xf bound_ctrl:1
	v_mov_b32_dpp v96, v80 row_ror:2 row_mask:0xf bank_mask:0xf bound_ctrl:1
	v_mov_b32_dpp v165, v85 row_shr:1 row_mask:0xf bank_mask:0xf
	v_mov_b32_dpp v167, v85 row_shr:2 row_mask:0xf bank_mask:0xf
	v_mov_b32_dpp v157, v81 row_shr:1 row_mask:0xf bank_mask:0xf
	v_mov_b32_dpp v161, v81 row_shr:2 row_mask:0xf bank_mask:0xf
	v_mov_b32_dpp v141, v85 row_ror:1 row_mask:0xf bank_mask:0xf bound_ctrl:1
	v_mov_b32_dpp v93, v81 row_ror:1 row_mask:0xf bank_mask:0xf bound_ctrl:1
	v_mov_b32_dpp v143, v85 row_ror:2 row_mask:0xf bank_mask:0xf bound_ctrl:1
	v_mov_b32_dpp v97, v81 row_ror:2 row_mask:0xf bank_mask:0xf bound_ctrl:1
	v_mov_b32_dpp v158, v86 row_shr:1 row_mask:0xf bank_mask:0xf
	v_mov_b32_dpp v162, v86 row_shr:2 row_mask:0xf bank_mask:0xf
	v_mov_b32_dpp v150, v82 row_shr:1 row_mask:0xf bank_mask:0xf
	v_mov_b32_dpp v154, v82 row_shr:2 row_mask:0xf bank_mask:0xf
	v_mov_b32_dpp v94, v86 row_ror:1 row_mask:0xf bank_mask:0xf bound_ctrl:1
	v_mov_b32_dpp v88, v82 row_ror:1 row_mask:0xf bank_mask:0xf bound_ctrl:1
	v_mov_b32_dpp v98, v86 row_ror:2 row_mask:0xf bank_mask:0xf bound_ctrl:1
	v_mov_b32_dpp v90, v82 row_ror:2 row_mask:0xf bank_mask:0xf bound_ctrl:1
	v_mov_b32_dpp v159, v87 row_shr:1 row_mask:0xf bank_mask:0xf
	v_mov_b32_dpp v163, v87 row_shr:2 row_mask:0xf bank_mask:0xf
	v_mov_b32_dpp v151, v83 row_shr:1 row_mask:0xf bank_mask:0xf
	v_mov_b32_dpp v155, v83 row_shr:2 row_mask:0xf bank_mask:0xf
	v_mov_b32_dpp v95, v87 row_ror:1 row_mask:0xf bank_mask:0xf bound_ctrl:1
	v_mov_b32_dpp v89, v83 row_ror:1 row_mask:0xf bank_mask:0xf bound_ctrl:1
	v_mov_b32_dpp v99, v87 row_ror:2 row_mask:0xf bank_mask:0xf bound_ctrl:1
	v_mov_b32_dpp v91, v83 row_ror:2 row_mask:0xf bank_mask:0xf bound_ctrl:1
	s_and_b64 s[86:87], s[16:17], vcc
	v_ashrrev_i32_e32 v137, 31, v136
	s_and_saveexec_b64 s[88:89], s[86:87]
	s_cbranch_execz .LBB0_1268
	v_pk_fma_f32 v[100:101], v[120:121], v[166:167], v[132:133]
	v_pk_fma_f32 v[102:103], v[104:105], v[160:161], v[116:117]
	v_pk_fma_f32 v[100:101], v[124:125], v[164:165], v[100:101]
	v_pk_fma_f32 v[102:103], v[108:109], v[156:157], v[102:103]
	v_pk_fma_f32 v[84:85], v[84:85], v[128:129], v[100:101]
	v_pk_fma_f32 v[80:81], v[80:81], v[112:113], v[102:103]
	v_mul_f32_e32 v100, 0x3d372713, v84
	v_mul_f32_e32 v101, 0x3d372713, v85
	v_fma_f32 v100, v84, v100, 1.0
	v_fma_f32 v101, v85, v101, 1.0
	v_mul_f32_e32 v100, v84, v100
	v_mul_f32_e32 v101, v85, v101
	v_mul_f32_e32 v100, 0x40135761, v100
	v_mul_f32_e32 v101, 0x40135761, v101
	v_exp_f32_e32 v100, v100
	v_exp_f32_e32 v101, v101
	v_add_f32_e32 v100, 1.0, v100
	v_add_f32_e32 v101, 1.0, v101
	v_rcp_f32_e32 v100, v100
	v_rcp_f32_e32 v101, v101
	s_nop 0
	v_pk_fma_f32 v[84:85], v[84:85], v[100:101], v[84:85] neg_lo:[1,0,0] neg_hi:[1,0,0]
	v_pk_fma_f32 v[100:101], v[122:123], v[162:163], v[134:135]
	v_pk_mul_f32 v[80:81], v[80:81], v[84:85]
	v_pk_fma_f32 v[100:101], v[126:127], v[158:159], v[100:101]
	v_cvt_pk_bf16_f32 v80, v80, v81
	v_pk_fma_f32 v[86:87], v[86:87], v[130:131], v[100:101]
	s_nop 0
	v_mul_f32_e32 v100, 0x3d372713, v86
	v_mul_f32_e32 v101, 0x3d372713, v87
	v_fma_f32 v100, v86, v100, 1.0
	v_fma_f32 v101, v87, v101, 1.0
	v_mul_f32_e32 v100, v86, v100
	v_mul_f32_e32 v101, v87, v101
	v_mul_f32_e32 v100, 0x40135761, v100
	v_mul_f32_e32 v101, 0x40135761, v101
	v_exp_f32_e32 v100, v100
	v_exp_f32_e32 v101, v101
	v_add_f32_e32 v84, 1.0, v100
	v_add_f32_e32 v85, 1.0, v101
	v_rcp_f32_e32 v84, v84
	v_rcp_f32_e32 v85, v85
	v_pk_fma_f32 v[100:101], v[106:107], v[154:155], v[118:119]
	v_pk_fma_f32 v[84:85], v[86:87], v[84:85], v[86:87] neg_lo:[1,0,0] neg_hi:[1,0,0]
	v_pk_fma_f32 v[100:101], v[110:111], v[150:151], v[100:101]
	s_nop 0
	v_pk_fma_f32 v[82:83], v[82:83], v[114:115], v[100:101]
	s_nop 0
	v_pk_mul_f32 v[82:83], v[82:83], v[84:85]
	v_mov_b64_e32 v[84:85], s[44:45]
	v_cvt_pk_bf16_f32 v81, v82, v83
	v_lshl_add_u64 v[82:83], s[72:73], 0, v[136:137]
	v_mad_u64_u32 v[84:85], s[90:91], v82, s1, v[84:85]
	v_mad_i32_i24 v85, v83, s1, v85
	v_lshl_add_u64 v[82:83], v[192:193], 1, v[84:85]
	global_store_dwordx2 v[82:83], v[80:81], off
.LBB0_1268:
	s_or_b64 exec, exec, s[88:89]
	v_cmp_gt_u32_e32 vcc, s39, v234
	v_add_u32_e32 v138, 0xa0, v194
	v_mov_b32_dpp v140, v76 row_shr:1 row_mask:0xf bank_mask:0xf
	v_mov_b32_dpp v142, v76 row_shr:2 row_mask:0xf bank_mask:0xf
	v_mov_b32_dpp v92, v72 row_shr:1 row_mask:0xf bank_mask:0xf
	v_mov_b32_dpp v96, v72 row_shr:2 row_mask:0xf bank_mask:0xf
	v_mov_b32_dpp v150, v76 row_ror:1 row_mask:0xf bank_mask:0xf bound_ctrl:1
	v_mov_b32_dpp v84, v72 row_ror:1 row_mask:0xf bank_mask:0xf bound_ctrl:1
	v_mov_b32_dpp v154, v76 row_ror:2 row_mask:0xf bank_mask:0xf bound_ctrl:1
	v_mov_b32_dpp v100, v72 row_ror:2 row_mask:0xf bank_mask:0xf bound_ctrl:1
	v_mov_b32_dpp v141, v77 row_shr:1 row_mask:0xf bank_mask:0xf
	v_mov_b32_dpp v143, v77 row_shr:2 row_mask:0xf bank_mask:0xf
	v_mov_b32_dpp v93, v73 row_shr:1 row_mask:0xf bank_mask:0xf
	v_mov_b32_dpp v97, v73 row_shr:2 row_mask:0xf bank_mask:0xf
	v_mov_b32_dpp v151, v77 row_ror:1 row_mask:0xf bank_mask:0xf bound_ctrl:1
	v_mov_b32_dpp v85, v73 row_ror:1 row_mask:0xf bank_mask:0xf bound_ctrl:1
	v_mov_b32_dpp v155, v77 row_ror:2 row_mask:0xf bank_mask:0xf bound_ctrl:1
	v_mov_b32_dpp v101, v73 row_ror:2 row_mask:0xf bank_mask:0xf bound_ctrl:1
	v_mov_b32_dpp v94, v78 row_shr:1 row_mask:0xf bank_mask:0xf
	v_mov_b32_dpp v98, v78 row_shr:2 row_mask:0xf bank_mask:0xf
	v_mov_b32_dpp v88, v74 row_shr:1 row_mask:0xf bank_mask:0xf
	v_mov_b32_dpp v90, v74 row_shr:2 row_mask:0xf bank_mask:0xf
	v_mov_b32_dpp v86, v78 row_ror:1 row_mask:0xf bank_mask:0xf bound_ctrl:1
	v_mov_b32_dpp v80, v74 row_ror:1 row_mask:0xf bank_mask:0xf bound_ctrl:1
	v_mov_b32_dpp v102, v78 row_ror:2 row_mask:0xf bank_mask:0xf bound_ctrl:1
	v_mov_b32_dpp v82, v74 row_ror:2 row_mask:0xf bank_mask:0xf bound_ctrl:1
	v_mov_b32_dpp v95, v79 row_shr:1 row_mask:0xf bank_mask:0xf
	v_mov_b32_dpp v99, v79 row_shr:2 row_mask:0xf bank_mask:0xf
	v_mov_b32_dpp v89, v75 row_shr:1 row_mask:0xf bank_mask:0xf
	v_mov_b32_dpp v91, v75 row_shr:2 row_mask:0xf bank_mask:0xf
	v_mov_b32_dpp v87, v79 row_ror:1 row_mask:0xf bank_mask:0xf bound_ctrl:1
	v_mov_b32_dpp v81, v75 row_ror:1 row_mask:0xf bank_mask:0xf bound_ctrl:1
	v_mov_b32_dpp v103, v79 row_ror:2 row_mask:0xf bank_mask:0xf bound_ctrl:1
	v_mov_b32_dpp v83, v75 row_ror:2 row_mask:0xf bank_mask:0xf bound_ctrl:1
	s_and_b64 s[88:89], s[18:19], vcc
	v_ashrrev_i32_e32 v139, 31, v138
	s_and_saveexec_b64 s[90:91], s[88:89]
	s_cbranch_execz .LBB0_1270
	v_pk_fma_f32 v[142:143], v[120:121], v[142:143], v[132:133]
	v_pk_fma_f32 v[96:97], v[104:105], v[96:97], v[116:117]
	v_pk_fma_f32 v[140:141], v[124:125], v[140:141], v[142:143]
	v_pk_fma_f32 v[92:93], v[108:109], v[92:93], v[96:97]
	v_pk_fma_f32 v[76:77], v[76:77], v[128:129], v[140:141]
	v_pk_fma_f32 v[72:73], v[72:73], v[112:113], v[92:93]
	v_mul_f32_e32 v140, 0x3d372713, v76
	v_mul_f32_e32 v141, 0x3d372713, v77
	v_fma_f32 v140, v76, v140, 1.0
	v_fma_f32 v141, v77, v141, 1.0
	v_mul_f32_e32 v140, v76, v140
	v_mul_f32_e32 v141, v77, v141
	v_mul_f32_e32 v140, 0x40135761, v140
	v_mul_f32_e32 v141, 0x40135761, v141
	v_pk_fma_f32 v[92:93], v[122:123], v[98:99], v[134:135]
	v_exp_f32_e32 v140, v140
	v_exp_f32_e32 v141, v141
	v_pk_fma_f32 v[92:93], v[126:127], v[94:95], v[92:93]
	v_pk_fma_f32 v[90:91], v[106:107], v[90:91], v[118:119]
	v_pk_fma_f32 v[78:79], v[78:79], v[130:131], v[92:93]
	v_add_f32_e32 v140, 1.0, v140
	v_mul_f32_e32 v92, 0x3d372713, v78
	v_mul_f32_e32 v93, 0x3d372713, v79
	v_fma_f32 v92, v78, v92, 1.0
	v_fma_f32 v93, v79, v93, 1.0
	v_add_f32_e32 v141, 1.0, v141
	v_mul_f32_e32 v92, v78, v92
	v_mul_f32_e32 v93, v79, v93
	v_rcp_f32_e32 v140, v140
	v_rcp_f32_e32 v141, v141
	v_mul_f32_e32 v92, 0x40135761, v92
	v_mul_f32_e32 v93, 0x40135761, v93
	v_exp_f32_e32 v92, v92
	v_exp_f32_e32 v93, v93
	v_pk_fma_f32 v[76:77], v[76:77], v[140:141], v[76:77] neg_lo:[1,0,0] neg_hi:[1,0,0]
	v_pk_fma_f32 v[88:89], v[110:111], v[88:89], v[90:91]
	v_pk_mul_f32 v[72:73], v[72:73], v[76:77]
	v_add_f32_e32 v76, 1.0, v92
	v_add_f32_e32 v77, 1.0, v93
	v_rcp_f32_e32 v76, v76
	v_rcp_f32_e32 v77, v77
	v_pk_fma_f32 v[74:75], v[74:75], v[114:115], v[88:89]
	v_cvt_pk_bf16_f32 v72, v72, v73
	v_pk_fma_f32 v[76:77], v[78:79], v[76:77], v[78:79] neg_lo:[1,0,0] neg_hi:[1,0,0]
	s_nop 0
	v_pk_mul_f32 v[74:75], v[74:75], v[76:77]
	v_mov_b64_e32 v[76:77], s[44:45]
	v_cvt_pk_bf16_f32 v73, v74, v75
	v_lshl_add_u64 v[74:75], s[72:73], 0, v[138:139]
	v_mad_u64_u32 v[76:77], s[92:93], v74, s1, v[76:77]
	v_mad_i32_i24 v77, v75, s1, v77
	v_lshl_add_u64 v[74:75], v[192:193], 1, v[76:77]
	global_store_dwordx2 v[74:75], v[72:73], off
.LBB0_1270:
	s_or_b64 exec, exec, s[90:91]
	v_cmp_gt_u32_e32 vcc, s39, v235
	v_add_u32_e32 v140, 0xb0, v194
	v_mov_b32_dpp v150, v68 row_shr:1 row_mask:0xf bank_mask:0xf
	v_mov_b32_dpp v154, v68 row_shr:2 row_mask:0xf bank_mask:0xf
	v_mov_b32_dpp v84, v64 row_shr:1 row_mask:0xf bank_mask:0xf
	v_mov_b32_dpp v100, v64 row_shr:2 row_mask:0xf bank_mask:0xf
	v_mov_b32_dpp v151, v69 row_shr:1 row_mask:0xf bank_mask:0xf
	v_mov_b32_dpp v155, v69 row_shr:2 row_mask:0xf bank_mask:0xf
	v_mov_b32_dpp v85, v65 row_shr:1 row_mask:0xf bank_mask:0xf
	v_mov_b32_dpp v101, v65 row_shr:2 row_mask:0xf bank_mask:0xf
	v_mov_b32_dpp v86, v70 row_shr:1 row_mask:0xf bank_mask:0xf
	v_mov_b32_dpp v102, v70 row_shr:2 row_mask:0xf bank_mask:0xf
	v_mov_b32_dpp v80, v66 row_shr:1 row_mask:0xf bank_mask:0xf
	v_mov_b32_dpp v82, v66 row_shr:2 row_mask:0xf bank_mask:0xf
	v_mov_b32_dpp v87, v71 row_shr:1 row_mask:0xf bank_mask:0xf
	v_mov_b32_dpp v103, v71 row_shr:2 row_mask:0xf bank_mask:0xf
	v_mov_b32_dpp v81, v67 row_shr:1 row_mask:0xf bank_mask:0xf
	v_mov_b32_dpp v83, v67 row_shr:2 row_mask:0xf bank_mask:0xf
	s_and_b64 s[90:91], s[20:21], vcc
	v_ashrrev_i32_e32 v141, 31, v140
	s_and_saveexec_b64 s[92:93], s[90:91]
	s_cbranch_execz .LBB0_1272
	v_pk_fma_f32 v[72:73], v[120:121], v[154:155], v[132:133]
	v_pk_fma_f32 v[74:75], v[104:105], v[100:101], v[116:117]
	v_pk_fma_f32 v[72:73], v[124:125], v[150:151], v[72:73]
	v_pk_fma_f32 v[74:75], v[108:109], v[84:85], v[74:75]
	v_pk_fma_f32 v[68:69], v[68:69], v[128:129], v[72:73]
	v_pk_fma_f32 v[64:65], v[64:65], v[112:113], v[74:75]
	v_mul_f32_e32 v72, 0x3d372713, v68
	v_mul_f32_e32 v73, 0x3d372713, v69
	v_fma_f32 v72, v68, v72, 1.0
	v_fma_f32 v73, v69, v73, 1.0
	v_mul_f32_e32 v72, v68, v72
	v_mul_f32_e32 v73, v69, v73
	v_mul_f32_e32 v72, 0x40135761, v72
	v_mul_f32_e32 v73, 0x40135761, v73
	v_exp_f32_e32 v72, v72
	v_exp_f32_e32 v73, v73
	v_add_f32_e32 v72, 1.0, v72
	v_add_f32_e32 v73, 1.0, v73
	v_rcp_f32_e32 v72, v72
	v_rcp_f32_e32 v73, v73
	s_nop 0
	v_pk_fma_f32 v[68:69], v[68:69], v[72:73], v[68:69] neg_lo:[1,0,0] neg_hi:[1,0,0]
	v_pk_fma_f32 v[72:73], v[122:123], v[102:103], v[134:135]
	v_pk_mul_f32 v[64:65], v[64:65], v[68:69]
	v_pk_fma_f32 v[72:73], v[126:127], v[86:87], v[72:73]
	v_cvt_pk_bf16_f32 v64, v64, v65
	v_pk_fma_f32 v[70:71], v[70:71], v[130:131], v[72:73]
	s_nop 0
	v_mul_f32_e32 v72, 0x3d372713, v70
	v_mul_f32_e32 v73, 0x3d372713, v71
	v_fma_f32 v72, v70, v72, 1.0
	v_fma_f32 v73, v71, v73, 1.0
	v_mul_f32_e32 v72, v70, v72
	v_mul_f32_e32 v73, v71, v73
	v_mul_f32_e32 v72, 0x40135761, v72
	v_mul_f32_e32 v73, 0x40135761, v73
	v_exp_f32_e32 v72, v72
	v_exp_f32_e32 v73, v73
	v_add_f32_e32 v68, 1.0, v72
	v_add_f32_e32 v69, 1.0, v73
	v_rcp_f32_e32 v68, v68
	v_rcp_f32_e32 v69, v69
	v_pk_fma_f32 v[72:73], v[106:107], v[82:83], v[118:119]
	v_pk_fma_f32 v[68:69], v[70:71], v[68:69], v[70:71] neg_lo:[1,0,0] neg_hi:[1,0,0]
	v_pk_fma_f32 v[72:73], v[110:111], v[80:81], v[72:73]
	s_nop 0
	v_pk_fma_f32 v[66:67], v[66:67], v[114:115], v[72:73]
	s_nop 0
	v_pk_mul_f32 v[66:67], v[66:67], v[68:69]
	v_mov_b64_e32 v[68:69], s[44:45]
	v_cvt_pk_bf16_f32 v65, v66, v67
	v_lshl_add_u64 v[66:67], s[72:73], 0, v[140:141]
	v_mad_u64_u32 v[68:69], vcc, v66, s1, v[68:69]
	v_mad_i32_i24 v69, v67, s1, v69
	v_lshl_add_u64 v[66:67], v[192:193], 1, v[68:69]
	global_store_dwordx2 v[66:67], v[64:65], off

.LBB0_1276:
	s_or_b64 exec, exec, s[24:25]
	v_mov_b32_dpp v120, v52 row_shr:1 row_mask:0xf bank_mask:0xf
	v_mov_b32_dpp v122, v52 row_shr:2 row_mask:0xf bank_mask:0xf
	v_mov_b32_dpp v112, v48 row_shr:1 row_mask:0xf bank_mask:0xf
	v_mov_b32_dpp v116, v48 row_shr:2 row_mask:0xf bank_mask:0xf
	v_mov_b32_dpp v104, v52 row_ror:1 row_mask:0xf bank_mask:0xf bound_ctrl:1
	v_mov_b32_dpp v96, v48 row_ror:1 row_mask:0xf bank_mask:0xf bound_ctrl:1
	v_mov_b32_dpp v106, v52 row_ror:2 row_mask:0xf bank_mask:0xf bound_ctrl:1
	v_mov_b32_dpp v100, v48 row_ror:2 row_mask:0xf bank_mask:0xf bound_ctrl:1
	v_mov_b32_dpp v121, v53 row_shr:1 row_mask:0xf bank_mask:0xf
	v_mov_b32_dpp v123, v53 row_shr:2 row_mask:0xf bank_mask:0xf
	v_mov_b32_dpp v113, v49 row_shr:1 row_mask:0xf bank_mask:0xf
	v_mov_b32_dpp v117, v49 row_shr:2 row_mask:0xf bank_mask:0xf
	v_mov_b32_dpp v105, v53 row_ror:1 row_mask:0xf bank_mask:0xf bound_ctrl:1
	v_mov_b32_dpp v97, v49 row_ror:1 row_mask:0xf bank_mask:0xf bound_ctrl:1
	v_mov_b32_dpp v107, v53 row_ror:2 row_mask:0xf bank_mask:0xf bound_ctrl:1
	v_mov_b32_dpp v101, v49 row_ror:2 row_mask:0xf bank_mask:0xf bound_ctrl:1
	v_mov_b32_dpp v114, v54 row_shr:1 row_mask:0xf bank_mask:0xf
	v_mov_b32_dpp v118, v54 row_shr:2 row_mask:0xf bank_mask:0xf
	v_mov_b32_dpp v56, v50 row_shr:1 row_mask:0xf bank_mask:0xf
	v_mov_b32_dpp v58, v50 row_shr:2 row_mask:0xf bank_mask:0xf
	v_mov_b32_dpp v98, v54 row_ror:1 row_mask:0xf bank_mask:0xf bound_ctrl:1
	v_mov_b32_dpp v60, v50 row_ror:1 row_mask:0xf bank_mask:0xf bound_ctrl:1
	v_mov_b32_dpp v102, v54 row_ror:2 row_mask:0xf bank_mask:0xf bound_ctrl:1
	v_mov_b32_dpp v62, v50 row_ror:2 row_mask:0xf bank_mask:0xf bound_ctrl:1
	v_mov_b32_dpp v115, v55 row_shr:1 row_mask:0xf bank_mask:0xf
	v_mov_b32_dpp v119, v55 row_shr:2 row_mask:0xf bank_mask:0xf
	v_mov_b32_dpp v57, v51 row_shr:1 row_mask:0xf bank_mask:0xf
	v_mov_b32_dpp v59, v51 row_shr:2 row_mask:0xf bank_mask:0xf
	v_mov_b32_dpp v99, v55 row_ror:1 row_mask:0xf bank_mask:0xf bound_ctrl:1
	v_mov_b32_dpp v61, v51 row_ror:1 row_mask:0xf bank_mask:0xf bound_ctrl:1
	v_mov_b32_dpp v103, v55 row_ror:2 row_mask:0xf bank_mask:0xf bound_ctrl:1
	v_mov_b32_dpp v63, v51 row_ror:2 row_mask:0xf bank_mask:0xf bound_ctrl:1
	s_and_saveexec_b64 s[24:25], s[78:79]
	s_cbranch_execz .LBB0_1278
	v_pk_fma_f32 v[108:109], v[80:81], v[122:123], v[92:93]
	v_pk_fma_f32 v[110:111], v[64:65], v[116:117], v[76:77]
	v_pk_fma_f32 v[108:109], v[84:85], v[120:121], v[108:109]
	v_pk_fma_f32 v[110:111], v[68:69], v[112:113], v[110:111]
	v_pk_fma_f32 v[52:53], v[52:53], v[88:89], v[108:109]
	v_pk_fma_f32 v[48:49], v[48:49], v[72:73], v[110:111]
	v_mul_f32_e32 v108, 0x3d372713, v52
	v_mul_f32_e32 v109, 0x3d372713, v53
	v_fma_f32 v108, v52, v108, 1.0
	v_fma_f32 v109, v53, v109, 1.0
	v_mul_f32_e32 v108, v52, v108
	v_mul_f32_e32 v109, v53, v109
	v_mul_f32_e32 v108, 0x40135761, v108
	v_mul_f32_e32 v109, 0x40135761, v109
	v_exp_f32_e32 v108, v108
	v_exp_f32_e32 v109, v109
	v_pk_fma_f32 v[58:59], v[66:67], v[58:59], v[78:79]
	v_add_f32_e32 v108, 1.0, v108
	v_add_f32_e32 v109, 1.0, v109
	v_rcp_f32_e32 v108, v108
	v_rcp_f32_e32 v109, v109
	v_pk_fma_f32 v[56:57], v[70:71], v[56:57], v[58:59]
	v_pk_fma_f32 v[52:53], v[52:53], v[108:109], v[52:53] neg_lo:[1,0,0] neg_hi:[1,0,0]
	v_pk_fma_f32 v[108:109], v[82:83], v[118:119], v[94:95]
	v_pk_mul_f32 v[48:49], v[48:49], v[52:53]
	v_pk_fma_f32 v[108:109], v[86:87], v[114:115], v[108:109]
	v_pk_fma_f32 v[50:51], v[50:51], v[74:75], v[56:57]
	v_pk_fma_f32 v[54:55], v[54:55], v[90:91], v[108:109]
	v_cvt_pk_bf16_f32 v48, v48, v49
	v_mul_f32_e32 v108, 0x3d372713, v54
	v_mul_f32_e32 v109, 0x3d372713, v55
	v_fma_f32 v108, v54, v108, 1.0
	v_fma_f32 v109, v55, v109, 1.0
	v_mul_f32_e32 v108, v54, v108
	v_mul_f32_e32 v109, v55, v109
	v_mul_f32_e32 v108, 0x40135761, v108
	v_mul_f32_e32 v109, 0x40135761, v109
	v_exp_f32_e32 v108, v108
	v_exp_f32_e32 v109, v109
	v_add_f32_e32 v52, 1.0, v108
	v_add_f32_e32 v53, 1.0, v109
	v_rcp_f32_e32 v52, v52
	v_rcp_f32_e32 v53, v53
	s_nop 0
	v_pk_fma_f32 v[52:53], v[54:55], v[52:53], v[54:55] neg_lo:[1,0,0] neg_hi:[1,0,0]
	s_nop 0
	v_pk_mul_f32 v[50:51], v[50:51], v[52:53]
	v_mov_b64_e32 v[52:53], s[44:45]
	v_cvt_pk_bf16_f32 v49, v50, v51
	v_lshl_add_u64 v[50:51], s[72:73], 0, v[152:153]
	v_mad_u64_u32 v[52:53], s[74:75], v50, s1, v[52:53]
	v_mad_i32_i24 v53, v51, s1, v53
	v_lshl_add_u64 v[50:51], v[192:193], 1, v[52:53]
	global_store_dwordx2 v[50:51], v[48:49], off offset:8
.LBB0_1278:
	s_or_b64 exec, exec, s[24:25]
	v_mov_b32_dpp v104, v44 row_shr:1 row_mask:0xf bank_mask:0xf
	v_mov_b32_dpp v106, v44 row_shr:2 row_mask:0xf bank_mask:0xf
	v_mov_b32_dpp v96, v40 row_shr:1 row_mask:0xf bank_mask:0xf
	v_mov_b32_dpp v100, v40 row_shr:2 row_mask:0xf bank_mask:0xf
	v_mov_b32_dpp v108, v44 row_ror:1 row_mask:0xf bank_mask:0xf bound_ctrl:1
	v_mov_b32_dpp v52, v40 row_ror:1 row_mask:0xf bank_mask:0xf bound_ctrl:1
	v_mov_b32_dpp v110, v44 row_ror:2 row_mask:0xf bank_mask:0xf bound_ctrl:1
	v_mov_b32_dpp v56, v40 row_ror:2 row_mask:0xf bank_mask:0xf bound_ctrl:1
	v_mov_b32_dpp v105, v45 row_shr:1 row_mask:0xf bank_mask:0xf
	v_mov_b32_dpp v107, v45 row_shr:2 row_mask:0xf bank_mask:0xf
	v_mov_b32_dpp v97, v41 row_shr:1 row_mask:0xf bank_mask:0xf
	v_mov_b32_dpp v101, v41 row_shr:2 row_mask:0xf bank_mask:0xf
	v_mov_b32_dpp v109, v45 row_ror:1 row_mask:0xf bank_mask:0xf bound_ctrl:1
	v_mov_b32_dpp v53, v41 row_ror:1 row_mask:0xf bank_mask:0xf bound_ctrl:1
	v_mov_b32_dpp v111, v45 row_ror:2 row_mask:0xf bank_mask:0xf bound_ctrl:1
	v_mov_b32_dpp v57, v41 row_ror:2 row_mask:0xf bank_mask:0xf bound_ctrl:1
	v_mov_b32_dpp v98, v46 row_shr:1 row_mask:0xf bank_mask:0xf
	v_mov_b32_dpp v102, v46 row_shr:2 row_mask:0xf bank_mask:0xf
	v_mov_b32_dpp v60, v42 row_shr:1 row_mask:0xf bank_mask:0xf
	v_mov_b32_dpp v62, v42 row_shr:2 row_mask:0xf bank_mask:0xf
	v_mov_b32_dpp v54, v46 row_ror:1 row_mask:0xf bank_mask:0xf bound_ctrl:1
	v_mov_b32_dpp v48, v42 row_ror:1 row_mask:0xf bank_mask:0xf bound_ctrl:1
	v_mov_b32_dpp v58, v46 row_ror:2 row_mask:0xf bank_mask:0xf bound_ctrl:1
	v_mov_b32_dpp v50, v42 row_ror:2 row_mask:0xf bank_mask:0xf bound_ctrl:1
	v_mov_b32_dpp v99, v47 row_shr:1 row_mask:0xf bank_mask:0xf
	v_mov_b32_dpp v103, v47 row_shr:2 row_mask:0xf bank_mask:0xf
	v_mov_b32_dpp v61, v43 row_shr:1 row_mask:0xf bank_mask:0xf
	v_mov_b32_dpp v63, v43 row_shr:2 row_mask:0xf bank_mask:0xf
	v_mov_b32_dpp v55, v47 row_ror:1 row_mask:0xf bank_mask:0xf bound_ctrl:1
	v_mov_b32_dpp v49, v43 row_ror:1 row_mask:0xf bank_mask:0xf bound_ctrl:1
	v_mov_b32_dpp v59, v47 row_ror:2 row_mask:0xf bank_mask:0xf bound_ctrl:1
	v_mov_b32_dpp v51, v43 row_ror:2 row_mask:0xf bank_mask:0xf bound_ctrl:1
	s_and_saveexec_b64 s[24:25], s[80:81]
	s_cbranch_execz .LBB0_1280
	v_pk_fma_f32 v[106:107], v[80:81], v[106:107], v[92:93]
	v_pk_fma_f32 v[100:101], v[64:65], v[100:101], v[76:77]
	v_pk_fma_f32 v[104:105], v[84:85], v[104:105], v[106:107]
	v_pk_fma_f32 v[96:97], v[68:69], v[96:97], v[100:101]
	v_pk_fma_f32 v[44:45], v[44:45], v[88:89], v[104:105]
	v_pk_fma_f32 v[40:41], v[40:41], v[72:73], v[96:97]
	v_mul_f32_e32 v104, 0x3d372713, v44
	v_mul_f32_e32 v105, 0x3d372713, v45
	v_fma_f32 v104, v44, v104, 1.0
	v_fma_f32 v105, v45, v105, 1.0
	v_mul_f32_e32 v104, v44, v104
	v_mul_f32_e32 v105, v45, v105
	v_mul_f32_e32 v104, 0x40135761, v104
	v_mul_f32_e32 v105, 0x40135761, v105
	v_pk_fma_f32 v[96:97], v[82:83], v[102:103], v[94:95]
	v_exp_f32_e32 v104, v104
	v_exp_f32_e32 v105, v105
	v_pk_fma_f32 v[96:97], v[86:87], v[98:99], v[96:97]
	v_pk_fma_f32 v[62:63], v[66:67], v[62:63], v[78:79]
	v_pk_fma_f32 v[46:47], v[46:47], v[90:91], v[96:97]
	v_add_f32_e32 v104, 1.0, v104
	v_mul_f32_e32 v96, 0x3d372713, v46
	v_mul_f32_e32 v97, 0x3d372713, v47
	v_fma_f32 v96, v46, v96, 1.0
	v_fma_f32 v97, v47, v97, 1.0
	v_add_f32_e32 v105, 1.0, v105
	v_mul_f32_e32 v96, v46, v96
	v_mul_f32_e32 v97, v47, v97
	v_rcp_f32_e32 v104, v104
	v_rcp_f32_e32 v105, v105
	v_mul_f32_e32 v96, 0x40135761, v96
	v_mul_f32_e32 v97, 0x40135761, v97
	v_exp_f32_e32 v96, v96
	v_exp_f32_e32 v97, v97
	v_pk_fma_f32 v[44:45], v[44:45], v[104:105], v[44:45] neg_lo:[1,0,0] neg_hi:[1,0,0]
	v_pk_fma_f32 v[60:61], v[70:71], v[60:61], v[62:63]
	v_pk_mul_f32 v[40:41], v[40:41], v[44:45]
	v_add_f32_e32 v44, 1.0, v96
	v_add_f32_e32 v45, 1.0, v97
	v_rcp_f32_e32 v44, v44
	v_rcp_f32_e32 v45, v45
	v_pk_fma_f32 v[42:43], v[42:43], v[74:75], v[60:61]
	v_cvt_pk_bf16_f32 v40, v40, v41
	v_pk_fma_f32 v[44:45], v[46:47], v[44:45], v[46:47] neg_lo:[1,0,0] neg_hi:[1,0,0]
	s_nop 0
	v_pk_mul_f32 v[42:43], v[42:43], v[44:45]
	v_mov_b64_e32 v[44:45], s[44:45]
	v_cvt_pk_bf16_f32 v41, v42, v43
	v_lshl_add_u64 v[42:43], s[72:73], 0, v[146:147]
	v_mad_u64_u32 v[44:45], s[74:75], v42, s1, v[44:45]
	v_mad_i32_i24 v45, v43, s1, v45
	v_lshl_add_u64 v[42:43], v[192:193], 1, v[44:45]
	global_store_dwordx2 v[42:43], v[40:41], off offset:8
.LBB0_1280:
	s_or_b64 exec, exec, s[24:25]
	v_mov_b32_dpp v108, v36 row_shr:1 row_mask:0xf bank_mask:0xf
	v_mov_b32_dpp v110, v36 row_shr:2 row_mask:0xf bank_mask:0xf
	v_mov_b32_dpp v52, v32 row_shr:1 row_mask:0xf bank_mask:0xf
	v_mov_b32_dpp v56, v32 row_shr:2 row_mask:0xf bank_mask:0xf
	v_mov_b32_dpp v109, v37 row_shr:1 row_mask:0xf bank_mask:0xf
	v_mov_b32_dpp v111, v37 row_shr:2 row_mask:0xf bank_mask:0xf
	v_mov_b32_dpp v53, v33 row_shr:1 row_mask:0xf bank_mask:0xf
	v_mov_b32_dpp v57, v33 row_shr:2 row_mask:0xf bank_mask:0xf
	v_mov_b32_dpp v54, v38 row_shr:1 row_mask:0xf bank_mask:0xf
	v_mov_b32_dpp v58, v38 row_shr:2 row_mask:0xf bank_mask:0xf
	v_mov_b32_dpp v48, v34 row_shr:1 row_mask:0xf bank_mask:0xf
	v_mov_b32_dpp v50, v34 row_shr:2 row_mask:0xf bank_mask:0xf
	v_mov_b32_dpp v55, v39 row_shr:1 row_mask:0xf bank_mask:0xf
	v_mov_b32_dpp v59, v39 row_shr:2 row_mask:0xf bank_mask:0xf
	v_mov_b32_dpp v49, v35 row_shr:1 row_mask:0xf bank_mask:0xf
	v_mov_b32_dpp v51, v35 row_shr:2 row_mask:0xf bank_mask:0xf
	s_and_saveexec_b64 s[24:25], s[82:83]
	s_cbranch_execz .LBB0_1282
	v_pk_fma_f32 v[40:41], v[80:81], v[110:111], v[92:93]
	v_pk_fma_f32 v[42:43], v[64:65], v[56:57], v[76:77]
	v_pk_fma_f32 v[40:41], v[84:85], v[108:109], v[40:41]
	v_pk_fma_f32 v[42:43], v[68:69], v[52:53], v[42:43]
	v_pk_fma_f32 v[36:37], v[36:37], v[88:89], v[40:41]
	v_pk_fma_f32 v[32:33], v[32:33], v[72:73], v[42:43]
	v_mul_f32_e32 v40, 0x3d372713, v36
	v_mul_f32_e32 v41, 0x3d372713, v37
	v_fma_f32 v40, v36, v40, 1.0
	v_fma_f32 v41, v37, v41, 1.0
	v_mul_f32_e32 v40, v36, v40
	v_mul_f32_e32 v41, v37, v41
	v_mul_f32_e32 v40, 0x40135761, v40
	v_mul_f32_e32 v41, 0x40135761, v41
	v_exp_f32_e32 v40, v40
	v_exp_f32_e32 v41, v41
	v_add_f32_e32 v40, 1.0, v40
	v_add_f32_e32 v41, 1.0, v41
	v_rcp_f32_e32 v40, v40
	v_rcp_f32_e32 v41, v41
	s_nop 0
	v_pk_fma_f32 v[36:37], v[36:37], v[40:41], v[36:37] neg_lo:[1,0,0] neg_hi:[1,0,0]
	v_pk_fma_f32 v[40:41], v[82:83], v[58:59], v[94:95]
	v_pk_mul_f32 v[32:33], v[32:33], v[36:37]
	v_pk_fma_f32 v[40:41], v[86:87], v[54:55], v[40:41]
	v_cvt_pk_bf16_f32 v32, v32, v33
	v_pk_fma_f32 v[38:39], v[38:39], v[90:91], v[40:41]
	s_nop 0
	v_mul_f32_e32 v40, 0x3d372713, v38
	v_mul_f32_e32 v41, 0x3d372713, v39
	v_fma_f32 v40, v38, v40, 1.0
	v_fma_f32 v41, v39, v41, 1.0
	v_mul_f32_e32 v40, v38, v40
	v_mul_f32_e32 v41, v39, v41
	v_mul_f32_e32 v40, 0x40135761, v40
	v_mul_f32_e32 v41, 0x40135761, v41
	v_exp_f32_e32 v40, v40
	v_exp_f32_e32 v41, v41
	v_add_f32_e32 v36, 1.0, v40
	v_add_f32_e32 v37, 1.0, v41
	v_rcp_f32_e32 v36, v36
	v_rcp_f32_e32 v37, v37
	v_pk_fma_f32 v[40:41], v[66:67], v[50:51], v[78:79]
	v_pk_fma_f32 v[36:37], v[38:39], v[36:37], v[38:39] neg_lo:[1,0,0] neg_hi:[1,0,0]
	v_pk_fma_f32 v[40:41], v[70:71], v[48:49], v[40:41]
	s_nop 0
	v_pk_fma_f32 v[34:35], v[34:35], v[74:75], v[40:41]
	s_nop 0
	v_pk_mul_f32 v[34:35], v[34:35], v[36:37]
	v_mov_b64_e32 v[36:37], s[44:45]
	v_cvt_pk_bf16_f32 v33, v34, v35
	v_lshl_add_u64 v[34:35], s[72:73], 0, v[148:149]
	v_mad_u64_u32 v[36:37], s[74:75], v34, s1, v[36:37]
	v_mad_i32_i24 v37, v35, s1, v37
	v_lshl_add_u64 v[34:35], v[192:193], 1, v[36:37]
	global_store_dwordx2 v[34:35], v[32:33], off offset:8
.LBB0_1282:
	s_or_b64 exec, exec, s[24:25]
	v_add_u32_e32 v32, 0x1180, v241
	v_add_u32_e32 v36, 0x1080, v241
	ds_read2_b64 v[40:43], v32 offset1:1
	ds_read2_b64 v[44:47], v36 offset1:1
	v_add_u32_e32 v32, 0x1190, v241
	v_add_u32_e32 v36, 0x1090, v241
	ds_read2_b64 v[32:35], v32 offset1:1
	ds_read2_b64 v[36:39], v36 offset1:1
	s_waitcnt lgkmcnt(3)
	v_cndmask_b32_e64 v100, v41, v40, s[10:11]
	v_cndmask_b32_e64 v101, v43, v42, s[10:11]
	s_waitcnt lgkmcnt(2)
	v_cndmask_b32_e64 v102, v45, v44, s[10:11]
	s_waitcnt lgkmcnt(1)
	v_cndmask_b32_e64 v96, v33, v32, s[10:11]
	v_cndmask_b32_e64 v97, v35, v34, s[10:11]
	v_cndmask_b32_e64 v103, v47, v46, s[10:11]
	s_waitcnt lgkmcnt(0)
	v_cndmask_b32_e64 v98, v37, v36, s[10:11]
	v_cndmask_b32_e64 v99, v39, v38, s[10:11]
	v_mov_b32_dpp v45, v28 row_shr:1 row_mask:0xf bank_mask:0xf
	v_mov_b32_dpp v102, v28 row_shr:2 row_mask:0xf bank_mask:0xf
	v_mov_b32_dpp v41, v24 row_shr:1 row_mask:0xf bank_mask:0xf
	v_mov_b32_dpp v100, v24 row_shr:2 row_mask:0xf bank_mask:0xf
	v_mov_b32_dpp v60, v28 row_ror:1 row_mask:0xf bank_mask:0xf bound_ctrl:1
	v_mov_b32_dpp v52, v24 row_ror:1 row_mask:0xf bank_mask:0xf bound_ctrl:1
	v_mov_b32_dpp v62, v28 row_ror:2 row_mask:0xf bank_mask:0xf bound_ctrl:1
	v_mov_b32_dpp v56, v24 row_ror:2 row_mask:0xf bank_mask:0xf bound_ctrl:1
	v_mov_b32_dpp v47, v29 row_shr:1 row_mask:0xf bank_mask:0xf
	v_mov_b32_dpp v103, v29 row_shr:2 row_mask:0xf bank_mask:0xf
	v_mov_b32_dpp v43, v25 row_shr:1 row_mask:0xf bank_mask:0xf
	v_mov_b32_dpp v101, v25 row_shr:2 row_mask:0xf bank_mask:0xf
	v_mov_b32_dpp v61, v29 row_ror:1 row_mask:0xf bank_mask:0xf bound_ctrl:1
	v_mov_b32_dpp v53, v25 row_ror:1 row_mask:0xf bank_mask:0xf bound_ctrl:1
	v_mov_b32_dpp v63, v29 row_ror:2 row_mask:0xf bank_mask:0xf bound_ctrl:1
	v_mov_b32_dpp v57, v25 row_ror:2 row_mask:0xf bank_mask:0xf bound_ctrl:1
	v_mov_b32_dpp v37, v30 row_shr:1 row_mask:0xf bank_mask:0xf
	v_mov_b32_dpp v98, v30 row_shr:2 row_mask:0xf bank_mask:0xf
	v_mov_b32_dpp v33, v26 row_shr:1 row_mask:0xf bank_mask:0xf
	v_mov_b32_dpp v96, v26 row_shr:2 row_mask:0xf bank_mask:0xf
	v_mov_b32_dpp v54, v30 row_ror:1 row_mask:0xf bank_mask:0xf bound_ctrl:1
	v_mov_b32_dpp v48, v26 row_ror:1 row_mask:0xf bank_mask:0xf bound_ctrl:1
	v_mov_b32_dpp v58, v30 row_ror:2 row_mask:0xf bank_mask:0xf bound_ctrl:1
	v_mov_b32_dpp v50, v26 row_ror:2 row_mask:0xf bank_mask:0xf bound_ctrl:1
	v_mov_b32_dpp v39, v31 row_shr:1 row_mask:0xf bank_mask:0xf
	v_mov_b32_dpp v99, v31 row_shr:2 row_mask:0xf bank_mask:0xf
	v_mov_b32_dpp v35, v27 row_shr:1 row_mask:0xf bank_mask:0xf
	v_mov_b32_dpp v97, v27 row_shr:2 row_mask:0xf bank_mask:0xf
	v_mov_b32_dpp v55, v31 row_ror:1 row_mask:0xf bank_mask:0xf bound_ctrl:1
	v_mov_b32_dpp v49, v27 row_ror:1 row_mask:0xf bank_mask:0xf bound_ctrl:1
	v_mov_b32_dpp v59, v31 row_ror:2 row_mask:0xf bank_mask:0xf bound_ctrl:1
	v_mov_b32_dpp v51, v27 row_ror:2 row_mask:0xf bank_mask:0xf bound_ctrl:1
	s_and_saveexec_b64 s[24:25], s[84:85]
	s_cbranch_execz .LBB0_1284
	v_mov_b32_e32 v46, v45
	v_pk_fma_f32 v[44:45], v[80:81], v[102:103], v[92:93]
	v_mov_b32_e32 v42, v41
	v_pk_fma_f32 v[44:45], v[84:85], v[46:47], v[44:45]
	v_mov_b32_e32 v38, v37
	v_pk_fma_f32 v[28:29], v[28:29], v[88:89], v[44:45]
	v_pk_fma_f32 v[44:45], v[64:65], v[100:101], v[76:77]
	v_mul_f32_e32 v32, 0x3d372713, v28
	v_fma_f32 v32, v28, v32, 1.0
	v_mul_f32_e32 v34, 0x3d372713, v29
	v_mul_f32_e32 v32, v28, v32
	v_fma_f32 v34, v29, v34, 1.0
	v_mul_f32_e32 v32, 0x40135761, v32
	v_mul_f32_e32 v34, v29, v34
	v_exp_f32_e32 v32, v32
	v_mul_f32_e32 v34, 0x40135761, v34
	v_exp_f32_e32 v34, v34
	v_pk_fma_f32 v[42:43], v[68:69], v[42:43], v[44:45]
	v_add_f32_e32 v32, 1.0, v32
	v_rcp_f32_e32 v40, v32
	v_add_f32_e32 v32, 1.0, v34
	v_rcp_f32_e32 v41, v32
	v_pk_fma_f32 v[24:25], v[24:25], v[72:73], v[42:43]
	v_mov_b32_e32 v34, v33
	v_pk_fma_f32 v[32:33], v[66:67], v[96:97], v[78:79]
	v_pk_fma_f32 v[28:29], v[28:29], v[40:41], v[28:29] neg_lo:[1,0,0] neg_hi:[1,0,0]
	v_pk_fma_f32 v[32:33], v[70:71], v[34:35], v[32:33]
	v_pk_mul_f32 v[24:25], v[24:25], v[28:29]
	v_pk_fma_f32 v[28:29], v[82:83], v[98:99], v[94:95]
	v_pk_fma_f32 v[26:27], v[26:27], v[74:75], v[32:33]
	v_pk_fma_f32 v[28:29], v[86:87], v[38:39], v[28:29]
	v_cvt_pk_bf16_f32 v24, v24, v25
	v_pk_fma_f32 v[28:29], v[30:31], v[90:91], v[28:29]
	s_nop 0
	v_mul_f32_e32 v30, 0x3d372713, v28
	v_mul_f32_e32 v31, 0x3d372713, v29
	v_fma_f32 v30, v28, v30, 1.0
	v_fma_f32 v31, v29, v31, 1.0
	v_mul_f32_e32 v30, v28, v30
	v_mul_f32_e32 v31, v29, v31
	v_mul_f32_e32 v30, 0x40135761, v30
	v_mul_f32_e32 v31, 0x40135761, v31
	v_exp_f32_e32 v30, v30
	v_exp_f32_e32 v31, v31
	v_add_f32_e32 v30, 1.0, v30
	v_add_f32_e32 v31, 1.0, v31
	v_rcp_f32_e32 v30, v30
	v_rcp_f32_e32 v31, v31
	s_nop 0
	v_pk_fma_f32 v[28:29], v[28:29], v[30:31], v[28:29] neg_lo:[1,0,0] neg_hi:[1,0,0]
	s_nop 0
	v_pk_mul_f32 v[26:27], v[26:27], v[28:29]
	v_mov_b64_e32 v[28:29], s[44:45]
	v_cvt_pk_bf16_f32 v25, v26, v27
	v_lshl_add_u64 v[26:27], s[72:73], 0, v[144:145]
	v_mad_u64_u32 v[28:29], s[74:75], v26, s1, v[28:29]
	v_mad_i32_i24 v29, v27, s1, v29
	v_lshl_add_u64 v[26:27], v[192:193], 1, v[28:29]
	global_store_dwordx2 v[26:27], v[24:25], off offset:8
.LBB0_1284:
	s_or_b64 exec, exec, s[24:25]
	v_mov_b32_dpp v60, v20 row_shr:1 row_mask:0xf bank_mask:0xf
	v_mov_b32_dpp v62, v20 row_shr:2 row_mask:0xf bank_mask:0xf
	v_mov_b32_dpp v52, v16 row_shr:1 row_mask:0xf bank_mask:0xf
	v_mov_b32_dpp v56, v16 row_shr:2 row_mask:0xf bank_mask:0xf
	v_mov_b32_dpp v40, v20 row_ror:1 row_mask:0xf bank_mask:0xf bound_ctrl:1
	v_mov_b32_dpp v28, v16 row_ror:1 row_mask:0xf bank_mask:0xf bound_ctrl:1
	v_mov_b32_dpp v42, v20 row_ror:2 row_mask:0xf bank_mask:0xf bound_ctrl:1
	v_mov_b32_dpp v32, v16 row_ror:2 row_mask:0xf bank_mask:0xf bound_ctrl:1
	v_mov_b32_dpp v61, v21 row_shr:1 row_mask:0xf bank_mask:0xf
	v_mov_b32_dpp v63, v21 row_shr:2 row_mask:0xf bank_mask:0xf
	v_mov_b32_dpp v53, v17 row_shr:1 row_mask:0xf bank_mask:0xf
	v_mov_b32_dpp v57, v17 row_shr:2 row_mask:0xf bank_mask:0xf
	v_mov_b32_dpp v41, v21 row_ror:1 row_mask:0xf bank_mask:0xf bound_ctrl:1
	v_mov_b32_dpp v29, v17 row_ror:1 row_mask:0xf bank_mask:0xf bound_ctrl:1
	v_mov_b32_dpp v43, v21 row_ror:2 row_mask:0xf bank_mask:0xf bound_ctrl:1
	v_mov_b32_dpp v33, v17 row_ror:2 row_mask:0xf bank_mask:0xf bound_ctrl:1
	v_mov_b32_dpp v54, v22 row_shr:1 row_mask:0xf bank_mask:0xf
	v_mov_b32_dpp v58, v22 row_shr:2 row_mask:0xf bank_mask:0xf
	v_mov_b32_dpp v48, v18 row_shr:1 row_mask:0xf bank_mask:0xf
	v_mov_b32_dpp v50, v18 row_shr:2 row_mask:0xf bank_mask:0xf
	v_mov_b32_dpp v30, v22 row_ror:1 row_mask:0xf bank_mask:0xf bound_ctrl:1
	v_mov_b32_dpp v24, v18 row_ror:1 row_mask:0xf bank_mask:0xf bound_ctrl:1
	v_mov_b32_dpp v34, v22 row_ror:2 row_mask:0xf bank_mask:0xf bound_ctrl:1
	v_mov_b32_dpp v26, v18 row_ror:2 row_mask:0xf bank_mask:0xf bound_ctrl:1
	v_mov_b32_dpp v55, v23 row_shr:1 row_mask:0xf bank_mask:0xf
	v_mov_b32_dpp v59, v23 row_shr:2 row_mask:0xf bank_mask:0xf
	v_mov_b32_dpp v49, v19 row_shr:1 row_mask:0xf bank_mask:0xf
	v_mov_b32_dpp v51, v19 row_shr:2 row_mask:0xf bank_mask:0xf
	v_mov_b32_dpp v31, v23 row_ror:1 row_mask:0xf bank_mask:0xf bound_ctrl:1
	v_mov_b32_dpp v25, v19 row_ror:1 row_mask:0xf bank_mask:0xf bound_ctrl:1
	v_mov_b32_dpp v35, v23 row_ror:2 row_mask:0xf bank_mask:0xf bound_ctrl:1
	v_mov_b32_dpp v27, v19 row_ror:2 row_mask:0xf bank_mask:0xf bound_ctrl:1
	s_and_saveexec_b64 s[24:25], s[86:87]
	s_cbranch_execz .LBB0_1286
	v_pk_fma_f32 v[36:37], v[80:81], v[62:63], v[92:93]
	v_pk_fma_f32 v[38:39], v[64:65], v[56:57], v[76:77]
	v_pk_fma_f32 v[36:37], v[84:85], v[60:61], v[36:37]
	v_pk_fma_f32 v[38:39], v[68:69], v[52:53], v[38:39]
	v_pk_fma_f32 v[20:21], v[20:21], v[88:89], v[36:37]
	v_pk_fma_f32 v[16:17], v[16:17], v[72:73], v[38:39]
	v_mul_f32_e32 v36, 0x3d372713, v20
	v_mul_f32_e32 v37, 0x3d372713, v21
	v_fma_f32 v36, v20, v36, 1.0
	v_fma_f32 v37, v21, v37, 1.0
	v_mul_f32_e32 v36, v20, v36
	v_mul_f32_e32 v37, v21, v37
	v_mul_f32_e32 v36, 0x40135761, v36
	v_mul_f32_e32 v37, 0x40135761, v37
	v_exp_f32_e32 v36, v36
	v_exp_f32_e32 v37, v37
	v_add_f32_e32 v36, 1.0, v36
	v_add_f32_e32 v37, 1.0, v37
	v_rcp_f32_e32 v36, v36
	v_rcp_f32_e32 v37, v37
	s_nop 0
	v_pk_fma_f32 v[20:21], v[20:21], v[36:37], v[20:21] neg_lo:[1,0,0] neg_hi:[1,0,0]
	v_pk_fma_f32 v[36:37], v[82:83], v[58:59], v[94:95]
	v_pk_mul_f32 v[16:17], v[16:17], v[20:21]
	v_pk_fma_f32 v[36:37], v[86:87], v[54:55], v[36:37]
	v_cvt_pk_bf16_f32 v16, v16, v17
	v_pk_fma_f32 v[22:23], v[22:23], v[90:91], v[36:37]
	s_nop 0
	v_mul_f32_e32 v36, 0x3d372713, v22
	v_mul_f32_e32 v37, 0x3d372713, v23
	v_fma_f32 v36, v22, v36, 1.0
	v_fma_f32 v37, v23, v37, 1.0
	v_mul_f32_e32 v36, v22, v36
	v_mul_f32_e32 v37, v23, v37
	v_mul_f32_e32 v36, 0x40135761, v36
	v_mul_f32_e32 v37, 0x40135761, v37
	v_exp_f32_e32 v36, v36
	v_exp_f32_e32 v37, v37
	v_add_f32_e32 v20, 1.0, v36
	v_add_f32_e32 v21, 1.0, v37
	v_rcp_f32_e32 v20, v20
	v_rcp_f32_e32 v21, v21
	v_pk_fma_f32 v[36:37], v[66:67], v[50:51], v[78:79]
	v_pk_fma_f32 v[20:21], v[22:23], v[20:21], v[22:23] neg_lo:[1,0,0] neg_hi:[1,0,0]
	v_pk_fma_f32 v[36:37], v[70:71], v[48:49], v[36:37]
	s_nop 0
	v_pk_fma_f32 v[18:19], v[18:19], v[74:75], v[36:37]
	s_nop 0
	v_pk_mul_f32 v[18:19], v[18:19], v[20:21]
	v_mov_b64_e32 v[20:21], s[44:45]
	v_cvt_pk_bf16_f32 v17, v18, v19
	v_lshl_add_u64 v[18:19], s[72:73], 0, v[136:137]
	v_mad_u64_u32 v[20:21], s[74:75], v18, s1, v[20:21]
	v_mad_i32_i24 v21, v19, s1, v21
	v_lshl_add_u64 v[18:19], v[192:193], 1, v[20:21]
	global_store_dwordx2 v[18:19], v[16:17], off offset:8
.LBB0_1286:
	s_or_b64 exec, exec, s[24:25]
	v_mov_b32_dpp v40, v12 row_shr:1 row_mask:0xf bank_mask:0xf
	v_mov_b32_dpp v42, v12 row_shr:2 row_mask:0xf bank_mask:0xf
	v_mov_b32_dpp v28, v8 row_shr:1 row_mask:0xf bank_mask:0xf
	v_mov_b32_dpp v32, v8 row_shr:2 row_mask:0xf bank_mask:0xf
	v_mov_b32_dpp v44, v12 row_ror:1 row_mask:0xf bank_mask:0xf bound_ctrl:1
	v_mov_b32_dpp v20, v8 row_ror:1 row_mask:0xf bank_mask:0xf bound_ctrl:1
	v_mov_b32_dpp v46, v12 row_ror:2 row_mask:0xf bank_mask:0xf bound_ctrl:1
	v_mov_b32_dpp v36, v8 row_ror:2 row_mask:0xf bank_mask:0xf bound_ctrl:1
	v_mov_b32_dpp v41, v13 row_shr:1 row_mask:0xf bank_mask:0xf
	v_mov_b32_dpp v43, v13 row_shr:2 row_mask:0xf bank_mask:0xf
	v_mov_b32_dpp v29, v9 row_shr:1 row_mask:0xf bank_mask:0xf
	v_mov_b32_dpp v33, v9 row_shr:2 row_mask:0xf bank_mask:0xf
	v_mov_b32_dpp v45, v13 row_ror:1 row_mask:0xf bank_mask:0xf bound_ctrl:1
	v_mov_b32_dpp v21, v9 row_ror:1 row_mask:0xf bank_mask:0xf bound_ctrl:1
	v_mov_b32_dpp v47, v13 row_ror:2 row_mask:0xf bank_mask:0xf bound_ctrl:1
	v_mov_b32_dpp v37, v9 row_ror:2 row_mask:0xf bank_mask:0xf bound_ctrl:1
	v_mov_b32_dpp v30, v14 row_shr:1 row_mask:0xf bank_mask:0xf
	v_mov_b32_dpp v34, v14 row_shr:2 row_mask:0xf bank_mask:0xf
	v_mov_b32_dpp v24, v10 row_shr:1 row_mask:0xf bank_mask:0xf
	v_mov_b32_dpp v26, v10 row_shr:2 row_mask:0xf bank_mask:0xf
	v_mov_b32_dpp v22, v14 row_ror:1 row_mask:0xf bank_mask:0xf bound_ctrl:1
	v_mov_b32_dpp v16, v10 row_ror:1 row_mask:0xf bank_mask:0xf bound_ctrl:1
	v_mov_b32_dpp v38, v14 row_ror:2 row_mask:0xf bank_mask:0xf bound_ctrl:1
	v_mov_b32_dpp v18, v10 row_ror:2 row_mask:0xf bank_mask:0xf bound_ctrl:1
	v_mov_b32_dpp v31, v15 row_shr:1 row_mask:0xf bank_mask:0xf
	v_mov_b32_dpp v35, v15 row_shr:2 row_mask:0xf bank_mask:0xf
	v_mov_b32_dpp v25, v11 row_shr:1 row_mask:0xf bank_mask:0xf
	v_mov_b32_dpp v27, v11 row_shr:2 row_mask:0xf bank_mask:0xf
	v_mov_b32_dpp v23, v15 row_ror:1 row_mask:0xf bank_mask:0xf bound_ctrl:1
	v_mov_b32_dpp v17, v11 row_ror:1 row_mask:0xf bank_mask:0xf bound_ctrl:1
	v_mov_b32_dpp v39, v15 row_ror:2 row_mask:0xf bank_mask:0xf bound_ctrl:1
	v_mov_b32_dpp v19, v11 row_ror:2 row_mask:0xf bank_mask:0xf bound_ctrl:1
	s_and_saveexec_b64 s[24:25], s[88:89]
	s_cbranch_execz .LBB0_1288
	v_pk_fma_f32 v[42:43], v[80:81], v[42:43], v[92:93]
	v_pk_fma_f32 v[32:33], v[64:65], v[32:33], v[76:77]
	v_pk_fma_f32 v[40:41], v[84:85], v[40:41], v[42:43]
	v_pk_fma_f32 v[28:29], v[68:69], v[28:29], v[32:33]
	v_pk_fma_f32 v[12:13], v[12:13], v[88:89], v[40:41]
	v_pk_fma_f32 v[8:9], v[8:9], v[72:73], v[28:29]
	v_mul_f32_e32 v40, 0x3d372713, v12
	v_mul_f32_e32 v41, 0x3d372713, v13
	v_fma_f32 v40, v12, v40, 1.0
	v_fma_f32 v41, v13, v41, 1.0
	v_mul_f32_e32 v40, v12, v40
	v_mul_f32_e32 v41, v13, v41
	v_mul_f32_e32 v40, 0x40135761, v40
	v_mul_f32_e32 v41, 0x40135761, v41
	v_pk_fma_f32 v[28:29], v[82:83], v[34:35], v[94:95]
	v_exp_f32_e32 v40, v40
	v_exp_f32_e32 v41, v41
	v_pk_fma_f32 v[28:29], v[86:87], v[30:31], v[28:29]
	v_pk_fma_f32 v[26:27], v[66:67], v[26:27], v[78:79]
	v_pk_fma_f32 v[14:15], v[14:15], v[90:91], v[28:29]
	v_add_f32_e32 v40, 1.0, v40
	v_mul_f32_e32 v28, 0x3d372713, v14
	v_mul_f32_e32 v29, 0x3d372713, v15
	v_fma_f32 v28, v14, v28, 1.0
	v_fma_f32 v29, v15, v29, 1.0
	v_add_f32_e32 v41, 1.0, v41
	v_mul_f32_e32 v28, v14, v28
	v_mul_f32_e32 v29, v15, v29
	v_rcp_f32_e32 v40, v40
	v_rcp_f32_e32 v41, v41
	v_mul_f32_e32 v28, 0x40135761, v28
	v_mul_f32_e32 v29, 0x40135761, v29
	v_exp_f32_e32 v28, v28
	v_exp_f32_e32 v29, v29
	v_pk_fma_f32 v[12:13], v[12:13], v[40:41], v[12:13] neg_lo:[1,0,0] neg_hi:[1,0,0]
	v_pk_fma_f32 v[24:25], v[70:71], v[24:25], v[26:27]
	v_pk_mul_f32 v[8:9], v[8:9], v[12:13]
	v_add_f32_e32 v12, 1.0, v28
	v_add_f32_e32 v13, 1.0, v29
	v_rcp_f32_e32 v12, v12
	v_rcp_f32_e32 v13, v13
	v_pk_fma_f32 v[10:11], v[10:11], v[74:75], v[24:25]
	v_cvt_pk_bf16_f32 v8, v8, v9
	v_pk_fma_f32 v[12:13], v[14:15], v[12:13], v[14:15] neg_lo:[1,0,0] neg_hi:[1,0,0]
	s_nop 0
	v_pk_mul_f32 v[10:11], v[10:11], v[12:13]
	v_mov_b64_e32 v[12:13], s[44:45]
	v_cvt_pk_bf16_f32 v9, v10, v11
	v_lshl_add_u64 v[10:11], s[72:73], 0, v[138:139]
	v_mad_u64_u32 v[12:13], s[74:75], v10, s1, v[12:13]
	v_mad_i32_i24 v13, v11, s1, v13
	v_lshl_add_u64 v[10:11], v[192:193], 1, v[12:13]
	global_store_dwordx2 v[10:11], v[8:9], off offset:8
.LBB0_1288:
	s_or_b64 exec, exec, s[24:25]
	v_mov_b32_dpp v44, v4 row_shr:1 row_mask:0xf bank_mask:0xf
	v_mov_b32_dpp v46, v4 row_shr:2 row_mask:0xf bank_mask:0xf
	v_mov_b32_dpp v20, v0 row_shr:1 row_mask:0xf bank_mask:0xf
	v_mov_b32_dpp v36, v0 row_shr:2 row_mask:0xf bank_mask:0xf
	v_mov_b32_dpp v45, v5 row_shr:1 row_mask:0xf bank_mask:0xf
	v_mov_b32_dpp v47, v5 row_shr:2 row_mask:0xf bank_mask:0xf
	v_mov_b32_dpp v21, v1 row_shr:1 row_mask:0xf bank_mask:0xf
	v_mov_b32_dpp v37, v1 row_shr:2 row_mask:0xf bank_mask:0xf
	v_mov_b32_dpp v22, v6 row_shr:1 row_mask:0xf bank_mask:0xf
	v_mov_b32_dpp v38, v6 row_shr:2 row_mask:0xf bank_mask:0xf
	v_mov_b32_dpp v16, v2 row_shr:1 row_mask:0xf bank_mask:0xf
	v_mov_b32_dpp v18, v2 row_shr:2 row_mask:0xf bank_mask:0xf
	v_mov_b32_dpp v23, v7 row_shr:1 row_mask:0xf bank_mask:0xf
	v_mov_b32_dpp v39, v7 row_shr:2 row_mask:0xf bank_mask:0xf
	v_mov_b32_dpp v17, v3 row_shr:1 row_mask:0xf bank_mask:0xf
	v_mov_b32_dpp v19, v3 row_shr:2 row_mask:0xf bank_mask:0xf
	s_and_saveexec_b64 s[24:25], s[90:91]
	s_cbranch_execz .LBB0_1290
	v_pk_fma_f32 v[8:9], v[80:81], v[46:47], v[92:93]
	v_pk_fma_f32 v[10:11], v[64:65], v[36:37], v[76:77]
	v_pk_fma_f32 v[8:9], v[84:85], v[44:45], v[8:9]
	v_pk_fma_f32 v[10:11], v[68:69], v[20:21], v[10:11]
	v_pk_fma_f32 v[4:5], v[4:5], v[88:89], v[8:9]
	v_pk_fma_f32 v[0:1], v[0:1], v[72:73], v[10:11]
	v_mul_f32_e32 v8, 0x3d372713, v4
	v_mul_f32_e32 v9, 0x3d372713, v5
	v_fma_f32 v8, v4, v8, 1.0
	v_fma_f32 v9, v5, v9, 1.0
	v_mul_f32_e32 v8, v4, v8
	v_mul_f32_e32 v9, v5, v9
	v_mul_f32_e32 v8, 0x40135761, v8
	v_mul_f32_e32 v9, 0x40135761, v9
	v_exp_f32_e32 v8, v8
	v_exp_f32_e32 v9, v9
	v_add_f32_e32 v8, 1.0, v8
	v_add_f32_e32 v9, 1.0, v9
	v_rcp_f32_e32 v8, v8
	v_rcp_f32_e32 v9, v9
	s_nop 0
	v_pk_fma_f32 v[4:5], v[4:5], v[8:9], v[4:5] neg_lo:[1,0,0] neg_hi:[1,0,0]
	v_pk_fma_f32 v[8:9], v[82:83], v[38:39], v[94:95]
	v_pk_mul_f32 v[0:1], v[0:1], v[4:5]
	v_pk_fma_f32 v[8:9], v[86:87], v[22:23], v[8:9]
	v_cvt_pk_bf16_f32 v0, v0, v1
	v_pk_fma_f32 v[6:7], v[6:7], v[90:91], v[8:9]
	s_nop 0
	v_mul_f32_e32 v8, 0x3d372713, v6
	v_mul_f32_e32 v9, 0x3d372713, v7
	v_fma_f32 v8, v6, v8, 1.0
	v_fma_f32 v9, v7, v9, 1.0
	v_mul_f32_e32 v8, v6, v8
	v_mul_f32_e32 v9, v7, v9
	v_mul_f32_e32 v8, 0x40135761, v8
	v_mul_f32_e32 v9, 0x40135761, v9
	v_exp_f32_e32 v8, v8
	v_exp_f32_e32 v9, v9
	v_add_f32_e32 v4, 1.0, v8
	v_add_f32_e32 v5, 1.0, v9
	v_rcp_f32_e32 v4, v4
	v_rcp_f32_e32 v5, v5
	v_pk_fma_f32 v[8:9], v[66:67], v[18:19], v[78:79]
	v_pk_fma_f32 v[4:5], v[6:7], v[4:5], v[6:7] neg_lo:[1,0,0] neg_hi:[1,0,0]
	v_pk_fma_f32 v[8:9], v[70:71], v[16:17], v[8:9]
	s_nop 0
	v_pk_fma_f32 v[2:3], v[2:3], v[74:75], v[8:9]
	s_nop 0
	v_pk_mul_f32 v[2:3], v[2:3], v[4:5]
	v_mov_b64_e32 v[4:5], s[44:45]
	v_cvt_pk_bf16_f32 v1, v2, v3
	v_lshl_add_u64 v[2:3], s[72:73], 0, v[140:141]
	v_mad_u64_u32 v[4:5], s[72:73], v2, s1, v[4:5]
	v_mad_i32_i24 v5, v3, s1, v5
	v_lshl_add_u64 v[2:3], v[192:193], 1, v[4:5]
	global_store_dwordx2 v[2:3], v[0:1], off offset:8

.LBB0_1945:
	s_mul_hi_i32 s71, s1, 0x3e0f83e1
	s_lshr_b32 s76, s71, 31
	s_ashr_i32 s71, s71, 3
	s_add_i32 s76, s71, s76
	s_mul_i32 s71, s76, 33
	s_sub_i32 s1, s1, s71
	s_mul_i32 s71, s1, 0xfe
	v_add_u32_e32 v194, s71, v224
	s_or_b32 s71, s1, s40
	s_cmp_eq_u32 s71, 0
	s_cselect_b64 s[78:79], -1, 0
	s_cmp_eq_u32 s1, 32
	s_movk_i32 s1, 0x42
	s_cselect_b32 s1, s1, 0x100
	s_and_b64 s[78:79], s[78:79], s[12:13]
	s_ashr_i32 s77, s76, 31
	v_cndmask_b32_e64 v217, v159, 0, s[78:79]
	v_cndmask_b32_e64 v216, v158, 0, s[78:79]
	v_cndmask_b32_e64 v219, v157, 0, s[78:79]
	v_cndmask_b32_e64 v218, v156, 0, s[78:79]
	v_cndmask_b32_e64 v159, v155, 0, s[78:79]
	v_cndmask_b32_e64 v158, v154, 0, s[78:79]
	v_cndmask_b32_e64 v153, v153, 0, s[78:79]
	v_cndmask_b32_e64 v152, v152, 0, s[78:79]
	v_cmp_gt_u32_e32 vcc, s1, v220
	s_lshl_b64 s[76:77], s[76:77], 13
	v_mov_b32_dpp v173, v218 row_shr:1 row_mask:0xf bank_mask:0xf
	v_mov_b32_dpp v214, v218 row_shr:2 row_mask:0xf bank_mask:0xf
	v_mov_b32_dpp v169, v152 row_shr:1 row_mask:0xf bank_mask:0xf
	v_mov_b32_dpp v212, v152 row_shr:2 row_mask:0xf bank_mask:0xf
	v_mov_b32_dpp v204, v218 row_ror:1 row_mask:0xf bank_mask:0xf bound_ctrl:1
	v_mov_b32_dpp v196, v152 row_ror:1 row_mask:0xf bank_mask:0xf bound_ctrl:1
	v_mov_b32_dpp v206, v218 row_ror:2 row_mask:0xf bank_mask:0xf bound_ctrl:1
	v_mov_b32_dpp v200, v152 row_ror:2 row_mask:0xf bank_mask:0xf bound_ctrl:1
	v_mov_b32_dpp v175, v219 row_shr:1 row_mask:0xf bank_mask:0xf
	v_mov_b32_dpp v215, v219 row_shr:2 row_mask:0xf bank_mask:0xf
	v_mov_b32_dpp v171, v153 row_shr:1 row_mask:0xf bank_mask:0xf
	v_mov_b32_dpp v213, v153 row_shr:2 row_mask:0xf bank_mask:0xf
	v_mov_b32_dpp v205, v219 row_ror:1 row_mask:0xf bank_mask:0xf bound_ctrl:1
	v_mov_b32_dpp v197, v153 row_ror:1 row_mask:0xf bank_mask:0xf bound_ctrl:1
	v_mov_b32_dpp v207, v219 row_ror:2 row_mask:0xf bank_mask:0xf bound_ctrl:1
	v_mov_b32_dpp v201, v153 row_ror:2 row_mask:0xf bank_mask:0xf bound_ctrl:1
	v_mov_b32_dpp v165, v216 row_shr:1 row_mask:0xf bank_mask:0xf
	v_mov_b32_dpp v210, v216 row_shr:2 row_mask:0xf bank_mask:0xf
	v_mov_b32_dpp v161, v158 row_shr:1 row_mask:0xf bank_mask:0xf
	v_mov_b32_dpp v208, v158 row_shr:2 row_mask:0xf bank_mask:0xf
	v_mov_b32_dpp v198, v216 row_ror:1 row_mask:0xf bank_mask:0xf bound_ctrl:1
	v_mov_b32_dpp v154, v158 row_ror:1 row_mask:0xf bank_mask:0xf bound_ctrl:1
	v_mov_b32_dpp v202, v216 row_ror:2 row_mask:0xf bank_mask:0xf bound_ctrl:1
	v_mov_b32_dpp v156, v158 row_ror:2 row_mask:0xf bank_mask:0xf bound_ctrl:1
	v_mov_b32_dpp v167, v217 row_shr:1 row_mask:0xf bank_mask:0xf
	v_mov_b32_dpp v211, v217 row_shr:2 row_mask:0xf bank_mask:0xf
	v_mov_b32_dpp v163, v159 row_shr:1 row_mask:0xf bank_mask:0xf
	v_mov_b32_dpp v209, v159 row_shr:2 row_mask:0xf bank_mask:0xf
	v_mov_b32_dpp v199, v217 row_ror:1 row_mask:0xf bank_mask:0xf bound_ctrl:1
	v_mov_b32_dpp v155, v159 row_ror:1 row_mask:0xf bank_mask:0xf bound_ctrl:1
	v_mov_b32_dpp v203, v217 row_ror:2 row_mask:0xf bank_mask:0xf bound_ctrl:1
	v_mov_b32_dpp v157, v159 row_ror:2 row_mask:0xf bank_mask:0xf bound_ctrl:1
	s_and_b64 s[80:81], s[16:17], vcc
	v_ashrrev_i32_e32 v195, 31, v194
	s_waitcnt vmcnt(0)
	s_and_saveexec_b64 s[82:83], s[80:81]
	s_cbranch_execz .LBB0_1947
	v_mov_b32_e32 v174, v173
	v_pk_fma_f32 v[172:173], v[120:121], v[214:215], v[132:133]
	v_mov_b32_e32 v166, v165
	v_pk_fma_f32 v[172:173], v[124:125], v[174:175], v[172:173]
	v_pk_fma_f32 v[164:165], v[122:123], v[210:211], v[134:135]
	v_pk_fma_f32 v[172:173], v[218:219], v[128:129], v[172:173]
	v_pk_fma_f32 v[164:165], v[126:127], v[166:167], v[164:165]
	v_mul_f32_e32 v160, 0x3d372713, v172
	v_fma_f32 v160, v172, v160, 1.0
	v_mul_f32_e32 v162, 0x3d372713, v173
	v_mul_f32_e32 v160, v172, v160
	v_fma_f32 v162, v173, v162, 1.0
	v_mul_f32_e32 v160, 0x40135761, v160
	v_mul_f32_e32 v162, v173, v162
	v_exp_f32_e32 v160, v160
	v_mul_f32_e32 v162, 0x40135761, v162
	v_exp_f32_e32 v162, v162
	v_pk_fma_f32 v[164:165], v[216:217], v[130:131], v[164:165]
	v_add_f32_e32 v160, 1.0, v160
	v_rcp_f32_e32 v168, v160
	v_add_f32_e32 v160, 1.0, v162
	v_mov_b32_e32 v170, v169
	v_rcp_f32_e32 v169, v160
	v_mul_f32_e32 v160, 0x3d372713, v164
	v_mul_f32_e32 v162, 0x3d372713, v165
	v_fma_f32 v160, v164, v160, 1.0
	v_fma_f32 v162, v165, v162, 1.0
	v_mul_f32_e32 v160, v164, v160
	v_mul_f32_e32 v162, v165, v162
	v_mul_f32_e32 v160, 0x40135761, v160
	v_mul_f32_e32 v162, 0x40135761, v162
	v_exp_f32_e32 v160, v160
	v_exp_f32_e32 v166, v162
	v_mov_b32_e32 v162, v161
	v_pk_fma_f32 v[174:175], v[104:105], v[212:213], v[116:117]
	v_add_f32_e32 v160, 1.0, v160
	v_add_f32_e32 v161, 1.0, v166
	v_rcp_f32_e32 v160, v160
	v_rcp_f32_e32 v161, v161
	v_pk_fma_f32 v[166:167], v[106:107], v[208:209], v[118:119]
	v_pk_fma_f32 v[170:171], v[108:109], v[170:171], v[174:175]
	v_pk_fma_f32 v[162:163], v[110:111], v[162:163], v[166:167]
	v_pk_fma_f32 v[152:153], v[152:153], v[112:113], v[170:171]
	v_pk_fma_f32 v[168:169], v[172:173], v[168:169], v[172:173] neg_lo:[1,0,0] neg_hi:[1,0,0]
	v_pk_fma_f32 v[158:159], v[158:159], v[114:115], v[162:163]
	v_pk_fma_f32 v[160:161], v[164:165], v[160:161], v[164:165] neg_lo:[1,0,0] neg_hi:[1,0,0]
	v_pk_mul_f32 v[152:153], v[152:153], v[168:169]
	v_pk_mul_f32 v[158:159], v[158:159], v[160:161]
	v_cvt_pk_bf16_f32 v152, v152, v153
	v_cvt_pk_bf16_f32 v153, v158, v159
	v_lshl_add_u64 v[158:159], s[76:77], 0, v[194:195]
	v_mov_b64_e32 v[160:161], s[46:47]
	v_mad_u64_u32 v[160:161], s[84:85], v158, s45, v[160:161]
	v_mad_i32_i24 v161, v159, s45, v161
	v_lshl_add_u64 v[158:159], v[192:193], 1, v[160:161]
	global_store_dwordx2 v[158:159], v[152:153], off
.LBB0_1947:
	s_or_b64 exec, exec, s[82:83]
	v_cmp_gt_i32_e32 vcc, s1, v225
	v_add_u32_e32 v152, 16, v194
	v_mov_b32_dpp v204, v148 row_shr:1 row_mask:0xf bank_mask:0xf
	v_mov_b32_dpp v206, v148 row_shr:2 row_mask:0xf bank_mask:0xf
	v_mov_b32_dpp v196, v144 row_shr:1 row_mask:0xf bank_mask:0xf
	v_mov_b32_dpp v200, v144 row_shr:2 row_mask:0xf bank_mask:0xf
	v_mov_b32_dpp v174, v148 row_ror:1 row_mask:0xf bank_mask:0xf bound_ctrl:1
	v_mov_b32_dpp v162, v144 row_ror:1 row_mask:0xf bank_mask:0xf bound_ctrl:1
	v_mov_b32_dpp v208, v148 row_ror:2 row_mask:0xf bank_mask:0xf bound_ctrl:1
	v_mov_b32_dpp v166, v144 row_ror:2 row_mask:0xf bank_mask:0xf bound_ctrl:1
	v_mov_b32_dpp v205, v149 row_shr:1 row_mask:0xf bank_mask:0xf
	v_mov_b32_dpp v207, v149 row_shr:2 row_mask:0xf bank_mask:0xf
	v_mov_b32_dpp v197, v145 row_shr:1 row_mask:0xf bank_mask:0xf
	v_mov_b32_dpp v201, v145 row_shr:2 row_mask:0xf bank_mask:0xf
	v_mov_b32_dpp v175, v149 row_ror:1 row_mask:0xf bank_mask:0xf bound_ctrl:1
	v_mov_b32_dpp v163, v145 row_ror:1 row_mask:0xf bank_mask:0xf bound_ctrl:1
	v_mov_b32_dpp v209, v149 row_ror:2 row_mask:0xf bank_mask:0xf bound_ctrl:1
	v_mov_b32_dpp v167, v145 row_ror:2 row_mask:0xf bank_mask:0xf bound_ctrl:1
	v_mov_b32_dpp v198, v150 row_shr:1 row_mask:0xf bank_mask:0xf
	v_mov_b32_dpp v202, v150 row_shr:2 row_mask:0xf bank_mask:0xf
	v_mov_b32_dpp v154, v146 row_shr:1 row_mask:0xf bank_mask:0xf
	v_mov_b32_dpp v156, v146 row_shr:2 row_mask:0xf bank_mask:0xf
	v_mov_b32_dpp v164, v150 row_ror:1 row_mask:0xf bank_mask:0xf bound_ctrl:1
	v_mov_b32_dpp v158, v146 row_ror:1 row_mask:0xf bank_mask:0xf bound_ctrl:1
	v_mov_b32_dpp v168, v150 row_ror:2 row_mask:0xf bank_mask:0xf bound_ctrl:1
	v_mov_b32_dpp v160, v146 row_ror:2 row_mask:0xf bank_mask:0xf bound_ctrl:1
	v_mov_b32_dpp v199, v151 row_shr:1 row_mask:0xf bank_mask:0xf
	v_mov_b32_dpp v203, v151 row_shr:2 row_mask:0xf bank_mask:0xf
	v_mov_b32_dpp v155, v147 row_shr:1 row_mask:0xf bank_mask:0xf
	v_mov_b32_dpp v157, v147 row_shr:2 row_mask:0xf bank_mask:0xf
	v_mov_b32_dpp v165, v151 row_ror:1 row_mask:0xf bank_mask:0xf bound_ctrl:1
	v_mov_b32_dpp v159, v147 row_ror:1 row_mask:0xf bank_mask:0xf bound_ctrl:1
	v_mov_b32_dpp v169, v151 row_ror:2 row_mask:0xf bank_mask:0xf bound_ctrl:1
	v_mov_b32_dpp v161, v147 row_ror:2 row_mask:0xf bank_mask:0xf bound_ctrl:1
	s_and_b64 s[82:83], s[58:59], vcc
	v_ashrrev_i32_e32 v153, 31, v152
	s_and_saveexec_b64 s[84:85], s[82:83]
	s_cbranch_execz .LBB0_1949
	v_pk_fma_f32 v[170:171], v[120:121], v[206:207], v[132:133]
	v_pk_fma_f32 v[172:173], v[104:105], v[200:201], v[116:117]
	v_pk_fma_f32 v[170:171], v[124:125], v[204:205], v[170:171]
	v_pk_fma_f32 v[172:173], v[108:109], v[196:197], v[172:173]
	v_pk_fma_f32 v[148:149], v[148:149], v[128:129], v[170:171]
	v_pk_fma_f32 v[144:145], v[144:145], v[112:113], v[172:173]
	v_mul_f32_e32 v170, 0x3d372713, v148
	v_mul_f32_e32 v171, 0x3d372713, v149
	v_fma_f32 v170, v148, v170, 1.0
	v_fma_f32 v171, v149, v171, 1.0
	v_mul_f32_e32 v170, v148, v170
	v_mul_f32_e32 v171, v149, v171
	v_mul_f32_e32 v170, 0x40135761, v170
	v_mul_f32_e32 v171, 0x40135761, v171
	v_exp_f32_e32 v170, v170
	v_exp_f32_e32 v171, v171
	v_pk_fma_f32 v[156:157], v[106:107], v[156:157], v[118:119]
	v_add_f32_e32 v170, 1.0, v170
	v_add_f32_e32 v171, 1.0, v171
	v_rcp_f32_e32 v170, v170
	v_rcp_f32_e32 v171, v171
	v_pk_fma_f32 v[154:155], v[110:111], v[154:155], v[156:157]
	v_pk_fma_f32 v[148:149], v[148:149], v[170:171], v[148:149] neg_lo:[1,0,0] neg_hi:[1,0,0]
	v_pk_fma_f32 v[170:171], v[122:123], v[202:203], v[134:135]
	v_pk_mul_f32 v[144:145], v[144:145], v[148:149]
	v_pk_fma_f32 v[170:171], v[126:127], v[198:199], v[170:171]
	v_pk_fma_f32 v[146:147], v[146:147], v[114:115], v[154:155]
	v_pk_fma_f32 v[150:151], v[150:151], v[130:131], v[170:171]
	v_cvt_pk_bf16_f32 v144, v144, v145
	v_mul_f32_e32 v170, 0x3d372713, v150
	v_mul_f32_e32 v171, 0x3d372713, v151
	v_fma_f32 v170, v150, v170, 1.0
	v_fma_f32 v171, v151, v171, 1.0
	v_mul_f32_e32 v170, v150, v170
	v_mul_f32_e32 v171, v151, v171
	v_mul_f32_e32 v170, 0x40135761, v170
	v_mul_f32_e32 v171, 0x40135761, v171
	v_exp_f32_e32 v170, v170
	v_exp_f32_e32 v171, v171
	v_add_f32_e32 v148, 1.0, v170
	v_add_f32_e32 v149, 1.0, v171
	v_rcp_f32_e32 v148, v148
	v_rcp_f32_e32 v149, v149
	s_nop 0
	v_pk_fma_f32 v[148:149], v[150:151], v[148:149], v[150:151] neg_lo:[1,0,0] neg_hi:[1,0,0]
	s_nop 0
	v_pk_mul_f32 v[146:147], v[146:147], v[148:149]
	v_mov_b64_e32 v[148:149], s[46:47]
	v_cvt_pk_bf16_f32 v145, v146, v147
	v_lshl_add_u64 v[146:147], s[76:77], 0, v[152:153]
	v_mad_u64_u32 v[148:149], s[86:87], v146, s45, v[148:149]
	v_mad_i32_i24 v149, v147, s45, v149
	v_lshl_add_u64 v[146:147], v[192:193], 1, v[148:149]
	global_store_dwordx2 v[146:147], v[144:145], off
.LBB0_1949:
	s_or_b64 exec, exec, s[84:85]
	v_cmp_gt_i32_e32 vcc, s1, v226
	v_add_u32_e32 v146, 32, v194
	v_mov_b32_dpp v174, v140 row_shr:1 row_mask:0xf bank_mask:0xf
	v_mov_b32_dpp v208, v140 row_shr:2 row_mask:0xf bank_mask:0xf
	v_mov_b32_dpp v162, v136 row_shr:1 row_mask:0xf bank_mask:0xf
	v_mov_b32_dpp v166, v136 row_shr:2 row_mask:0xf bank_mask:0xf
	v_mov_b32_dpp v196, v140 row_ror:1 row_mask:0xf bank_mask:0xf bound_ctrl:1
	v_mov_b32_dpp v154, v136 row_ror:1 row_mask:0xf bank_mask:0xf bound_ctrl:1
	v_mov_b32_dpp v198, v140 row_ror:2 row_mask:0xf bank_mask:0xf bound_ctrl:1
	v_mov_b32_dpp v170, v136 row_ror:2 row_mask:0xf bank_mask:0xf bound_ctrl:1
	v_mov_b32_dpp v175, v141 row_shr:1 row_mask:0xf bank_mask:0xf
	v_mov_b32_dpp v209, v141 row_shr:2 row_mask:0xf bank_mask:0xf
	v_mov_b32_dpp v163, v137 row_shr:1 row_mask:0xf bank_mask:0xf
	v_mov_b32_dpp v167, v137 row_shr:2 row_mask:0xf bank_mask:0xf
	v_mov_b32_dpp v197, v141 row_ror:1 row_mask:0xf bank_mask:0xf bound_ctrl:1
	v_mov_b32_dpp v155, v137 row_ror:1 row_mask:0xf bank_mask:0xf bound_ctrl:1
	v_mov_b32_dpp v199, v141 row_ror:2 row_mask:0xf bank_mask:0xf bound_ctrl:1
	v_mov_b32_dpp v171, v137 row_ror:2 row_mask:0xf bank_mask:0xf bound_ctrl:1
	v_mov_b32_dpp v164, v142 row_shr:1 row_mask:0xf bank_mask:0xf
	v_mov_b32_dpp v168, v142 row_shr:2 row_mask:0xf bank_mask:0xf
	v_mov_b32_dpp v158, v138 row_shr:1 row_mask:0xf bank_mask:0xf
	v_mov_b32_dpp v160, v138 row_shr:2 row_mask:0xf bank_mask:0xf
	v_mov_b32_dpp v156, v142 row_ror:1 row_mask:0xf bank_mask:0xf bound_ctrl:1
	v_mov_b32_dpp v144, v138 row_ror:1 row_mask:0xf bank_mask:0xf bound_ctrl:1
	v_mov_b32_dpp v172, v142 row_ror:2 row_mask:0xf bank_mask:0xf bound_ctrl:1
	v_mov_b32_dpp v150, v138 row_ror:2 row_mask:0xf bank_mask:0xf bound_ctrl:1
	v_mov_b32_dpp v165, v143 row_shr:1 row_mask:0xf bank_mask:0xf
	v_mov_b32_dpp v169, v143 row_shr:2 row_mask:0xf bank_mask:0xf
	v_mov_b32_dpp v159, v139 row_shr:1 row_mask:0xf bank_mask:0xf
	v_mov_b32_dpp v161, v139 row_shr:2 row_mask:0xf bank_mask:0xf
	v_mov_b32_dpp v157, v143 row_ror:1 row_mask:0xf bank_mask:0xf bound_ctrl:1
	v_mov_b32_dpp v145, v139 row_ror:1 row_mask:0xf bank_mask:0xf bound_ctrl:1
	v_mov_b32_dpp v173, v143 row_ror:2 row_mask:0xf bank_mask:0xf bound_ctrl:1
	v_mov_b32_dpp v151, v139 row_ror:2 row_mask:0xf bank_mask:0xf bound_ctrl:1
	s_and_b64 s[84:85], s[58:59], vcc
	v_ashrrev_i32_e32 v147, 31, v146
	s_and_saveexec_b64 s[86:87], s[84:85]
	s_cbranch_execz .LBB0_1951
	v_pk_fma_f32 v[148:149], v[120:121], v[208:209], v[132:133]
	v_pk_fma_f32 v[166:167], v[104:105], v[166:167], v[116:117]
	v_pk_fma_f32 v[148:149], v[124:125], v[174:175], v[148:149]
	v_pk_fma_f32 v[162:163], v[108:109], v[162:163], v[166:167]
	v_pk_fma_f32 v[140:141], v[140:141], v[128:129], v[148:149]
	v_pk_fma_f32 v[136:137], v[136:137], v[112:113], v[162:163]
	v_mul_f32_e32 v148, 0x3d372713, v140
	v_mul_f32_e32 v149, 0x3d372713, v141
	v_fma_f32 v148, v140, v148, 1.0
	v_fma_f32 v149, v141, v149, 1.0
	v_mul_f32_e32 v148, v140, v148
	v_mul_f32_e32 v149, v141, v149
	v_mul_f32_e32 v148, 0x40135761, v148
	v_mul_f32_e32 v149, 0x40135761, v149
	v_exp_f32_e32 v148, v148
	v_exp_f32_e32 v149, v149
	v_add_f32_e32 v148, 1.0, v148
	v_add_f32_e32 v149, 1.0, v149
	v_rcp_f32_e32 v148, v148
	v_rcp_f32_e32 v149, v149
	s_nop 0
	v_pk_fma_f32 v[140:141], v[140:141], v[148:149], v[140:141] neg_lo:[1,0,0] neg_hi:[1,0,0]
	v_pk_fma_f32 v[148:149], v[122:123], v[168:169], v[134:135]
	v_pk_mul_f32 v[136:137], v[136:137], v[140:141]
	v_pk_fma_f32 v[148:149], v[126:127], v[164:165], v[148:149]
	v_cvt_pk_bf16_f32 v136, v136, v137
	v_pk_fma_f32 v[142:143], v[142:143], v[130:131], v[148:149]
	s_nop 0
	v_mul_f32_e32 v148, 0x3d372713, v142
	v_mul_f32_e32 v149, 0x3d372713, v143
	v_fma_f32 v148, v142, v148, 1.0
	v_fma_f32 v149, v143, v149, 1.0
	v_mul_f32_e32 v148, v142, v148
	v_mul_f32_e32 v149, v143, v149
	v_mul_f32_e32 v148, 0x40135761, v148
	v_mul_f32_e32 v149, 0x40135761, v149
	v_exp_f32_e32 v148, v148
	v_exp_f32_e32 v149, v149
	v_add_f32_e32 v140, 1.0, v148
	v_add_f32_e32 v141, 1.0, v149
	v_rcp_f32_e32 v140, v140
	v_rcp_f32_e32 v141, v141
	v_pk_fma_f32 v[148:149], v[106:107], v[160:161], v[118:119]
	v_pk_fma_f32 v[140:141], v[142:143], v[140:141], v[142:143] neg_lo:[1,0,0] neg_hi:[1,0,0]
	v_pk_fma_f32 v[148:149], v[110:111], v[158:159], v[148:149]
	s_nop 0
	v_pk_fma_f32 v[138:139], v[138:139], v[114:115], v[148:149]
	s_nop 0
	v_pk_mul_f32 v[138:139], v[138:139], v[140:141]
	v_mov_b64_e32 v[140:141], s[46:47]
	v_cvt_pk_bf16_f32 v137, v138, v139
	v_lshl_add_u64 v[138:139], s[76:77], 0, v[146:147]
	v_mad_u64_u32 v[140:141], s[88:89], v138, s45, v[140:141]
	v_mad_i32_i24 v141, v139, s45, v141
	v_lshl_add_u64 v[138:139], v[192:193], 1, v[140:141]
	global_store_dwordx2 v[138:139], v[136:137], off
.LBB0_1951:
	s_or_b64 exec, exec, s[86:87]
	v_cmp_gt_i32_e32 vcc, s1, v227
	v_add_u32_e32 v148, 48, v194
	v_mov_b32_dpp v196, v100 row_shr:1 row_mask:0xf bank_mask:0xf
	v_mov_b32_dpp v198, v100 row_shr:2 row_mask:0xf bank_mask:0xf
	v_mov_b32_dpp v154, v96 row_shr:1 row_mask:0xf bank_mask:0xf
	v_mov_b32_dpp v170, v96 row_shr:2 row_mask:0xf bank_mask:0xf
	v_mov_b32_dpp v197, v101 row_shr:1 row_mask:0xf bank_mask:0xf
	v_mov_b32_dpp v199, v101 row_shr:2 row_mask:0xf bank_mask:0xf
	v_mov_b32_dpp v155, v97 row_shr:1 row_mask:0xf bank_mask:0xf
	v_mov_b32_dpp v171, v97 row_shr:2 row_mask:0xf bank_mask:0xf
	v_mov_b32_dpp v156, v102 row_shr:1 row_mask:0xf bank_mask:0xf
	v_mov_b32_dpp v172, v102 row_shr:2 row_mask:0xf bank_mask:0xf
	v_mov_b32_dpp v144, v98 row_shr:1 row_mask:0xf bank_mask:0xf
	v_mov_b32_dpp v150, v98 row_shr:2 row_mask:0xf bank_mask:0xf
	v_mov_b32_dpp v157, v103 row_shr:1 row_mask:0xf bank_mask:0xf
	v_mov_b32_dpp v173, v103 row_shr:2 row_mask:0xf bank_mask:0xf
	v_mov_b32_dpp v145, v99 row_shr:1 row_mask:0xf bank_mask:0xf
	v_mov_b32_dpp v151, v99 row_shr:2 row_mask:0xf bank_mask:0xf
	s_and_b64 s[86:87], s[58:59], vcc
	v_ashrrev_i32_e32 v149, 31, v148
	s_and_saveexec_b64 s[88:89], s[86:87]
	s_cbranch_execz .LBB0_1953
	v_pk_fma_f32 v[136:137], v[120:121], v[198:199], v[132:133]
	v_pk_fma_f32 v[138:139], v[104:105], v[170:171], v[116:117]
	v_pk_fma_f32 v[136:137], v[124:125], v[196:197], v[136:137]
	v_pk_fma_f32 v[138:139], v[108:109], v[154:155], v[138:139]
	v_pk_fma_f32 v[100:101], v[100:101], v[128:129], v[136:137]
	v_pk_fma_f32 v[96:97], v[96:97], v[112:113], v[138:139]
	v_mul_f32_e32 v136, 0x3d372713, v100
	v_mul_f32_e32 v137, 0x3d372713, v101
	v_fma_f32 v136, v100, v136, 1.0
	v_fma_f32 v137, v101, v137, 1.0
	v_mul_f32_e32 v136, v100, v136
	v_mul_f32_e32 v137, v101, v137
	v_mul_f32_e32 v136, 0x40135761, v136
	v_mul_f32_e32 v137, 0x40135761, v137
	v_exp_f32_e32 v136, v136
	v_exp_f32_e32 v137, v137
	v_add_f32_e32 v136, 1.0, v136
	v_add_f32_e32 v137, 1.0, v137
	v_rcp_f32_e32 v136, v136
	v_rcp_f32_e32 v137, v137
	s_nop 0
	v_pk_fma_f32 v[100:101], v[100:101], v[136:137], v[100:101] neg_lo:[1,0,0] neg_hi:[1,0,0]
	v_pk_fma_f32 v[136:137], v[122:123], v[172:173], v[134:135]
	v_pk_mul_f32 v[96:97], v[96:97], v[100:101]
	v_pk_fma_f32 v[136:137], v[126:127], v[156:157], v[136:137]
	v_cvt_pk_bf16_f32 v96, v96, v97
	v_pk_fma_f32 v[102:103], v[102:103], v[130:131], v[136:137]
	s_nop 0
	v_mul_f32_e32 v136, 0x3d372713, v102
	v_mul_f32_e32 v137, 0x3d372713, v103
	v_fma_f32 v136, v102, v136, 1.0
	v_fma_f32 v137, v103, v137, 1.0
	v_mul_f32_e32 v136, v102, v136
	v_mul_f32_e32 v137, v103, v137
	v_mul_f32_e32 v136, 0x40135761, v136
	v_mul_f32_e32 v137, 0x40135761, v137
	v_exp_f32_e32 v136, v136
	v_exp_f32_e32 v137, v137
	v_add_f32_e32 v100, 1.0, v136
	v_add_f32_e32 v101, 1.0, v137
	v_rcp_f32_e32 v100, v100
	v_rcp_f32_e32 v101, v101
	v_pk_fma_f32 v[136:137], v[106:107], v[150:151], v[118:119]
	v_pk_fma_f32 v[100:101], v[102:103], v[100:101], v[102:103] neg_lo:[1,0,0] neg_hi:[1,0,0]
	v_pk_fma_f32 v[136:137], v[110:111], v[144:145], v[136:137]
	s_nop 0
	v_pk_fma_f32 v[98:99], v[98:99], v[114:115], v[136:137]
	s_nop 0
	v_pk_mul_f32 v[98:99], v[98:99], v[100:101]
	v_mov_b64_e32 v[100:101], s[46:47]
	v_cvt_pk_bf16_f32 v97, v98, v99
	v_lshl_add_u64 v[98:99], s[76:77], 0, v[148:149]
	v_mad_u64_u32 v[100:101], s[90:91], v98, s45, v[100:101]
	v_mad_i32_i24 v101, v99, s45, v101
	v_lshl_add_u64 v[98:99], v[192:193], 1, v[100:101]
	global_store_dwordx2 v[98:99], v[96:97], off
.LBB0_1953:
	s_or_b64 exec, exec, s[88:89]
	v_add_u32_e32 v96, 0x1100, v237
	v_add_u32_e32 v100, 0x1000, v237
	ds_read2_b64 v[136:139], v96 offset1:1
	ds_read2_b64 v[140:143], v100 offset1:1
	v_add_u32_e32 v96, 0x1110, v237
	v_add_u32_e32 v100, 0x1010, v237
	ds_read2_b64 v[96:99], v96 offset1:1
	ds_read2_b64 v[100:103], v100 offset1:1
	s_waitcnt lgkmcnt(0)
	v_cndmask_b32_e64 v172, v137, v136, s[14:15]
	v_cndmask_b32_e64 v173, v139, v138, s[14:15]
	v_cndmask_b32_e64 v174, v141, v140, s[14:15]
	v_cndmask_b32_e64 v168, v97, v96, s[14:15]
	v_cndmask_b32_e64 v169, v99, v98, s[14:15]
	v_cndmask_b32_e64 v175, v143, v142, s[14:15]
	v_cndmask_b32_e64 v170, v101, v100, s[14:15]
	v_cndmask_b32_e64 v171, v103, v102, s[14:15]
	v_add_u32_e32 v144, 0x80, v194
	v_cmp_gt_u32_e32 vcc, s1, v228
	v_mov_b32_dpp v141, v92 row_shr:1 row_mask:0xf bank_mask:0xf
	v_mov_b32_dpp v174, v92 row_shr:2 row_mask:0xf bank_mask:0xf
	v_mov_b32_dpp v137, v88 row_shr:1 row_mask:0xf bank_mask:0xf
	v_mov_b32_dpp v172, v88 row_shr:2 row_mask:0xf bank_mask:0xf
	v_mov_b32_dpp v164, v92 row_ror:1 row_mask:0xf bank_mask:0xf bound_ctrl:1
	v_mov_b32_dpp v156, v88 row_ror:1 row_mask:0xf bank_mask:0xf bound_ctrl:1
	v_mov_b32_dpp v166, v92 row_ror:2 row_mask:0xf bank_mask:0xf bound_ctrl:1
	v_mov_b32_dpp v160, v88 row_ror:2 row_mask:0xf bank_mask:0xf bound_ctrl:1
	v_mov_b32_dpp v143, v93 row_shr:1 row_mask:0xf bank_mask:0xf
	v_mov_b32_dpp v175, v93 row_shr:2 row_mask:0xf bank_mask:0xf
	v_mov_b32_dpp v139, v89 row_shr:1 row_mask:0xf bank_mask:0xf
	v_mov_b32_dpp v173, v89 row_shr:2 row_mask:0xf bank_mask:0xf
	v_mov_b32_dpp v165, v93 row_ror:1 row_mask:0xf bank_mask:0xf bound_ctrl:1
	v_mov_b32_dpp v157, v89 row_ror:1 row_mask:0xf bank_mask:0xf bound_ctrl:1
	v_mov_b32_dpp v167, v93 row_ror:2 row_mask:0xf bank_mask:0xf bound_ctrl:1
	v_mov_b32_dpp v161, v89 row_ror:2 row_mask:0xf bank_mask:0xf bound_ctrl:1
	v_mov_b32_dpp v101, v94 row_shr:1 row_mask:0xf bank_mask:0xf
	v_mov_b32_dpp v170, v94 row_shr:2 row_mask:0xf bank_mask:0xf
	v_mov_b32_dpp v97, v90 row_shr:1 row_mask:0xf bank_mask:0xf
	v_mov_b32_dpp v168, v90 row_shr:2 row_mask:0xf bank_mask:0xf
	v_mov_b32_dpp v158, v94 row_ror:1 row_mask:0xf bank_mask:0xf bound_ctrl:1
	v_mov_b32_dpp v150, v90 row_ror:1 row_mask:0xf bank_mask:0xf bound_ctrl:1
	v_mov_b32_dpp v162, v94 row_ror:2 row_mask:0xf bank_mask:0xf bound_ctrl:1
	v_mov_b32_dpp v154, v90 row_ror:2 row_mask:0xf bank_mask:0xf bound_ctrl:1
	v_mov_b32_dpp v103, v95 row_shr:1 row_mask:0xf bank_mask:0xf
	v_mov_b32_dpp v171, v95 row_shr:2 row_mask:0xf bank_mask:0xf
	v_mov_b32_dpp v99, v91 row_shr:1 row_mask:0xf bank_mask:0xf
	v_mov_b32_dpp v169, v91 row_shr:2 row_mask:0xf bank_mask:0xf
	v_mov_b32_dpp v159, v95 row_ror:1 row_mask:0xf bank_mask:0xf bound_ctrl:1
	v_mov_b32_dpp v151, v91 row_ror:1 row_mask:0xf bank_mask:0xf bound_ctrl:1
	v_mov_b32_dpp v163, v95 row_ror:2 row_mask:0xf bank_mask:0xf bound_ctrl:1
	v_mov_b32_dpp v155, v91 row_ror:2 row_mask:0xf bank_mask:0xf bound_ctrl:1
	s_and_b64 s[88:89], s[18:19], vcc
	v_ashrrev_i32_e32 v145, 31, v144
	s_and_saveexec_b64 s[90:91], s[88:89]
	s_cbranch_execz .LBB0_1955
	v_mov_b32_e32 v142, v141
	v_pk_fma_f32 v[140:141], v[120:121], v[174:175], v[132:133]
	v_mov_b32_e32 v138, v137
	v_pk_fma_f32 v[140:141], v[124:125], v[142:143], v[140:141]
	v_mov_b32_e32 v102, v101
	v_pk_fma_f32 v[92:93], v[92:93], v[128:129], v[140:141]
	v_pk_fma_f32 v[140:141], v[104:105], v[172:173], v[116:117]
	v_mul_f32_e32 v96, 0x3d372713, v92
	v_fma_f32 v96, v92, v96, 1.0
	v_mul_f32_e32 v98, 0x3d372713, v93
	v_mul_f32_e32 v96, v92, v96
	v_fma_f32 v98, v93, v98, 1.0
	v_mul_f32_e32 v96, 0x40135761, v96
	v_mul_f32_e32 v98, v93, v98
	v_exp_f32_e32 v96, v96
	v_mul_f32_e32 v98, 0x40135761, v98
	v_exp_f32_e32 v98, v98
	v_pk_fma_f32 v[138:139], v[108:109], v[138:139], v[140:141]
	v_add_f32_e32 v96, 1.0, v96
	v_rcp_f32_e32 v136, v96
	v_add_f32_e32 v96, 1.0, v98
	v_rcp_f32_e32 v137, v96
	v_pk_fma_f32 v[88:89], v[88:89], v[112:113], v[138:139]
	v_mov_b32_e32 v98, v97
	v_pk_fma_f32 v[96:97], v[106:107], v[168:169], v[118:119]
	v_pk_fma_f32 v[92:93], v[92:93], v[136:137], v[92:93] neg_lo:[1,0,0] neg_hi:[1,0,0]
	v_pk_fma_f32 v[96:97], v[110:111], v[98:99], v[96:97]
	v_pk_mul_f32 v[88:89], v[88:89], v[92:93]
	v_pk_fma_f32 v[92:93], v[122:123], v[170:171], v[134:135]
	v_pk_fma_f32 v[90:91], v[90:91], v[114:115], v[96:97]
	v_pk_fma_f32 v[92:93], v[126:127], v[102:103], v[92:93]
	v_cvt_pk_bf16_f32 v88, v88, v89
	v_pk_fma_f32 v[92:93], v[94:95], v[130:131], v[92:93]
	s_nop 0
	v_mul_f32_e32 v94, 0x3d372713, v92
	v_mul_f32_e32 v95, 0x3d372713, v93
	v_fma_f32 v94, v92, v94, 1.0
	v_fma_f32 v95, v93, v95, 1.0
	v_mul_f32_e32 v94, v92, v94
	v_mul_f32_e32 v95, v93, v95
	v_mul_f32_e32 v94, 0x40135761, v94
	v_mul_f32_e32 v95, 0x40135761, v95
	v_exp_f32_e32 v94, v94
	v_exp_f32_e32 v95, v95
	v_add_f32_e32 v94, 1.0, v94
	v_add_f32_e32 v95, 1.0, v95
	v_rcp_f32_e32 v94, v94
	v_rcp_f32_e32 v95, v95
	s_nop 0
	v_pk_fma_f32 v[92:93], v[92:93], v[94:95], v[92:93] neg_lo:[1,0,0] neg_hi:[1,0,0]
	s_nop 0
	v_pk_mul_f32 v[90:91], v[90:91], v[92:93]
	v_mov_b64_e32 v[92:93], s[46:47]
	v_cvt_pk_bf16_f32 v89, v90, v91
	v_lshl_add_u64 v[90:91], s[76:77], 0, v[144:145]
	v_mad_u64_u32 v[92:93], s[92:93], v90, s45, v[92:93]
	v_mad_i32_i24 v93, v91, s45, v93
	v_lshl_add_u64 v[90:91], v[192:193], 1, v[92:93]
	global_store_dwordx2 v[90:91], v[88:89], off
.LBB0_1955:
	s_or_b64 exec, exec, s[90:91]
	v_cmp_gt_u32_e32 vcc, s1, v229
	v_add_u32_e32 v136, 0x90, v194
	v_mov_b32_dpp v164, v84 row_shr:1 row_mask:0xf bank_mask:0xf
	v_mov_b32_dpp v166, v84 row_shr:2 row_mask:0xf bank_mask:0xf
	v_mov_b32_dpp v156, v80 row_shr:1 row_mask:0xf bank_mask:0xf
	v_mov_b32_dpp v160, v80 row_shr:2 row_mask:0xf bank_mask:0xf
	v_mov_b32_dpp v140, v84 row_ror:1 row_mask:0xf bank_mask:0xf bound_ctrl:1
	v_mov_b32_dpp v92, v80 row_ror:1 row_mask:0xf bank_mask:0xf bound_ctrl:1
	v_mov_b32_dpp v142, v84 row_ror:2 row_mask:0xf bank_mask:0xf bound_ctrl:1
	v_mov_b32_dpp v96, v80 row_ror:2 row_mask:0xf bank_mask:0xf bound_ctrl:1
	v_mov_b32_dpp v165, v85 row_shr:1 row_mask:0xf bank_mask:0xf
	v_mov_b32_dpp v167, v85 row_shr:2 row_mask:0xf bank_mask:0xf
	v_mov_b32_dpp v157, v81 row_shr:1 row_mask:0xf bank_mask:0xf
	v_mov_b32_dpp v161, v81 row_shr:2 row_mask:0xf bank_mask:0xf
	v_mov_b32_dpp v141, v85 row_ror:1 row_mask:0xf bank_mask:0xf bound_ctrl:1
	v_mov_b32_dpp v93, v81 row_ror:1 row_mask:0xf bank_mask:0xf bound_ctrl:1
	v_mov_b32_dpp v143, v85 row_ror:2 row_mask:0xf bank_mask:0xf bound_ctrl:1
	v_mov_b32_dpp v97, v81 row_ror:2 row_mask:0xf bank_mask:0xf bound_ctrl:1
	v_mov_b32_dpp v158, v86 row_shr:1 row_mask:0xf bank_mask:0xf
	v_mov_b32_dpp v162, v86 row_shr:2 row_mask:0xf bank_mask:0xf
	v_mov_b32_dpp v150, v82 row_shr:1 row_mask:0xf bank_mask:0xf
	v_mov_b32_dpp v154, v82 row_shr:2 row_mask:0xf bank_mask:0xf
	v_mov_b32_dpp v94, v86 row_ror:1 row_mask:0xf bank_mask:0xf bound_ctrl:1
	v_mov_b32_dpp v88, v82 row_ror:1 row_mask:0xf bank_mask:0xf bound_ctrl:1
	v_mov_b32_dpp v98, v86 row_ror:2 row_mask:0xf bank_mask:0xf bound_ctrl:1
	v_mov_b32_dpp v90, v82 row_ror:2 row_mask:0xf bank_mask:0xf bound_ctrl:1
	v_mov_b32_dpp v159, v87 row_shr:1 row_mask:0xf bank_mask:0xf
	v_mov_b32_dpp v163, v87 row_shr:2 row_mask:0xf bank_mask:0xf
	v_mov_b32_dpp v151, v83 row_shr:1 row_mask:0xf bank_mask:0xf
	v_mov_b32_dpp v155, v83 row_shr:2 row_mask:0xf bank_mask:0xf
	v_mov_b32_dpp v95, v87 row_ror:1 row_mask:0xf bank_mask:0xf bound_ctrl:1
	v_mov_b32_dpp v89, v83 row_ror:1 row_mask:0xf bank_mask:0xf bound_ctrl:1
	v_mov_b32_dpp v99, v87 row_ror:2 row_mask:0xf bank_mask:0xf bound_ctrl:1
	v_mov_b32_dpp v91, v83 row_ror:2 row_mask:0xf bank_mask:0xf bound_ctrl:1
	s_and_b64 s[90:91], s[20:21], vcc
	v_ashrrev_i32_e32 v137, 31, v136
	s_and_saveexec_b64 s[92:93], s[90:91]
	s_cbranch_execz .LBB0_1957
	v_pk_fma_f32 v[100:101], v[120:121], v[166:167], v[132:133]
	v_pk_fma_f32 v[102:103], v[104:105], v[160:161], v[116:117]
	v_pk_fma_f32 v[100:101], v[124:125], v[164:165], v[100:101]
	v_pk_fma_f32 v[102:103], v[108:109], v[156:157], v[102:103]
	v_pk_fma_f32 v[84:85], v[84:85], v[128:129], v[100:101]
	v_pk_fma_f32 v[80:81], v[80:81], v[112:113], v[102:103]
	v_mul_f32_e32 v100, 0x3d372713, v84
	v_mul_f32_e32 v101, 0x3d372713, v85
	v_fma_f32 v100, v84, v100, 1.0
	v_fma_f32 v101, v85, v101, 1.0
	v_mul_f32_e32 v100, v84, v100
	v_mul_f32_e32 v101, v85, v101
	v_mul_f32_e32 v100, 0x40135761, v100
	v_mul_f32_e32 v101, 0x40135761, v101
	v_exp_f32_e32 v100, v100
	v_exp_f32_e32 v101, v101
	v_add_f32_e32 v100, 1.0, v100
	v_add_f32_e32 v101, 1.0, v101
	v_rcp_f32_e32 v100, v100
	v_rcp_f32_e32 v101, v101
	s_nop 0
	v_pk_fma_f32 v[84:85], v[84:85], v[100:101], v[84:85] neg_lo:[1,0,0] neg_hi:[1,0,0]
	v_pk_fma_f32 v[100:101], v[122:123], v[162:163], v[134:135]
	v_pk_mul_f32 v[80:81], v[80:81], v[84:85]
	v_pk_fma_f32 v[100:101], v[126:127], v[158:159], v[100:101]
	v_cvt_pk_bf16_f32 v80, v80, v81
	v_pk_fma_f32 v[86:87], v[86:87], v[130:131], v[100:101]
	s_nop 0
	v_mul_f32_e32 v100, 0x3d372713, v86
	v_mul_f32_e32 v101, 0x3d372713, v87
	v_fma_f32 v100, v86, v100, 1.0
	v_fma_f32 v101, v87, v101, 1.0
	v_mul_f32_e32 v100, v86, v100
	v_mul_f32_e32 v101, v87, v101
	v_mul_f32_e32 v100, 0x40135761, v100
	v_mul_f32_e32 v101, 0x40135761, v101
	v_exp_f32_e32 v100, v100
	v_exp_f32_e32 v101, v101
	v_add_f32_e32 v84, 1.0, v100
	v_add_f32_e32 v85, 1.0, v101
	v_rcp_f32_e32 v84, v84
	v_rcp_f32_e32 v85, v85
	v_pk_fma_f32 v[100:101], v[106:107], v[154:155], v[118:119]
	v_pk_fma_f32 v[84:85], v[86:87], v[84:85], v[86:87] neg_lo:[1,0,0] neg_hi:[1,0,0]
	v_pk_fma_f32 v[100:101], v[110:111], v[150:151], v[100:101]
	s_nop 0
	v_pk_fma_f32 v[82:83], v[82:83], v[114:115], v[100:101]
	s_nop 0
	v_pk_mul_f32 v[82:83], v[82:83], v[84:85]
	v_mov_b64_e32 v[84:85], s[46:47]
	v_cvt_pk_bf16_f32 v81, v82, v83
	v_lshl_add_u64 v[82:83], s[76:77], 0, v[136:137]
	v_mad_u64_u32 v[84:85], s[94:95], v82, s45, v[84:85]
	v_mad_i32_i24 v85, v83, s45, v85
	v_lshl_add_u64 v[82:83], v[192:193], 1, v[84:85]
	global_store_dwordx2 v[82:83], v[80:81], off
.LBB0_1957:
	s_or_b64 exec, exec, s[92:93]
	v_cmp_gt_u32_e32 vcc, s1, v230
	v_add_u32_e32 v138, 0xa0, v194
	v_mov_b32_dpp v140, v76 row_shr:1 row_mask:0xf bank_mask:0xf
	v_mov_b32_dpp v142, v76 row_shr:2 row_mask:0xf bank_mask:0xf
	v_mov_b32_dpp v92, v72 row_shr:1 row_mask:0xf bank_mask:0xf
	v_mov_b32_dpp v96, v72 row_shr:2 row_mask:0xf bank_mask:0xf
	v_mov_b32_dpp v150, v76 row_ror:1 row_mask:0xf bank_mask:0xf bound_ctrl:1
	v_mov_b32_dpp v84, v72 row_ror:1 row_mask:0xf bank_mask:0xf bound_ctrl:1
	v_mov_b32_dpp v154, v76 row_ror:2 row_mask:0xf bank_mask:0xf bound_ctrl:1
	v_mov_b32_dpp v100, v72 row_ror:2 row_mask:0xf bank_mask:0xf bound_ctrl:1
	v_mov_b32_dpp v141, v77 row_shr:1 row_mask:0xf bank_mask:0xf
	v_mov_b32_dpp v143, v77 row_shr:2 row_mask:0xf bank_mask:0xf
	v_mov_b32_dpp v93, v73 row_shr:1 row_mask:0xf bank_mask:0xf
	v_mov_b32_dpp v97, v73 row_shr:2 row_mask:0xf bank_mask:0xf
	v_mov_b32_dpp v151, v77 row_ror:1 row_mask:0xf bank_mask:0xf bound_ctrl:1
	v_mov_b32_dpp v85, v73 row_ror:1 row_mask:0xf bank_mask:0xf bound_ctrl:1
	v_mov_b32_dpp v155, v77 row_ror:2 row_mask:0xf bank_mask:0xf bound_ctrl:1
	v_mov_b32_dpp v101, v73 row_ror:2 row_mask:0xf bank_mask:0xf bound_ctrl:1
	v_mov_b32_dpp v94, v78 row_shr:1 row_mask:0xf bank_mask:0xf
	v_mov_b32_dpp v98, v78 row_shr:2 row_mask:0xf bank_mask:0xf
	v_mov_b32_dpp v88, v74 row_shr:1 row_mask:0xf bank_mask:0xf
	v_mov_b32_dpp v90, v74 row_shr:2 row_mask:0xf bank_mask:0xf
	v_mov_b32_dpp v86, v78 row_ror:1 row_mask:0xf bank_mask:0xf bound_ctrl:1
	v_mov_b32_dpp v80, v74 row_ror:1 row_mask:0xf bank_mask:0xf bound_ctrl:1
	v_mov_b32_dpp v102, v78 row_ror:2 row_mask:0xf bank_mask:0xf bound_ctrl:1
	v_mov_b32_dpp v82, v74 row_ror:2 row_mask:0xf bank_mask:0xf bound_ctrl:1
	v_mov_b32_dpp v95, v79 row_shr:1 row_mask:0xf bank_mask:0xf
	v_mov_b32_dpp v99, v79 row_shr:2 row_mask:0xf bank_mask:0xf
	v_mov_b32_dpp v89, v75 row_shr:1 row_mask:0xf bank_mask:0xf
	v_mov_b32_dpp v91, v75 row_shr:2 row_mask:0xf bank_mask:0xf
	v_mov_b32_dpp v87, v79 row_ror:1 row_mask:0xf bank_mask:0xf bound_ctrl:1
	v_mov_b32_dpp v81, v75 row_ror:1 row_mask:0xf bank_mask:0xf bound_ctrl:1
	v_mov_b32_dpp v103, v79 row_ror:2 row_mask:0xf bank_mask:0xf bound_ctrl:1
	v_mov_b32_dpp v83, v75 row_ror:2 row_mask:0xf bank_mask:0xf bound_ctrl:1
	s_and_b64 s[92:93], s[22:23], vcc
	v_ashrrev_i32_e32 v139, 31, v138
	s_and_saveexec_b64 s[94:95], s[92:93]
	s_cbranch_execz .LBB0_1959
	v_pk_fma_f32 v[142:143], v[120:121], v[142:143], v[132:133]
	v_pk_fma_f32 v[96:97], v[104:105], v[96:97], v[116:117]
	v_pk_fma_f32 v[140:141], v[124:125], v[140:141], v[142:143]
	v_pk_fma_f32 v[92:93], v[108:109], v[92:93], v[96:97]
	v_pk_fma_f32 v[76:77], v[76:77], v[128:129], v[140:141]
	v_pk_fma_f32 v[72:73], v[72:73], v[112:113], v[92:93]
	v_mul_f32_e32 v140, 0x3d372713, v76
	v_mul_f32_e32 v141, 0x3d372713, v77
	v_fma_f32 v140, v76, v140, 1.0
	v_fma_f32 v141, v77, v141, 1.0
	v_mul_f32_e32 v140, v76, v140
	v_mul_f32_e32 v141, v77, v141
	v_mul_f32_e32 v140, 0x40135761, v140
	v_mul_f32_e32 v141, 0x40135761, v141
	v_pk_fma_f32 v[92:93], v[122:123], v[98:99], v[134:135]
	v_exp_f32_e32 v140, v140
	v_exp_f32_e32 v141, v141
	v_pk_fma_f32 v[92:93], v[126:127], v[94:95], v[92:93]
	v_pk_fma_f32 v[90:91], v[106:107], v[90:91], v[118:119]
	v_pk_fma_f32 v[78:79], v[78:79], v[130:131], v[92:93]
	v_add_f32_e32 v140, 1.0, v140
	v_mul_f32_e32 v92, 0x3d372713, v78
	v_mul_f32_e32 v93, 0x3d372713, v79
	v_fma_f32 v92, v78, v92, 1.0
	v_fma_f32 v93, v79, v93, 1.0
	v_add_f32_e32 v141, 1.0, v141
	v_mul_f32_e32 v92, v78, v92
	v_mul_f32_e32 v93, v79, v93
	v_rcp_f32_e32 v140, v140
	v_rcp_f32_e32 v141, v141
	v_mul_f32_e32 v92, 0x40135761, v92
	v_mul_f32_e32 v93, 0x40135761, v93
	v_exp_f32_e32 v92, v92
	v_exp_f32_e32 v93, v93
	v_pk_fma_f32 v[76:77], v[76:77], v[140:141], v[76:77] neg_lo:[1,0,0] neg_hi:[1,0,0]
	v_pk_fma_f32 v[88:89], v[110:111], v[88:89], v[90:91]
	v_pk_mul_f32 v[72:73], v[72:73], v[76:77]
	v_add_f32_e32 v76, 1.0, v92
	v_add_f32_e32 v77, 1.0, v93
	v_rcp_f32_e32 v76, v76
	v_rcp_f32_e32 v77, v77
	v_pk_fma_f32 v[74:75], v[74:75], v[114:115], v[88:89]
	v_cvt_pk_bf16_f32 v72, v72, v73
	v_pk_fma_f32 v[76:77], v[78:79], v[76:77], v[78:79] neg_lo:[1,0,0] neg_hi:[1,0,0]
	s_nop 0
	v_pk_mul_f32 v[74:75], v[74:75], v[76:77]
	v_mov_b64_e32 v[76:77], s[46:47]
	v_cvt_pk_bf16_f32 v73, v74, v75
	v_lshl_add_u64 v[74:75], s[76:77], 0, v[138:139]
	v_mad_u64_u32 v[76:77], s[96:97], v74, s45, v[76:77]
	v_mad_i32_i24 v77, v75, s45, v77
	v_lshl_add_u64 v[74:75], v[192:193], 1, v[76:77]
	global_store_dwordx2 v[74:75], v[72:73], off
.LBB0_1959:
	s_or_b64 exec, exec, s[94:95]
	v_cmp_gt_u32_e32 vcc, s1, v231
	v_add_u32_e32 v140, 0xb0, v194
	v_mov_b32_dpp v150, v68 row_shr:1 row_mask:0xf bank_mask:0xf
	v_mov_b32_dpp v154, v68 row_shr:2 row_mask:0xf bank_mask:0xf
	v_mov_b32_dpp v84, v64 row_shr:1 row_mask:0xf bank_mask:0xf
	v_mov_b32_dpp v100, v64 row_shr:2 row_mask:0xf bank_mask:0xf
	v_mov_b32_dpp v151, v69 row_shr:1 row_mask:0xf bank_mask:0xf
	v_mov_b32_dpp v155, v69 row_shr:2 row_mask:0xf bank_mask:0xf
	v_mov_b32_dpp v85, v65 row_shr:1 row_mask:0xf bank_mask:0xf
	v_mov_b32_dpp v101, v65 row_shr:2 row_mask:0xf bank_mask:0xf
	v_mov_b32_dpp v86, v70 row_shr:1 row_mask:0xf bank_mask:0xf
	v_mov_b32_dpp v102, v70 row_shr:2 row_mask:0xf bank_mask:0xf
	v_mov_b32_dpp v80, v66 row_shr:1 row_mask:0xf bank_mask:0xf
	v_mov_b32_dpp v82, v66 row_shr:2 row_mask:0xf bank_mask:0xf
	v_mov_b32_dpp v87, v71 row_shr:1 row_mask:0xf bank_mask:0xf
	v_mov_b32_dpp v103, v71 row_shr:2 row_mask:0xf bank_mask:0xf
	v_mov_b32_dpp v81, v67 row_shr:1 row_mask:0xf bank_mask:0xf
	v_mov_b32_dpp v83, v67 row_shr:2 row_mask:0xf bank_mask:0xf
	s_and_b64 s[94:95], s[24:25], vcc
	v_ashrrev_i32_e32 v141, 31, v140
	s_and_saveexec_b64 s[96:97], s[94:95]
	s_cbranch_execz .LBB0_1961
	v_pk_fma_f32 v[72:73], v[120:121], v[154:155], v[132:133]
	v_pk_fma_f32 v[74:75], v[104:105], v[100:101], v[116:117]
	v_pk_fma_f32 v[72:73], v[124:125], v[150:151], v[72:73]
	v_pk_fma_f32 v[74:75], v[108:109], v[84:85], v[74:75]
	v_pk_fma_f32 v[68:69], v[68:69], v[128:129], v[72:73]
	v_pk_fma_f32 v[64:65], v[64:65], v[112:113], v[74:75]
	v_mul_f32_e32 v72, 0x3d372713, v68
	v_mul_f32_e32 v73, 0x3d372713, v69
	v_fma_f32 v72, v68, v72, 1.0
	v_fma_f32 v73, v69, v73, 1.0
	v_mul_f32_e32 v72, v68, v72
	v_mul_f32_e32 v73, v69, v73
	v_mul_f32_e32 v72, 0x40135761, v72
	v_mul_f32_e32 v73, 0x40135761, v73
	v_exp_f32_e32 v72, v72
	v_exp_f32_e32 v73, v73
	v_add_f32_e32 v72, 1.0, v72
	v_add_f32_e32 v73, 1.0, v73
	v_rcp_f32_e32 v72, v72
	v_rcp_f32_e32 v73, v73
	s_nop 0
	v_pk_fma_f32 v[68:69], v[68:69], v[72:73], v[68:69] neg_lo:[1,0,0] neg_hi:[1,0,0]
	v_pk_fma_f32 v[72:73], v[122:123], v[102:103], v[134:135]
	v_pk_mul_f32 v[64:65], v[64:65], v[68:69]
	v_pk_fma_f32 v[72:73], v[126:127], v[86:87], v[72:73]
	v_cvt_pk_bf16_f32 v64, v64, v65
	v_pk_fma_f32 v[70:71], v[70:71], v[130:131], v[72:73]
	s_nop 0
	v_mul_f32_e32 v72, 0x3d372713, v70
	v_mul_f32_e32 v73, 0x3d372713, v71
	v_fma_f32 v72, v70, v72, 1.0
	v_fma_f32 v73, v71, v73, 1.0
	v_mul_f32_e32 v72, v70, v72
	v_mul_f32_e32 v73, v71, v73
	v_mul_f32_e32 v72, 0x40135761, v72
	v_mul_f32_e32 v73, 0x40135761, v73
	v_exp_f32_e32 v72, v72
	v_exp_f32_e32 v73, v73
	v_add_f32_e32 v68, 1.0, v72
	v_add_f32_e32 v69, 1.0, v73
	v_rcp_f32_e32 v68, v68
	v_rcp_f32_e32 v69, v69
	v_pk_fma_f32 v[72:73], v[106:107], v[82:83], v[118:119]
	v_pk_fma_f32 v[68:69], v[70:71], v[68:69], v[70:71] neg_lo:[1,0,0] neg_hi:[1,0,0]
	v_pk_fma_f32 v[72:73], v[110:111], v[80:81], v[72:73]
	s_nop 0
	v_pk_fma_f32 v[66:67], v[66:67], v[114:115], v[72:73]
	s_nop 0
	v_pk_mul_f32 v[66:67], v[66:67], v[68:69]
	v_mov_b64_e32 v[68:69], s[46:47]
	v_cvt_pk_bf16_f32 v65, v66, v67
	v_lshl_add_u64 v[66:67], s[76:77], 0, v[140:141]
	v_mad_u64_u32 v[68:69], vcc, v66, s45, v[68:69]
	v_mad_i32_i24 v69, v67, s45, v69
	v_lshl_add_u64 v[66:67], v[192:193], 1, v[68:69]
	global_store_dwordx2 v[66:67], v[64:65], off

.LBB0_1965:
	s_or_b64 exec, exec, s[28:29]
	v_mov_b32_dpp v120, v52 row_shr:1 row_mask:0xf bank_mask:0xf
	v_mov_b32_dpp v122, v52 row_shr:2 row_mask:0xf bank_mask:0xf
	v_mov_b32_dpp v112, v48 row_shr:1 row_mask:0xf bank_mask:0xf
	v_mov_b32_dpp v116, v48 row_shr:2 row_mask:0xf bank_mask:0xf
	v_mov_b32_dpp v104, v52 row_ror:1 row_mask:0xf bank_mask:0xf bound_ctrl:1
	v_mov_b32_dpp v96, v48 row_ror:1 row_mask:0xf bank_mask:0xf bound_ctrl:1
	v_mov_b32_dpp v106, v52 row_ror:2 row_mask:0xf bank_mask:0xf bound_ctrl:1
	v_mov_b32_dpp v100, v48 row_ror:2 row_mask:0xf bank_mask:0xf bound_ctrl:1
	v_mov_b32_dpp v121, v53 row_shr:1 row_mask:0xf bank_mask:0xf
	v_mov_b32_dpp v123, v53 row_shr:2 row_mask:0xf bank_mask:0xf
	v_mov_b32_dpp v113, v49 row_shr:1 row_mask:0xf bank_mask:0xf
	v_mov_b32_dpp v117, v49 row_shr:2 row_mask:0xf bank_mask:0xf
	v_mov_b32_dpp v105, v53 row_ror:1 row_mask:0xf bank_mask:0xf bound_ctrl:1
	v_mov_b32_dpp v97, v49 row_ror:1 row_mask:0xf bank_mask:0xf bound_ctrl:1
	v_mov_b32_dpp v107, v53 row_ror:2 row_mask:0xf bank_mask:0xf bound_ctrl:1
	v_mov_b32_dpp v101, v49 row_ror:2 row_mask:0xf bank_mask:0xf bound_ctrl:1
	v_mov_b32_dpp v114, v54 row_shr:1 row_mask:0xf bank_mask:0xf
	v_mov_b32_dpp v118, v54 row_shr:2 row_mask:0xf bank_mask:0xf
	v_mov_b32_dpp v56, v50 row_shr:1 row_mask:0xf bank_mask:0xf
	v_mov_b32_dpp v58, v50 row_shr:2 row_mask:0xf bank_mask:0xf
	v_mov_b32_dpp v98, v54 row_ror:1 row_mask:0xf bank_mask:0xf bound_ctrl:1
	v_mov_b32_dpp v60, v50 row_ror:1 row_mask:0xf bank_mask:0xf bound_ctrl:1
	v_mov_b32_dpp v102, v54 row_ror:2 row_mask:0xf bank_mask:0xf bound_ctrl:1
	v_mov_b32_dpp v62, v50 row_ror:2 row_mask:0xf bank_mask:0xf bound_ctrl:1
	v_mov_b32_dpp v115, v55 row_shr:1 row_mask:0xf bank_mask:0xf
	v_mov_b32_dpp v119, v55 row_shr:2 row_mask:0xf bank_mask:0xf
	v_mov_b32_dpp v57, v51 row_shr:1 row_mask:0xf bank_mask:0xf
	v_mov_b32_dpp v59, v51 row_shr:2 row_mask:0xf bank_mask:0xf
	v_mov_b32_dpp v99, v55 row_ror:1 row_mask:0xf bank_mask:0xf bound_ctrl:1
	v_mov_b32_dpp v61, v51 row_ror:1 row_mask:0xf bank_mask:0xf bound_ctrl:1
	v_mov_b32_dpp v103, v55 row_ror:2 row_mask:0xf bank_mask:0xf bound_ctrl:1
	v_mov_b32_dpp v63, v51 row_ror:2 row_mask:0xf bank_mask:0xf bound_ctrl:1
	s_and_saveexec_b64 s[28:29], s[82:83]
	s_cbranch_execz .LBB0_1967
	v_pk_fma_f32 v[108:109], v[80:81], v[122:123], v[92:93]
	v_pk_fma_f32 v[110:111], v[64:65], v[116:117], v[76:77]
	v_pk_fma_f32 v[108:109], v[84:85], v[120:121], v[108:109]
	v_pk_fma_f32 v[110:111], v[68:69], v[112:113], v[110:111]
	v_pk_fma_f32 v[52:53], v[52:53], v[88:89], v[108:109]
	v_pk_fma_f32 v[48:49], v[48:49], v[72:73], v[110:111]
	v_mul_f32_e32 v108, 0x3d372713, v52
	v_mul_f32_e32 v109, 0x3d372713, v53
	v_fma_f32 v108, v52, v108, 1.0
	v_fma_f32 v109, v53, v109, 1.0
	v_mul_f32_e32 v108, v52, v108
	v_mul_f32_e32 v109, v53, v109
	v_mul_f32_e32 v108, 0x40135761, v108
	v_mul_f32_e32 v109, 0x40135761, v109
	v_exp_f32_e32 v108, v108
	v_exp_f32_e32 v109, v109
	v_pk_fma_f32 v[58:59], v[66:67], v[58:59], v[78:79]
	v_add_f32_e32 v108, 1.0, v108
	v_add_f32_e32 v109, 1.0, v109
	v_rcp_f32_e32 v108, v108
	v_rcp_f32_e32 v109, v109
	v_pk_fma_f32 v[56:57], v[70:71], v[56:57], v[58:59]
	v_pk_fma_f32 v[52:53], v[52:53], v[108:109], v[52:53] neg_lo:[1,0,0] neg_hi:[1,0,0]
	v_pk_fma_f32 v[108:109], v[82:83], v[118:119], v[94:95]
	v_pk_mul_f32 v[48:49], v[48:49], v[52:53]
	v_pk_fma_f32 v[108:109], v[86:87], v[114:115], v[108:109]
	v_pk_fma_f32 v[50:51], v[50:51], v[74:75], v[56:57]
	v_pk_fma_f32 v[54:55], v[54:55], v[90:91], v[108:109]
	v_cvt_pk_bf16_f32 v48, v48, v49
	v_mul_f32_e32 v108, 0x3d372713, v54
	v_mul_f32_e32 v109, 0x3d372713, v55
	v_fma_f32 v108, v54, v108, 1.0
	v_fma_f32 v109, v55, v109, 1.0
	v_mul_f32_e32 v108, v54, v108
	v_mul_f32_e32 v109, v55, v109
	v_mul_f32_e32 v108, 0x40135761, v108
	v_mul_f32_e32 v109, 0x40135761, v109
	v_exp_f32_e32 v108, v108
	v_exp_f32_e32 v109, v109
	v_add_f32_e32 v52, 1.0, v108
	v_add_f32_e32 v53, 1.0, v109
	v_rcp_f32_e32 v52, v52
	v_rcp_f32_e32 v53, v53
	s_nop 0
	v_pk_fma_f32 v[52:53], v[54:55], v[52:53], v[54:55] neg_lo:[1,0,0] neg_hi:[1,0,0]
	s_nop 0
	v_pk_mul_f32 v[50:51], v[50:51], v[52:53]
	v_mov_b64_e32 v[52:53], s[46:47]
	v_cvt_pk_bf16_f32 v49, v50, v51
	v_lshl_add_u64 v[50:51], s[76:77], 0, v[152:153]
	v_mad_u64_u32 v[52:53], s[78:79], v50, s45, v[52:53]
	v_mad_i32_i24 v53, v51, s45, v53
	v_lshl_add_u64 v[50:51], v[192:193], 1, v[52:53]
	global_store_dwordx2 v[50:51], v[48:49], off offset:8
.LBB0_1967:
	s_or_b64 exec, exec, s[28:29]
	v_mov_b32_dpp v104, v44 row_shr:1 row_mask:0xf bank_mask:0xf
	v_mov_b32_dpp v106, v44 row_shr:2 row_mask:0xf bank_mask:0xf
	v_mov_b32_dpp v96, v40 row_shr:1 row_mask:0xf bank_mask:0xf
	v_mov_b32_dpp v100, v40 row_shr:2 row_mask:0xf bank_mask:0xf
	v_mov_b32_dpp v108, v44 row_ror:1 row_mask:0xf bank_mask:0xf bound_ctrl:1
	v_mov_b32_dpp v52, v40 row_ror:1 row_mask:0xf bank_mask:0xf bound_ctrl:1
	v_mov_b32_dpp v110, v44 row_ror:2 row_mask:0xf bank_mask:0xf bound_ctrl:1
	v_mov_b32_dpp v56, v40 row_ror:2 row_mask:0xf bank_mask:0xf bound_ctrl:1
	v_mov_b32_dpp v105, v45 row_shr:1 row_mask:0xf bank_mask:0xf
	v_mov_b32_dpp v107, v45 row_shr:2 row_mask:0xf bank_mask:0xf
	v_mov_b32_dpp v97, v41 row_shr:1 row_mask:0xf bank_mask:0xf
	v_mov_b32_dpp v101, v41 row_shr:2 row_mask:0xf bank_mask:0xf
	v_mov_b32_dpp v109, v45 row_ror:1 row_mask:0xf bank_mask:0xf bound_ctrl:1
	v_mov_b32_dpp v53, v41 row_ror:1 row_mask:0xf bank_mask:0xf bound_ctrl:1
	v_mov_b32_dpp v111, v45 row_ror:2 row_mask:0xf bank_mask:0xf bound_ctrl:1
	v_mov_b32_dpp v57, v41 row_ror:2 row_mask:0xf bank_mask:0xf bound_ctrl:1
	v_mov_b32_dpp v98, v46 row_shr:1 row_mask:0xf bank_mask:0xf
	v_mov_b32_dpp v102, v46 row_shr:2 row_mask:0xf bank_mask:0xf
	v_mov_b32_dpp v60, v42 row_shr:1 row_mask:0xf bank_mask:0xf
	v_mov_b32_dpp v62, v42 row_shr:2 row_mask:0xf bank_mask:0xf
	v_mov_b32_dpp v54, v46 row_ror:1 row_mask:0xf bank_mask:0xf bound_ctrl:1
	v_mov_b32_dpp v48, v42 row_ror:1 row_mask:0xf bank_mask:0xf bound_ctrl:1
	v_mov_b32_dpp v58, v46 row_ror:2 row_mask:0xf bank_mask:0xf bound_ctrl:1
	v_mov_b32_dpp v50, v42 row_ror:2 row_mask:0xf bank_mask:0xf bound_ctrl:1
	v_mov_b32_dpp v99, v47 row_shr:1 row_mask:0xf bank_mask:0xf
	v_mov_b32_dpp v103, v47 row_shr:2 row_mask:0xf bank_mask:0xf
	v_mov_b32_dpp v61, v43 row_shr:1 row_mask:0xf bank_mask:0xf
	v_mov_b32_dpp v63, v43 row_shr:2 row_mask:0xf bank_mask:0xf
	v_mov_b32_dpp v55, v47 row_ror:1 row_mask:0xf bank_mask:0xf bound_ctrl:1
	v_mov_b32_dpp v49, v43 row_ror:1 row_mask:0xf bank_mask:0xf bound_ctrl:1
	v_mov_b32_dpp v59, v47 row_ror:2 row_mask:0xf bank_mask:0xf bound_ctrl:1
	v_mov_b32_dpp v51, v43 row_ror:2 row_mask:0xf bank_mask:0xf bound_ctrl:1
	s_and_saveexec_b64 s[28:29], s[84:85]
	s_cbranch_execz .LBB0_1969
	v_pk_fma_f32 v[106:107], v[80:81], v[106:107], v[92:93]
	v_pk_fma_f32 v[100:101], v[64:65], v[100:101], v[76:77]
	v_pk_fma_f32 v[104:105], v[84:85], v[104:105], v[106:107]
	v_pk_fma_f32 v[96:97], v[68:69], v[96:97], v[100:101]
	v_pk_fma_f32 v[44:45], v[44:45], v[88:89], v[104:105]
	v_pk_fma_f32 v[40:41], v[40:41], v[72:73], v[96:97]
	v_mul_f32_e32 v104, 0x3d372713, v44
	v_mul_f32_e32 v105, 0x3d372713, v45
	v_fma_f32 v104, v44, v104, 1.0
	v_fma_f32 v105, v45, v105, 1.0
	v_mul_f32_e32 v104, v44, v104
	v_mul_f32_e32 v105, v45, v105
	v_mul_f32_e32 v104, 0x40135761, v104
	v_mul_f32_e32 v105, 0x40135761, v105
	v_pk_fma_f32 v[96:97], v[82:83], v[102:103], v[94:95]
	v_exp_f32_e32 v104, v104
	v_exp_f32_e32 v105, v105
	v_pk_fma_f32 v[96:97], v[86:87], v[98:99], v[96:97]
	v_pk_fma_f32 v[62:63], v[66:67], v[62:63], v[78:79]
	v_pk_fma_f32 v[46:47], v[46:47], v[90:91], v[96:97]
	v_add_f32_e32 v104, 1.0, v104
	v_mul_f32_e32 v96, 0x3d372713, v46
	v_mul_f32_e32 v97, 0x3d372713, v47
	v_fma_f32 v96, v46, v96, 1.0
	v_fma_f32 v97, v47, v97, 1.0
	v_add_f32_e32 v105, 1.0, v105
	v_mul_f32_e32 v96, v46, v96
	v_mul_f32_e32 v97, v47, v97
	v_rcp_f32_e32 v104, v104
	v_rcp_f32_e32 v105, v105
	v_mul_f32_e32 v96, 0x40135761, v96
	v_mul_f32_e32 v97, 0x40135761, v97
	v_exp_f32_e32 v96, v96
	v_exp_f32_e32 v97, v97
	v_pk_fma_f32 v[44:45], v[44:45], v[104:105], v[44:45] neg_lo:[1,0,0] neg_hi:[1,0,0]
	v_pk_fma_f32 v[60:61], v[70:71], v[60:61], v[62:63]
	v_pk_mul_f32 v[40:41], v[40:41], v[44:45]
	v_add_f32_e32 v44, 1.0, v96
	v_add_f32_e32 v45, 1.0, v97
	v_rcp_f32_e32 v44, v44
	v_rcp_f32_e32 v45, v45
	v_pk_fma_f32 v[42:43], v[42:43], v[74:75], v[60:61]
	v_cvt_pk_bf16_f32 v40, v40, v41
	v_pk_fma_f32 v[44:45], v[46:47], v[44:45], v[46:47] neg_lo:[1,0,0] neg_hi:[1,0,0]
	s_nop 0
	v_pk_mul_f32 v[42:43], v[42:43], v[44:45]
	v_mov_b64_e32 v[44:45], s[46:47]
	v_cvt_pk_bf16_f32 v41, v42, v43
	v_lshl_add_u64 v[42:43], s[76:77], 0, v[146:147]
	v_mad_u64_u32 v[44:45], s[78:79], v42, s45, v[44:45]
	v_mad_i32_i24 v45, v43, s45, v45
	v_lshl_add_u64 v[42:43], v[192:193], 1, v[44:45]
	global_store_dwordx2 v[42:43], v[40:41], off offset:8
.LBB0_1969:
	s_or_b64 exec, exec, s[28:29]
	v_mov_b32_dpp v108, v36 row_shr:1 row_mask:0xf bank_mask:0xf
	v_mov_b32_dpp v110, v36 row_shr:2 row_mask:0xf bank_mask:0xf
	v_mov_b32_dpp v52, v32 row_shr:1 row_mask:0xf bank_mask:0xf
	v_mov_b32_dpp v56, v32 row_shr:2 row_mask:0xf bank_mask:0xf
	v_mov_b32_dpp v109, v37 row_shr:1 row_mask:0xf bank_mask:0xf
	v_mov_b32_dpp v111, v37 row_shr:2 row_mask:0xf bank_mask:0xf
	v_mov_b32_dpp v53, v33 row_shr:1 row_mask:0xf bank_mask:0xf
	v_mov_b32_dpp v57, v33 row_shr:2 row_mask:0xf bank_mask:0xf
	v_mov_b32_dpp v54, v38 row_shr:1 row_mask:0xf bank_mask:0xf
	v_mov_b32_dpp v58, v38 row_shr:2 row_mask:0xf bank_mask:0xf
	v_mov_b32_dpp v48, v34 row_shr:1 row_mask:0xf bank_mask:0xf
	v_mov_b32_dpp v50, v34 row_shr:2 row_mask:0xf bank_mask:0xf
	v_mov_b32_dpp v55, v39 row_shr:1 row_mask:0xf bank_mask:0xf
	v_mov_b32_dpp v59, v39 row_shr:2 row_mask:0xf bank_mask:0xf
	v_mov_b32_dpp v49, v35 row_shr:1 row_mask:0xf bank_mask:0xf
	v_mov_b32_dpp v51, v35 row_shr:2 row_mask:0xf bank_mask:0xf
	s_and_saveexec_b64 s[28:29], s[86:87]
	s_cbranch_execz .LBB0_1971
	v_pk_fma_f32 v[40:41], v[80:81], v[110:111], v[92:93]
	v_pk_fma_f32 v[42:43], v[64:65], v[56:57], v[76:77]
	v_pk_fma_f32 v[40:41], v[84:85], v[108:109], v[40:41]
	v_pk_fma_f32 v[42:43], v[68:69], v[52:53], v[42:43]
	v_pk_fma_f32 v[36:37], v[36:37], v[88:89], v[40:41]
	v_pk_fma_f32 v[32:33], v[32:33], v[72:73], v[42:43]
	v_mul_f32_e32 v40, 0x3d372713, v36
	v_mul_f32_e32 v41, 0x3d372713, v37
	v_fma_f32 v40, v36, v40, 1.0
	v_fma_f32 v41, v37, v41, 1.0
	v_mul_f32_e32 v40, v36, v40
	v_mul_f32_e32 v41, v37, v41
	v_mul_f32_e32 v40, 0x40135761, v40
	v_mul_f32_e32 v41, 0x40135761, v41
	v_exp_f32_e32 v40, v40
	v_exp_f32_e32 v41, v41
	v_add_f32_e32 v40, 1.0, v40
	v_add_f32_e32 v41, 1.0, v41
	v_rcp_f32_e32 v40, v40
	v_rcp_f32_e32 v41, v41
	s_nop 0
	v_pk_fma_f32 v[36:37], v[36:37], v[40:41], v[36:37] neg_lo:[1,0,0] neg_hi:[1,0,0]
	v_pk_fma_f32 v[40:41], v[82:83], v[58:59], v[94:95]
	v_pk_mul_f32 v[32:33], v[32:33], v[36:37]
	v_pk_fma_f32 v[40:41], v[86:87], v[54:55], v[40:41]
	v_cvt_pk_bf16_f32 v32, v32, v33
	v_pk_fma_f32 v[38:39], v[38:39], v[90:91], v[40:41]
	s_nop 0
	v_mul_f32_e32 v40, 0x3d372713, v38
	v_mul_f32_e32 v41, 0x3d372713, v39
	v_fma_f32 v40, v38, v40, 1.0
	v_fma_f32 v41, v39, v41, 1.0
	v_mul_f32_e32 v40, v38, v40
	v_mul_f32_e32 v41, v39, v41
	v_mul_f32_e32 v40, 0x40135761, v40
	v_mul_f32_e32 v41, 0x40135761, v41
	v_exp_f32_e32 v40, v40
	v_exp_f32_e32 v41, v41
	v_add_f32_e32 v36, 1.0, v40
	v_add_f32_e32 v37, 1.0, v41
	v_rcp_f32_e32 v36, v36
	v_rcp_f32_e32 v37, v37
	v_pk_fma_f32 v[40:41], v[66:67], v[50:51], v[78:79]
	v_pk_fma_f32 v[36:37], v[38:39], v[36:37], v[38:39] neg_lo:[1,0,0] neg_hi:[1,0,0]
	v_pk_fma_f32 v[40:41], v[70:71], v[48:49], v[40:41]
	s_nop 0
	v_pk_fma_f32 v[34:35], v[34:35], v[74:75], v[40:41]
	s_nop 0
	v_pk_mul_f32 v[34:35], v[34:35], v[36:37]
	v_mov_b64_e32 v[36:37], s[46:47]
	v_cvt_pk_bf16_f32 v33, v34, v35
	v_lshl_add_u64 v[34:35], s[76:77], 0, v[148:149]
	v_mad_u64_u32 v[36:37], s[78:79], v34, s45, v[36:37]
	v_mad_i32_i24 v37, v35, s45, v37
	v_lshl_add_u64 v[34:35], v[192:193], 1, v[36:37]
	global_store_dwordx2 v[34:35], v[32:33], off offset:8
.LBB0_1971:
	s_or_b64 exec, exec, s[28:29]
	v_add_u32_e32 v32, 0x1180, v237
	v_add_u32_e32 v36, 0x1080, v237
	ds_read2_b64 v[40:43], v32 offset1:1
	ds_read2_b64 v[44:47], v36 offset1:1
	v_add_u32_e32 v32, 0x1190, v237
	v_add_u32_e32 v36, 0x1090, v237
	ds_read2_b64 v[32:35], v32 offset1:1
	ds_read2_b64 v[36:39], v36 offset1:1
	s_waitcnt lgkmcnt(3)
	v_cndmask_b32_e64 v100, v41, v40, s[14:15]
	v_cndmask_b32_e64 v101, v43, v42, s[14:15]
	s_waitcnt lgkmcnt(2)
	v_cndmask_b32_e64 v102, v45, v44, s[14:15]
	s_waitcnt lgkmcnt(1)
	v_cndmask_b32_e64 v96, v33, v32, s[14:15]
	v_cndmask_b32_e64 v97, v35, v34, s[14:15]
	v_cndmask_b32_e64 v103, v47, v46, s[14:15]
	s_waitcnt lgkmcnt(0)
	v_cndmask_b32_e64 v98, v37, v36, s[14:15]
	v_cndmask_b32_e64 v99, v39, v38, s[14:15]
	v_mov_b32_dpp v45, v28 row_shr:1 row_mask:0xf bank_mask:0xf
	v_mov_b32_dpp v102, v28 row_shr:2 row_mask:0xf bank_mask:0xf
	v_mov_b32_dpp v41, v24 row_shr:1 row_mask:0xf bank_mask:0xf
	v_mov_b32_dpp v100, v24 row_shr:2 row_mask:0xf bank_mask:0xf
	v_mov_b32_dpp v60, v28 row_ror:1 row_mask:0xf bank_mask:0xf bound_ctrl:1
	v_mov_b32_dpp v52, v24 row_ror:1 row_mask:0xf bank_mask:0xf bound_ctrl:1
	v_mov_b32_dpp v62, v28 row_ror:2 row_mask:0xf bank_mask:0xf bound_ctrl:1
	v_mov_b32_dpp v56, v24 row_ror:2 row_mask:0xf bank_mask:0xf bound_ctrl:1
	v_mov_b32_dpp v47, v29 row_shr:1 row_mask:0xf bank_mask:0xf
	v_mov_b32_dpp v103, v29 row_shr:2 row_mask:0xf bank_mask:0xf
	v_mov_b32_dpp v43, v25 row_shr:1 row_mask:0xf bank_mask:0xf
	v_mov_b32_dpp v101, v25 row_shr:2 row_mask:0xf bank_mask:0xf
	v_mov_b32_dpp v61, v29 row_ror:1 row_mask:0xf bank_mask:0xf bound_ctrl:1
	v_mov_b32_dpp v53, v25 row_ror:1 row_mask:0xf bank_mask:0xf bound_ctrl:1
	v_mov_b32_dpp v63, v29 row_ror:2 row_mask:0xf bank_mask:0xf bound_ctrl:1
	v_mov_b32_dpp v57, v25 row_ror:2 row_mask:0xf bank_mask:0xf bound_ctrl:1
	v_mov_b32_dpp v37, v30 row_shr:1 row_mask:0xf bank_mask:0xf
	v_mov_b32_dpp v98, v30 row_shr:2 row_mask:0xf bank_mask:0xf
	v_mov_b32_dpp v33, v26 row_shr:1 row_mask:0xf bank_mask:0xf
	v_mov_b32_dpp v96, v26 row_shr:2 row_mask:0xf bank_mask:0xf
	v_mov_b32_dpp v54, v30 row_ror:1 row_mask:0xf bank_mask:0xf bound_ctrl:1
	v_mov_b32_dpp v48, v26 row_ror:1 row_mask:0xf bank_mask:0xf bound_ctrl:1
	v_mov_b32_dpp v58, v30 row_ror:2 row_mask:0xf bank_mask:0xf bound_ctrl:1
	v_mov_b32_dpp v50, v26 row_ror:2 row_mask:0xf bank_mask:0xf bound_ctrl:1
	v_mov_b32_dpp v39, v31 row_shr:1 row_mask:0xf bank_mask:0xf
	v_mov_b32_dpp v99, v31 row_shr:2 row_mask:0xf bank_mask:0xf
	v_mov_b32_dpp v35, v27 row_shr:1 row_mask:0xf bank_mask:0xf
	v_mov_b32_dpp v97, v27 row_shr:2 row_mask:0xf bank_mask:0xf
	v_mov_b32_dpp v55, v31 row_ror:1 row_mask:0xf bank_mask:0xf bound_ctrl:1
	v_mov_b32_dpp v49, v27 row_ror:1 row_mask:0xf bank_mask:0xf bound_ctrl:1
	v_mov_b32_dpp v59, v31 row_ror:2 row_mask:0xf bank_mask:0xf bound_ctrl:1
	v_mov_b32_dpp v51, v27 row_ror:2 row_mask:0xf bank_mask:0xf bound_ctrl:1
	s_and_saveexec_b64 s[28:29], s[88:89]
	s_cbranch_execz .LBB0_1973
	v_mov_b32_e32 v46, v45
	v_pk_fma_f32 v[44:45], v[80:81], v[102:103], v[92:93]
	v_mov_b32_e32 v42, v41
	v_pk_fma_f32 v[44:45], v[84:85], v[46:47], v[44:45]
	v_mov_b32_e32 v38, v37
	v_pk_fma_f32 v[28:29], v[28:29], v[88:89], v[44:45]
	v_pk_fma_f32 v[44:45], v[64:65], v[100:101], v[76:77]
	v_mul_f32_e32 v32, 0x3d372713, v28
	v_fma_f32 v32, v28, v32, 1.0
	v_mul_f32_e32 v34, 0x3d372713, v29
	v_mul_f32_e32 v32, v28, v32
	v_fma_f32 v34, v29, v34, 1.0
	v_mul_f32_e32 v32, 0x40135761, v32
	v_mul_f32_e32 v34, v29, v34
	v_exp_f32_e32 v32, v32
	v_mul_f32_e32 v34, 0x40135761, v34
	v_exp_f32_e32 v34, v34
	v_pk_fma_f32 v[42:43], v[68:69], v[42:43], v[44:45]
	v_add_f32_e32 v32, 1.0, v32
	v_rcp_f32_e32 v40, v32
	v_add_f32_e32 v32, 1.0, v34
	v_rcp_f32_e32 v41, v32
	v_pk_fma_f32 v[24:25], v[24:25], v[72:73], v[42:43]
	v_mov_b32_e32 v34, v33
	v_pk_fma_f32 v[32:33], v[66:67], v[96:97], v[78:79]
	v_pk_fma_f32 v[28:29], v[28:29], v[40:41], v[28:29] neg_lo:[1,0,0] neg_hi:[1,0,0]
	v_pk_fma_f32 v[32:33], v[70:71], v[34:35], v[32:33]
	v_pk_mul_f32 v[24:25], v[24:25], v[28:29]
	v_pk_fma_f32 v[28:29], v[82:83], v[98:99], v[94:95]
	v_pk_fma_f32 v[26:27], v[26:27], v[74:75], v[32:33]
	v_pk_fma_f32 v[28:29], v[86:87], v[38:39], v[28:29]
	v_cvt_pk_bf16_f32 v24, v24, v25
	v_pk_fma_f32 v[28:29], v[30:31], v[90:91], v[28:29]
	s_nop 0
	v_mul_f32_e32 v30, 0x3d372713, v28
	v_mul_f32_e32 v31, 0x3d372713, v29
	v_fma_f32 v30, v28, v30, 1.0
	v_fma_f32 v31, v29, v31, 1.0
	v_mul_f32_e32 v30, v28, v30
	v_mul_f32_e32 v31, v29, v31
	v_mul_f32_e32 v30, 0x40135761, v30
	v_mul_f32_e32 v31, 0x40135761, v31
	v_exp_f32_e32 v30, v30
	v_exp_f32_e32 v31, v31
	v_add_f32_e32 v30, 1.0, v30
	v_add_f32_e32 v31, 1.0, v31
	v_rcp_f32_e32 v30, v30
	v_rcp_f32_e32 v31, v31
	s_nop 0
	v_pk_fma_f32 v[28:29], v[28:29], v[30:31], v[28:29] neg_lo:[1,0,0] neg_hi:[1,0,0]
	s_nop 0
	v_pk_mul_f32 v[26:27], v[26:27], v[28:29]
	v_mov_b64_e32 v[28:29], s[46:47]
	v_cvt_pk_bf16_f32 v25, v26, v27
	v_lshl_add_u64 v[26:27], s[76:77], 0, v[144:145]
	v_mad_u64_u32 v[28:29], s[78:79], v26, s45, v[28:29]
	v_mad_i32_i24 v29, v27, s45, v29
	v_lshl_add_u64 v[26:27], v[192:193], 1, v[28:29]
	global_store_dwordx2 v[26:27], v[24:25], off offset:8
.LBB0_1973:
	s_or_b64 exec, exec, s[28:29]
	v_mov_b32_dpp v60, v20 row_shr:1 row_mask:0xf bank_mask:0xf
	v_mov_b32_dpp v62, v20 row_shr:2 row_mask:0xf bank_mask:0xf
	v_mov_b32_dpp v52, v16 row_shr:1 row_mask:0xf bank_mask:0xf
	v_mov_b32_dpp v56, v16 row_shr:2 row_mask:0xf bank_mask:0xf
	v_mov_b32_dpp v40, v20 row_ror:1 row_mask:0xf bank_mask:0xf bound_ctrl:1
	v_mov_b32_dpp v28, v16 row_ror:1 row_mask:0xf bank_mask:0xf bound_ctrl:1
	v_mov_b32_dpp v42, v20 row_ror:2 row_mask:0xf bank_mask:0xf bound_ctrl:1
	v_mov_b32_dpp v32, v16 row_ror:2 row_mask:0xf bank_mask:0xf bound_ctrl:1
	v_mov_b32_dpp v61, v21 row_shr:1 row_mask:0xf bank_mask:0xf
	v_mov_b32_dpp v63, v21 row_shr:2 row_mask:0xf bank_mask:0xf
	v_mov_b32_dpp v53, v17 row_shr:1 row_mask:0xf bank_mask:0xf
	v_mov_b32_dpp v57, v17 row_shr:2 row_mask:0xf bank_mask:0xf
	v_mov_b32_dpp v41, v21 row_ror:1 row_mask:0xf bank_mask:0xf bound_ctrl:1
	v_mov_b32_dpp v29, v17 row_ror:1 row_mask:0xf bank_mask:0xf bound_ctrl:1
	v_mov_b32_dpp v43, v21 row_ror:2 row_mask:0xf bank_mask:0xf bound_ctrl:1
	v_mov_b32_dpp v33, v17 row_ror:2 row_mask:0xf bank_mask:0xf bound_ctrl:1
	v_mov_b32_dpp v54, v22 row_shr:1 row_mask:0xf bank_mask:0xf
	v_mov_b32_dpp v58, v22 row_shr:2 row_mask:0xf bank_mask:0xf
	v_mov_b32_dpp v48, v18 row_shr:1 row_mask:0xf bank_mask:0xf
	v_mov_b32_dpp v50, v18 row_shr:2 row_mask:0xf bank_mask:0xf
	v_mov_b32_dpp v30, v22 row_ror:1 row_mask:0xf bank_mask:0xf bound_ctrl:1
	v_mov_b32_dpp v24, v18 row_ror:1 row_mask:0xf bank_mask:0xf bound_ctrl:1
	v_mov_b32_dpp v34, v22 row_ror:2 row_mask:0xf bank_mask:0xf bound_ctrl:1
	v_mov_b32_dpp v26, v18 row_ror:2 row_mask:0xf bank_mask:0xf bound_ctrl:1
	v_mov_b32_dpp v55, v23 row_shr:1 row_mask:0xf bank_mask:0xf
	v_mov_b32_dpp v59, v23 row_shr:2 row_mask:0xf bank_mask:0xf
	v_mov_b32_dpp v49, v19 row_shr:1 row_mask:0xf bank_mask:0xf
	v_mov_b32_dpp v51, v19 row_shr:2 row_mask:0xf bank_mask:0xf
	v_mov_b32_dpp v31, v23 row_ror:1 row_mask:0xf bank_mask:0xf bound_ctrl:1
	v_mov_b32_dpp v25, v19 row_ror:1 row_mask:0xf bank_mask:0xf bound_ctrl:1
	v_mov_b32_dpp v35, v23 row_ror:2 row_mask:0xf bank_mask:0xf bound_ctrl:1
	v_mov_b32_dpp v27, v19 row_ror:2 row_mask:0xf bank_mask:0xf bound_ctrl:1
	s_and_saveexec_b64 s[28:29], s[90:91]
	s_cbranch_execz .LBB0_1975
	v_pk_fma_f32 v[36:37], v[80:81], v[62:63], v[92:93]
	v_pk_fma_f32 v[38:39], v[64:65], v[56:57], v[76:77]
	v_pk_fma_f32 v[36:37], v[84:85], v[60:61], v[36:37]
	v_pk_fma_f32 v[38:39], v[68:69], v[52:53], v[38:39]
	v_pk_fma_f32 v[20:21], v[20:21], v[88:89], v[36:37]
	v_pk_fma_f32 v[16:17], v[16:17], v[72:73], v[38:39]
	v_mul_f32_e32 v36, 0x3d372713, v20
	v_mul_f32_e32 v37, 0x3d372713, v21
	v_fma_f32 v36, v20, v36, 1.0
	v_fma_f32 v37, v21, v37, 1.0
	v_mul_f32_e32 v36, v20, v36
	v_mul_f32_e32 v37, v21, v37
	v_mul_f32_e32 v36, 0x40135761, v36
	v_mul_f32_e32 v37, 0x40135761, v37
	v_exp_f32_e32 v36, v36
	v_exp_f32_e32 v37, v37
	v_add_f32_e32 v36, 1.0, v36
	v_add_f32_e32 v37, 1.0, v37
	v_rcp_f32_e32 v36, v36
	v_rcp_f32_e32 v37, v37
	s_nop 0
	v_pk_fma_f32 v[20:21], v[20:21], v[36:37], v[20:21] neg_lo:[1,0,0] neg_hi:[1,0,0]
	v_pk_fma_f32 v[36:37], v[82:83], v[58:59], v[94:95]
	v_pk_mul_f32 v[16:17], v[16:17], v[20:21]
	v_pk_fma_f32 v[36:37], v[86:87], v[54:55], v[36:37]
	v_cvt_pk_bf16_f32 v16, v16, v17
	v_pk_fma_f32 v[22:23], v[22:23], v[90:91], v[36:37]
	s_nop 0
	v_mul_f32_e32 v36, 0x3d372713, v22
	v_mul_f32_e32 v37, 0x3d372713, v23
	v_fma_f32 v36, v22, v36, 1.0
	v_fma_f32 v37, v23, v37, 1.0
	v_mul_f32_e32 v36, v22, v36
	v_mul_f32_e32 v37, v23, v37
	v_mul_f32_e32 v36, 0x40135761, v36
	v_mul_f32_e32 v37, 0x40135761, v37
	v_exp_f32_e32 v36, v36
	v_exp_f32_e32 v37, v37
	v_add_f32_e32 v20, 1.0, v36
	v_add_f32_e32 v21, 1.0, v37
	v_rcp_f32_e32 v20, v20
	v_rcp_f32_e32 v21, v21
	v_pk_fma_f32 v[36:37], v[66:67], v[50:51], v[78:79]
	v_pk_fma_f32 v[20:21], v[22:23], v[20:21], v[22:23] neg_lo:[1,0,0] neg_hi:[1,0,0]
	v_pk_fma_f32 v[36:37], v[70:71], v[48:49], v[36:37]
	s_nop 0
	v_pk_fma_f32 v[18:19], v[18:19], v[74:75], v[36:37]
	s_nop 0
	v_pk_mul_f32 v[18:19], v[18:19], v[20:21]
	v_mov_b64_e32 v[20:21], s[46:47]
	v_cvt_pk_bf16_f32 v17, v18, v19
	v_lshl_add_u64 v[18:19], s[76:77], 0, v[136:137]
	v_mad_u64_u32 v[20:21], s[78:79], v18, s45, v[20:21]
	v_mad_i32_i24 v21, v19, s45, v21
	v_lshl_add_u64 v[18:19], v[192:193], 1, v[20:21]
	global_store_dwordx2 v[18:19], v[16:17], off offset:8
.LBB0_1975:
	s_or_b64 exec, exec, s[28:29]
	v_mov_b32_dpp v40, v12 row_shr:1 row_mask:0xf bank_mask:0xf
	v_mov_b32_dpp v42, v12 row_shr:2 row_mask:0xf bank_mask:0xf
	v_mov_b32_dpp v28, v8 row_shr:1 row_mask:0xf bank_mask:0xf
	v_mov_b32_dpp v32, v8 row_shr:2 row_mask:0xf bank_mask:0xf
	v_mov_b32_dpp v44, v12 row_ror:1 row_mask:0xf bank_mask:0xf bound_ctrl:1
	v_mov_b32_dpp v20, v8 row_ror:1 row_mask:0xf bank_mask:0xf bound_ctrl:1
	v_mov_b32_dpp v46, v12 row_ror:2 row_mask:0xf bank_mask:0xf bound_ctrl:1
	v_mov_b32_dpp v36, v8 row_ror:2 row_mask:0xf bank_mask:0xf bound_ctrl:1
	v_mov_b32_dpp v41, v13 row_shr:1 row_mask:0xf bank_mask:0xf
	v_mov_b32_dpp v43, v13 row_shr:2 row_mask:0xf bank_mask:0xf
	v_mov_b32_dpp v29, v9 row_shr:1 row_mask:0xf bank_mask:0xf
	v_mov_b32_dpp v33, v9 row_shr:2 row_mask:0xf bank_mask:0xf
	v_mov_b32_dpp v45, v13 row_ror:1 row_mask:0xf bank_mask:0xf bound_ctrl:1
	v_mov_b32_dpp v21, v9 row_ror:1 row_mask:0xf bank_mask:0xf bound_ctrl:1
	v_mov_b32_dpp v47, v13 row_ror:2 row_mask:0xf bank_mask:0xf bound_ctrl:1
	v_mov_b32_dpp v37, v9 row_ror:2 row_mask:0xf bank_mask:0xf bound_ctrl:1
	v_mov_b32_dpp v30, v14 row_shr:1 row_mask:0xf bank_mask:0xf
	v_mov_b32_dpp v34, v14 row_shr:2 row_mask:0xf bank_mask:0xf
	v_mov_b32_dpp v24, v10 row_shr:1 row_mask:0xf bank_mask:0xf
	v_mov_b32_dpp v26, v10 row_shr:2 row_mask:0xf bank_mask:0xf
	v_mov_b32_dpp v22, v14 row_ror:1 row_mask:0xf bank_mask:0xf bound_ctrl:1
	v_mov_b32_dpp v16, v10 row_ror:1 row_mask:0xf bank_mask:0xf bound_ctrl:1
	v_mov_b32_dpp v38, v14 row_ror:2 row_mask:0xf bank_mask:0xf bound_ctrl:1
	v_mov_b32_dpp v18, v10 row_ror:2 row_mask:0xf bank_mask:0xf bound_ctrl:1
	v_mov_b32_dpp v31, v15 row_shr:1 row_mask:0xf bank_mask:0xf
	v_mov_b32_dpp v35, v15 row_shr:2 row_mask:0xf bank_mask:0xf
	v_mov_b32_dpp v25, v11 row_shr:1 row_mask:0xf bank_mask:0xf
	v_mov_b32_dpp v27, v11 row_shr:2 row_mask:0xf bank_mask:0xf
	v_mov_b32_dpp v23, v15 row_ror:1 row_mask:0xf bank_mask:0xf bound_ctrl:1
	v_mov_b32_dpp v17, v11 row_ror:1 row_mask:0xf bank_mask:0xf bound_ctrl:1
	v_mov_b32_dpp v39, v15 row_ror:2 row_mask:0xf bank_mask:0xf bound_ctrl:1
	v_mov_b32_dpp v19, v11 row_ror:2 row_mask:0xf bank_mask:0xf bound_ctrl:1
	s_and_saveexec_b64 s[28:29], s[92:93]
	s_cbranch_execz .LBB0_1977
	v_pk_fma_f32 v[42:43], v[80:81], v[42:43], v[92:93]
	v_pk_fma_f32 v[32:33], v[64:65], v[32:33], v[76:77]
	v_pk_fma_f32 v[40:41], v[84:85], v[40:41], v[42:43]
	v_pk_fma_f32 v[28:29], v[68:69], v[28:29], v[32:33]
	v_pk_fma_f32 v[12:13], v[12:13], v[88:89], v[40:41]
	v_pk_fma_f32 v[8:9], v[8:9], v[72:73], v[28:29]
	v_mul_f32_e32 v40, 0x3d372713, v12
	v_mul_f32_e32 v41, 0x3d372713, v13
	v_fma_f32 v40, v12, v40, 1.0
	v_fma_f32 v41, v13, v41, 1.0
	v_mul_f32_e32 v40, v12, v40
	v_mul_f32_e32 v41, v13, v41
	v_mul_f32_e32 v40, 0x40135761, v40
	v_mul_f32_e32 v41, 0x40135761, v41
	v_pk_fma_f32 v[28:29], v[82:83], v[34:35], v[94:95]
	v_exp_f32_e32 v40, v40
	v_exp_f32_e32 v41, v41
	v_pk_fma_f32 v[28:29], v[86:87], v[30:31], v[28:29]
	v_pk_fma_f32 v[26:27], v[66:67], v[26:27], v[78:79]
	v_pk_fma_f32 v[14:15], v[14:15], v[90:91], v[28:29]
	v_add_f32_e32 v40, 1.0, v40
	v_mul_f32_e32 v28, 0x3d372713, v14
	v_mul_f32_e32 v29, 0x3d372713, v15
	v_fma_f32 v28, v14, v28, 1.0
	v_fma_f32 v29, v15, v29, 1.0
	v_add_f32_e32 v41, 1.0, v41
	v_mul_f32_e32 v28, v14, v28
	v_mul_f32_e32 v29, v15, v29
	v_rcp_f32_e32 v40, v40
	v_rcp_f32_e32 v41, v41
	v_mul_f32_e32 v28, 0x40135761, v28
	v_mul_f32_e32 v29, 0x40135761, v29
	v_exp_f32_e32 v28, v28
	v_exp_f32_e32 v29, v29
	v_pk_fma_f32 v[12:13], v[12:13], v[40:41], v[12:13] neg_lo:[1,0,0] neg_hi:[1,0,0]
	v_pk_fma_f32 v[24:25], v[70:71], v[24:25], v[26:27]
	v_pk_mul_f32 v[8:9], v[8:9], v[12:13]
	v_add_f32_e32 v12, 1.0, v28
	v_add_f32_e32 v13, 1.0, v29
	v_rcp_f32_e32 v12, v12
	v_rcp_f32_e32 v13, v13
	v_pk_fma_f32 v[10:11], v[10:11], v[74:75], v[24:25]
	v_cvt_pk_bf16_f32 v8, v8, v9
	v_pk_fma_f32 v[12:13], v[14:15], v[12:13], v[14:15] neg_lo:[1,0,0] neg_hi:[1,0,0]
	s_nop 0
	v_pk_mul_f32 v[10:11], v[10:11], v[12:13]
	v_mov_b64_e32 v[12:13], s[46:47]
	v_cvt_pk_bf16_f32 v9, v10, v11
	v_lshl_add_u64 v[10:11], s[76:77], 0, v[138:139]
	v_mad_u64_u32 v[12:13], s[78:79], v10, s45, v[12:13]
	v_mad_i32_i24 v13, v11, s45, v13
	v_lshl_add_u64 v[10:11], v[192:193], 1, v[12:13]
	global_store_dwordx2 v[10:11], v[8:9], off offset:8
.LBB0_1977:
	s_or_b64 exec, exec, s[28:29]
	v_mov_b32_dpp v44, v4 row_shr:1 row_mask:0xf bank_mask:0xf
	v_mov_b32_dpp v46, v4 row_shr:2 row_mask:0xf bank_mask:0xf
	v_mov_b32_dpp v20, v0 row_shr:1 row_mask:0xf bank_mask:0xf
	v_mov_b32_dpp v36, v0 row_shr:2 row_mask:0xf bank_mask:0xf
	v_mov_b32_dpp v45, v5 row_shr:1 row_mask:0xf bank_mask:0xf
	v_mov_b32_dpp v47, v5 row_shr:2 row_mask:0xf bank_mask:0xf
	v_mov_b32_dpp v21, v1 row_shr:1 row_mask:0xf bank_mask:0xf
	v_mov_b32_dpp v37, v1 row_shr:2 row_mask:0xf bank_mask:0xf
	v_mov_b32_dpp v22, v6 row_shr:1 row_mask:0xf bank_mask:0xf
	v_mov_b32_dpp v38, v6 row_shr:2 row_mask:0xf bank_mask:0xf
	v_mov_b32_dpp v16, v2 row_shr:1 row_mask:0xf bank_mask:0xf
	v_mov_b32_dpp v18, v2 row_shr:2 row_mask:0xf bank_mask:0xf
	v_mov_b32_dpp v23, v7 row_shr:1 row_mask:0xf bank_mask:0xf
	v_mov_b32_dpp v39, v7 row_shr:2 row_mask:0xf bank_mask:0xf
	v_mov_b32_dpp v17, v3 row_shr:1 row_mask:0xf bank_mask:0xf
	v_mov_b32_dpp v19, v3 row_shr:2 row_mask:0xf bank_mask:0xf
	s_and_saveexec_b64 s[28:29], s[94:95]
	s_cbranch_execz .LBB0_1979
	v_pk_fma_f32 v[8:9], v[80:81], v[46:47], v[92:93]
	v_pk_fma_f32 v[10:11], v[64:65], v[36:37], v[76:77]
	v_pk_fma_f32 v[8:9], v[84:85], v[44:45], v[8:9]
	v_pk_fma_f32 v[10:11], v[68:69], v[20:21], v[10:11]
	v_pk_fma_f32 v[4:5], v[4:5], v[88:89], v[8:9]
	v_pk_fma_f32 v[0:1], v[0:1], v[72:73], v[10:11]
	v_mul_f32_e32 v8, 0x3d372713, v4
	v_mul_f32_e32 v9, 0x3d372713, v5
	v_fma_f32 v8, v4, v8, 1.0
	v_fma_f32 v9, v5, v9, 1.0
	v_mul_f32_e32 v8, v4, v8
	v_mul_f32_e32 v9, v5, v9
	v_mul_f32_e32 v8, 0x40135761, v8
	v_mul_f32_e32 v9, 0x40135761, v9
	v_exp_f32_e32 v8, v8
	v_exp_f32_e32 v9, v9
	v_add_f32_e32 v8, 1.0, v8
	v_add_f32_e32 v9, 1.0, v9
	v_rcp_f32_e32 v8, v8
	v_rcp_f32_e32 v9, v9
	s_nop 0
	v_pk_fma_f32 v[4:5], v[4:5], v[8:9], v[4:5] neg_lo:[1,0,0] neg_hi:[1,0,0]
	v_pk_fma_f32 v[8:9], v[82:83], v[38:39], v[94:95]
	v_pk_mul_f32 v[0:1], v[0:1], v[4:5]
	v_pk_fma_f32 v[8:9], v[86:87], v[22:23], v[8:9]
	v_cvt_pk_bf16_f32 v0, v0, v1
	v_pk_fma_f32 v[6:7], v[6:7], v[90:91], v[8:9]
	s_nop 0
	v_mul_f32_e32 v8, 0x3d372713, v6
	v_mul_f32_e32 v9, 0x3d372713, v7
	v_fma_f32 v8, v6, v8, 1.0
	v_fma_f32 v9, v7, v9, 1.0
	v_mul_f32_e32 v8, v6, v8
	v_mul_f32_e32 v9, v7, v9
	v_mul_f32_e32 v8, 0x40135761, v8
	v_mul_f32_e32 v9, 0x40135761, v9
	v_exp_f32_e32 v8, v8
	v_exp_f32_e32 v9, v9
	v_add_f32_e32 v4, 1.0, v8
	v_add_f32_e32 v5, 1.0, v9
	v_rcp_f32_e32 v4, v4
	v_rcp_f32_e32 v5, v5
	v_pk_fma_f32 v[8:9], v[66:67], v[18:19], v[78:79]
	v_pk_fma_f32 v[4:5], v[6:7], v[4:5], v[6:7] neg_lo:[1,0,0] neg_hi:[1,0,0]
	v_pk_fma_f32 v[8:9], v[70:71], v[16:17], v[8:9]
	s_nop 0
	v_pk_fma_f32 v[2:3], v[2:3], v[74:75], v[8:9]
	s_nop 0
	v_pk_mul_f32 v[2:3], v[2:3], v[4:5]
	v_mov_b64_e32 v[4:5], s[46:47]
	v_cvt_pk_bf16_f32 v1, v2, v3
	v_lshl_add_u64 v[2:3], s[76:77], 0, v[140:141]
	v_mad_u64_u32 v[4:5], s[76:77], v2, s45, v[4:5]
	v_mad_i32_i24 v5, v3, s45, v5
	v_lshl_add_u64 v[2:3], v[192:193], 1, v[4:5]
	global_store_dwordx2 v[2:3], v[0:1], off offset:8

.LBB0_3357:
	s_mul_hi_i32 s67, s41, 0x3e0f83e1
	s_lshr_b32 s72, s67, 31
	s_ashr_i32 s67, s67, 3
	s_add_i32 s72, s67, s72
	s_mul_i32 s67, s72, 33
	s_sub_i32 s41, s41, s67
	s_mul_i32 s67, s41, 0xfe
	v_add_u32_e32 v194, s67, v224
	s_or_b32 s67, s41, s94
	s_cmp_eq_u32 s67, 0
	s_cselect_b64 s[74:75], -1, 0
	s_cmp_eq_u32 s41, 32
	s_movk_i32 s41, 0x42
	s_cselect_b32 s41, s41, 0x100
	s_and_b64 s[74:75], s[74:75], s[12:13]
	s_ashr_i32 s73, s72, 31
	v_cndmask_b32_e64 v217, v159, 0, s[74:75]
	v_cndmask_b32_e64 v216, v158, 0, s[74:75]
	v_cndmask_b32_e64 v219, v157, 0, s[74:75]
	v_cndmask_b32_e64 v218, v156, 0, s[74:75]
	v_cndmask_b32_e64 v159, v155, 0, s[74:75]
	v_cndmask_b32_e64 v158, v154, 0, s[74:75]
	v_cndmask_b32_e64 v153, v153, 0, s[74:75]
	v_cndmask_b32_e64 v152, v152, 0, s[74:75]
	v_cmp_gt_u32_e32 vcc, s41, v220
	s_lshl_b64 s[72:73], s[72:73], 13
	v_mov_b32_dpp v173, v218 row_shr:1 row_mask:0xf bank_mask:0xf
	v_mov_b32_dpp v214, v218 row_shr:2 row_mask:0xf bank_mask:0xf
	v_mov_b32_dpp v169, v152 row_shr:1 row_mask:0xf bank_mask:0xf
	v_mov_b32_dpp v212, v152 row_shr:2 row_mask:0xf bank_mask:0xf
	v_mov_b32_dpp v204, v218 row_ror:1 row_mask:0xf bank_mask:0xf bound_ctrl:1
	v_mov_b32_dpp v196, v152 row_ror:1 row_mask:0xf bank_mask:0xf bound_ctrl:1
	v_mov_b32_dpp v206, v218 row_ror:2 row_mask:0xf bank_mask:0xf bound_ctrl:1
	v_mov_b32_dpp v200, v152 row_ror:2 row_mask:0xf bank_mask:0xf bound_ctrl:1
	v_mov_b32_dpp v175, v219 row_shr:1 row_mask:0xf bank_mask:0xf
	v_mov_b32_dpp v215, v219 row_shr:2 row_mask:0xf bank_mask:0xf
	v_mov_b32_dpp v171, v153 row_shr:1 row_mask:0xf bank_mask:0xf
	v_mov_b32_dpp v213, v153 row_shr:2 row_mask:0xf bank_mask:0xf
	v_mov_b32_dpp v205, v219 row_ror:1 row_mask:0xf bank_mask:0xf bound_ctrl:1
	v_mov_b32_dpp v197, v153 row_ror:1 row_mask:0xf bank_mask:0xf bound_ctrl:1
	v_mov_b32_dpp v207, v219 row_ror:2 row_mask:0xf bank_mask:0xf bound_ctrl:1
	v_mov_b32_dpp v201, v153 row_ror:2 row_mask:0xf bank_mask:0xf bound_ctrl:1
	v_mov_b32_dpp v165, v216 row_shr:1 row_mask:0xf bank_mask:0xf
	v_mov_b32_dpp v210, v216 row_shr:2 row_mask:0xf bank_mask:0xf
	v_mov_b32_dpp v161, v158 row_shr:1 row_mask:0xf bank_mask:0xf
	v_mov_b32_dpp v208, v158 row_shr:2 row_mask:0xf bank_mask:0xf
	v_mov_b32_dpp v198, v216 row_ror:1 row_mask:0xf bank_mask:0xf bound_ctrl:1
	v_mov_b32_dpp v154, v158 row_ror:1 row_mask:0xf bank_mask:0xf bound_ctrl:1
	v_mov_b32_dpp v202, v216 row_ror:2 row_mask:0xf bank_mask:0xf bound_ctrl:1
	v_mov_b32_dpp v156, v158 row_ror:2 row_mask:0xf bank_mask:0xf bound_ctrl:1
	v_mov_b32_dpp v167, v217 row_shr:1 row_mask:0xf bank_mask:0xf
	v_mov_b32_dpp v211, v217 row_shr:2 row_mask:0xf bank_mask:0xf
	v_mov_b32_dpp v163, v159 row_shr:1 row_mask:0xf bank_mask:0xf
	v_mov_b32_dpp v209, v159 row_shr:2 row_mask:0xf bank_mask:0xf
	v_mov_b32_dpp v199, v217 row_ror:1 row_mask:0xf bank_mask:0xf bound_ctrl:1
	v_mov_b32_dpp v155, v159 row_ror:1 row_mask:0xf bank_mask:0xf bound_ctrl:1
	v_mov_b32_dpp v203, v217 row_ror:2 row_mask:0xf bank_mask:0xf bound_ctrl:1
	v_mov_b32_dpp v157, v159 row_ror:2 row_mask:0xf bank_mask:0xf bound_ctrl:1
	s_and_b64 s[76:77], s[16:17], vcc
	v_ashrrev_i32_e32 v195, 31, v194
	s_waitcnt vmcnt(0)
	s_and_saveexec_b64 s[78:79], s[76:77]
	s_cbranch_execz .LBB0_3359
	v_mov_b32_e32 v174, v173
	v_pk_fma_f32 v[172:173], v[120:121], v[214:215], v[132:133]
	v_mov_b32_e32 v166, v165
	v_pk_fma_f32 v[172:173], v[124:125], v[174:175], v[172:173]
	v_pk_fma_f32 v[164:165], v[122:123], v[210:211], v[134:135]
	v_pk_fma_f32 v[172:173], v[218:219], v[128:129], v[172:173]
	v_pk_fma_f32 v[164:165], v[126:127], v[166:167], v[164:165]
	v_mul_f32_e32 v160, 0x3d372713, v172
	v_fma_f32 v160, v172, v160, 1.0
	v_mul_f32_e32 v162, 0x3d372713, v173
	v_mul_f32_e32 v160, v172, v160
	v_fma_f32 v162, v173, v162, 1.0
	v_mul_f32_e32 v160, 0x40135761, v160
	v_mul_f32_e32 v162, v173, v162
	v_exp_f32_e32 v160, v160
	v_mul_f32_e32 v162, 0x40135761, v162
	v_exp_f32_e32 v162, v162
	v_pk_fma_f32 v[164:165], v[216:217], v[130:131], v[164:165]
	v_add_f32_e32 v160, 1.0, v160
	v_rcp_f32_e32 v168, v160
	v_add_f32_e32 v160, 1.0, v162
	v_mov_b32_e32 v170, v169
	v_rcp_f32_e32 v169, v160
	v_mul_f32_e32 v160, 0x3d372713, v164
	v_mul_f32_e32 v162, 0x3d372713, v165
	v_fma_f32 v160, v164, v160, 1.0
	v_fma_f32 v162, v165, v162, 1.0
	v_mul_f32_e32 v160, v164, v160
	v_mul_f32_e32 v162, v165, v162
	v_mul_f32_e32 v160, 0x40135761, v160
	v_mul_f32_e32 v162, 0x40135761, v162
	v_exp_f32_e32 v160, v160
	v_exp_f32_e32 v166, v162
	v_mov_b32_e32 v162, v161
	v_pk_fma_f32 v[174:175], v[104:105], v[212:213], v[116:117]
	v_add_f32_e32 v160, 1.0, v160
	v_add_f32_e32 v161, 1.0, v166
	v_rcp_f32_e32 v160, v160
	v_rcp_f32_e32 v161, v161
	v_pk_fma_f32 v[166:167], v[106:107], v[208:209], v[118:119]
	v_pk_fma_f32 v[170:171], v[108:109], v[170:171], v[174:175]
	v_pk_fma_f32 v[162:163], v[110:111], v[162:163], v[166:167]
	v_pk_fma_f32 v[152:153], v[152:153], v[112:113], v[170:171]
	v_pk_fma_f32 v[168:169], v[172:173], v[168:169], v[172:173] neg_lo:[1,0,0] neg_hi:[1,0,0]
	v_pk_fma_f32 v[158:159], v[158:159], v[114:115], v[162:163]
	v_pk_fma_f32 v[160:161], v[164:165], v[160:161], v[164:165] neg_lo:[1,0,0] neg_hi:[1,0,0]
	v_pk_mul_f32 v[152:153], v[152:153], v[168:169]
	v_pk_mul_f32 v[158:159], v[158:159], v[160:161]
	v_cvt_pk_bf16_f32 v152, v152, v153
	v_cvt_pk_bf16_f32 v153, v158, v159
	v_lshl_add_u64 v[158:159], s[72:73], 0, v[194:195]
	v_mov_b64_e32 v[160:161], s[42:43]
	v_mad_u64_u32 v[160:161], s[80:81], v158, s1, v[160:161]
	v_mad_i32_i24 v161, v159, s1, v161
	v_lshl_add_u64 v[158:159], v[192:193], 1, v[160:161]
	global_store_dwordx2 v[158:159], v[152:153], off
.LBB0_3359:
	s_or_b64 exec, exec, s[78:79]
	v_cmp_gt_i32_e32 vcc, s41, v225
	v_add_u32_e32 v152, 16, v194
	v_mov_b32_dpp v204, v148 row_shr:1 row_mask:0xf bank_mask:0xf
	v_mov_b32_dpp v206, v148 row_shr:2 row_mask:0xf bank_mask:0xf
	v_mov_b32_dpp v196, v144 row_shr:1 row_mask:0xf bank_mask:0xf
	v_mov_b32_dpp v200, v144 row_shr:2 row_mask:0xf bank_mask:0xf
	v_mov_b32_dpp v174, v148 row_ror:1 row_mask:0xf bank_mask:0xf bound_ctrl:1
	v_mov_b32_dpp v162, v144 row_ror:1 row_mask:0xf bank_mask:0xf bound_ctrl:1
	v_mov_b32_dpp v208, v148 row_ror:2 row_mask:0xf bank_mask:0xf bound_ctrl:1
	v_mov_b32_dpp v166, v144 row_ror:2 row_mask:0xf bank_mask:0xf bound_ctrl:1
	v_mov_b32_dpp v205, v149 row_shr:1 row_mask:0xf bank_mask:0xf
	v_mov_b32_dpp v207, v149 row_shr:2 row_mask:0xf bank_mask:0xf
	v_mov_b32_dpp v197, v145 row_shr:1 row_mask:0xf bank_mask:0xf
	v_mov_b32_dpp v201, v145 row_shr:2 row_mask:0xf bank_mask:0xf
	v_mov_b32_dpp v175, v149 row_ror:1 row_mask:0xf bank_mask:0xf bound_ctrl:1
	v_mov_b32_dpp v163, v145 row_ror:1 row_mask:0xf bank_mask:0xf bound_ctrl:1
	v_mov_b32_dpp v209, v149 row_ror:2 row_mask:0xf bank_mask:0xf bound_ctrl:1
	v_mov_b32_dpp v167, v145 row_ror:2 row_mask:0xf bank_mask:0xf bound_ctrl:1
	v_mov_b32_dpp v198, v150 row_shr:1 row_mask:0xf bank_mask:0xf
	v_mov_b32_dpp v202, v150 row_shr:2 row_mask:0xf bank_mask:0xf
	v_mov_b32_dpp v154, v146 row_shr:1 row_mask:0xf bank_mask:0xf
	v_mov_b32_dpp v156, v146 row_shr:2 row_mask:0xf bank_mask:0xf
	v_mov_b32_dpp v164, v150 row_ror:1 row_mask:0xf bank_mask:0xf bound_ctrl:1
	v_mov_b32_dpp v158, v146 row_ror:1 row_mask:0xf bank_mask:0xf bound_ctrl:1
	v_mov_b32_dpp v168, v150 row_ror:2 row_mask:0xf bank_mask:0xf bound_ctrl:1
	v_mov_b32_dpp v160, v146 row_ror:2 row_mask:0xf bank_mask:0xf bound_ctrl:1
	v_mov_b32_dpp v199, v151 row_shr:1 row_mask:0xf bank_mask:0xf
	v_mov_b32_dpp v203, v151 row_shr:2 row_mask:0xf bank_mask:0xf
	v_mov_b32_dpp v155, v147 row_shr:1 row_mask:0xf bank_mask:0xf
	v_mov_b32_dpp v157, v147 row_shr:2 row_mask:0xf bank_mask:0xf
	v_mov_b32_dpp v165, v151 row_ror:1 row_mask:0xf bank_mask:0xf bound_ctrl:1
	v_mov_b32_dpp v159, v147 row_ror:1 row_mask:0xf bank_mask:0xf bound_ctrl:1
	v_mov_b32_dpp v169, v151 row_ror:2 row_mask:0xf bank_mask:0xf bound_ctrl:1
	v_mov_b32_dpp v161, v147 row_ror:2 row_mask:0xf bank_mask:0xf bound_ctrl:1
	s_and_b64 s[78:79], s[54:55], vcc
	v_ashrrev_i32_e32 v153, 31, v152
	s_and_saveexec_b64 s[80:81], s[78:79]
	s_cbranch_execz .LBB0_3361
	v_pk_fma_f32 v[170:171], v[120:121], v[206:207], v[132:133]
	v_pk_fma_f32 v[172:173], v[104:105], v[200:201], v[116:117]
	v_pk_fma_f32 v[170:171], v[124:125], v[204:205], v[170:171]
	v_pk_fma_f32 v[172:173], v[108:109], v[196:197], v[172:173]
	v_pk_fma_f32 v[148:149], v[148:149], v[128:129], v[170:171]
	v_pk_fma_f32 v[144:145], v[144:145], v[112:113], v[172:173]
	v_mul_f32_e32 v170, 0x3d372713, v148
	v_mul_f32_e32 v171, 0x3d372713, v149
	v_fma_f32 v170, v148, v170, 1.0
	v_fma_f32 v171, v149, v171, 1.0
	v_mul_f32_e32 v170, v148, v170
	v_mul_f32_e32 v171, v149, v171
	v_mul_f32_e32 v170, 0x40135761, v170
	v_mul_f32_e32 v171, 0x40135761, v171
	v_exp_f32_e32 v170, v170
	v_exp_f32_e32 v171, v171
	v_pk_fma_f32 v[156:157], v[106:107], v[156:157], v[118:119]
	v_add_f32_e32 v170, 1.0, v170
	v_add_f32_e32 v171, 1.0, v171
	v_rcp_f32_e32 v170, v170
	v_rcp_f32_e32 v171, v171
	v_pk_fma_f32 v[154:155], v[110:111], v[154:155], v[156:157]
	v_pk_fma_f32 v[148:149], v[148:149], v[170:171], v[148:149] neg_lo:[1,0,0] neg_hi:[1,0,0]
	v_pk_fma_f32 v[170:171], v[122:123], v[202:203], v[134:135]
	v_pk_mul_f32 v[144:145], v[144:145], v[148:149]
	v_pk_fma_f32 v[170:171], v[126:127], v[198:199], v[170:171]
	v_pk_fma_f32 v[146:147], v[146:147], v[114:115], v[154:155]
	v_pk_fma_f32 v[150:151], v[150:151], v[130:131], v[170:171]
	v_cvt_pk_bf16_f32 v144, v144, v145
	v_mul_f32_e32 v170, 0x3d372713, v150
	v_mul_f32_e32 v171, 0x3d372713, v151
	v_fma_f32 v170, v150, v170, 1.0
	v_fma_f32 v171, v151, v171, 1.0
	v_mul_f32_e32 v170, v150, v170
	v_mul_f32_e32 v171, v151, v171
	v_mul_f32_e32 v170, 0x40135761, v170
	v_mul_f32_e32 v171, 0x40135761, v171
	v_exp_f32_e32 v170, v170
	v_exp_f32_e32 v171, v171
	v_add_f32_e32 v148, 1.0, v170
	v_add_f32_e32 v149, 1.0, v171
	v_rcp_f32_e32 v148, v148
	v_rcp_f32_e32 v149, v149
	s_nop 0
	v_pk_fma_f32 v[148:149], v[150:151], v[148:149], v[150:151] neg_lo:[1,0,0] neg_hi:[1,0,0]
	s_nop 0
	v_pk_mul_f32 v[146:147], v[146:147], v[148:149]
	v_mov_b64_e32 v[148:149], s[42:43]
	v_cvt_pk_bf16_f32 v145, v146, v147
	v_lshl_add_u64 v[146:147], s[72:73], 0, v[152:153]
	v_mad_u64_u32 v[148:149], s[82:83], v146, s1, v[148:149]
	v_mad_i32_i24 v149, v147, s1, v149
	v_lshl_add_u64 v[146:147], v[192:193], 1, v[148:149]
	global_store_dwordx2 v[146:147], v[144:145], off
.LBB0_3361:
	s_or_b64 exec, exec, s[80:81]
	v_cmp_gt_i32_e32 vcc, s41, v226
	v_add_u32_e32 v146, 32, v194
	v_mov_b32_dpp v174, v140 row_shr:1 row_mask:0xf bank_mask:0xf
	v_mov_b32_dpp v208, v140 row_shr:2 row_mask:0xf bank_mask:0xf
	v_mov_b32_dpp v162, v136 row_shr:1 row_mask:0xf bank_mask:0xf
	v_mov_b32_dpp v166, v136 row_shr:2 row_mask:0xf bank_mask:0xf
	v_mov_b32_dpp v196, v140 row_ror:1 row_mask:0xf bank_mask:0xf bound_ctrl:1
	v_mov_b32_dpp v154, v136 row_ror:1 row_mask:0xf bank_mask:0xf bound_ctrl:1
	v_mov_b32_dpp v198, v140 row_ror:2 row_mask:0xf bank_mask:0xf bound_ctrl:1
	v_mov_b32_dpp v170, v136 row_ror:2 row_mask:0xf bank_mask:0xf bound_ctrl:1
	v_mov_b32_dpp v175, v141 row_shr:1 row_mask:0xf bank_mask:0xf
	v_mov_b32_dpp v209, v141 row_shr:2 row_mask:0xf bank_mask:0xf
	v_mov_b32_dpp v163, v137 row_shr:1 row_mask:0xf bank_mask:0xf
	v_mov_b32_dpp v167, v137 row_shr:2 row_mask:0xf bank_mask:0xf
	v_mov_b32_dpp v197, v141 row_ror:1 row_mask:0xf bank_mask:0xf bound_ctrl:1
	v_mov_b32_dpp v155, v137 row_ror:1 row_mask:0xf bank_mask:0xf bound_ctrl:1
	v_mov_b32_dpp v199, v141 row_ror:2 row_mask:0xf bank_mask:0xf bound_ctrl:1
	v_mov_b32_dpp v171, v137 row_ror:2 row_mask:0xf bank_mask:0xf bound_ctrl:1
	v_mov_b32_dpp v164, v142 row_shr:1 row_mask:0xf bank_mask:0xf
	v_mov_b32_dpp v168, v142 row_shr:2 row_mask:0xf bank_mask:0xf
	v_mov_b32_dpp v158, v138 row_shr:1 row_mask:0xf bank_mask:0xf
	v_mov_b32_dpp v160, v138 row_shr:2 row_mask:0xf bank_mask:0xf
	v_mov_b32_dpp v156, v142 row_ror:1 row_mask:0xf bank_mask:0xf bound_ctrl:1
	v_mov_b32_dpp v144, v138 row_ror:1 row_mask:0xf bank_mask:0xf bound_ctrl:1
	v_mov_b32_dpp v172, v142 row_ror:2 row_mask:0xf bank_mask:0xf bound_ctrl:1
	v_mov_b32_dpp v150, v138 row_ror:2 row_mask:0xf bank_mask:0xf bound_ctrl:1
	v_mov_b32_dpp v165, v143 row_shr:1 row_mask:0xf bank_mask:0xf
	v_mov_b32_dpp v169, v143 row_shr:2 row_mask:0xf bank_mask:0xf
	v_mov_b32_dpp v159, v139 row_shr:1 row_mask:0xf bank_mask:0xf
	v_mov_b32_dpp v161, v139 row_shr:2 row_mask:0xf bank_mask:0xf
	v_mov_b32_dpp v157, v143 row_ror:1 row_mask:0xf bank_mask:0xf bound_ctrl:1
	v_mov_b32_dpp v145, v139 row_ror:1 row_mask:0xf bank_mask:0xf bound_ctrl:1
	v_mov_b32_dpp v173, v143 row_ror:2 row_mask:0xf bank_mask:0xf bound_ctrl:1
	v_mov_b32_dpp v151, v139 row_ror:2 row_mask:0xf bank_mask:0xf bound_ctrl:1
	s_and_b64 s[80:81], s[54:55], vcc
	v_ashrrev_i32_e32 v147, 31, v146
	s_and_saveexec_b64 s[82:83], s[80:81]
	s_cbranch_execz .LBB0_3363
	v_pk_fma_f32 v[148:149], v[120:121], v[208:209], v[132:133]
	v_pk_fma_f32 v[166:167], v[104:105], v[166:167], v[116:117]
	v_pk_fma_f32 v[148:149], v[124:125], v[174:175], v[148:149]
	v_pk_fma_f32 v[162:163], v[108:109], v[162:163], v[166:167]
	v_pk_fma_f32 v[140:141], v[140:141], v[128:129], v[148:149]
	v_pk_fma_f32 v[136:137], v[136:137], v[112:113], v[162:163]
	v_mul_f32_e32 v148, 0x3d372713, v140
	v_mul_f32_e32 v149, 0x3d372713, v141
	v_fma_f32 v148, v140, v148, 1.0
	v_fma_f32 v149, v141, v149, 1.0
	v_mul_f32_e32 v148, v140, v148
	v_mul_f32_e32 v149, v141, v149
	v_mul_f32_e32 v148, 0x40135761, v148
	v_mul_f32_e32 v149, 0x40135761, v149
	v_exp_f32_e32 v148, v148
	v_exp_f32_e32 v149, v149
	v_add_f32_e32 v148, 1.0, v148
	v_add_f32_e32 v149, 1.0, v149
	v_rcp_f32_e32 v148, v148
	v_rcp_f32_e32 v149, v149
	s_nop 0
	v_pk_fma_f32 v[140:141], v[140:141], v[148:149], v[140:141] neg_lo:[1,0,0] neg_hi:[1,0,0]
	v_pk_fma_f32 v[148:149], v[122:123], v[168:169], v[134:135]
	v_pk_mul_f32 v[136:137], v[136:137], v[140:141]
	v_pk_fma_f32 v[148:149], v[126:127], v[164:165], v[148:149]
	v_cvt_pk_bf16_f32 v136, v136, v137
	v_pk_fma_f32 v[142:143], v[142:143], v[130:131], v[148:149]
	s_nop 0
	v_mul_f32_e32 v148, 0x3d372713, v142
	v_mul_f32_e32 v149, 0x3d372713, v143
	v_fma_f32 v148, v142, v148, 1.0
	v_fma_f32 v149, v143, v149, 1.0
	v_mul_f32_e32 v148, v142, v148
	v_mul_f32_e32 v149, v143, v149
	v_mul_f32_e32 v148, 0x40135761, v148
	v_mul_f32_e32 v149, 0x40135761, v149
	v_exp_f32_e32 v148, v148
	v_exp_f32_e32 v149, v149
	v_add_f32_e32 v140, 1.0, v148
	v_add_f32_e32 v141, 1.0, v149
	v_rcp_f32_e32 v140, v140
	v_rcp_f32_e32 v141, v141
	v_pk_fma_f32 v[148:149], v[106:107], v[160:161], v[118:119]
	v_pk_fma_f32 v[140:141], v[142:143], v[140:141], v[142:143] neg_lo:[1,0,0] neg_hi:[1,0,0]
	v_pk_fma_f32 v[148:149], v[110:111], v[158:159], v[148:149]
	s_nop 0
	v_pk_fma_f32 v[138:139], v[138:139], v[114:115], v[148:149]
	s_nop 0
	v_pk_mul_f32 v[138:139], v[138:139], v[140:141]
	v_mov_b64_e32 v[140:141], s[42:43]
	v_cvt_pk_bf16_f32 v137, v138, v139
	v_lshl_add_u64 v[138:139], s[72:73], 0, v[146:147]
	v_mad_u64_u32 v[140:141], s[84:85], v138, s1, v[140:141]
	v_mad_i32_i24 v141, v139, s1, v141
	v_lshl_add_u64 v[138:139], v[192:193], 1, v[140:141]
	global_store_dwordx2 v[138:139], v[136:137], off
.LBB0_3363:
	s_or_b64 exec, exec, s[82:83]
	v_cmp_gt_i32_e32 vcc, s41, v227
	v_add_u32_e32 v148, 48, v194
	v_mov_b32_dpp v196, v100 row_shr:1 row_mask:0xf bank_mask:0xf
	v_mov_b32_dpp v198, v100 row_shr:2 row_mask:0xf bank_mask:0xf
	v_mov_b32_dpp v154, v96 row_shr:1 row_mask:0xf bank_mask:0xf
	v_mov_b32_dpp v170, v96 row_shr:2 row_mask:0xf bank_mask:0xf
	v_mov_b32_dpp v197, v101 row_shr:1 row_mask:0xf bank_mask:0xf
	v_mov_b32_dpp v199, v101 row_shr:2 row_mask:0xf bank_mask:0xf
	v_mov_b32_dpp v155, v97 row_shr:1 row_mask:0xf bank_mask:0xf
	v_mov_b32_dpp v171, v97 row_shr:2 row_mask:0xf bank_mask:0xf
	v_mov_b32_dpp v156, v102 row_shr:1 row_mask:0xf bank_mask:0xf
	v_mov_b32_dpp v172, v102 row_shr:2 row_mask:0xf bank_mask:0xf
	v_mov_b32_dpp v144, v98 row_shr:1 row_mask:0xf bank_mask:0xf
	v_mov_b32_dpp v150, v98 row_shr:2 row_mask:0xf bank_mask:0xf
	v_mov_b32_dpp v157, v103 row_shr:1 row_mask:0xf bank_mask:0xf
	v_mov_b32_dpp v173, v103 row_shr:2 row_mask:0xf bank_mask:0xf
	v_mov_b32_dpp v145, v99 row_shr:1 row_mask:0xf bank_mask:0xf
	v_mov_b32_dpp v151, v99 row_shr:2 row_mask:0xf bank_mask:0xf
	s_and_b64 s[82:83], s[54:55], vcc
	v_ashrrev_i32_e32 v149, 31, v148
	s_and_saveexec_b64 s[84:85], s[82:83]
	s_cbranch_execz .LBB0_3365
	v_pk_fma_f32 v[136:137], v[120:121], v[198:199], v[132:133]
	v_pk_fma_f32 v[138:139], v[104:105], v[170:171], v[116:117]
	v_pk_fma_f32 v[136:137], v[124:125], v[196:197], v[136:137]
	v_pk_fma_f32 v[138:139], v[108:109], v[154:155], v[138:139]
	v_pk_fma_f32 v[100:101], v[100:101], v[128:129], v[136:137]
	v_pk_fma_f32 v[96:97], v[96:97], v[112:113], v[138:139]
	v_mul_f32_e32 v136, 0x3d372713, v100
	v_mul_f32_e32 v137, 0x3d372713, v101
	v_fma_f32 v136, v100, v136, 1.0
	v_fma_f32 v137, v101, v137, 1.0
	v_mul_f32_e32 v136, v100, v136
	v_mul_f32_e32 v137, v101, v137
	v_mul_f32_e32 v136, 0x40135761, v136
	v_mul_f32_e32 v137, 0x40135761, v137
	v_exp_f32_e32 v136, v136
	v_exp_f32_e32 v137, v137
	v_add_f32_e32 v136, 1.0, v136
	v_add_f32_e32 v137, 1.0, v137
	v_rcp_f32_e32 v136, v136
	v_rcp_f32_e32 v137, v137
	s_nop 0
	v_pk_fma_f32 v[100:101], v[100:101], v[136:137], v[100:101] neg_lo:[1,0,0] neg_hi:[1,0,0]
	v_pk_fma_f32 v[136:137], v[122:123], v[172:173], v[134:135]
	v_pk_mul_f32 v[96:97], v[96:97], v[100:101]
	v_pk_fma_f32 v[136:137], v[126:127], v[156:157], v[136:137]
	v_cvt_pk_bf16_f32 v96, v96, v97
	v_pk_fma_f32 v[102:103], v[102:103], v[130:131], v[136:137]
	s_nop 0
	v_mul_f32_e32 v136, 0x3d372713, v102
	v_mul_f32_e32 v137, 0x3d372713, v103
	v_fma_f32 v136, v102, v136, 1.0
	v_fma_f32 v137, v103, v137, 1.0
	v_mul_f32_e32 v136, v102, v136
	v_mul_f32_e32 v137, v103, v137
	v_mul_f32_e32 v136, 0x40135761, v136
	v_mul_f32_e32 v137, 0x40135761, v137
	v_exp_f32_e32 v136, v136
	v_exp_f32_e32 v137, v137
	v_add_f32_e32 v100, 1.0, v136
	v_add_f32_e32 v101, 1.0, v137
	v_rcp_f32_e32 v100, v100
	v_rcp_f32_e32 v101, v101
	v_pk_fma_f32 v[136:137], v[106:107], v[150:151], v[118:119]
	v_pk_fma_f32 v[100:101], v[102:103], v[100:101], v[102:103] neg_lo:[1,0,0] neg_hi:[1,0,0]
	v_pk_fma_f32 v[136:137], v[110:111], v[144:145], v[136:137]
	s_nop 0
	v_pk_fma_f32 v[98:99], v[98:99], v[114:115], v[136:137]
	s_nop 0
	v_pk_mul_f32 v[98:99], v[98:99], v[100:101]
	v_mov_b64_e32 v[100:101], s[42:43]
	v_cvt_pk_bf16_f32 v97, v98, v99
	v_lshl_add_u64 v[98:99], s[72:73], 0, v[148:149]
	v_mad_u64_u32 v[100:101], s[86:87], v98, s1, v[100:101]
	v_mad_i32_i24 v101, v99, s1, v101
	v_lshl_add_u64 v[98:99], v[192:193], 1, v[100:101]
	global_store_dwordx2 v[98:99], v[96:97], off
.LBB0_3365:
	s_or_b64 exec, exec, s[84:85]
	v_add_u32_e32 v96, 0x1100, v237
	v_add_u32_e32 v100, 0x1000, v237
	ds_read2_b64 v[136:139], v96 offset1:1
	ds_read2_b64 v[140:143], v100 offset1:1
	v_add_u32_e32 v96, 0x1110, v237
	v_add_u32_e32 v100, 0x1010, v237
	ds_read2_b64 v[96:99], v96 offset1:1
	ds_read2_b64 v[100:103], v100 offset1:1
	s_waitcnt lgkmcnt(0)
	v_cndmask_b32_e64 v172, v137, v136, s[14:15]
	v_cndmask_b32_e64 v173, v139, v138, s[14:15]
	v_cndmask_b32_e64 v174, v141, v140, s[14:15]
	v_cndmask_b32_e64 v168, v97, v96, s[14:15]
	v_cndmask_b32_e64 v169, v99, v98, s[14:15]
	v_cndmask_b32_e64 v175, v143, v142, s[14:15]
	v_cndmask_b32_e64 v170, v101, v100, s[14:15]
	v_cndmask_b32_e64 v171, v103, v102, s[14:15]
	v_add_u32_e32 v144, 0x80, v194
	v_cmp_gt_u32_e32 vcc, s41, v228
	v_mov_b32_dpp v141, v92 row_shr:1 row_mask:0xf bank_mask:0xf
	v_mov_b32_dpp v174, v92 row_shr:2 row_mask:0xf bank_mask:0xf
	v_mov_b32_dpp v137, v88 row_shr:1 row_mask:0xf bank_mask:0xf
	v_mov_b32_dpp v172, v88 row_shr:2 row_mask:0xf bank_mask:0xf
	v_mov_b32_dpp v164, v92 row_ror:1 row_mask:0xf bank_mask:0xf bound_ctrl:1
	v_mov_b32_dpp v156, v88 row_ror:1 row_mask:0xf bank_mask:0xf bound_ctrl:1
	v_mov_b32_dpp v166, v92 row_ror:2 row_mask:0xf bank_mask:0xf bound_ctrl:1
	v_mov_b32_dpp v160, v88 row_ror:2 row_mask:0xf bank_mask:0xf bound_ctrl:1
	v_mov_b32_dpp v143, v93 row_shr:1 row_mask:0xf bank_mask:0xf
	v_mov_b32_dpp v175, v93 row_shr:2 row_mask:0xf bank_mask:0xf
	v_mov_b32_dpp v139, v89 row_shr:1 row_mask:0xf bank_mask:0xf
	v_mov_b32_dpp v173, v89 row_shr:2 row_mask:0xf bank_mask:0xf
	v_mov_b32_dpp v165, v93 row_ror:1 row_mask:0xf bank_mask:0xf bound_ctrl:1
	v_mov_b32_dpp v157, v89 row_ror:1 row_mask:0xf bank_mask:0xf bound_ctrl:1
	v_mov_b32_dpp v167, v93 row_ror:2 row_mask:0xf bank_mask:0xf bound_ctrl:1
	v_mov_b32_dpp v161, v89 row_ror:2 row_mask:0xf bank_mask:0xf bound_ctrl:1
	v_mov_b32_dpp v101, v94 row_shr:1 row_mask:0xf bank_mask:0xf
	v_mov_b32_dpp v170, v94 row_shr:2 row_mask:0xf bank_mask:0xf
	v_mov_b32_dpp v97, v90 row_shr:1 row_mask:0xf bank_mask:0xf
	v_mov_b32_dpp v168, v90 row_shr:2 row_mask:0xf bank_mask:0xf
	v_mov_b32_dpp v158, v94 row_ror:1 row_mask:0xf bank_mask:0xf bound_ctrl:1
	v_mov_b32_dpp v150, v90 row_ror:1 row_mask:0xf bank_mask:0xf bound_ctrl:1
	v_mov_b32_dpp v162, v94 row_ror:2 row_mask:0xf bank_mask:0xf bound_ctrl:1
	v_mov_b32_dpp v154, v90 row_ror:2 row_mask:0xf bank_mask:0xf bound_ctrl:1
	v_mov_b32_dpp v103, v95 row_shr:1 row_mask:0xf bank_mask:0xf
	v_mov_b32_dpp v171, v95 row_shr:2 row_mask:0xf bank_mask:0xf
	v_mov_b32_dpp v99, v91 row_shr:1 row_mask:0xf bank_mask:0xf
	v_mov_b32_dpp v169, v91 row_shr:2 row_mask:0xf bank_mask:0xf
	v_mov_b32_dpp v159, v95 row_ror:1 row_mask:0xf bank_mask:0xf bound_ctrl:1
	v_mov_b32_dpp v151, v91 row_ror:1 row_mask:0xf bank_mask:0xf bound_ctrl:1
	v_mov_b32_dpp v163, v95 row_ror:2 row_mask:0xf bank_mask:0xf bound_ctrl:1
	v_mov_b32_dpp v155, v91 row_ror:2 row_mask:0xf bank_mask:0xf bound_ctrl:1
	s_and_b64 s[84:85], s[18:19], vcc
	v_ashrrev_i32_e32 v145, 31, v144
	s_and_saveexec_b64 s[86:87], s[84:85]
	s_cbranch_execz .LBB0_3367
	v_mov_b32_e32 v142, v141
	v_pk_fma_f32 v[140:141], v[120:121], v[174:175], v[132:133]
	v_mov_b32_e32 v138, v137
	v_pk_fma_f32 v[140:141], v[124:125], v[142:143], v[140:141]
	v_mov_b32_e32 v102, v101
	v_pk_fma_f32 v[92:93], v[92:93], v[128:129], v[140:141]
	v_pk_fma_f32 v[140:141], v[104:105], v[172:173], v[116:117]
	v_mul_f32_e32 v96, 0x3d372713, v92
	v_fma_f32 v96, v92, v96, 1.0
	v_mul_f32_e32 v98, 0x3d372713, v93
	v_mul_f32_e32 v96, v92, v96
	v_fma_f32 v98, v93, v98, 1.0
	v_mul_f32_e32 v96, 0x40135761, v96
	v_mul_f32_e32 v98, v93, v98
	v_exp_f32_e32 v96, v96
	v_mul_f32_e32 v98, 0x40135761, v98
	v_exp_f32_e32 v98, v98
	v_pk_fma_f32 v[138:139], v[108:109], v[138:139], v[140:141]
	v_add_f32_e32 v96, 1.0, v96
	v_rcp_f32_e32 v136, v96
	v_add_f32_e32 v96, 1.0, v98
	v_rcp_f32_e32 v137, v96
	v_pk_fma_f32 v[88:89], v[88:89], v[112:113], v[138:139]
	v_mov_b32_e32 v98, v97
	v_pk_fma_f32 v[96:97], v[106:107], v[168:169], v[118:119]
	v_pk_fma_f32 v[92:93], v[92:93], v[136:137], v[92:93] neg_lo:[1,0,0] neg_hi:[1,0,0]
	v_pk_fma_f32 v[96:97], v[110:111], v[98:99], v[96:97]
	v_pk_mul_f32 v[88:89], v[88:89], v[92:93]
	v_pk_fma_f32 v[92:93], v[122:123], v[170:171], v[134:135]
	v_pk_fma_f32 v[90:91], v[90:91], v[114:115], v[96:97]
	v_pk_fma_f32 v[92:93], v[126:127], v[102:103], v[92:93]
	v_cvt_pk_bf16_f32 v88, v88, v89
	v_pk_fma_f32 v[92:93], v[94:95], v[130:131], v[92:93]
	s_nop 0
	v_mul_f32_e32 v94, 0x3d372713, v92
	v_mul_f32_e32 v95, 0x3d372713, v93
	v_fma_f32 v94, v92, v94, 1.0
	v_fma_f32 v95, v93, v95, 1.0
	v_mul_f32_e32 v94, v92, v94
	v_mul_f32_e32 v95, v93, v95
	v_mul_f32_e32 v94, 0x40135761, v94
	v_mul_f32_e32 v95, 0x40135761, v95
	v_exp_f32_e32 v94, v94
	v_exp_f32_e32 v95, v95
	v_add_f32_e32 v94, 1.0, v94
	v_add_f32_e32 v95, 1.0, v95
	v_rcp_f32_e32 v94, v94
	v_rcp_f32_e32 v95, v95
	s_nop 0
	v_pk_fma_f32 v[92:93], v[92:93], v[94:95], v[92:93] neg_lo:[1,0,0] neg_hi:[1,0,0]
	s_nop 0
	v_pk_mul_f32 v[90:91], v[90:91], v[92:93]
	v_mov_b64_e32 v[92:93], s[42:43]
	v_cvt_pk_bf16_f32 v89, v90, v91
	v_lshl_add_u64 v[90:91], s[72:73], 0, v[144:145]
	v_mad_u64_u32 v[92:93], s[88:89], v90, s1, v[92:93]
	v_mad_i32_i24 v93, v91, s1, v93
	v_lshl_add_u64 v[90:91], v[192:193], 1, v[92:93]
	global_store_dwordx2 v[90:91], v[88:89], off
.LBB0_3367:
	s_or_b64 exec, exec, s[86:87]
	v_cmp_gt_u32_e32 vcc, s41, v229
	v_add_u32_e32 v136, 0x90, v194
	v_mov_b32_dpp v164, v84 row_shr:1 row_mask:0xf bank_mask:0xf
	v_mov_b32_dpp v166, v84 row_shr:2 row_mask:0xf bank_mask:0xf
	v_mov_b32_dpp v156, v80 row_shr:1 row_mask:0xf bank_mask:0xf
	v_mov_b32_dpp v160, v80 row_shr:2 row_mask:0xf bank_mask:0xf
	v_mov_b32_dpp v140, v84 row_ror:1 row_mask:0xf bank_mask:0xf bound_ctrl:1
	v_mov_b32_dpp v92, v80 row_ror:1 row_mask:0xf bank_mask:0xf bound_ctrl:1
	v_mov_b32_dpp v142, v84 row_ror:2 row_mask:0xf bank_mask:0xf bound_ctrl:1
	v_mov_b32_dpp v96, v80 row_ror:2 row_mask:0xf bank_mask:0xf bound_ctrl:1
	v_mov_b32_dpp v165, v85 row_shr:1 row_mask:0xf bank_mask:0xf
	v_mov_b32_dpp v167, v85 row_shr:2 row_mask:0xf bank_mask:0xf
	v_mov_b32_dpp v157, v81 row_shr:1 row_mask:0xf bank_mask:0xf
	v_mov_b32_dpp v161, v81 row_shr:2 row_mask:0xf bank_mask:0xf
	v_mov_b32_dpp v141, v85 row_ror:1 row_mask:0xf bank_mask:0xf bound_ctrl:1
	v_mov_b32_dpp v93, v81 row_ror:1 row_mask:0xf bank_mask:0xf bound_ctrl:1
	v_mov_b32_dpp v143, v85 row_ror:2 row_mask:0xf bank_mask:0xf bound_ctrl:1
	v_mov_b32_dpp v97, v81 row_ror:2 row_mask:0xf bank_mask:0xf bound_ctrl:1
	v_mov_b32_dpp v158, v86 row_shr:1 row_mask:0xf bank_mask:0xf
	v_mov_b32_dpp v162, v86 row_shr:2 row_mask:0xf bank_mask:0xf
	v_mov_b32_dpp v150, v82 row_shr:1 row_mask:0xf bank_mask:0xf
	v_mov_b32_dpp v154, v82 row_shr:2 row_mask:0xf bank_mask:0xf
	v_mov_b32_dpp v94, v86 row_ror:1 row_mask:0xf bank_mask:0xf bound_ctrl:1
	v_mov_b32_dpp v88, v82 row_ror:1 row_mask:0xf bank_mask:0xf bound_ctrl:1
	v_mov_b32_dpp v98, v86 row_ror:2 row_mask:0xf bank_mask:0xf bound_ctrl:1
	v_mov_b32_dpp v90, v82 row_ror:2 row_mask:0xf bank_mask:0xf bound_ctrl:1
	v_mov_b32_dpp v159, v87 row_shr:1 row_mask:0xf bank_mask:0xf
	v_mov_b32_dpp v163, v87 row_shr:2 row_mask:0xf bank_mask:0xf
	v_mov_b32_dpp v151, v83 row_shr:1 row_mask:0xf bank_mask:0xf
	v_mov_b32_dpp v155, v83 row_shr:2 row_mask:0xf bank_mask:0xf
	v_mov_b32_dpp v95, v87 row_ror:1 row_mask:0xf bank_mask:0xf bound_ctrl:1
	v_mov_b32_dpp v89, v83 row_ror:1 row_mask:0xf bank_mask:0xf bound_ctrl:1
	v_mov_b32_dpp v99, v87 row_ror:2 row_mask:0xf bank_mask:0xf bound_ctrl:1
	v_mov_b32_dpp v91, v83 row_ror:2 row_mask:0xf bank_mask:0xf bound_ctrl:1
	s_and_b64 s[86:87], s[20:21], vcc
	v_ashrrev_i32_e32 v137, 31, v136
	s_and_saveexec_b64 s[88:89], s[86:87]
	s_cbranch_execz .LBB0_3369
	v_pk_fma_f32 v[100:101], v[120:121], v[166:167], v[132:133]
	v_pk_fma_f32 v[102:103], v[104:105], v[160:161], v[116:117]
	v_pk_fma_f32 v[100:101], v[124:125], v[164:165], v[100:101]
	v_pk_fma_f32 v[102:103], v[108:109], v[156:157], v[102:103]
	v_pk_fma_f32 v[84:85], v[84:85], v[128:129], v[100:101]
	v_pk_fma_f32 v[80:81], v[80:81], v[112:113], v[102:103]
	v_mul_f32_e32 v100, 0x3d372713, v84
	v_mul_f32_e32 v101, 0x3d372713, v85
	v_fma_f32 v100, v84, v100, 1.0
	v_fma_f32 v101, v85, v101, 1.0
	v_mul_f32_e32 v100, v84, v100
	v_mul_f32_e32 v101, v85, v101
	v_mul_f32_e32 v100, 0x40135761, v100
	v_mul_f32_e32 v101, 0x40135761, v101
	v_exp_f32_e32 v100, v100
	v_exp_f32_e32 v101, v101
	v_add_f32_e32 v100, 1.0, v100
	v_add_f32_e32 v101, 1.0, v101
	v_rcp_f32_e32 v100, v100
	v_rcp_f32_e32 v101, v101
	s_nop 0
	v_pk_fma_f32 v[84:85], v[84:85], v[100:101], v[84:85] neg_lo:[1,0,0] neg_hi:[1,0,0]
	v_pk_fma_f32 v[100:101], v[122:123], v[162:163], v[134:135]
	v_pk_mul_f32 v[80:81], v[80:81], v[84:85]
	v_pk_fma_f32 v[100:101], v[126:127], v[158:159], v[100:101]
	v_cvt_pk_bf16_f32 v80, v80, v81
	v_pk_fma_f32 v[86:87], v[86:87], v[130:131], v[100:101]
	s_nop 0
	v_mul_f32_e32 v100, 0x3d372713, v86
	v_mul_f32_e32 v101, 0x3d372713, v87
	v_fma_f32 v100, v86, v100, 1.0
	v_fma_f32 v101, v87, v101, 1.0
	v_mul_f32_e32 v100, v86, v100
	v_mul_f32_e32 v101, v87, v101
	v_mul_f32_e32 v100, 0x40135761, v100
	v_mul_f32_e32 v101, 0x40135761, v101
	v_exp_f32_e32 v100, v100
	v_exp_f32_e32 v101, v101
	v_add_f32_e32 v84, 1.0, v100
	v_add_f32_e32 v85, 1.0, v101
	v_rcp_f32_e32 v84, v84
	v_rcp_f32_e32 v85, v85
	v_pk_fma_f32 v[100:101], v[106:107], v[154:155], v[118:119]
	v_pk_fma_f32 v[84:85], v[86:87], v[84:85], v[86:87] neg_lo:[1,0,0] neg_hi:[1,0,0]
	v_pk_fma_f32 v[100:101], v[110:111], v[150:151], v[100:101]
	s_nop 0
	v_pk_fma_f32 v[82:83], v[82:83], v[114:115], v[100:101]
	s_nop 0
	v_pk_mul_f32 v[82:83], v[82:83], v[84:85]
	v_mov_b64_e32 v[84:85], s[42:43]
	v_cvt_pk_bf16_f32 v81, v82, v83
	v_lshl_add_u64 v[82:83], s[72:73], 0, v[136:137]
	v_mad_u64_u32 v[84:85], s[90:91], v82, s1, v[84:85]
	v_mad_i32_i24 v85, v83, s1, v85
	v_lshl_add_u64 v[82:83], v[192:193], 1, v[84:85]
	global_store_dwordx2 v[82:83], v[80:81], off
.LBB0_3369:
	s_or_b64 exec, exec, s[88:89]
	v_cmp_gt_u32_e32 vcc, s41, v230
	v_add_u32_e32 v138, 0xa0, v194
	v_mov_b32_dpp v140, v76 row_shr:1 row_mask:0xf bank_mask:0xf
	v_mov_b32_dpp v142, v76 row_shr:2 row_mask:0xf bank_mask:0xf
	v_mov_b32_dpp v92, v72 row_shr:1 row_mask:0xf bank_mask:0xf
	v_mov_b32_dpp v96, v72 row_shr:2 row_mask:0xf bank_mask:0xf
	v_mov_b32_dpp v150, v76 row_ror:1 row_mask:0xf bank_mask:0xf bound_ctrl:1
	v_mov_b32_dpp v84, v72 row_ror:1 row_mask:0xf bank_mask:0xf bound_ctrl:1
	v_mov_b32_dpp v154, v76 row_ror:2 row_mask:0xf bank_mask:0xf bound_ctrl:1
	v_mov_b32_dpp v100, v72 row_ror:2 row_mask:0xf bank_mask:0xf bound_ctrl:1
	v_mov_b32_dpp v141, v77 row_shr:1 row_mask:0xf bank_mask:0xf
	v_mov_b32_dpp v143, v77 row_shr:2 row_mask:0xf bank_mask:0xf
	v_mov_b32_dpp v93, v73 row_shr:1 row_mask:0xf bank_mask:0xf
	v_mov_b32_dpp v97, v73 row_shr:2 row_mask:0xf bank_mask:0xf
	v_mov_b32_dpp v151, v77 row_ror:1 row_mask:0xf bank_mask:0xf bound_ctrl:1
	v_mov_b32_dpp v85, v73 row_ror:1 row_mask:0xf bank_mask:0xf bound_ctrl:1
	v_mov_b32_dpp v155, v77 row_ror:2 row_mask:0xf bank_mask:0xf bound_ctrl:1
	v_mov_b32_dpp v101, v73 row_ror:2 row_mask:0xf bank_mask:0xf bound_ctrl:1
	v_mov_b32_dpp v94, v78 row_shr:1 row_mask:0xf bank_mask:0xf
	v_mov_b32_dpp v98, v78 row_shr:2 row_mask:0xf bank_mask:0xf
	v_mov_b32_dpp v88, v74 row_shr:1 row_mask:0xf bank_mask:0xf
	v_mov_b32_dpp v90, v74 row_shr:2 row_mask:0xf bank_mask:0xf
	v_mov_b32_dpp v86, v78 row_ror:1 row_mask:0xf bank_mask:0xf bound_ctrl:1
	v_mov_b32_dpp v80, v74 row_ror:1 row_mask:0xf bank_mask:0xf bound_ctrl:1
	v_mov_b32_dpp v102, v78 row_ror:2 row_mask:0xf bank_mask:0xf bound_ctrl:1
	v_mov_b32_dpp v82, v74 row_ror:2 row_mask:0xf bank_mask:0xf bound_ctrl:1
	v_mov_b32_dpp v95, v79 row_shr:1 row_mask:0xf bank_mask:0xf
	v_mov_b32_dpp v99, v79 row_shr:2 row_mask:0xf bank_mask:0xf
	v_mov_b32_dpp v89, v75 row_shr:1 row_mask:0xf bank_mask:0xf
	v_mov_b32_dpp v91, v75 row_shr:2 row_mask:0xf bank_mask:0xf
	v_mov_b32_dpp v87, v79 row_ror:1 row_mask:0xf bank_mask:0xf bound_ctrl:1
	v_mov_b32_dpp v81, v75 row_ror:1 row_mask:0xf bank_mask:0xf bound_ctrl:1
	v_mov_b32_dpp v103, v79 row_ror:2 row_mask:0xf bank_mask:0xf bound_ctrl:1
	v_mov_b32_dpp v83, v75 row_ror:2 row_mask:0xf bank_mask:0xf bound_ctrl:1
	s_and_b64 s[88:89], s[22:23], vcc
	v_ashrrev_i32_e32 v139, 31, v138
	s_and_saveexec_b64 s[90:91], s[88:89]
	s_cbranch_execz .LBB0_3371
	v_pk_fma_f32 v[142:143], v[120:121], v[142:143], v[132:133]
	v_pk_fma_f32 v[96:97], v[104:105], v[96:97], v[116:117]
	v_pk_fma_f32 v[140:141], v[124:125], v[140:141], v[142:143]
	v_pk_fma_f32 v[92:93], v[108:109], v[92:93], v[96:97]
	v_pk_fma_f32 v[76:77], v[76:77], v[128:129], v[140:141]
	v_pk_fma_f32 v[72:73], v[72:73], v[112:113], v[92:93]
	v_mul_f32_e32 v140, 0x3d372713, v76
	v_mul_f32_e32 v141, 0x3d372713, v77
	v_fma_f32 v140, v76, v140, 1.0
	v_fma_f32 v141, v77, v141, 1.0
	v_mul_f32_e32 v140, v76, v140
	v_mul_f32_e32 v141, v77, v141
	v_mul_f32_e32 v140, 0x40135761, v140
	v_mul_f32_e32 v141, 0x40135761, v141
	v_pk_fma_f32 v[92:93], v[122:123], v[98:99], v[134:135]
	v_exp_f32_e32 v140, v140
	v_exp_f32_e32 v141, v141
	v_pk_fma_f32 v[92:93], v[126:127], v[94:95], v[92:93]
	v_pk_fma_f32 v[90:91], v[106:107], v[90:91], v[118:119]
	v_pk_fma_f32 v[78:79], v[78:79], v[130:131], v[92:93]
	v_add_f32_e32 v140, 1.0, v140
	v_mul_f32_e32 v92, 0x3d372713, v78
	v_mul_f32_e32 v93, 0x3d372713, v79
	v_fma_f32 v92, v78, v92, 1.0
	v_fma_f32 v93, v79, v93, 1.0
	v_add_f32_e32 v141, 1.0, v141
	v_mul_f32_e32 v92, v78, v92
	v_mul_f32_e32 v93, v79, v93
	v_rcp_f32_e32 v140, v140
	v_rcp_f32_e32 v141, v141
	v_mul_f32_e32 v92, 0x40135761, v92
	v_mul_f32_e32 v93, 0x40135761, v93
	v_exp_f32_e32 v92, v92
	v_exp_f32_e32 v93, v93
	v_pk_fma_f32 v[76:77], v[76:77], v[140:141], v[76:77] neg_lo:[1,0,0] neg_hi:[1,0,0]
	v_pk_fma_f32 v[88:89], v[110:111], v[88:89], v[90:91]
	v_pk_mul_f32 v[72:73], v[72:73], v[76:77]
	v_add_f32_e32 v76, 1.0, v92
	v_add_f32_e32 v77, 1.0, v93
	v_rcp_f32_e32 v76, v76
	v_rcp_f32_e32 v77, v77
	v_pk_fma_f32 v[74:75], v[74:75], v[114:115], v[88:89]
	v_cvt_pk_bf16_f32 v72, v72, v73
	v_pk_fma_f32 v[76:77], v[78:79], v[76:77], v[78:79] neg_lo:[1,0,0] neg_hi:[1,0,0]
	s_nop 0
	v_pk_mul_f32 v[74:75], v[74:75], v[76:77]
	v_mov_b64_e32 v[76:77], s[42:43]
	v_cvt_pk_bf16_f32 v73, v74, v75
	v_lshl_add_u64 v[74:75], s[72:73], 0, v[138:139]
	v_mad_u64_u32 v[76:77], s[92:93], v74, s1, v[76:77]
	v_mad_i32_i24 v77, v75, s1, v77
	v_lshl_add_u64 v[74:75], v[192:193], 1, v[76:77]
	global_store_dwordx2 v[74:75], v[72:73], off
.LBB0_3371:
	s_or_b64 exec, exec, s[90:91]
	v_cmp_gt_u32_e32 vcc, s41, v231
	v_add_u32_e32 v140, 0xb0, v194
	v_mov_b32_dpp v150, v68 row_shr:1 row_mask:0xf bank_mask:0xf
	v_mov_b32_dpp v154, v68 row_shr:2 row_mask:0xf bank_mask:0xf
	v_mov_b32_dpp v84, v64 row_shr:1 row_mask:0xf bank_mask:0xf
	v_mov_b32_dpp v100, v64 row_shr:2 row_mask:0xf bank_mask:0xf
	v_mov_b32_dpp v151, v69 row_shr:1 row_mask:0xf bank_mask:0xf
	v_mov_b32_dpp v155, v69 row_shr:2 row_mask:0xf bank_mask:0xf
	v_mov_b32_dpp v85, v65 row_shr:1 row_mask:0xf bank_mask:0xf
	v_mov_b32_dpp v101, v65 row_shr:2 row_mask:0xf bank_mask:0xf
	v_mov_b32_dpp v86, v70 row_shr:1 row_mask:0xf bank_mask:0xf
	v_mov_b32_dpp v102, v70 row_shr:2 row_mask:0xf bank_mask:0xf
	v_mov_b32_dpp v80, v66 row_shr:1 row_mask:0xf bank_mask:0xf
	v_mov_b32_dpp v82, v66 row_shr:2 row_mask:0xf bank_mask:0xf
	v_mov_b32_dpp v87, v71 row_shr:1 row_mask:0xf bank_mask:0xf
	v_mov_b32_dpp v103, v71 row_shr:2 row_mask:0xf bank_mask:0xf
	v_mov_b32_dpp v81, v67 row_shr:1 row_mask:0xf bank_mask:0xf
	v_mov_b32_dpp v83, v67 row_shr:2 row_mask:0xf bank_mask:0xf
	s_and_b64 s[90:91], s[24:25], vcc
	v_ashrrev_i32_e32 v141, 31, v140
	s_and_saveexec_b64 s[92:93], s[90:91]
	s_cbranch_execz .LBB0_3373
	v_pk_fma_f32 v[72:73], v[120:121], v[154:155], v[132:133]
	v_pk_fma_f32 v[74:75], v[104:105], v[100:101], v[116:117]
	v_pk_fma_f32 v[72:73], v[124:125], v[150:151], v[72:73]
	v_pk_fma_f32 v[74:75], v[108:109], v[84:85], v[74:75]
	v_pk_fma_f32 v[68:69], v[68:69], v[128:129], v[72:73]
	v_pk_fma_f32 v[64:65], v[64:65], v[112:113], v[74:75]
	v_mul_f32_e32 v72, 0x3d372713, v68
	v_mul_f32_e32 v73, 0x3d372713, v69
	v_fma_f32 v72, v68, v72, 1.0
	v_fma_f32 v73, v69, v73, 1.0
	v_mul_f32_e32 v72, v68, v72
	v_mul_f32_e32 v73, v69, v73
	v_mul_f32_e32 v72, 0x40135761, v72
	v_mul_f32_e32 v73, 0x40135761, v73
	v_exp_f32_e32 v72, v72
	v_exp_f32_e32 v73, v73
	v_add_f32_e32 v72, 1.0, v72
	v_add_f32_e32 v73, 1.0, v73
	v_rcp_f32_e32 v72, v72
	v_rcp_f32_e32 v73, v73
	s_nop 0
	v_pk_fma_f32 v[68:69], v[68:69], v[72:73], v[68:69] neg_lo:[1,0,0] neg_hi:[1,0,0]
	v_pk_fma_f32 v[72:73], v[122:123], v[102:103], v[134:135]
	v_pk_mul_f32 v[64:65], v[64:65], v[68:69]
	v_pk_fma_f32 v[72:73], v[126:127], v[86:87], v[72:73]
	v_cvt_pk_bf16_f32 v64, v64, v65
	v_pk_fma_f32 v[70:71], v[70:71], v[130:131], v[72:73]
	s_nop 0
	v_mul_f32_e32 v72, 0x3d372713, v70
	v_mul_f32_e32 v73, 0x3d372713, v71
	v_fma_f32 v72, v70, v72, 1.0
	v_fma_f32 v73, v71, v73, 1.0
	v_mul_f32_e32 v72, v70, v72
	v_mul_f32_e32 v73, v71, v73
	v_mul_f32_e32 v72, 0x40135761, v72
	v_mul_f32_e32 v73, 0x40135761, v73
	v_exp_f32_e32 v72, v72
	v_exp_f32_e32 v73, v73
	v_add_f32_e32 v68, 1.0, v72
	v_add_f32_e32 v69, 1.0, v73
	v_rcp_f32_e32 v68, v68
	v_rcp_f32_e32 v69, v69
	v_pk_fma_f32 v[72:73], v[106:107], v[82:83], v[118:119]
	v_pk_fma_f32 v[68:69], v[70:71], v[68:69], v[70:71] neg_lo:[1,0,0] neg_hi:[1,0,0]
	v_pk_fma_f32 v[72:73], v[110:111], v[80:81], v[72:73]
	s_nop 0
	v_pk_fma_f32 v[66:67], v[66:67], v[114:115], v[72:73]
	s_nop 0
	v_pk_mul_f32 v[66:67], v[66:67], v[68:69]
	v_mov_b64_e32 v[68:69], s[42:43]
	v_cvt_pk_bf16_f32 v65, v66, v67
	v_lshl_add_u64 v[66:67], s[72:73], 0, v[140:141]
	v_mad_u64_u32 v[68:69], vcc, v66, s1, v[68:69]
	v_mad_i32_i24 v69, v67, s1, v69
	v_lshl_add_u64 v[66:67], v[192:193], 1, v[68:69]
	global_store_dwordx2 v[66:67], v[64:65], off

.LBB0_3377:
	s_or_b64 exec, exec, s[28:29]
	v_mov_b32_dpp v120, v52 row_shr:1 row_mask:0xf bank_mask:0xf
	v_mov_b32_dpp v122, v52 row_shr:2 row_mask:0xf bank_mask:0xf
	v_mov_b32_dpp v112, v48 row_shr:1 row_mask:0xf bank_mask:0xf
	v_mov_b32_dpp v116, v48 row_shr:2 row_mask:0xf bank_mask:0xf
	v_mov_b32_dpp v104, v52 row_ror:1 row_mask:0xf bank_mask:0xf bound_ctrl:1
	v_mov_b32_dpp v96, v48 row_ror:1 row_mask:0xf bank_mask:0xf bound_ctrl:1
	v_mov_b32_dpp v106, v52 row_ror:2 row_mask:0xf bank_mask:0xf bound_ctrl:1
	v_mov_b32_dpp v100, v48 row_ror:2 row_mask:0xf bank_mask:0xf bound_ctrl:1
	v_mov_b32_dpp v121, v53 row_shr:1 row_mask:0xf bank_mask:0xf
	v_mov_b32_dpp v123, v53 row_shr:2 row_mask:0xf bank_mask:0xf
	v_mov_b32_dpp v113, v49 row_shr:1 row_mask:0xf bank_mask:0xf
	v_mov_b32_dpp v117, v49 row_shr:2 row_mask:0xf bank_mask:0xf
	v_mov_b32_dpp v105, v53 row_ror:1 row_mask:0xf bank_mask:0xf bound_ctrl:1
	v_mov_b32_dpp v97, v49 row_ror:1 row_mask:0xf bank_mask:0xf bound_ctrl:1
	v_mov_b32_dpp v107, v53 row_ror:2 row_mask:0xf bank_mask:0xf bound_ctrl:1
	v_mov_b32_dpp v101, v49 row_ror:2 row_mask:0xf bank_mask:0xf bound_ctrl:1
	v_mov_b32_dpp v114, v54 row_shr:1 row_mask:0xf bank_mask:0xf
	v_mov_b32_dpp v118, v54 row_shr:2 row_mask:0xf bank_mask:0xf
	v_mov_b32_dpp v56, v50 row_shr:1 row_mask:0xf bank_mask:0xf
	v_mov_b32_dpp v58, v50 row_shr:2 row_mask:0xf bank_mask:0xf
	v_mov_b32_dpp v98, v54 row_ror:1 row_mask:0xf bank_mask:0xf bound_ctrl:1
	v_mov_b32_dpp v60, v50 row_ror:1 row_mask:0xf bank_mask:0xf bound_ctrl:1
	v_mov_b32_dpp v102, v54 row_ror:2 row_mask:0xf bank_mask:0xf bound_ctrl:1
	v_mov_b32_dpp v62, v50 row_ror:2 row_mask:0xf bank_mask:0xf bound_ctrl:1
	v_mov_b32_dpp v115, v55 row_shr:1 row_mask:0xf bank_mask:0xf
	v_mov_b32_dpp v119, v55 row_shr:2 row_mask:0xf bank_mask:0xf
	v_mov_b32_dpp v57, v51 row_shr:1 row_mask:0xf bank_mask:0xf
	v_mov_b32_dpp v59, v51 row_shr:2 row_mask:0xf bank_mask:0xf
	v_mov_b32_dpp v99, v55 row_ror:1 row_mask:0xf bank_mask:0xf bound_ctrl:1
	v_mov_b32_dpp v61, v51 row_ror:1 row_mask:0xf bank_mask:0xf bound_ctrl:1
	v_mov_b32_dpp v103, v55 row_ror:2 row_mask:0xf bank_mask:0xf bound_ctrl:1
	v_mov_b32_dpp v63, v51 row_ror:2 row_mask:0xf bank_mask:0xf bound_ctrl:1
	s_and_saveexec_b64 s[28:29], s[78:79]
	s_cbranch_execz .LBB0_3379
	v_pk_fma_f32 v[108:109], v[80:81], v[122:123], v[92:93]
	v_pk_fma_f32 v[110:111], v[64:65], v[116:117], v[76:77]
	v_pk_fma_f32 v[108:109], v[84:85], v[120:121], v[108:109]
	v_pk_fma_f32 v[110:111], v[68:69], v[112:113], v[110:111]
	v_pk_fma_f32 v[52:53], v[52:53], v[88:89], v[108:109]
	v_pk_fma_f32 v[48:49], v[48:49], v[72:73], v[110:111]
	v_mul_f32_e32 v108, 0x3d372713, v52
	v_mul_f32_e32 v109, 0x3d372713, v53
	v_fma_f32 v108, v52, v108, 1.0
	v_fma_f32 v109, v53, v109, 1.0
	v_mul_f32_e32 v108, v52, v108
	v_mul_f32_e32 v109, v53, v109
	v_mul_f32_e32 v108, 0x40135761, v108
	v_mul_f32_e32 v109, 0x40135761, v109
	v_exp_f32_e32 v108, v108
	v_exp_f32_e32 v109, v109
	v_pk_fma_f32 v[58:59], v[66:67], v[58:59], v[78:79]
	v_add_f32_e32 v108, 1.0, v108
	v_add_f32_e32 v109, 1.0, v109
	v_rcp_f32_e32 v108, v108
	v_rcp_f32_e32 v109, v109
	v_pk_fma_f32 v[56:57], v[70:71], v[56:57], v[58:59]
	v_pk_fma_f32 v[52:53], v[52:53], v[108:109], v[52:53] neg_lo:[1,0,0] neg_hi:[1,0,0]
	v_pk_fma_f32 v[108:109], v[82:83], v[118:119], v[94:95]
	v_pk_mul_f32 v[48:49], v[48:49], v[52:53]
	v_pk_fma_f32 v[108:109], v[86:87], v[114:115], v[108:109]
	v_pk_fma_f32 v[50:51], v[50:51], v[74:75], v[56:57]
	v_pk_fma_f32 v[54:55], v[54:55], v[90:91], v[108:109]
	v_cvt_pk_bf16_f32 v48, v48, v49
	v_mul_f32_e32 v108, 0x3d372713, v54
	v_mul_f32_e32 v109, 0x3d372713, v55
	v_fma_f32 v108, v54, v108, 1.0
	v_fma_f32 v109, v55, v109, 1.0
	v_mul_f32_e32 v108, v54, v108
	v_mul_f32_e32 v109, v55, v109
	v_mul_f32_e32 v108, 0x40135761, v108
	v_mul_f32_e32 v109, 0x40135761, v109
	v_exp_f32_e32 v108, v108
	v_exp_f32_e32 v109, v109
	v_add_f32_e32 v52, 1.0, v108
	v_add_f32_e32 v53, 1.0, v109
	v_rcp_f32_e32 v52, v52
	v_rcp_f32_e32 v53, v53
	s_nop 0
	v_pk_fma_f32 v[52:53], v[54:55], v[52:53], v[54:55] neg_lo:[1,0,0] neg_hi:[1,0,0]
	s_nop 0
	v_pk_mul_f32 v[50:51], v[50:51], v[52:53]
	v_mov_b64_e32 v[52:53], s[42:43]
	v_cvt_pk_bf16_f32 v49, v50, v51
	v_lshl_add_u64 v[50:51], s[72:73], 0, v[152:153]
	v_mad_u64_u32 v[52:53], s[74:75], v50, s1, v[52:53]
	v_mad_i32_i24 v53, v51, s1, v53
	v_lshl_add_u64 v[50:51], v[192:193], 1, v[52:53]
	global_store_dwordx2 v[50:51], v[48:49], off offset:8
.LBB0_3379:
	s_or_b64 exec, exec, s[28:29]
	v_mov_b32_dpp v104, v44 row_shr:1 row_mask:0xf bank_mask:0xf
	v_mov_b32_dpp v106, v44 row_shr:2 row_mask:0xf bank_mask:0xf
	v_mov_b32_dpp v96, v40 row_shr:1 row_mask:0xf bank_mask:0xf
	v_mov_b32_dpp v100, v40 row_shr:2 row_mask:0xf bank_mask:0xf
	v_mov_b32_dpp v108, v44 row_ror:1 row_mask:0xf bank_mask:0xf bound_ctrl:1
	v_mov_b32_dpp v52, v40 row_ror:1 row_mask:0xf bank_mask:0xf bound_ctrl:1
	v_mov_b32_dpp v110, v44 row_ror:2 row_mask:0xf bank_mask:0xf bound_ctrl:1
	v_mov_b32_dpp v56, v40 row_ror:2 row_mask:0xf bank_mask:0xf bound_ctrl:1
	v_mov_b32_dpp v105, v45 row_shr:1 row_mask:0xf bank_mask:0xf
	v_mov_b32_dpp v107, v45 row_shr:2 row_mask:0xf bank_mask:0xf
	v_mov_b32_dpp v97, v41 row_shr:1 row_mask:0xf bank_mask:0xf
	v_mov_b32_dpp v101, v41 row_shr:2 row_mask:0xf bank_mask:0xf
	v_mov_b32_dpp v109, v45 row_ror:1 row_mask:0xf bank_mask:0xf bound_ctrl:1
	v_mov_b32_dpp v53, v41 row_ror:1 row_mask:0xf bank_mask:0xf bound_ctrl:1
	v_mov_b32_dpp v111, v45 row_ror:2 row_mask:0xf bank_mask:0xf bound_ctrl:1
	v_mov_b32_dpp v57, v41 row_ror:2 row_mask:0xf bank_mask:0xf bound_ctrl:1
	v_mov_b32_dpp v98, v46 row_shr:1 row_mask:0xf bank_mask:0xf
	v_mov_b32_dpp v102, v46 row_shr:2 row_mask:0xf bank_mask:0xf
	v_mov_b32_dpp v60, v42 row_shr:1 row_mask:0xf bank_mask:0xf
	v_mov_b32_dpp v62, v42 row_shr:2 row_mask:0xf bank_mask:0xf
	v_mov_b32_dpp v54, v46 row_ror:1 row_mask:0xf bank_mask:0xf bound_ctrl:1
	v_mov_b32_dpp v48, v42 row_ror:1 row_mask:0xf bank_mask:0xf bound_ctrl:1
	v_mov_b32_dpp v58, v46 row_ror:2 row_mask:0xf bank_mask:0xf bound_ctrl:1
	v_mov_b32_dpp v50, v42 row_ror:2 row_mask:0xf bank_mask:0xf bound_ctrl:1
	v_mov_b32_dpp v99, v47 row_shr:1 row_mask:0xf bank_mask:0xf
	v_mov_b32_dpp v103, v47 row_shr:2 row_mask:0xf bank_mask:0xf
	v_mov_b32_dpp v61, v43 row_shr:1 row_mask:0xf bank_mask:0xf
	v_mov_b32_dpp v63, v43 row_shr:2 row_mask:0xf bank_mask:0xf
	v_mov_b32_dpp v55, v47 row_ror:1 row_mask:0xf bank_mask:0xf bound_ctrl:1
	v_mov_b32_dpp v49, v43 row_ror:1 row_mask:0xf bank_mask:0xf bound_ctrl:1
	v_mov_b32_dpp v59, v47 row_ror:2 row_mask:0xf bank_mask:0xf bound_ctrl:1
	v_mov_b32_dpp v51, v43 row_ror:2 row_mask:0xf bank_mask:0xf bound_ctrl:1
	s_and_saveexec_b64 s[28:29], s[80:81]
	s_cbranch_execz .LBB0_3381
	v_pk_fma_f32 v[106:107], v[80:81], v[106:107], v[92:93]
	v_pk_fma_f32 v[100:101], v[64:65], v[100:101], v[76:77]
	v_pk_fma_f32 v[104:105], v[84:85], v[104:105], v[106:107]
	v_pk_fma_f32 v[96:97], v[68:69], v[96:97], v[100:101]
	v_pk_fma_f32 v[44:45], v[44:45], v[88:89], v[104:105]
	v_pk_fma_f32 v[40:41], v[40:41], v[72:73], v[96:97]
	v_mul_f32_e32 v104, 0x3d372713, v44
	v_mul_f32_e32 v105, 0x3d372713, v45
	v_fma_f32 v104, v44, v104, 1.0
	v_fma_f32 v105, v45, v105, 1.0
	v_mul_f32_e32 v104, v44, v104
	v_mul_f32_e32 v105, v45, v105
	v_mul_f32_e32 v104, 0x40135761, v104
	v_mul_f32_e32 v105, 0x40135761, v105
	v_pk_fma_f32 v[96:97], v[82:83], v[102:103], v[94:95]
	v_exp_f32_e32 v104, v104
	v_exp_f32_e32 v105, v105
	v_pk_fma_f32 v[96:97], v[86:87], v[98:99], v[96:97]
	v_pk_fma_f32 v[62:63], v[66:67], v[62:63], v[78:79]
	v_pk_fma_f32 v[46:47], v[46:47], v[90:91], v[96:97]
	v_add_f32_e32 v104, 1.0, v104
	v_mul_f32_e32 v96, 0x3d372713, v46
	v_mul_f32_e32 v97, 0x3d372713, v47
	v_fma_f32 v96, v46, v96, 1.0
	v_fma_f32 v97, v47, v97, 1.0
	v_add_f32_e32 v105, 1.0, v105
	v_mul_f32_e32 v96, v46, v96
	v_mul_f32_e32 v97, v47, v97
	v_rcp_f32_e32 v104, v104
	v_rcp_f32_e32 v105, v105
	v_mul_f32_e32 v96, 0x40135761, v96
	v_mul_f32_e32 v97, 0x40135761, v97
	v_exp_f32_e32 v96, v96
	v_exp_f32_e32 v97, v97
	v_pk_fma_f32 v[44:45], v[44:45], v[104:105], v[44:45] neg_lo:[1,0,0] neg_hi:[1,0,0]
	v_pk_fma_f32 v[60:61], v[70:71], v[60:61], v[62:63]
	v_pk_mul_f32 v[40:41], v[40:41], v[44:45]
	v_add_f32_e32 v44, 1.0, v96
	v_add_f32_e32 v45, 1.0, v97
	v_rcp_f32_e32 v44, v44
	v_rcp_f32_e32 v45, v45
	v_pk_fma_f32 v[42:43], v[42:43], v[74:75], v[60:61]
	v_cvt_pk_bf16_f32 v40, v40, v41
	v_pk_fma_f32 v[44:45], v[46:47], v[44:45], v[46:47] neg_lo:[1,0,0] neg_hi:[1,0,0]
	s_nop 0
	v_pk_mul_f32 v[42:43], v[42:43], v[44:45]
	v_mov_b64_e32 v[44:45], s[42:43]
	v_cvt_pk_bf16_f32 v41, v42, v43
	v_lshl_add_u64 v[42:43], s[72:73], 0, v[146:147]
	v_mad_u64_u32 v[44:45], s[74:75], v42, s1, v[44:45]
	v_mad_i32_i24 v45, v43, s1, v45
	v_lshl_add_u64 v[42:43], v[192:193], 1, v[44:45]
	global_store_dwordx2 v[42:43], v[40:41], off offset:8
.LBB0_3381:
	s_or_b64 exec, exec, s[28:29]
	v_mov_b32_dpp v108, v36 row_shr:1 row_mask:0xf bank_mask:0xf
	v_mov_b32_dpp v110, v36 row_shr:2 row_mask:0xf bank_mask:0xf
	v_mov_b32_dpp v52, v32 row_shr:1 row_mask:0xf bank_mask:0xf
	v_mov_b32_dpp v56, v32 row_shr:2 row_mask:0xf bank_mask:0xf
	v_mov_b32_dpp v109, v37 row_shr:1 row_mask:0xf bank_mask:0xf
	v_mov_b32_dpp v111, v37 row_shr:2 row_mask:0xf bank_mask:0xf
	v_mov_b32_dpp v53, v33 row_shr:1 row_mask:0xf bank_mask:0xf
	v_mov_b32_dpp v57, v33 row_shr:2 row_mask:0xf bank_mask:0xf
	v_mov_b32_dpp v54, v38 row_shr:1 row_mask:0xf bank_mask:0xf
	v_mov_b32_dpp v58, v38 row_shr:2 row_mask:0xf bank_mask:0xf
	v_mov_b32_dpp v48, v34 row_shr:1 row_mask:0xf bank_mask:0xf
	v_mov_b32_dpp v50, v34 row_shr:2 row_mask:0xf bank_mask:0xf
	v_mov_b32_dpp v55, v39 row_shr:1 row_mask:0xf bank_mask:0xf
	v_mov_b32_dpp v59, v39 row_shr:2 row_mask:0xf bank_mask:0xf
	v_mov_b32_dpp v49, v35 row_shr:1 row_mask:0xf bank_mask:0xf
	v_mov_b32_dpp v51, v35 row_shr:2 row_mask:0xf bank_mask:0xf
	s_and_saveexec_b64 s[28:29], s[82:83]
	s_cbranch_execz .LBB0_3383
	v_pk_fma_f32 v[40:41], v[80:81], v[110:111], v[92:93]
	v_pk_fma_f32 v[42:43], v[64:65], v[56:57], v[76:77]
	v_pk_fma_f32 v[40:41], v[84:85], v[108:109], v[40:41]
	v_pk_fma_f32 v[42:43], v[68:69], v[52:53], v[42:43]
	v_pk_fma_f32 v[36:37], v[36:37], v[88:89], v[40:41]
	v_pk_fma_f32 v[32:33], v[32:33], v[72:73], v[42:43]
	v_mul_f32_e32 v40, 0x3d372713, v36
	v_mul_f32_e32 v41, 0x3d372713, v37
	v_fma_f32 v40, v36, v40, 1.0
	v_fma_f32 v41, v37, v41, 1.0
	v_mul_f32_e32 v40, v36, v40
	v_mul_f32_e32 v41, v37, v41
	v_mul_f32_e32 v40, 0x40135761, v40
	v_mul_f32_e32 v41, 0x40135761, v41
	v_exp_f32_e32 v40, v40
	v_exp_f32_e32 v41, v41
	v_add_f32_e32 v40, 1.0, v40
	v_add_f32_e32 v41, 1.0, v41
	v_rcp_f32_e32 v40, v40
	v_rcp_f32_e32 v41, v41
	s_nop 0
	v_pk_fma_f32 v[36:37], v[36:37], v[40:41], v[36:37] neg_lo:[1,0,0] neg_hi:[1,0,0]
	v_pk_fma_f32 v[40:41], v[82:83], v[58:59], v[94:95]
	v_pk_mul_f32 v[32:33], v[32:33], v[36:37]
	v_pk_fma_f32 v[40:41], v[86:87], v[54:55], v[40:41]
	v_cvt_pk_bf16_f32 v32, v32, v33
	v_pk_fma_f32 v[38:39], v[38:39], v[90:91], v[40:41]
	s_nop 0
	v_mul_f32_e32 v40, 0x3d372713, v38
	v_mul_f32_e32 v41, 0x3d372713, v39
	v_fma_f32 v40, v38, v40, 1.0
	v_fma_f32 v41, v39, v41, 1.0
	v_mul_f32_e32 v40, v38, v40
	v_mul_f32_e32 v41, v39, v41
	v_mul_f32_e32 v40, 0x40135761, v40
	v_mul_f32_e32 v41, 0x40135761, v41
	v_exp_f32_e32 v40, v40
	v_exp_f32_e32 v41, v41
	v_add_f32_e32 v36, 1.0, v40
	v_add_f32_e32 v37, 1.0, v41
	v_rcp_f32_e32 v36, v36
	v_rcp_f32_e32 v37, v37
	v_pk_fma_f32 v[40:41], v[66:67], v[50:51], v[78:79]
	v_pk_fma_f32 v[36:37], v[38:39], v[36:37], v[38:39] neg_lo:[1,0,0] neg_hi:[1,0,0]
	v_pk_fma_f32 v[40:41], v[70:71], v[48:49], v[40:41]
	s_nop 0
	v_pk_fma_f32 v[34:35], v[34:35], v[74:75], v[40:41]
	s_nop 0
	v_pk_mul_f32 v[34:35], v[34:35], v[36:37]
	v_mov_b64_e32 v[36:37], s[42:43]
	v_cvt_pk_bf16_f32 v33, v34, v35
	v_lshl_add_u64 v[34:35], s[72:73], 0, v[148:149]
	v_mad_u64_u32 v[36:37], s[74:75], v34, s1, v[36:37]
	v_mad_i32_i24 v37, v35, s1, v37
	v_lshl_add_u64 v[34:35], v[192:193], 1, v[36:37]
	global_store_dwordx2 v[34:35], v[32:33], off offset:8
.LBB0_3383:
	s_or_b64 exec, exec, s[28:29]
	v_add_u32_e32 v32, 0x1180, v237
	v_add_u32_e32 v36, 0x1080, v237
	ds_read2_b64 v[40:43], v32 offset1:1
	ds_read2_b64 v[44:47], v36 offset1:1
	v_add_u32_e32 v32, 0x1190, v237
	v_add_u32_e32 v36, 0x1090, v237
	ds_read2_b64 v[32:35], v32 offset1:1
	ds_read2_b64 v[36:39], v36 offset1:1
	s_waitcnt lgkmcnt(3)
	v_cndmask_b32_e64 v100, v41, v40, s[14:15]
	v_cndmask_b32_e64 v101, v43, v42, s[14:15]
	s_waitcnt lgkmcnt(2)
	v_cndmask_b32_e64 v102, v45, v44, s[14:15]
	s_waitcnt lgkmcnt(1)
	v_cndmask_b32_e64 v96, v33, v32, s[14:15]
	v_cndmask_b32_e64 v97, v35, v34, s[14:15]
	v_cndmask_b32_e64 v103, v47, v46, s[14:15]
	s_waitcnt lgkmcnt(0)
	v_cndmask_b32_e64 v98, v37, v36, s[14:15]
	v_cndmask_b32_e64 v99, v39, v38, s[14:15]
	v_mov_b32_dpp v45, v28 row_shr:1 row_mask:0xf bank_mask:0xf
	v_mov_b32_dpp v102, v28 row_shr:2 row_mask:0xf bank_mask:0xf
	v_mov_b32_dpp v41, v24 row_shr:1 row_mask:0xf bank_mask:0xf
	v_mov_b32_dpp v100, v24 row_shr:2 row_mask:0xf bank_mask:0xf
	v_mov_b32_dpp v60, v28 row_ror:1 row_mask:0xf bank_mask:0xf bound_ctrl:1
	v_mov_b32_dpp v52, v24 row_ror:1 row_mask:0xf bank_mask:0xf bound_ctrl:1
	v_mov_b32_dpp v62, v28 row_ror:2 row_mask:0xf bank_mask:0xf bound_ctrl:1
	v_mov_b32_dpp v56, v24 row_ror:2 row_mask:0xf bank_mask:0xf bound_ctrl:1
	v_mov_b32_dpp v47, v29 row_shr:1 row_mask:0xf bank_mask:0xf
	v_mov_b32_dpp v103, v29 row_shr:2 row_mask:0xf bank_mask:0xf
	v_mov_b32_dpp v43, v25 row_shr:1 row_mask:0xf bank_mask:0xf
	v_mov_b32_dpp v101, v25 row_shr:2 row_mask:0xf bank_mask:0xf
	v_mov_b32_dpp v61, v29 row_ror:1 row_mask:0xf bank_mask:0xf bound_ctrl:1
	v_mov_b32_dpp v53, v25 row_ror:1 row_mask:0xf bank_mask:0xf bound_ctrl:1
	v_mov_b32_dpp v63, v29 row_ror:2 row_mask:0xf bank_mask:0xf bound_ctrl:1
	v_mov_b32_dpp v57, v25 row_ror:2 row_mask:0xf bank_mask:0xf bound_ctrl:1
	v_mov_b32_dpp v37, v30 row_shr:1 row_mask:0xf bank_mask:0xf
	v_mov_b32_dpp v98, v30 row_shr:2 row_mask:0xf bank_mask:0xf
	v_mov_b32_dpp v33, v26 row_shr:1 row_mask:0xf bank_mask:0xf
	v_mov_b32_dpp v96, v26 row_shr:2 row_mask:0xf bank_mask:0xf
	v_mov_b32_dpp v54, v30 row_ror:1 row_mask:0xf bank_mask:0xf bound_ctrl:1
	v_mov_b32_dpp v48, v26 row_ror:1 row_mask:0xf bank_mask:0xf bound_ctrl:1
	v_mov_b32_dpp v58, v30 row_ror:2 row_mask:0xf bank_mask:0xf bound_ctrl:1
	v_mov_b32_dpp v50, v26 row_ror:2 row_mask:0xf bank_mask:0xf bound_ctrl:1
	v_mov_b32_dpp v39, v31 row_shr:1 row_mask:0xf bank_mask:0xf
	v_mov_b32_dpp v99, v31 row_shr:2 row_mask:0xf bank_mask:0xf
	v_mov_b32_dpp v35, v27 row_shr:1 row_mask:0xf bank_mask:0xf
	v_mov_b32_dpp v97, v27 row_shr:2 row_mask:0xf bank_mask:0xf
	v_mov_b32_dpp v55, v31 row_ror:1 row_mask:0xf bank_mask:0xf bound_ctrl:1
	v_mov_b32_dpp v49, v27 row_ror:1 row_mask:0xf bank_mask:0xf bound_ctrl:1
	v_mov_b32_dpp v59, v31 row_ror:2 row_mask:0xf bank_mask:0xf bound_ctrl:1
	v_mov_b32_dpp v51, v27 row_ror:2 row_mask:0xf bank_mask:0xf bound_ctrl:1
	s_and_saveexec_b64 s[28:29], s[84:85]
	s_cbranch_execz .LBB0_3385
	v_mov_b32_e32 v46, v45
	v_pk_fma_f32 v[44:45], v[80:81], v[102:103], v[92:93]
	v_mov_b32_e32 v42, v41
	v_pk_fma_f32 v[44:45], v[84:85], v[46:47], v[44:45]
	v_mov_b32_e32 v38, v37
	v_pk_fma_f32 v[28:29], v[28:29], v[88:89], v[44:45]
	v_pk_fma_f32 v[44:45], v[64:65], v[100:101], v[76:77]
	v_mul_f32_e32 v32, 0x3d372713, v28
	v_fma_f32 v32, v28, v32, 1.0
	v_mul_f32_e32 v34, 0x3d372713, v29
	v_mul_f32_e32 v32, v28, v32
	v_fma_f32 v34, v29, v34, 1.0
	v_mul_f32_e32 v32, 0x40135761, v32
	v_mul_f32_e32 v34, v29, v34
	v_exp_f32_e32 v32, v32
	v_mul_f32_e32 v34, 0x40135761, v34
	v_exp_f32_e32 v34, v34
	v_pk_fma_f32 v[42:43], v[68:69], v[42:43], v[44:45]
	v_add_f32_e32 v32, 1.0, v32
	v_rcp_f32_e32 v40, v32
	v_add_f32_e32 v32, 1.0, v34
	v_rcp_f32_e32 v41, v32
	v_pk_fma_f32 v[24:25], v[24:25], v[72:73], v[42:43]
	v_mov_b32_e32 v34, v33
	v_pk_fma_f32 v[32:33], v[66:67], v[96:97], v[78:79]
	v_pk_fma_f32 v[28:29], v[28:29], v[40:41], v[28:29] neg_lo:[1,0,0] neg_hi:[1,0,0]
	v_pk_fma_f32 v[32:33], v[70:71], v[34:35], v[32:33]
	v_pk_mul_f32 v[24:25], v[24:25], v[28:29]
	v_pk_fma_f32 v[28:29], v[82:83], v[98:99], v[94:95]
	v_pk_fma_f32 v[26:27], v[26:27], v[74:75], v[32:33]
	v_pk_fma_f32 v[28:29], v[86:87], v[38:39], v[28:29]
	v_cvt_pk_bf16_f32 v24, v24, v25
	v_pk_fma_f32 v[28:29], v[30:31], v[90:91], v[28:29]
	s_nop 0
	v_mul_f32_e32 v30, 0x3d372713, v28
	v_mul_f32_e32 v31, 0x3d372713, v29
	v_fma_f32 v30, v28, v30, 1.0
	v_fma_f32 v31, v29, v31, 1.0
	v_mul_f32_e32 v30, v28, v30
	v_mul_f32_e32 v31, v29, v31
	v_mul_f32_e32 v30, 0x40135761, v30
	v_mul_f32_e32 v31, 0x40135761, v31
	v_exp_f32_e32 v30, v30
	v_exp_f32_e32 v31, v31
	v_add_f32_e32 v30, 1.0, v30
	v_add_f32_e32 v31, 1.0, v31
	v_rcp_f32_e32 v30, v30
	v_rcp_f32_e32 v31, v31
	s_nop 0
	v_pk_fma_f32 v[28:29], v[28:29], v[30:31], v[28:29] neg_lo:[1,0,0] neg_hi:[1,0,0]
	s_nop 0
	v_pk_mul_f32 v[26:27], v[26:27], v[28:29]
	v_mov_b64_e32 v[28:29], s[42:43]
	v_cvt_pk_bf16_f32 v25, v26, v27
	v_lshl_add_u64 v[26:27], s[72:73], 0, v[144:145]
	v_mad_u64_u32 v[28:29], s[74:75], v26, s1, v[28:29]
	v_mad_i32_i24 v29, v27, s1, v29
	v_lshl_add_u64 v[26:27], v[192:193], 1, v[28:29]
	global_store_dwordx2 v[26:27], v[24:25], off offset:8
.LBB0_3385:
	s_or_b64 exec, exec, s[28:29]
	v_mov_b32_dpp v60, v20 row_shr:1 row_mask:0xf bank_mask:0xf
	v_mov_b32_dpp v62, v20 row_shr:2 row_mask:0xf bank_mask:0xf
	v_mov_b32_dpp v52, v16 row_shr:1 row_mask:0xf bank_mask:0xf
	v_mov_b32_dpp v56, v16 row_shr:2 row_mask:0xf bank_mask:0xf
	v_mov_b32_dpp v40, v20 row_ror:1 row_mask:0xf bank_mask:0xf bound_ctrl:1
	v_mov_b32_dpp v28, v16 row_ror:1 row_mask:0xf bank_mask:0xf bound_ctrl:1
	v_mov_b32_dpp v42, v20 row_ror:2 row_mask:0xf bank_mask:0xf bound_ctrl:1
	v_mov_b32_dpp v32, v16 row_ror:2 row_mask:0xf bank_mask:0xf bound_ctrl:1
	v_mov_b32_dpp v61, v21 row_shr:1 row_mask:0xf bank_mask:0xf
	v_mov_b32_dpp v63, v21 row_shr:2 row_mask:0xf bank_mask:0xf
	v_mov_b32_dpp v53, v17 row_shr:1 row_mask:0xf bank_mask:0xf
	v_mov_b32_dpp v57, v17 row_shr:2 row_mask:0xf bank_mask:0xf
	v_mov_b32_dpp v41, v21 row_ror:1 row_mask:0xf bank_mask:0xf bound_ctrl:1
	v_mov_b32_dpp v29, v17 row_ror:1 row_mask:0xf bank_mask:0xf bound_ctrl:1
	v_mov_b32_dpp v43, v21 row_ror:2 row_mask:0xf bank_mask:0xf bound_ctrl:1
	v_mov_b32_dpp v33, v17 row_ror:2 row_mask:0xf bank_mask:0xf bound_ctrl:1
	v_mov_b32_dpp v54, v22 row_shr:1 row_mask:0xf bank_mask:0xf
	v_mov_b32_dpp v58, v22 row_shr:2 row_mask:0xf bank_mask:0xf
	v_mov_b32_dpp v48, v18 row_shr:1 row_mask:0xf bank_mask:0xf
	v_mov_b32_dpp v50, v18 row_shr:2 row_mask:0xf bank_mask:0xf
	v_mov_b32_dpp v30, v22 row_ror:1 row_mask:0xf bank_mask:0xf bound_ctrl:1
	v_mov_b32_dpp v24, v18 row_ror:1 row_mask:0xf bank_mask:0xf bound_ctrl:1
	v_mov_b32_dpp v34, v22 row_ror:2 row_mask:0xf bank_mask:0xf bound_ctrl:1
	v_mov_b32_dpp v26, v18 row_ror:2 row_mask:0xf bank_mask:0xf bound_ctrl:1
	v_mov_b32_dpp v55, v23 row_shr:1 row_mask:0xf bank_mask:0xf
	v_mov_b32_dpp v59, v23 row_shr:2 row_mask:0xf bank_mask:0xf
	v_mov_b32_dpp v49, v19 row_shr:1 row_mask:0xf bank_mask:0xf
	v_mov_b32_dpp v51, v19 row_shr:2 row_mask:0xf bank_mask:0xf
	v_mov_b32_dpp v31, v23 row_ror:1 row_mask:0xf bank_mask:0xf bound_ctrl:1
	v_mov_b32_dpp v25, v19 row_ror:1 row_mask:0xf bank_mask:0xf bound_ctrl:1
	v_mov_b32_dpp v35, v23 row_ror:2 row_mask:0xf bank_mask:0xf bound_ctrl:1
	v_mov_b32_dpp v27, v19 row_ror:2 row_mask:0xf bank_mask:0xf bound_ctrl:1
	s_and_saveexec_b64 s[28:29], s[86:87]
	s_cbranch_execz .LBB0_3387
	v_pk_fma_f32 v[36:37], v[80:81], v[62:63], v[92:93]
	v_pk_fma_f32 v[38:39], v[64:65], v[56:57], v[76:77]
	v_pk_fma_f32 v[36:37], v[84:85], v[60:61], v[36:37]
	v_pk_fma_f32 v[38:39], v[68:69], v[52:53], v[38:39]
	v_pk_fma_f32 v[20:21], v[20:21], v[88:89], v[36:37]
	v_pk_fma_f32 v[16:17], v[16:17], v[72:73], v[38:39]
	v_mul_f32_e32 v36, 0x3d372713, v20
	v_mul_f32_e32 v37, 0x3d372713, v21
	v_fma_f32 v36, v20, v36, 1.0
	v_fma_f32 v37, v21, v37, 1.0
	v_mul_f32_e32 v36, v20, v36
	v_mul_f32_e32 v37, v21, v37
	v_mul_f32_e32 v36, 0x40135761, v36
	v_mul_f32_e32 v37, 0x40135761, v37
	v_exp_f32_e32 v36, v36
	v_exp_f32_e32 v37, v37
	v_add_f32_e32 v36, 1.0, v36
	v_add_f32_e32 v37, 1.0, v37
	v_rcp_f32_e32 v36, v36
	v_rcp_f32_e32 v37, v37
	s_nop 0
	v_pk_fma_f32 v[20:21], v[20:21], v[36:37], v[20:21] neg_lo:[1,0,0] neg_hi:[1,0,0]
	v_pk_fma_f32 v[36:37], v[82:83], v[58:59], v[94:95]
	v_pk_mul_f32 v[16:17], v[16:17], v[20:21]
	v_pk_fma_f32 v[36:37], v[86:87], v[54:55], v[36:37]
	v_cvt_pk_bf16_f32 v16, v16, v17
	v_pk_fma_f32 v[22:23], v[22:23], v[90:91], v[36:37]
	s_nop 0
	v_mul_f32_e32 v36, 0x3d372713, v22
	v_mul_f32_e32 v37, 0x3d372713, v23
	v_fma_f32 v36, v22, v36, 1.0
	v_fma_f32 v37, v23, v37, 1.0
	v_mul_f32_e32 v36, v22, v36
	v_mul_f32_e32 v37, v23, v37
	v_mul_f32_e32 v36, 0x40135761, v36
	v_mul_f32_e32 v37, 0x40135761, v37
	v_exp_f32_e32 v36, v36
	v_exp_f32_e32 v37, v37
	v_add_f32_e32 v20, 1.0, v36
	v_add_f32_e32 v21, 1.0, v37
	v_rcp_f32_e32 v20, v20
	v_rcp_f32_e32 v21, v21
	v_pk_fma_f32 v[36:37], v[66:67], v[50:51], v[78:79]
	v_pk_fma_f32 v[20:21], v[22:23], v[20:21], v[22:23] neg_lo:[1,0,0] neg_hi:[1,0,0]
	v_pk_fma_f32 v[36:37], v[70:71], v[48:49], v[36:37]
	s_nop 0
	v_pk_fma_f32 v[18:19], v[18:19], v[74:75], v[36:37]
	s_nop 0
	v_pk_mul_f32 v[18:19], v[18:19], v[20:21]
	v_mov_b64_e32 v[20:21], s[42:43]
	v_cvt_pk_bf16_f32 v17, v18, v19
	v_lshl_add_u64 v[18:19], s[72:73], 0, v[136:137]
	v_mad_u64_u32 v[20:21], s[74:75], v18, s1, v[20:21]
	v_mad_i32_i24 v21, v19, s1, v21
	v_lshl_add_u64 v[18:19], v[192:193], 1, v[20:21]
	global_store_dwordx2 v[18:19], v[16:17], off offset:8
.LBB0_3387:
	s_or_b64 exec, exec, s[28:29]
	v_mov_b32_dpp v40, v12 row_shr:1 row_mask:0xf bank_mask:0xf
	v_mov_b32_dpp v42, v12 row_shr:2 row_mask:0xf bank_mask:0xf
	v_mov_b32_dpp v28, v8 row_shr:1 row_mask:0xf bank_mask:0xf
	v_mov_b32_dpp v32, v8 row_shr:2 row_mask:0xf bank_mask:0xf
	v_mov_b32_dpp v44, v12 row_ror:1 row_mask:0xf bank_mask:0xf bound_ctrl:1
	v_mov_b32_dpp v20, v8 row_ror:1 row_mask:0xf bank_mask:0xf bound_ctrl:1
	v_mov_b32_dpp v46, v12 row_ror:2 row_mask:0xf bank_mask:0xf bound_ctrl:1
	v_mov_b32_dpp v36, v8 row_ror:2 row_mask:0xf bank_mask:0xf bound_ctrl:1
	v_mov_b32_dpp v41, v13 row_shr:1 row_mask:0xf bank_mask:0xf
	v_mov_b32_dpp v43, v13 row_shr:2 row_mask:0xf bank_mask:0xf
	v_mov_b32_dpp v29, v9 row_shr:1 row_mask:0xf bank_mask:0xf
	v_mov_b32_dpp v33, v9 row_shr:2 row_mask:0xf bank_mask:0xf
	v_mov_b32_dpp v45, v13 row_ror:1 row_mask:0xf bank_mask:0xf bound_ctrl:1
	v_mov_b32_dpp v21, v9 row_ror:1 row_mask:0xf bank_mask:0xf bound_ctrl:1
	v_mov_b32_dpp v47, v13 row_ror:2 row_mask:0xf bank_mask:0xf bound_ctrl:1
	v_mov_b32_dpp v37, v9 row_ror:2 row_mask:0xf bank_mask:0xf bound_ctrl:1
	v_mov_b32_dpp v30, v14 row_shr:1 row_mask:0xf bank_mask:0xf
	v_mov_b32_dpp v34, v14 row_shr:2 row_mask:0xf bank_mask:0xf
	v_mov_b32_dpp v24, v10 row_shr:1 row_mask:0xf bank_mask:0xf
	v_mov_b32_dpp v26, v10 row_shr:2 row_mask:0xf bank_mask:0xf
	v_mov_b32_dpp v22, v14 row_ror:1 row_mask:0xf bank_mask:0xf bound_ctrl:1
	v_mov_b32_dpp v16, v10 row_ror:1 row_mask:0xf bank_mask:0xf bound_ctrl:1
	v_mov_b32_dpp v38, v14 row_ror:2 row_mask:0xf bank_mask:0xf bound_ctrl:1
	v_mov_b32_dpp v18, v10 row_ror:2 row_mask:0xf bank_mask:0xf bound_ctrl:1
	v_mov_b32_dpp v31, v15 row_shr:1 row_mask:0xf bank_mask:0xf
	v_mov_b32_dpp v35, v15 row_shr:2 row_mask:0xf bank_mask:0xf
	v_mov_b32_dpp v25, v11 row_shr:1 row_mask:0xf bank_mask:0xf
	v_mov_b32_dpp v27, v11 row_shr:2 row_mask:0xf bank_mask:0xf
	v_mov_b32_dpp v23, v15 row_ror:1 row_mask:0xf bank_mask:0xf bound_ctrl:1
	v_mov_b32_dpp v17, v11 row_ror:1 row_mask:0xf bank_mask:0xf bound_ctrl:1
	v_mov_b32_dpp v39, v15 row_ror:2 row_mask:0xf bank_mask:0xf bound_ctrl:1
	v_mov_b32_dpp v19, v11 row_ror:2 row_mask:0xf bank_mask:0xf bound_ctrl:1
	s_and_saveexec_b64 s[28:29], s[88:89]
	s_cbranch_execz .LBB0_3389
	v_pk_fma_f32 v[42:43], v[80:81], v[42:43], v[92:93]
	v_pk_fma_f32 v[32:33], v[64:65], v[32:33], v[76:77]
	v_pk_fma_f32 v[40:41], v[84:85], v[40:41], v[42:43]
	v_pk_fma_f32 v[28:29], v[68:69], v[28:29], v[32:33]
	v_pk_fma_f32 v[12:13], v[12:13], v[88:89], v[40:41]
	v_pk_fma_f32 v[8:9], v[8:9], v[72:73], v[28:29]
	v_mul_f32_e32 v40, 0x3d372713, v12
	v_mul_f32_e32 v41, 0x3d372713, v13
	v_fma_f32 v40, v12, v40, 1.0
	v_fma_f32 v41, v13, v41, 1.0
	v_mul_f32_e32 v40, v12, v40
	v_mul_f32_e32 v41, v13, v41
	v_mul_f32_e32 v40, 0x40135761, v40
	v_mul_f32_e32 v41, 0x40135761, v41
	v_pk_fma_f32 v[28:29], v[82:83], v[34:35], v[94:95]
	v_exp_f32_e32 v40, v40
	v_exp_f32_e32 v41, v41
	v_pk_fma_f32 v[28:29], v[86:87], v[30:31], v[28:29]
	v_pk_fma_f32 v[26:27], v[66:67], v[26:27], v[78:79]
	v_pk_fma_f32 v[14:15], v[14:15], v[90:91], v[28:29]
	v_add_f32_e32 v40, 1.0, v40
	v_mul_f32_e32 v28, 0x3d372713, v14
	v_mul_f32_e32 v29, 0x3d372713, v15
	v_fma_f32 v28, v14, v28, 1.0
	v_fma_f32 v29, v15, v29, 1.0
	v_add_f32_e32 v41, 1.0, v41
	v_mul_f32_e32 v28, v14, v28
	v_mul_f32_e32 v29, v15, v29
	v_rcp_f32_e32 v40, v40
	v_rcp_f32_e32 v41, v41
	v_mul_f32_e32 v28, 0x40135761, v28
	v_mul_f32_e32 v29, 0x40135761, v29
	v_exp_f32_e32 v28, v28
	v_exp_f32_e32 v29, v29
	v_pk_fma_f32 v[12:13], v[12:13], v[40:41], v[12:13] neg_lo:[1,0,0] neg_hi:[1,0,0]
	v_pk_fma_f32 v[24:25], v[70:71], v[24:25], v[26:27]
	v_pk_mul_f32 v[8:9], v[8:9], v[12:13]
	v_add_f32_e32 v12, 1.0, v28
	v_add_f32_e32 v13, 1.0, v29
	v_rcp_f32_e32 v12, v12
	v_rcp_f32_e32 v13, v13
	v_pk_fma_f32 v[10:11], v[10:11], v[74:75], v[24:25]
	v_cvt_pk_bf16_f32 v8, v8, v9
	v_pk_fma_f32 v[12:13], v[14:15], v[12:13], v[14:15] neg_lo:[1,0,0] neg_hi:[1,0,0]
	s_nop 0
	v_pk_mul_f32 v[10:11], v[10:11], v[12:13]
	v_mov_b64_e32 v[12:13], s[42:43]
	v_cvt_pk_bf16_f32 v9, v10, v11
	v_lshl_add_u64 v[10:11], s[72:73], 0, v[138:139]
	v_mad_u64_u32 v[12:13], s[74:75], v10, s1, v[12:13]
	v_mad_i32_i24 v13, v11, s1, v13
	v_lshl_add_u64 v[10:11], v[192:193], 1, v[12:13]
	global_store_dwordx2 v[10:11], v[8:9], off offset:8
.LBB0_3389:
	s_or_b64 exec, exec, s[28:29]
	v_mov_b32_dpp v44, v4 row_shr:1 row_mask:0xf bank_mask:0xf
	v_mov_b32_dpp v46, v4 row_shr:2 row_mask:0xf bank_mask:0xf
	v_mov_b32_dpp v20, v0 row_shr:1 row_mask:0xf bank_mask:0xf
	v_mov_b32_dpp v36, v0 row_shr:2 row_mask:0xf bank_mask:0xf
	v_mov_b32_dpp v45, v5 row_shr:1 row_mask:0xf bank_mask:0xf
	v_mov_b32_dpp v47, v5 row_shr:2 row_mask:0xf bank_mask:0xf
	v_mov_b32_dpp v21, v1 row_shr:1 row_mask:0xf bank_mask:0xf
	v_mov_b32_dpp v37, v1 row_shr:2 row_mask:0xf bank_mask:0xf
	v_mov_b32_dpp v22, v6 row_shr:1 row_mask:0xf bank_mask:0xf
	v_mov_b32_dpp v38, v6 row_shr:2 row_mask:0xf bank_mask:0xf
	v_mov_b32_dpp v16, v2 row_shr:1 row_mask:0xf bank_mask:0xf
	v_mov_b32_dpp v18, v2 row_shr:2 row_mask:0xf bank_mask:0xf
	v_mov_b32_dpp v23, v7 row_shr:1 row_mask:0xf bank_mask:0xf
	v_mov_b32_dpp v39, v7 row_shr:2 row_mask:0xf bank_mask:0xf
	v_mov_b32_dpp v17, v3 row_shr:1 row_mask:0xf bank_mask:0xf
	v_mov_b32_dpp v19, v3 row_shr:2 row_mask:0xf bank_mask:0xf
	s_and_saveexec_b64 s[28:29], s[90:91]
	s_cbranch_execz .LBB0_3391
	v_pk_fma_f32 v[8:9], v[80:81], v[46:47], v[92:93]
	v_pk_fma_f32 v[10:11], v[64:65], v[36:37], v[76:77]
	v_pk_fma_f32 v[8:9], v[84:85], v[44:45], v[8:9]
	v_pk_fma_f32 v[10:11], v[68:69], v[20:21], v[10:11]
	v_pk_fma_f32 v[4:5], v[4:5], v[88:89], v[8:9]
	v_pk_fma_f32 v[0:1], v[0:1], v[72:73], v[10:11]
	v_mul_f32_e32 v8, 0x3d372713, v4
	v_mul_f32_e32 v9, 0x3d372713, v5
	v_fma_f32 v8, v4, v8, 1.0
	v_fma_f32 v9, v5, v9, 1.0
	v_mul_f32_e32 v8, v4, v8
	v_mul_f32_e32 v9, v5, v9
	v_mul_f32_e32 v8, 0x40135761, v8
	v_mul_f32_e32 v9, 0x40135761, v9
	v_exp_f32_e32 v8, v8
	v_exp_f32_e32 v9, v9
	v_add_f32_e32 v8, 1.0, v8
	v_add_f32_e32 v9, 1.0, v9
	v_rcp_f32_e32 v8, v8
	v_rcp_f32_e32 v9, v9
	s_nop 0
	v_pk_fma_f32 v[4:5], v[4:5], v[8:9], v[4:5] neg_lo:[1,0,0] neg_hi:[1,0,0]
	v_pk_fma_f32 v[8:9], v[82:83], v[38:39], v[94:95]
	v_pk_mul_f32 v[0:1], v[0:1], v[4:5]
	v_pk_fma_f32 v[8:9], v[86:87], v[22:23], v[8:9]
	v_cvt_pk_bf16_f32 v0, v0, v1
	v_pk_fma_f32 v[6:7], v[6:7], v[90:91], v[8:9]
	s_nop 0
	v_mul_f32_e32 v8, 0x3d372713, v6
	v_mul_f32_e32 v9, 0x3d372713, v7
	v_fma_f32 v8, v6, v8, 1.0
	v_fma_f32 v9, v7, v9, 1.0
	v_mul_f32_e32 v8, v6, v8
	v_mul_f32_e32 v9, v7, v9
	v_mul_f32_e32 v8, 0x40135761, v8
	v_mul_f32_e32 v9, 0x40135761, v9
	v_exp_f32_e32 v8, v8
	v_exp_f32_e32 v9, v9
	v_add_f32_e32 v4, 1.0, v8
	v_add_f32_e32 v5, 1.0, v9
	v_rcp_f32_e32 v4, v4
	v_rcp_f32_e32 v5, v5
	v_pk_fma_f32 v[8:9], v[66:67], v[18:19], v[78:79]
	v_pk_fma_f32 v[4:5], v[6:7], v[4:5], v[6:7] neg_lo:[1,0,0] neg_hi:[1,0,0]
	v_pk_fma_f32 v[8:9], v[70:71], v[16:17], v[8:9]
	s_nop 0
	v_pk_fma_f32 v[2:3], v[2:3], v[74:75], v[8:9]
	s_nop 0
	v_pk_mul_f32 v[2:3], v[2:3], v[4:5]
	v_mov_b64_e32 v[4:5], s[42:43]
	v_cvt_pk_bf16_f32 v1, v2, v3
	v_lshl_add_u64 v[2:3], s[72:73], 0, v[140:141]
	v_mad_u64_u32 v[4:5], s[72:73], v2, s1, v[4:5]
	v_mad_i32_i24 v5, v3, s1, v5
	v_lshl_add_u64 v[2:3], v[192:193], 1, v[4:5]
	global_store_dwordx2 v[2:3], v[0:1], off offset:8

.LBB0_4046:
	s_mul_hi_i32 s61, s29, 0x3e0f83e1
	s_lshr_b32 s66, s61, 31
	s_ashr_i32 s61, s61, 3
	s_add_i32 s66, s61, s66
	s_mul_i32 s61, s66, 33
	s_sub_i32 s29, s29, s61
	s_mul_i32 s61, s29, 0xfe
	v_add_u32_e32 v194, s61, v224
	s_or_b32 s61, s29, s90
	s_cmp_eq_u32 s61, 0
	s_cselect_b64 s[68:69], -1, 0
	s_cmp_eq_u32 s29, 32
	s_movk_i32 s29, 0x42
	s_cselect_b32 s29, s29, 0x100
	s_and_b64 s[68:69], s[68:69], s[8:9]
	s_ashr_i32 s67, s66, 31
	v_cndmask_b32_e64 v217, v159, 0, s[68:69]
	v_cndmask_b32_e64 v216, v158, 0, s[68:69]
	v_cndmask_b32_e64 v219, v157, 0, s[68:69]
	v_cndmask_b32_e64 v218, v156, 0, s[68:69]
	v_cndmask_b32_e64 v159, v155, 0, s[68:69]
	v_cndmask_b32_e64 v158, v154, 0, s[68:69]
	v_cndmask_b32_e64 v153, v153, 0, s[68:69]
	v_cndmask_b32_e64 v152, v152, 0, s[68:69]
	v_cmp_gt_u32_e32 vcc, s29, v220
	s_lshl_b64 s[66:67], s[66:67], 13
	v_mov_b32_dpp v173, v218 row_shr:1 row_mask:0xf bank_mask:0xf
	v_mov_b32_dpp v214, v218 row_shr:2 row_mask:0xf bank_mask:0xf
	v_mov_b32_dpp v169, v152 row_shr:1 row_mask:0xf bank_mask:0xf
	v_mov_b32_dpp v212, v152 row_shr:2 row_mask:0xf bank_mask:0xf
	v_mov_b32_dpp v204, v218 row_ror:1 row_mask:0xf bank_mask:0xf bound_ctrl:1
	v_mov_b32_dpp v196, v152 row_ror:1 row_mask:0xf bank_mask:0xf bound_ctrl:1
	v_mov_b32_dpp v206, v218 row_ror:2 row_mask:0xf bank_mask:0xf bound_ctrl:1
	v_mov_b32_dpp v200, v152 row_ror:2 row_mask:0xf bank_mask:0xf bound_ctrl:1
	v_mov_b32_dpp v175, v219 row_shr:1 row_mask:0xf bank_mask:0xf
	v_mov_b32_dpp v215, v219 row_shr:2 row_mask:0xf bank_mask:0xf
	v_mov_b32_dpp v171, v153 row_shr:1 row_mask:0xf bank_mask:0xf
	v_mov_b32_dpp v213, v153 row_shr:2 row_mask:0xf bank_mask:0xf
	v_mov_b32_dpp v205, v219 row_ror:1 row_mask:0xf bank_mask:0xf bound_ctrl:1
	v_mov_b32_dpp v197, v153 row_ror:1 row_mask:0xf bank_mask:0xf bound_ctrl:1
	v_mov_b32_dpp v207, v219 row_ror:2 row_mask:0xf bank_mask:0xf bound_ctrl:1
	v_mov_b32_dpp v201, v153 row_ror:2 row_mask:0xf bank_mask:0xf bound_ctrl:1
	v_mov_b32_dpp v165, v216 row_shr:1 row_mask:0xf bank_mask:0xf
	v_mov_b32_dpp v210, v216 row_shr:2 row_mask:0xf bank_mask:0xf
	v_mov_b32_dpp v161, v158 row_shr:1 row_mask:0xf bank_mask:0xf
	v_mov_b32_dpp v208, v158 row_shr:2 row_mask:0xf bank_mask:0xf
	v_mov_b32_dpp v198, v216 row_ror:1 row_mask:0xf bank_mask:0xf bound_ctrl:1
	v_mov_b32_dpp v154, v158 row_ror:1 row_mask:0xf bank_mask:0xf bound_ctrl:1
	v_mov_b32_dpp v202, v216 row_ror:2 row_mask:0xf bank_mask:0xf bound_ctrl:1
	v_mov_b32_dpp v156, v158 row_ror:2 row_mask:0xf bank_mask:0xf bound_ctrl:1
	v_mov_b32_dpp v167, v217 row_shr:1 row_mask:0xf bank_mask:0xf
	v_mov_b32_dpp v211, v217 row_shr:2 row_mask:0xf bank_mask:0xf
	v_mov_b32_dpp v163, v159 row_shr:1 row_mask:0xf bank_mask:0xf
	v_mov_b32_dpp v209, v159 row_shr:2 row_mask:0xf bank_mask:0xf
	v_mov_b32_dpp v199, v217 row_ror:1 row_mask:0xf bank_mask:0xf bound_ctrl:1
	v_mov_b32_dpp v155, v159 row_ror:1 row_mask:0xf bank_mask:0xf bound_ctrl:1
	v_mov_b32_dpp v203, v217 row_ror:2 row_mask:0xf bank_mask:0xf bound_ctrl:1
	v_mov_b32_dpp v157, v159 row_ror:2 row_mask:0xf bank_mask:0xf bound_ctrl:1
	s_and_b64 s[70:71], s[12:13], vcc
	v_ashrrev_i32_e32 v195, 31, v194
	s_waitcnt vmcnt(0)
	s_and_saveexec_b64 s[72:73], s[70:71]
	s_cbranch_execz .LBB0_4048
	v_mov_b32_e32 v174, v173
	v_pk_fma_f32 v[172:173], v[120:121], v[214:215], v[132:133]
	v_mov_b32_e32 v166, v165
	v_pk_fma_f32 v[172:173], v[124:125], v[174:175], v[172:173]
	v_pk_fma_f32 v[164:165], v[122:123], v[210:211], v[134:135]
	v_pk_fma_f32 v[172:173], v[218:219], v[128:129], v[172:173]
	v_pk_fma_f32 v[164:165], v[126:127], v[166:167], v[164:165]
	v_mul_f32_e32 v160, 0x3d372713, v172
	v_fma_f32 v160, v172, v160, 1.0
	v_mul_f32_e32 v162, 0x3d372713, v173
	v_mul_f32_e32 v160, v172, v160
	v_fma_f32 v162, v173, v162, 1.0
	v_mul_f32_e32 v160, 0x40135761, v160
	v_mul_f32_e32 v162, v173, v162
	v_exp_f32_e32 v160, v160
	v_mul_f32_e32 v162, 0x40135761, v162
	v_exp_f32_e32 v162, v162
	v_pk_fma_f32 v[164:165], v[216:217], v[130:131], v[164:165]
	v_add_f32_e32 v160, 1.0, v160
	v_rcp_f32_e32 v168, v160
	v_add_f32_e32 v160, 1.0, v162
	v_mov_b32_e32 v170, v169
	v_rcp_f32_e32 v169, v160
	v_mul_f32_e32 v160, 0x3d372713, v164
	v_mul_f32_e32 v162, 0x3d372713, v165
	v_fma_f32 v160, v164, v160, 1.0
	v_fma_f32 v162, v165, v162, 1.0
	v_mul_f32_e32 v160, v164, v160
	v_mul_f32_e32 v162, v165, v162
	v_mul_f32_e32 v160, 0x40135761, v160
	v_mul_f32_e32 v162, 0x40135761, v162
	v_exp_f32_e32 v160, v160
	v_exp_f32_e32 v166, v162
	v_mov_b32_e32 v162, v161
	v_pk_fma_f32 v[174:175], v[104:105], v[212:213], v[116:117]
	v_add_f32_e32 v160, 1.0, v160
	v_add_f32_e32 v161, 1.0, v166
	v_rcp_f32_e32 v160, v160
	v_rcp_f32_e32 v161, v161
	v_pk_fma_f32 v[166:167], v[106:107], v[208:209], v[118:119]
	v_pk_fma_f32 v[170:171], v[108:109], v[170:171], v[174:175]
	v_pk_fma_f32 v[162:163], v[110:111], v[162:163], v[166:167]
	v_pk_fma_f32 v[152:153], v[152:153], v[112:113], v[170:171]
	v_pk_fma_f32 v[168:169], v[172:173], v[168:169], v[172:173] neg_lo:[1,0,0] neg_hi:[1,0,0]
	v_pk_fma_f32 v[158:159], v[158:159], v[114:115], v[162:163]
	v_pk_fma_f32 v[160:161], v[164:165], v[160:161], v[164:165] neg_lo:[1,0,0] neg_hi:[1,0,0]
	v_pk_mul_f32 v[152:153], v[152:153], v[168:169]
	v_pk_mul_f32 v[158:159], v[158:159], v[160:161]
	v_cvt_pk_bf16_f32 v152, v152, v153
	v_cvt_pk_bf16_f32 v153, v158, v159
	v_lshl_add_u64 v[158:159], s[66:67], 0, v[194:195]
	v_mov_b64_e32 v[160:161], s[30:31]
	v_mad_u64_u32 v[160:161], s[74:75], v158, s1, v[160:161]
	v_mad_i32_i24 v161, v159, s1, v161
	v_lshl_add_u64 v[158:159], v[192:193], 1, v[160:161]
	global_store_dwordx2 v[158:159], v[152:153], off
.LBB0_4048:
	s_or_b64 exec, exec, s[72:73]
	v_cmp_gt_i32_e32 vcc, s29, v225
	v_add_u32_e32 v152, 16, v194
	v_mov_b32_dpp v204, v148 row_shr:1 row_mask:0xf bank_mask:0xf
	v_mov_b32_dpp v206, v148 row_shr:2 row_mask:0xf bank_mask:0xf
	v_mov_b32_dpp v196, v144 row_shr:1 row_mask:0xf bank_mask:0xf
	v_mov_b32_dpp v200, v144 row_shr:2 row_mask:0xf bank_mask:0xf
	v_mov_b32_dpp v174, v148 row_ror:1 row_mask:0xf bank_mask:0xf bound_ctrl:1
	v_mov_b32_dpp v162, v144 row_ror:1 row_mask:0xf bank_mask:0xf bound_ctrl:1
	v_mov_b32_dpp v208, v148 row_ror:2 row_mask:0xf bank_mask:0xf bound_ctrl:1
	v_mov_b32_dpp v166, v144 row_ror:2 row_mask:0xf bank_mask:0xf bound_ctrl:1
	v_mov_b32_dpp v205, v149 row_shr:1 row_mask:0xf bank_mask:0xf
	v_mov_b32_dpp v207, v149 row_shr:2 row_mask:0xf bank_mask:0xf
	v_mov_b32_dpp v197, v145 row_shr:1 row_mask:0xf bank_mask:0xf
	v_mov_b32_dpp v201, v145 row_shr:2 row_mask:0xf bank_mask:0xf
	v_mov_b32_dpp v175, v149 row_ror:1 row_mask:0xf bank_mask:0xf bound_ctrl:1
	v_mov_b32_dpp v163, v145 row_ror:1 row_mask:0xf bank_mask:0xf bound_ctrl:1
	v_mov_b32_dpp v209, v149 row_ror:2 row_mask:0xf bank_mask:0xf bound_ctrl:1
	v_mov_b32_dpp v167, v145 row_ror:2 row_mask:0xf bank_mask:0xf bound_ctrl:1
	v_mov_b32_dpp v198, v150 row_shr:1 row_mask:0xf bank_mask:0xf
	v_mov_b32_dpp v202, v150 row_shr:2 row_mask:0xf bank_mask:0xf
	v_mov_b32_dpp v154, v146 row_shr:1 row_mask:0xf bank_mask:0xf
	v_mov_b32_dpp v156, v146 row_shr:2 row_mask:0xf bank_mask:0xf
	v_mov_b32_dpp v164, v150 row_ror:1 row_mask:0xf bank_mask:0xf bound_ctrl:1
	v_mov_b32_dpp v158, v146 row_ror:1 row_mask:0xf bank_mask:0xf bound_ctrl:1
	v_mov_b32_dpp v168, v150 row_ror:2 row_mask:0xf bank_mask:0xf bound_ctrl:1
	v_mov_b32_dpp v160, v146 row_ror:2 row_mask:0xf bank_mask:0xf bound_ctrl:1
	v_mov_b32_dpp v199, v151 row_shr:1 row_mask:0xf bank_mask:0xf
	v_mov_b32_dpp v203, v151 row_shr:2 row_mask:0xf bank_mask:0xf
	v_mov_b32_dpp v155, v147 row_shr:1 row_mask:0xf bank_mask:0xf
	v_mov_b32_dpp v157, v147 row_shr:2 row_mask:0xf bank_mask:0xf
	v_mov_b32_dpp v165, v151 row_ror:1 row_mask:0xf bank_mask:0xf bound_ctrl:1
	v_mov_b32_dpp v159, v147 row_ror:1 row_mask:0xf bank_mask:0xf bound_ctrl:1
	v_mov_b32_dpp v169, v151 row_ror:2 row_mask:0xf bank_mask:0xf bound_ctrl:1
	v_mov_b32_dpp v161, v147 row_ror:2 row_mask:0xf bank_mask:0xf bound_ctrl:1
	s_and_b64 s[72:73], s[48:49], vcc
	v_ashrrev_i32_e32 v153, 31, v152
	s_and_saveexec_b64 s[74:75], s[72:73]
	s_cbranch_execz .LBB0_4050
	v_pk_fma_f32 v[170:171], v[120:121], v[206:207], v[132:133]
	v_pk_fma_f32 v[172:173], v[104:105], v[200:201], v[116:117]
	v_pk_fma_f32 v[170:171], v[124:125], v[204:205], v[170:171]
	v_pk_fma_f32 v[172:173], v[108:109], v[196:197], v[172:173]
	v_pk_fma_f32 v[148:149], v[148:149], v[128:129], v[170:171]
	v_pk_fma_f32 v[144:145], v[144:145], v[112:113], v[172:173]
	v_mul_f32_e32 v170, 0x3d372713, v148
	v_mul_f32_e32 v171, 0x3d372713, v149
	v_fma_f32 v170, v148, v170, 1.0
	v_fma_f32 v171, v149, v171, 1.0
	v_mul_f32_e32 v170, v148, v170
	v_mul_f32_e32 v171, v149, v171
	v_mul_f32_e32 v170, 0x40135761, v170
	v_mul_f32_e32 v171, 0x40135761, v171
	v_exp_f32_e32 v170, v170
	v_exp_f32_e32 v171, v171
	v_pk_fma_f32 v[156:157], v[106:107], v[156:157], v[118:119]
	v_add_f32_e32 v170, 1.0, v170
	v_add_f32_e32 v171, 1.0, v171
	v_rcp_f32_e32 v170, v170
	v_rcp_f32_e32 v171, v171
	v_pk_fma_f32 v[154:155], v[110:111], v[154:155], v[156:157]
	v_pk_fma_f32 v[148:149], v[148:149], v[170:171], v[148:149] neg_lo:[1,0,0] neg_hi:[1,0,0]
	v_pk_fma_f32 v[170:171], v[122:123], v[202:203], v[134:135]
	v_pk_mul_f32 v[144:145], v[144:145], v[148:149]
	v_pk_fma_f32 v[170:171], v[126:127], v[198:199], v[170:171]
	v_pk_fma_f32 v[146:147], v[146:147], v[114:115], v[154:155]
	v_pk_fma_f32 v[150:151], v[150:151], v[130:131], v[170:171]
	v_cvt_pk_bf16_f32 v144, v144, v145
	v_mul_f32_e32 v170, 0x3d372713, v150
	v_mul_f32_e32 v171, 0x3d372713, v151
	v_fma_f32 v170, v150, v170, 1.0
	v_fma_f32 v171, v151, v171, 1.0
	v_mul_f32_e32 v170, v150, v170
	v_mul_f32_e32 v171, v151, v171
	v_mul_f32_e32 v170, 0x40135761, v170
	v_mul_f32_e32 v171, 0x40135761, v171
	v_exp_f32_e32 v170, v170
	v_exp_f32_e32 v171, v171
	v_add_f32_e32 v148, 1.0, v170
	v_add_f32_e32 v149, 1.0, v171
	v_rcp_f32_e32 v148, v148
	v_rcp_f32_e32 v149, v149
	s_nop 0
	v_pk_fma_f32 v[148:149], v[150:151], v[148:149], v[150:151] neg_lo:[1,0,0] neg_hi:[1,0,0]
	s_nop 0
	v_pk_mul_f32 v[146:147], v[146:147], v[148:149]
	v_mov_b64_e32 v[148:149], s[30:31]
	v_cvt_pk_bf16_f32 v145, v146, v147
	v_lshl_add_u64 v[146:147], s[66:67], 0, v[152:153]
	v_mad_u64_u32 v[148:149], s[76:77], v146, s1, v[148:149]
	v_mad_i32_i24 v149, v147, s1, v149
	v_lshl_add_u64 v[146:147], v[192:193], 1, v[148:149]
	global_store_dwordx2 v[146:147], v[144:145], off
.LBB0_4050:
	s_or_b64 exec, exec, s[74:75]
	v_cmp_gt_i32_e32 vcc, s29, v226
	v_add_u32_e32 v146, 32, v194
	v_mov_b32_dpp v174, v140 row_shr:1 row_mask:0xf bank_mask:0xf
	v_mov_b32_dpp v208, v140 row_shr:2 row_mask:0xf bank_mask:0xf
	v_mov_b32_dpp v162, v136 row_shr:1 row_mask:0xf bank_mask:0xf
	v_mov_b32_dpp v166, v136 row_shr:2 row_mask:0xf bank_mask:0xf
	v_mov_b32_dpp v196, v140 row_ror:1 row_mask:0xf bank_mask:0xf bound_ctrl:1
	v_mov_b32_dpp v154, v136 row_ror:1 row_mask:0xf bank_mask:0xf bound_ctrl:1
	v_mov_b32_dpp v198, v140 row_ror:2 row_mask:0xf bank_mask:0xf bound_ctrl:1
	v_mov_b32_dpp v170, v136 row_ror:2 row_mask:0xf bank_mask:0xf bound_ctrl:1
	v_mov_b32_dpp v175, v141 row_shr:1 row_mask:0xf bank_mask:0xf
	v_mov_b32_dpp v209, v141 row_shr:2 row_mask:0xf bank_mask:0xf
	v_mov_b32_dpp v163, v137 row_shr:1 row_mask:0xf bank_mask:0xf
	v_mov_b32_dpp v167, v137 row_shr:2 row_mask:0xf bank_mask:0xf
	v_mov_b32_dpp v197, v141 row_ror:1 row_mask:0xf bank_mask:0xf bound_ctrl:1
	v_mov_b32_dpp v155, v137 row_ror:1 row_mask:0xf bank_mask:0xf bound_ctrl:1
	v_mov_b32_dpp v199, v141 row_ror:2 row_mask:0xf bank_mask:0xf bound_ctrl:1
	v_mov_b32_dpp v171, v137 row_ror:2 row_mask:0xf bank_mask:0xf bound_ctrl:1
	v_mov_b32_dpp v164, v142 row_shr:1 row_mask:0xf bank_mask:0xf
	v_mov_b32_dpp v168, v142 row_shr:2 row_mask:0xf bank_mask:0xf
	v_mov_b32_dpp v158, v138 row_shr:1 row_mask:0xf bank_mask:0xf
	v_mov_b32_dpp v160, v138 row_shr:2 row_mask:0xf bank_mask:0xf
	v_mov_b32_dpp v156, v142 row_ror:1 row_mask:0xf bank_mask:0xf bound_ctrl:1
	v_mov_b32_dpp v144, v138 row_ror:1 row_mask:0xf bank_mask:0xf bound_ctrl:1
	v_mov_b32_dpp v172, v142 row_ror:2 row_mask:0xf bank_mask:0xf bound_ctrl:1
	v_mov_b32_dpp v150, v138 row_ror:2 row_mask:0xf bank_mask:0xf bound_ctrl:1
	v_mov_b32_dpp v165, v143 row_shr:1 row_mask:0xf bank_mask:0xf
	v_mov_b32_dpp v169, v143 row_shr:2 row_mask:0xf bank_mask:0xf
	v_mov_b32_dpp v159, v139 row_shr:1 row_mask:0xf bank_mask:0xf
	v_mov_b32_dpp v161, v139 row_shr:2 row_mask:0xf bank_mask:0xf
	v_mov_b32_dpp v157, v143 row_ror:1 row_mask:0xf bank_mask:0xf bound_ctrl:1
	v_mov_b32_dpp v145, v139 row_ror:1 row_mask:0xf bank_mask:0xf bound_ctrl:1
	v_mov_b32_dpp v173, v143 row_ror:2 row_mask:0xf bank_mask:0xf bound_ctrl:1
	v_mov_b32_dpp v151, v139 row_ror:2 row_mask:0xf bank_mask:0xf bound_ctrl:1
	s_and_b64 s[74:75], s[48:49], vcc
	v_ashrrev_i32_e32 v147, 31, v146
	s_and_saveexec_b64 s[76:77], s[74:75]
	s_cbranch_execz .LBB0_4052
	v_pk_fma_f32 v[148:149], v[120:121], v[208:209], v[132:133]
	v_pk_fma_f32 v[166:167], v[104:105], v[166:167], v[116:117]
	v_pk_fma_f32 v[148:149], v[124:125], v[174:175], v[148:149]
	v_pk_fma_f32 v[162:163], v[108:109], v[162:163], v[166:167]
	v_pk_fma_f32 v[140:141], v[140:141], v[128:129], v[148:149]
	v_pk_fma_f32 v[136:137], v[136:137], v[112:113], v[162:163]
	v_mul_f32_e32 v148, 0x3d372713, v140
	v_mul_f32_e32 v149, 0x3d372713, v141
	v_fma_f32 v148, v140, v148, 1.0
	v_fma_f32 v149, v141, v149, 1.0
	v_mul_f32_e32 v148, v140, v148
	v_mul_f32_e32 v149, v141, v149
	v_mul_f32_e32 v148, 0x40135761, v148
	v_mul_f32_e32 v149, 0x40135761, v149
	v_exp_f32_e32 v148, v148
	v_exp_f32_e32 v149, v149
	v_add_f32_e32 v148, 1.0, v148
	v_add_f32_e32 v149, 1.0, v149
	v_rcp_f32_e32 v148, v148
	v_rcp_f32_e32 v149, v149
	s_nop 0
	v_pk_fma_f32 v[140:141], v[140:141], v[148:149], v[140:141] neg_lo:[1,0,0] neg_hi:[1,0,0]
	v_pk_fma_f32 v[148:149], v[122:123], v[168:169], v[134:135]
	v_pk_mul_f32 v[136:137], v[136:137], v[140:141]
	v_pk_fma_f32 v[148:149], v[126:127], v[164:165], v[148:149]
	v_cvt_pk_bf16_f32 v136, v136, v137
	v_pk_fma_f32 v[142:143], v[142:143], v[130:131], v[148:149]
	s_nop 0
	v_mul_f32_e32 v148, 0x3d372713, v142
	v_mul_f32_e32 v149, 0x3d372713, v143
	v_fma_f32 v148, v142, v148, 1.0
	v_fma_f32 v149, v143, v149, 1.0
	v_mul_f32_e32 v148, v142, v148
	v_mul_f32_e32 v149, v143, v149
	v_mul_f32_e32 v148, 0x40135761, v148
	v_mul_f32_e32 v149, 0x40135761, v149
	v_exp_f32_e32 v148, v148
	v_exp_f32_e32 v149, v149
	v_add_f32_e32 v140, 1.0, v148
	v_add_f32_e32 v141, 1.0, v149
	v_rcp_f32_e32 v140, v140
	v_rcp_f32_e32 v141, v141
	v_pk_fma_f32 v[148:149], v[106:107], v[160:161], v[118:119]
	v_pk_fma_f32 v[140:141], v[142:143], v[140:141], v[142:143] neg_lo:[1,0,0] neg_hi:[1,0,0]
	v_pk_fma_f32 v[148:149], v[110:111], v[158:159], v[148:149]
	s_nop 0
	v_pk_fma_f32 v[138:139], v[138:139], v[114:115], v[148:149]
	s_nop 0
	v_pk_mul_f32 v[138:139], v[138:139], v[140:141]
	v_mov_b64_e32 v[140:141], s[30:31]
	v_cvt_pk_bf16_f32 v137, v138, v139
	v_lshl_add_u64 v[138:139], s[66:67], 0, v[146:147]
	v_mad_u64_u32 v[140:141], s[78:79], v138, s1, v[140:141]
	v_mad_i32_i24 v141, v139, s1, v141
	v_lshl_add_u64 v[138:139], v[192:193], 1, v[140:141]
	global_store_dwordx2 v[138:139], v[136:137], off
.LBB0_4052:
	s_or_b64 exec, exec, s[76:77]
	v_cmp_gt_i32_e32 vcc, s29, v227
	v_add_u32_e32 v148, 48, v194
	v_mov_b32_dpp v196, v100 row_shr:1 row_mask:0xf bank_mask:0xf
	v_mov_b32_dpp v198, v100 row_shr:2 row_mask:0xf bank_mask:0xf
	v_mov_b32_dpp v154, v96 row_shr:1 row_mask:0xf bank_mask:0xf
	v_mov_b32_dpp v170, v96 row_shr:2 row_mask:0xf bank_mask:0xf
	v_mov_b32_dpp v197, v101 row_shr:1 row_mask:0xf bank_mask:0xf
	v_mov_b32_dpp v199, v101 row_shr:2 row_mask:0xf bank_mask:0xf
	v_mov_b32_dpp v155, v97 row_shr:1 row_mask:0xf bank_mask:0xf
	v_mov_b32_dpp v171, v97 row_shr:2 row_mask:0xf bank_mask:0xf
	v_mov_b32_dpp v156, v102 row_shr:1 row_mask:0xf bank_mask:0xf
	v_mov_b32_dpp v172, v102 row_shr:2 row_mask:0xf bank_mask:0xf
	v_mov_b32_dpp v144, v98 row_shr:1 row_mask:0xf bank_mask:0xf
	v_mov_b32_dpp v150, v98 row_shr:2 row_mask:0xf bank_mask:0xf
	v_mov_b32_dpp v157, v103 row_shr:1 row_mask:0xf bank_mask:0xf
	v_mov_b32_dpp v173, v103 row_shr:2 row_mask:0xf bank_mask:0xf
	v_mov_b32_dpp v145, v99 row_shr:1 row_mask:0xf bank_mask:0xf
	v_mov_b32_dpp v151, v99 row_shr:2 row_mask:0xf bank_mask:0xf
	s_and_b64 s[76:77], s[48:49], vcc
	v_ashrrev_i32_e32 v149, 31, v148
	s_and_saveexec_b64 s[78:79], s[76:77]
	s_cbranch_execz .LBB0_4054
	v_pk_fma_f32 v[136:137], v[120:121], v[198:199], v[132:133]
	v_pk_fma_f32 v[138:139], v[104:105], v[170:171], v[116:117]
	v_pk_fma_f32 v[136:137], v[124:125], v[196:197], v[136:137]
	v_pk_fma_f32 v[138:139], v[108:109], v[154:155], v[138:139]
	v_pk_fma_f32 v[100:101], v[100:101], v[128:129], v[136:137]
	v_pk_fma_f32 v[96:97], v[96:97], v[112:113], v[138:139]
	v_mul_f32_e32 v136, 0x3d372713, v100
	v_mul_f32_e32 v137, 0x3d372713, v101
	v_fma_f32 v136, v100, v136, 1.0
	v_fma_f32 v137, v101, v137, 1.0
	v_mul_f32_e32 v136, v100, v136
	v_mul_f32_e32 v137, v101, v137
	v_mul_f32_e32 v136, 0x40135761, v136
	v_mul_f32_e32 v137, 0x40135761, v137
	v_exp_f32_e32 v136, v136
	v_exp_f32_e32 v137, v137
	v_add_f32_e32 v136, 1.0, v136
	v_add_f32_e32 v137, 1.0, v137
	v_rcp_f32_e32 v136, v136
	v_rcp_f32_e32 v137, v137
	s_nop 0
	v_pk_fma_f32 v[100:101], v[100:101], v[136:137], v[100:101] neg_lo:[1,0,0] neg_hi:[1,0,0]
	v_pk_fma_f32 v[136:137], v[122:123], v[172:173], v[134:135]
	v_pk_mul_f32 v[96:97], v[96:97], v[100:101]
	v_pk_fma_f32 v[136:137], v[126:127], v[156:157], v[136:137]
	v_cvt_pk_bf16_f32 v96, v96, v97
	v_pk_fma_f32 v[102:103], v[102:103], v[130:131], v[136:137]
	s_nop 0
	v_mul_f32_e32 v136, 0x3d372713, v102
	v_mul_f32_e32 v137, 0x3d372713, v103
	v_fma_f32 v136, v102, v136, 1.0
	v_fma_f32 v137, v103, v137, 1.0
	v_mul_f32_e32 v136, v102, v136
	v_mul_f32_e32 v137, v103, v137
	v_mul_f32_e32 v136, 0x40135761, v136
	v_mul_f32_e32 v137, 0x40135761, v137
	v_exp_f32_e32 v136, v136
	v_exp_f32_e32 v137, v137
	v_add_f32_e32 v100, 1.0, v136
	v_add_f32_e32 v101, 1.0, v137
	v_rcp_f32_e32 v100, v100
	v_rcp_f32_e32 v101, v101
	v_pk_fma_f32 v[136:137], v[106:107], v[150:151], v[118:119]
	v_pk_fma_f32 v[100:101], v[102:103], v[100:101], v[102:103] neg_lo:[1,0,0] neg_hi:[1,0,0]
	v_pk_fma_f32 v[136:137], v[110:111], v[144:145], v[136:137]
	s_nop 0
	v_pk_fma_f32 v[98:99], v[98:99], v[114:115], v[136:137]
	s_nop 0
	v_pk_mul_f32 v[98:99], v[98:99], v[100:101]
	v_mov_b64_e32 v[100:101], s[30:31]
	v_cvt_pk_bf16_f32 v97, v98, v99
	v_lshl_add_u64 v[98:99], s[66:67], 0, v[148:149]
	v_mad_u64_u32 v[100:101], s[80:81], v98, s1, v[100:101]
	v_mad_i32_i24 v101, v99, s1, v101
	v_lshl_add_u64 v[98:99], v[192:193], 1, v[100:101]
	global_store_dwordx2 v[98:99], v[96:97], off
.LBB0_4054:
	s_or_b64 exec, exec, s[78:79]
	v_add_u32_e32 v96, 0x1100, v237
	v_add_u32_e32 v100, 0x1000, v237
	ds_read2_b64 v[136:139], v96 offset1:1
	ds_read2_b64 v[140:143], v100 offset1:1
	v_add_u32_e32 v96, 0x1110, v237
	v_add_u32_e32 v100, 0x1010, v237
	ds_read2_b64 v[96:99], v96 offset1:1
	ds_read2_b64 v[100:103], v100 offset1:1
	s_waitcnt lgkmcnt(0)
	v_cndmask_b32_e64 v172, v137, v136, s[10:11]
	v_cndmask_b32_e64 v173, v139, v138, s[10:11]
	v_cndmask_b32_e64 v174, v141, v140, s[10:11]
	v_cndmask_b32_e64 v168, v97, v96, s[10:11]
	v_cndmask_b32_e64 v169, v99, v98, s[10:11]
	v_cndmask_b32_e64 v175, v143, v142, s[10:11]
	v_cndmask_b32_e64 v170, v101, v100, s[10:11]
	v_cndmask_b32_e64 v171, v103, v102, s[10:11]
	v_add_u32_e32 v144, 0x80, v194
	v_cmp_gt_u32_e32 vcc, s29, v228
	v_mov_b32_dpp v141, v92 row_shr:1 row_mask:0xf bank_mask:0xf
	v_mov_b32_dpp v174, v92 row_shr:2 row_mask:0xf bank_mask:0xf
	v_mov_b32_dpp v137, v88 row_shr:1 row_mask:0xf bank_mask:0xf
	v_mov_b32_dpp v172, v88 row_shr:2 row_mask:0xf bank_mask:0xf
	v_mov_b32_dpp v164, v92 row_ror:1 row_mask:0xf bank_mask:0xf bound_ctrl:1
	v_mov_b32_dpp v156, v88 row_ror:1 row_mask:0xf bank_mask:0xf bound_ctrl:1
	v_mov_b32_dpp v166, v92 row_ror:2 row_mask:0xf bank_mask:0xf bound_ctrl:1
	v_mov_b32_dpp v160, v88 row_ror:2 row_mask:0xf bank_mask:0xf bound_ctrl:1
	v_mov_b32_dpp v143, v93 row_shr:1 row_mask:0xf bank_mask:0xf
	v_mov_b32_dpp v175, v93 row_shr:2 row_mask:0xf bank_mask:0xf
	v_mov_b32_dpp v139, v89 row_shr:1 row_mask:0xf bank_mask:0xf
	v_mov_b32_dpp v173, v89 row_shr:2 row_mask:0xf bank_mask:0xf
	v_mov_b32_dpp v165, v93 row_ror:1 row_mask:0xf bank_mask:0xf bound_ctrl:1
	v_mov_b32_dpp v157, v89 row_ror:1 row_mask:0xf bank_mask:0xf bound_ctrl:1
	v_mov_b32_dpp v167, v93 row_ror:2 row_mask:0xf bank_mask:0xf bound_ctrl:1
	v_mov_b32_dpp v161, v89 row_ror:2 row_mask:0xf bank_mask:0xf bound_ctrl:1
	v_mov_b32_dpp v101, v94 row_shr:1 row_mask:0xf bank_mask:0xf
	v_mov_b32_dpp v170, v94 row_shr:2 row_mask:0xf bank_mask:0xf
	v_mov_b32_dpp v97, v90 row_shr:1 row_mask:0xf bank_mask:0xf
	v_mov_b32_dpp v168, v90 row_shr:2 row_mask:0xf bank_mask:0xf
	v_mov_b32_dpp v158, v94 row_ror:1 row_mask:0xf bank_mask:0xf bound_ctrl:1
	v_mov_b32_dpp v150, v90 row_ror:1 row_mask:0xf bank_mask:0xf bound_ctrl:1
	v_mov_b32_dpp v162, v94 row_ror:2 row_mask:0xf bank_mask:0xf bound_ctrl:1
	v_mov_b32_dpp v154, v90 row_ror:2 row_mask:0xf bank_mask:0xf bound_ctrl:1
	v_mov_b32_dpp v103, v95 row_shr:1 row_mask:0xf bank_mask:0xf
	v_mov_b32_dpp v171, v95 row_shr:2 row_mask:0xf bank_mask:0xf
	v_mov_b32_dpp v99, v91 row_shr:1 row_mask:0xf bank_mask:0xf
	v_mov_b32_dpp v169, v91 row_shr:2 row_mask:0xf bank_mask:0xf
	v_mov_b32_dpp v159, v95 row_ror:1 row_mask:0xf bank_mask:0xf bound_ctrl:1
	v_mov_b32_dpp v151, v91 row_ror:1 row_mask:0xf bank_mask:0xf bound_ctrl:1
	v_mov_b32_dpp v163, v95 row_ror:2 row_mask:0xf bank_mask:0xf bound_ctrl:1
	v_mov_b32_dpp v155, v91 row_ror:2 row_mask:0xf bank_mask:0xf bound_ctrl:1
	s_and_b64 s[78:79], s[14:15], vcc
	v_ashrrev_i32_e32 v145, 31, v144
	s_and_saveexec_b64 s[80:81], s[78:79]
	s_cbranch_execz .LBB0_4056
	v_mov_b32_e32 v142, v141
	v_pk_fma_f32 v[140:141], v[120:121], v[174:175], v[132:133]
	v_mov_b32_e32 v138, v137
	v_pk_fma_f32 v[140:141], v[124:125], v[142:143], v[140:141]
	v_mov_b32_e32 v102, v101
	v_pk_fma_f32 v[92:93], v[92:93], v[128:129], v[140:141]
	v_pk_fma_f32 v[140:141], v[104:105], v[172:173], v[116:117]
	v_mul_f32_e32 v96, 0x3d372713, v92
	v_fma_f32 v96, v92, v96, 1.0
	v_mul_f32_e32 v98, 0x3d372713, v93
	v_mul_f32_e32 v96, v92, v96
	v_fma_f32 v98, v93, v98, 1.0
	v_mul_f32_e32 v96, 0x40135761, v96
	v_mul_f32_e32 v98, v93, v98
	v_exp_f32_e32 v96, v96
	v_mul_f32_e32 v98, 0x40135761, v98
	v_exp_f32_e32 v98, v98
	v_pk_fma_f32 v[138:139], v[108:109], v[138:139], v[140:141]
	v_add_f32_e32 v96, 1.0, v96
	v_rcp_f32_e32 v136, v96
	v_add_f32_e32 v96, 1.0, v98
	v_rcp_f32_e32 v137, v96
	v_pk_fma_f32 v[88:89], v[88:89], v[112:113], v[138:139]
	v_mov_b32_e32 v98, v97
	v_pk_fma_f32 v[96:97], v[106:107], v[168:169], v[118:119]
	v_pk_fma_f32 v[92:93], v[92:93], v[136:137], v[92:93] neg_lo:[1,0,0] neg_hi:[1,0,0]
	v_pk_fma_f32 v[96:97], v[110:111], v[98:99], v[96:97]
	v_pk_mul_f32 v[88:89], v[88:89], v[92:93]
	v_pk_fma_f32 v[92:93], v[122:123], v[170:171], v[134:135]
	v_pk_fma_f32 v[90:91], v[90:91], v[114:115], v[96:97]
	v_pk_fma_f32 v[92:93], v[126:127], v[102:103], v[92:93]
	v_cvt_pk_bf16_f32 v88, v88, v89
	v_pk_fma_f32 v[92:93], v[94:95], v[130:131], v[92:93]
	s_nop 0
	v_mul_f32_e32 v94, 0x3d372713, v92
	v_mul_f32_e32 v95, 0x3d372713, v93
	v_fma_f32 v94, v92, v94, 1.0
	v_fma_f32 v95, v93, v95, 1.0
	v_mul_f32_e32 v94, v92, v94
	v_mul_f32_e32 v95, v93, v95
	v_mul_f32_e32 v94, 0x40135761, v94
	v_mul_f32_e32 v95, 0x40135761, v95
	v_exp_f32_e32 v94, v94
	v_exp_f32_e32 v95, v95
	v_add_f32_e32 v94, 1.0, v94
	v_add_f32_e32 v95, 1.0, v95
	v_rcp_f32_e32 v94, v94
	v_rcp_f32_e32 v95, v95
	s_nop 0
	v_pk_fma_f32 v[92:93], v[92:93], v[94:95], v[92:93] neg_lo:[1,0,0] neg_hi:[1,0,0]
	s_nop 0
	v_pk_mul_f32 v[90:91], v[90:91], v[92:93]
	v_mov_b64_e32 v[92:93], s[30:31]
	v_cvt_pk_bf16_f32 v89, v90, v91
	v_lshl_add_u64 v[90:91], s[66:67], 0, v[144:145]
	v_mad_u64_u32 v[92:93], s[82:83], v90, s1, v[92:93]
	v_mad_i32_i24 v93, v91, s1, v93
	v_lshl_add_u64 v[90:91], v[192:193], 1, v[92:93]
	global_store_dwordx2 v[90:91], v[88:89], off
.LBB0_4056:
	s_or_b64 exec, exec, s[80:81]
	v_cmp_gt_u32_e32 vcc, s29, v229
	v_add_u32_e32 v136, 0x90, v194
	v_mov_b32_dpp v164, v84 row_shr:1 row_mask:0xf bank_mask:0xf
	v_mov_b32_dpp v166, v84 row_shr:2 row_mask:0xf bank_mask:0xf
	v_mov_b32_dpp v156, v80 row_shr:1 row_mask:0xf bank_mask:0xf
	v_mov_b32_dpp v160, v80 row_shr:2 row_mask:0xf bank_mask:0xf
	v_mov_b32_dpp v140, v84 row_ror:1 row_mask:0xf bank_mask:0xf bound_ctrl:1
	v_mov_b32_dpp v92, v80 row_ror:1 row_mask:0xf bank_mask:0xf bound_ctrl:1
	v_mov_b32_dpp v142, v84 row_ror:2 row_mask:0xf bank_mask:0xf bound_ctrl:1
	v_mov_b32_dpp v96, v80 row_ror:2 row_mask:0xf bank_mask:0xf bound_ctrl:1
	v_mov_b32_dpp v165, v85 row_shr:1 row_mask:0xf bank_mask:0xf
	v_mov_b32_dpp v167, v85 row_shr:2 row_mask:0xf bank_mask:0xf
	v_mov_b32_dpp v157, v81 row_shr:1 row_mask:0xf bank_mask:0xf
	v_mov_b32_dpp v161, v81 row_shr:2 row_mask:0xf bank_mask:0xf
	v_mov_b32_dpp v141, v85 row_ror:1 row_mask:0xf bank_mask:0xf bound_ctrl:1
	v_mov_b32_dpp v93, v81 row_ror:1 row_mask:0xf bank_mask:0xf bound_ctrl:1
	v_mov_b32_dpp v143, v85 row_ror:2 row_mask:0xf bank_mask:0xf bound_ctrl:1
	v_mov_b32_dpp v97, v81 row_ror:2 row_mask:0xf bank_mask:0xf bound_ctrl:1
	v_mov_b32_dpp v158, v86 row_shr:1 row_mask:0xf bank_mask:0xf
	v_mov_b32_dpp v162, v86 row_shr:2 row_mask:0xf bank_mask:0xf
	v_mov_b32_dpp v150, v82 row_shr:1 row_mask:0xf bank_mask:0xf
	v_mov_b32_dpp v154, v82 row_shr:2 row_mask:0xf bank_mask:0xf
	v_mov_b32_dpp v94, v86 row_ror:1 row_mask:0xf bank_mask:0xf bound_ctrl:1
	v_mov_b32_dpp v88, v82 row_ror:1 row_mask:0xf bank_mask:0xf bound_ctrl:1
	v_mov_b32_dpp v98, v86 row_ror:2 row_mask:0xf bank_mask:0xf bound_ctrl:1
	v_mov_b32_dpp v90, v82 row_ror:2 row_mask:0xf bank_mask:0xf bound_ctrl:1
	v_mov_b32_dpp v159, v87 row_shr:1 row_mask:0xf bank_mask:0xf
	v_mov_b32_dpp v163, v87 row_shr:2 row_mask:0xf bank_mask:0xf
	v_mov_b32_dpp v151, v83 row_shr:1 row_mask:0xf bank_mask:0xf
	v_mov_b32_dpp v155, v83 row_shr:2 row_mask:0xf bank_mask:0xf
	v_mov_b32_dpp v95, v87 row_ror:1 row_mask:0xf bank_mask:0xf bound_ctrl:1
	v_mov_b32_dpp v89, v83 row_ror:1 row_mask:0xf bank_mask:0xf bound_ctrl:1
	v_mov_b32_dpp v99, v87 row_ror:2 row_mask:0xf bank_mask:0xf bound_ctrl:1
	v_mov_b32_dpp v91, v83 row_ror:2 row_mask:0xf bank_mask:0xf bound_ctrl:1
	s_and_b64 s[80:81], s[16:17], vcc
	v_ashrrev_i32_e32 v137, 31, v136
	s_and_saveexec_b64 s[82:83], s[80:81]
	s_cbranch_execz .LBB0_4058
	v_pk_fma_f32 v[100:101], v[120:121], v[166:167], v[132:133]
	v_pk_fma_f32 v[102:103], v[104:105], v[160:161], v[116:117]
	v_pk_fma_f32 v[100:101], v[124:125], v[164:165], v[100:101]
	v_pk_fma_f32 v[102:103], v[108:109], v[156:157], v[102:103]
	v_pk_fma_f32 v[84:85], v[84:85], v[128:129], v[100:101]
	v_pk_fma_f32 v[80:81], v[80:81], v[112:113], v[102:103]
	v_mul_f32_e32 v100, 0x3d372713, v84
	v_mul_f32_e32 v101, 0x3d372713, v85
	v_fma_f32 v100, v84, v100, 1.0
	v_fma_f32 v101, v85, v101, 1.0
	v_mul_f32_e32 v100, v84, v100
	v_mul_f32_e32 v101, v85, v101
	v_mul_f32_e32 v100, 0x40135761, v100
	v_mul_f32_e32 v101, 0x40135761, v101
	v_exp_f32_e32 v100, v100
	v_exp_f32_e32 v101, v101
	v_add_f32_e32 v100, 1.0, v100
	v_add_f32_e32 v101, 1.0, v101
	v_rcp_f32_e32 v100, v100
	v_rcp_f32_e32 v101, v101
	s_nop 0
	v_pk_fma_f32 v[84:85], v[84:85], v[100:101], v[84:85] neg_lo:[1,0,0] neg_hi:[1,0,0]
	v_pk_fma_f32 v[100:101], v[122:123], v[162:163], v[134:135]
	v_pk_mul_f32 v[80:81], v[80:81], v[84:85]
	v_pk_fma_f32 v[100:101], v[126:127], v[158:159], v[100:101]
	v_cvt_pk_bf16_f32 v80, v80, v81
	v_pk_fma_f32 v[86:87], v[86:87], v[130:131], v[100:101]
	s_nop 0
	v_mul_f32_e32 v100, 0x3d372713, v86
	v_mul_f32_e32 v101, 0x3d372713, v87
	v_fma_f32 v100, v86, v100, 1.0
	v_fma_f32 v101, v87, v101, 1.0
	v_mul_f32_e32 v100, v86, v100
	v_mul_f32_e32 v101, v87, v101
	v_mul_f32_e32 v100, 0x40135761, v100
	v_mul_f32_e32 v101, 0x40135761, v101
	v_exp_f32_e32 v100, v100
	v_exp_f32_e32 v101, v101
	v_add_f32_e32 v84, 1.0, v100
	v_add_f32_e32 v85, 1.0, v101
	v_rcp_f32_e32 v84, v84
	v_rcp_f32_e32 v85, v85
	v_pk_fma_f32 v[100:101], v[106:107], v[154:155], v[118:119]
	v_pk_fma_f32 v[84:85], v[86:87], v[84:85], v[86:87] neg_lo:[1,0,0] neg_hi:[1,0,0]
	v_pk_fma_f32 v[100:101], v[110:111], v[150:151], v[100:101]
	s_nop 0
	v_pk_fma_f32 v[82:83], v[82:83], v[114:115], v[100:101]
	s_nop 0
	v_pk_mul_f32 v[82:83], v[82:83], v[84:85]
	v_mov_b64_e32 v[84:85], s[30:31]
	v_cvt_pk_bf16_f32 v81, v82, v83
	v_lshl_add_u64 v[82:83], s[66:67], 0, v[136:137]
	v_mad_u64_u32 v[84:85], s[84:85], v82, s1, v[84:85]
	v_mad_i32_i24 v85, v83, s1, v85
	v_lshl_add_u64 v[82:83], v[192:193], 1, v[84:85]
	global_store_dwordx2 v[82:83], v[80:81], off
.LBB0_4058:
	s_or_b64 exec, exec, s[82:83]
	v_cmp_gt_u32_e32 vcc, s29, v230
	v_add_u32_e32 v138, 0xa0, v194
	v_mov_b32_dpp v140, v76 row_shr:1 row_mask:0xf bank_mask:0xf
	v_mov_b32_dpp v142, v76 row_shr:2 row_mask:0xf bank_mask:0xf
	v_mov_b32_dpp v92, v72 row_shr:1 row_mask:0xf bank_mask:0xf
	v_mov_b32_dpp v96, v72 row_shr:2 row_mask:0xf bank_mask:0xf
	v_mov_b32_dpp v150, v76 row_ror:1 row_mask:0xf bank_mask:0xf bound_ctrl:1
	v_mov_b32_dpp v84, v72 row_ror:1 row_mask:0xf bank_mask:0xf bound_ctrl:1
	v_mov_b32_dpp v154, v76 row_ror:2 row_mask:0xf bank_mask:0xf bound_ctrl:1
	v_mov_b32_dpp v100, v72 row_ror:2 row_mask:0xf bank_mask:0xf bound_ctrl:1
	v_mov_b32_dpp v141, v77 row_shr:1 row_mask:0xf bank_mask:0xf
	v_mov_b32_dpp v143, v77 row_shr:2 row_mask:0xf bank_mask:0xf
	v_mov_b32_dpp v93, v73 row_shr:1 row_mask:0xf bank_mask:0xf
	v_mov_b32_dpp v97, v73 row_shr:2 row_mask:0xf bank_mask:0xf
	v_mov_b32_dpp v151, v77 row_ror:1 row_mask:0xf bank_mask:0xf bound_ctrl:1
	v_mov_b32_dpp v85, v73 row_ror:1 row_mask:0xf bank_mask:0xf bound_ctrl:1
	v_mov_b32_dpp v155, v77 row_ror:2 row_mask:0xf bank_mask:0xf bound_ctrl:1
	v_mov_b32_dpp v101, v73 row_ror:2 row_mask:0xf bank_mask:0xf bound_ctrl:1
	v_mov_b32_dpp v94, v78 row_shr:1 row_mask:0xf bank_mask:0xf
	v_mov_b32_dpp v98, v78 row_shr:2 row_mask:0xf bank_mask:0xf
	v_mov_b32_dpp v88, v74 row_shr:1 row_mask:0xf bank_mask:0xf
	v_mov_b32_dpp v90, v74 row_shr:2 row_mask:0xf bank_mask:0xf
	v_mov_b32_dpp v86, v78 row_ror:1 row_mask:0xf bank_mask:0xf bound_ctrl:1
	v_mov_b32_dpp v80, v74 row_ror:1 row_mask:0xf bank_mask:0xf bound_ctrl:1
	v_mov_b32_dpp v102, v78 row_ror:2 row_mask:0xf bank_mask:0xf bound_ctrl:1
	v_mov_b32_dpp v82, v74 row_ror:2 row_mask:0xf bank_mask:0xf bound_ctrl:1
	v_mov_b32_dpp v95, v79 row_shr:1 row_mask:0xf bank_mask:0xf
	v_mov_b32_dpp v99, v79 row_shr:2 row_mask:0xf bank_mask:0xf
	v_mov_b32_dpp v89, v75 row_shr:1 row_mask:0xf bank_mask:0xf
	v_mov_b32_dpp v91, v75 row_shr:2 row_mask:0xf bank_mask:0xf
	v_mov_b32_dpp v87, v79 row_ror:1 row_mask:0xf bank_mask:0xf bound_ctrl:1
	v_mov_b32_dpp v81, v75 row_ror:1 row_mask:0xf bank_mask:0xf bound_ctrl:1
	v_mov_b32_dpp v103, v79 row_ror:2 row_mask:0xf bank_mask:0xf bound_ctrl:1
	v_mov_b32_dpp v83, v75 row_ror:2 row_mask:0xf bank_mask:0xf bound_ctrl:1
	s_and_b64 s[82:83], s[18:19], vcc
	v_ashrrev_i32_e32 v139, 31, v138
	s_and_saveexec_b64 s[84:85], s[82:83]
	s_cbranch_execz .LBB0_4060
	v_pk_fma_f32 v[142:143], v[120:121], v[142:143], v[132:133]
	v_pk_fma_f32 v[96:97], v[104:105], v[96:97], v[116:117]
	v_pk_fma_f32 v[140:141], v[124:125], v[140:141], v[142:143]
	v_pk_fma_f32 v[92:93], v[108:109], v[92:93], v[96:97]
	v_pk_fma_f32 v[76:77], v[76:77], v[128:129], v[140:141]
	v_pk_fma_f32 v[72:73], v[72:73], v[112:113], v[92:93]
	v_mul_f32_e32 v140, 0x3d372713, v76
	v_mul_f32_e32 v141, 0x3d372713, v77
	v_fma_f32 v140, v76, v140, 1.0
	v_fma_f32 v141, v77, v141, 1.0
	v_mul_f32_e32 v140, v76, v140
	v_mul_f32_e32 v141, v77, v141
	v_mul_f32_e32 v140, 0x40135761, v140
	v_mul_f32_e32 v141, 0x40135761, v141
	v_pk_fma_f32 v[92:93], v[122:123], v[98:99], v[134:135]
	v_exp_f32_e32 v140, v140
	v_exp_f32_e32 v141, v141
	v_pk_fma_f32 v[92:93], v[126:127], v[94:95], v[92:93]
	v_pk_fma_f32 v[90:91], v[106:107], v[90:91], v[118:119]
	v_pk_fma_f32 v[78:79], v[78:79], v[130:131], v[92:93]
	v_add_f32_e32 v140, 1.0, v140
	v_mul_f32_e32 v92, 0x3d372713, v78
	v_mul_f32_e32 v93, 0x3d372713, v79
	v_fma_f32 v92, v78, v92, 1.0
	v_fma_f32 v93, v79, v93, 1.0
	v_add_f32_e32 v141, 1.0, v141
	v_mul_f32_e32 v92, v78, v92
	v_mul_f32_e32 v93, v79, v93
	v_rcp_f32_e32 v140, v140
	v_rcp_f32_e32 v141, v141
	v_mul_f32_e32 v92, 0x40135761, v92
	v_mul_f32_e32 v93, 0x40135761, v93
	v_exp_f32_e32 v92, v92
	v_exp_f32_e32 v93, v93
	v_pk_fma_f32 v[76:77], v[76:77], v[140:141], v[76:77] neg_lo:[1,0,0] neg_hi:[1,0,0]
	v_pk_fma_f32 v[88:89], v[110:111], v[88:89], v[90:91]
	v_pk_mul_f32 v[72:73], v[72:73], v[76:77]
	v_add_f32_e32 v76, 1.0, v92
	v_add_f32_e32 v77, 1.0, v93
	v_rcp_f32_e32 v76, v76
	v_rcp_f32_e32 v77, v77
	v_pk_fma_f32 v[74:75], v[74:75], v[114:115], v[88:89]
	v_cvt_pk_bf16_f32 v72, v72, v73
	v_pk_fma_f32 v[76:77], v[78:79], v[76:77], v[78:79] neg_lo:[1,0,0] neg_hi:[1,0,0]
	s_nop 0
	v_pk_mul_f32 v[74:75], v[74:75], v[76:77]
	v_mov_b64_e32 v[76:77], s[30:31]
	v_cvt_pk_bf16_f32 v73, v74, v75
	v_lshl_add_u64 v[74:75], s[66:67], 0, v[138:139]
	v_mad_u64_u32 v[76:77], s[86:87], v74, s1, v[76:77]
	v_mad_i32_i24 v77, v75, s1, v77
	v_lshl_add_u64 v[74:75], v[192:193], 1, v[76:77]
	global_store_dwordx2 v[74:75], v[72:73], off
.LBB0_4060:
	s_or_b64 exec, exec, s[84:85]
	v_cmp_gt_u32_e32 vcc, s29, v231
	v_add_u32_e32 v140, 0xb0, v194
	v_mov_b32_dpp v150, v68 row_shr:1 row_mask:0xf bank_mask:0xf
	v_mov_b32_dpp v154, v68 row_shr:2 row_mask:0xf bank_mask:0xf
	v_mov_b32_dpp v84, v64 row_shr:1 row_mask:0xf bank_mask:0xf
	v_mov_b32_dpp v100, v64 row_shr:2 row_mask:0xf bank_mask:0xf
	v_mov_b32_dpp v151, v69 row_shr:1 row_mask:0xf bank_mask:0xf
	v_mov_b32_dpp v155, v69 row_shr:2 row_mask:0xf bank_mask:0xf
	v_mov_b32_dpp v85, v65 row_shr:1 row_mask:0xf bank_mask:0xf
	v_mov_b32_dpp v101, v65 row_shr:2 row_mask:0xf bank_mask:0xf
	v_mov_b32_dpp v86, v70 row_shr:1 row_mask:0xf bank_mask:0xf
	v_mov_b32_dpp v102, v70 row_shr:2 row_mask:0xf bank_mask:0xf
	v_mov_b32_dpp v80, v66 row_shr:1 row_mask:0xf bank_mask:0xf
	v_mov_b32_dpp v82, v66 row_shr:2 row_mask:0xf bank_mask:0xf
	v_mov_b32_dpp v87, v71 row_shr:1 row_mask:0xf bank_mask:0xf
	v_mov_b32_dpp v103, v71 row_shr:2 row_mask:0xf bank_mask:0xf
	v_mov_b32_dpp v81, v67 row_shr:1 row_mask:0xf bank_mask:0xf
	v_mov_b32_dpp v83, v67 row_shr:2 row_mask:0xf bank_mask:0xf
	s_and_b64 s[84:85], s[20:21], vcc
	v_ashrrev_i32_e32 v141, 31, v140
	s_and_saveexec_b64 s[86:87], s[84:85]
	s_cbranch_execz .LBB0_4062
	v_pk_fma_f32 v[72:73], v[120:121], v[154:155], v[132:133]
	v_pk_fma_f32 v[74:75], v[104:105], v[100:101], v[116:117]
	v_pk_fma_f32 v[72:73], v[124:125], v[150:151], v[72:73]
	v_pk_fma_f32 v[74:75], v[108:109], v[84:85], v[74:75]
	v_pk_fma_f32 v[68:69], v[68:69], v[128:129], v[72:73]
	v_pk_fma_f32 v[64:65], v[64:65], v[112:113], v[74:75]
	v_mul_f32_e32 v72, 0x3d372713, v68
	v_mul_f32_e32 v73, 0x3d372713, v69
	v_fma_f32 v72, v68, v72, 1.0
	v_fma_f32 v73, v69, v73, 1.0
	v_mul_f32_e32 v72, v68, v72
	v_mul_f32_e32 v73, v69, v73
	v_mul_f32_e32 v72, 0x40135761, v72
	v_mul_f32_e32 v73, 0x40135761, v73
	v_exp_f32_e32 v72, v72
	v_exp_f32_e32 v73, v73
	v_add_f32_e32 v72, 1.0, v72
	v_add_f32_e32 v73, 1.0, v73
	v_rcp_f32_e32 v72, v72
	v_rcp_f32_e32 v73, v73
	s_nop 0
	v_pk_fma_f32 v[68:69], v[68:69], v[72:73], v[68:69] neg_lo:[1,0,0] neg_hi:[1,0,0]
	v_pk_fma_f32 v[72:73], v[122:123], v[102:103], v[134:135]
	v_pk_mul_f32 v[64:65], v[64:65], v[68:69]
	v_pk_fma_f32 v[72:73], v[126:127], v[86:87], v[72:73]
	v_cvt_pk_bf16_f32 v64, v64, v65
	v_pk_fma_f32 v[70:71], v[70:71], v[130:131], v[72:73]
	s_nop 0
	v_mul_f32_e32 v72, 0x3d372713, v70
	v_mul_f32_e32 v73, 0x3d372713, v71
	v_fma_f32 v72, v70, v72, 1.0
	v_fma_f32 v73, v71, v73, 1.0
	v_mul_f32_e32 v72, v70, v72
	v_mul_f32_e32 v73, v71, v73
	v_mul_f32_e32 v72, 0x40135761, v72
	v_mul_f32_e32 v73, 0x40135761, v73
	v_exp_f32_e32 v72, v72
	v_exp_f32_e32 v73, v73
	v_add_f32_e32 v68, 1.0, v72
	v_add_f32_e32 v69, 1.0, v73
	v_rcp_f32_e32 v68, v68
	v_rcp_f32_e32 v69, v69
	v_pk_fma_f32 v[72:73], v[106:107], v[82:83], v[118:119]
	v_pk_fma_f32 v[68:69], v[70:71], v[68:69], v[70:71] neg_lo:[1,0,0] neg_hi:[1,0,0]
	v_pk_fma_f32 v[72:73], v[110:111], v[80:81], v[72:73]
	s_nop 0
	v_pk_fma_f32 v[66:67], v[66:67], v[114:115], v[72:73]
	s_nop 0
	v_pk_mul_f32 v[66:67], v[66:67], v[68:69]
	v_mov_b64_e32 v[68:69], s[30:31]
	v_cvt_pk_bf16_f32 v65, v66, v67
	v_lshl_add_u64 v[66:67], s[66:67], 0, v[140:141]
	v_mad_u64_u32 v[68:69], vcc, v66, s1, v[68:69]
	v_mad_i32_i24 v69, v67, s1, v69
	v_lshl_add_u64 v[66:67], v[192:193], 1, v[68:69]
	global_store_dwordx2 v[66:67], v[64:65], off

.LBB0_4066:
	s_or_b64 exec, exec, s[24:25]
	v_mov_b32_dpp v120, v52 row_shr:1 row_mask:0xf bank_mask:0xf
	v_mov_b32_dpp v122, v52 row_shr:2 row_mask:0xf bank_mask:0xf
	v_mov_b32_dpp v112, v48 row_shr:1 row_mask:0xf bank_mask:0xf
	v_mov_b32_dpp v116, v48 row_shr:2 row_mask:0xf bank_mask:0xf
	v_mov_b32_dpp v104, v52 row_ror:1 row_mask:0xf bank_mask:0xf bound_ctrl:1
	v_mov_b32_dpp v96, v48 row_ror:1 row_mask:0xf bank_mask:0xf bound_ctrl:1
	v_mov_b32_dpp v106, v52 row_ror:2 row_mask:0xf bank_mask:0xf bound_ctrl:1
	v_mov_b32_dpp v100, v48 row_ror:2 row_mask:0xf bank_mask:0xf bound_ctrl:1
	v_mov_b32_dpp v121, v53 row_shr:1 row_mask:0xf bank_mask:0xf
	v_mov_b32_dpp v123, v53 row_shr:2 row_mask:0xf bank_mask:0xf
	v_mov_b32_dpp v113, v49 row_shr:1 row_mask:0xf bank_mask:0xf
	v_mov_b32_dpp v117, v49 row_shr:2 row_mask:0xf bank_mask:0xf
	v_mov_b32_dpp v105, v53 row_ror:1 row_mask:0xf bank_mask:0xf bound_ctrl:1
	v_mov_b32_dpp v97, v49 row_ror:1 row_mask:0xf bank_mask:0xf bound_ctrl:1
	v_mov_b32_dpp v107, v53 row_ror:2 row_mask:0xf bank_mask:0xf bound_ctrl:1
	v_mov_b32_dpp v101, v49 row_ror:2 row_mask:0xf bank_mask:0xf bound_ctrl:1
	v_mov_b32_dpp v114, v54 row_shr:1 row_mask:0xf bank_mask:0xf
	v_mov_b32_dpp v118, v54 row_shr:2 row_mask:0xf bank_mask:0xf
	v_mov_b32_dpp v56, v50 row_shr:1 row_mask:0xf bank_mask:0xf
	v_mov_b32_dpp v58, v50 row_shr:2 row_mask:0xf bank_mask:0xf
	v_mov_b32_dpp v98, v54 row_ror:1 row_mask:0xf bank_mask:0xf bound_ctrl:1
	v_mov_b32_dpp v60, v50 row_ror:1 row_mask:0xf bank_mask:0xf bound_ctrl:1
	v_mov_b32_dpp v102, v54 row_ror:2 row_mask:0xf bank_mask:0xf bound_ctrl:1
	v_mov_b32_dpp v62, v50 row_ror:2 row_mask:0xf bank_mask:0xf bound_ctrl:1
	v_mov_b32_dpp v115, v55 row_shr:1 row_mask:0xf bank_mask:0xf
	v_mov_b32_dpp v119, v55 row_shr:2 row_mask:0xf bank_mask:0xf
	v_mov_b32_dpp v57, v51 row_shr:1 row_mask:0xf bank_mask:0xf
	v_mov_b32_dpp v59, v51 row_shr:2 row_mask:0xf bank_mask:0xf
	v_mov_b32_dpp v99, v55 row_ror:1 row_mask:0xf bank_mask:0xf bound_ctrl:1
	v_mov_b32_dpp v61, v51 row_ror:1 row_mask:0xf bank_mask:0xf bound_ctrl:1
	v_mov_b32_dpp v103, v55 row_ror:2 row_mask:0xf bank_mask:0xf bound_ctrl:1
	v_mov_b32_dpp v63, v51 row_ror:2 row_mask:0xf bank_mask:0xf bound_ctrl:1
	s_and_saveexec_b64 s[24:25], s[72:73]
	s_cbranch_execz .LBB0_4068
	v_pk_fma_f32 v[108:109], v[80:81], v[122:123], v[92:93]
	v_pk_fma_f32 v[110:111], v[64:65], v[116:117], v[76:77]
	v_pk_fma_f32 v[108:109], v[84:85], v[120:121], v[108:109]
	v_pk_fma_f32 v[110:111], v[68:69], v[112:113], v[110:111]
	v_pk_fma_f32 v[52:53], v[52:53], v[88:89], v[108:109]
	v_pk_fma_f32 v[48:49], v[48:49], v[72:73], v[110:111]
	v_mul_f32_e32 v108, 0x3d372713, v52
	v_mul_f32_e32 v109, 0x3d372713, v53
	v_fma_f32 v108, v52, v108, 1.0
	v_fma_f32 v109, v53, v109, 1.0
	v_mul_f32_e32 v108, v52, v108
	v_mul_f32_e32 v109, v53, v109
	v_mul_f32_e32 v108, 0x40135761, v108
	v_mul_f32_e32 v109, 0x40135761, v109
	v_exp_f32_e32 v108, v108
	v_exp_f32_e32 v109, v109
	v_pk_fma_f32 v[58:59], v[66:67], v[58:59], v[78:79]
	v_add_f32_e32 v108, 1.0, v108
	v_add_f32_e32 v109, 1.0, v109
	v_rcp_f32_e32 v108, v108
	v_rcp_f32_e32 v109, v109
	v_pk_fma_f32 v[56:57], v[70:71], v[56:57], v[58:59]
	v_pk_fma_f32 v[52:53], v[52:53], v[108:109], v[52:53] neg_lo:[1,0,0] neg_hi:[1,0,0]
	v_pk_fma_f32 v[108:109], v[82:83], v[118:119], v[94:95]
	v_pk_mul_f32 v[48:49], v[48:49], v[52:53]
	v_pk_fma_f32 v[108:109], v[86:87], v[114:115], v[108:109]
	v_pk_fma_f32 v[50:51], v[50:51], v[74:75], v[56:57]
	v_pk_fma_f32 v[54:55], v[54:55], v[90:91], v[108:109]
	v_cvt_pk_bf16_f32 v48, v48, v49
	v_mul_f32_e32 v108, 0x3d372713, v54
	v_mul_f32_e32 v109, 0x3d372713, v55
	v_fma_f32 v108, v54, v108, 1.0
	v_fma_f32 v109, v55, v109, 1.0
	v_mul_f32_e32 v108, v54, v108
	v_mul_f32_e32 v109, v55, v109
	v_mul_f32_e32 v108, 0x40135761, v108
	v_mul_f32_e32 v109, 0x40135761, v109
	v_exp_f32_e32 v108, v108
	v_exp_f32_e32 v109, v109
	v_add_f32_e32 v52, 1.0, v108
	v_add_f32_e32 v53, 1.0, v109
	v_rcp_f32_e32 v52, v52
	v_rcp_f32_e32 v53, v53
	s_nop 0
	v_pk_fma_f32 v[52:53], v[54:55], v[52:53], v[54:55] neg_lo:[1,0,0] neg_hi:[1,0,0]
	s_nop 0
	v_pk_mul_f32 v[50:51], v[50:51], v[52:53]
	v_mov_b64_e32 v[52:53], s[30:31]
	v_cvt_pk_bf16_f32 v49, v50, v51
	v_lshl_add_u64 v[50:51], s[66:67], 0, v[152:153]
	v_mad_u64_u32 v[52:53], s[68:69], v50, s1, v[52:53]
	v_mad_i32_i24 v53, v51, s1, v53
	v_lshl_add_u64 v[50:51], v[192:193], 1, v[52:53]
	global_store_dwordx2 v[50:51], v[48:49], off offset:8
.LBB0_4068:
	s_or_b64 exec, exec, s[24:25]
	v_mov_b32_dpp v104, v44 row_shr:1 row_mask:0xf bank_mask:0xf
	v_mov_b32_dpp v106, v44 row_shr:2 row_mask:0xf bank_mask:0xf
	v_mov_b32_dpp v96, v40 row_shr:1 row_mask:0xf bank_mask:0xf
	v_mov_b32_dpp v100, v40 row_shr:2 row_mask:0xf bank_mask:0xf
	v_mov_b32_dpp v108, v44 row_ror:1 row_mask:0xf bank_mask:0xf bound_ctrl:1
	v_mov_b32_dpp v52, v40 row_ror:1 row_mask:0xf bank_mask:0xf bound_ctrl:1
	v_mov_b32_dpp v110, v44 row_ror:2 row_mask:0xf bank_mask:0xf bound_ctrl:1
	v_mov_b32_dpp v56, v40 row_ror:2 row_mask:0xf bank_mask:0xf bound_ctrl:1
	v_mov_b32_dpp v105, v45 row_shr:1 row_mask:0xf bank_mask:0xf
	v_mov_b32_dpp v107, v45 row_shr:2 row_mask:0xf bank_mask:0xf
	v_mov_b32_dpp v97, v41 row_shr:1 row_mask:0xf bank_mask:0xf
	v_mov_b32_dpp v101, v41 row_shr:2 row_mask:0xf bank_mask:0xf
	v_mov_b32_dpp v109, v45 row_ror:1 row_mask:0xf bank_mask:0xf bound_ctrl:1
	v_mov_b32_dpp v53, v41 row_ror:1 row_mask:0xf bank_mask:0xf bound_ctrl:1
	v_mov_b32_dpp v111, v45 row_ror:2 row_mask:0xf bank_mask:0xf bound_ctrl:1
	v_mov_b32_dpp v57, v41 row_ror:2 row_mask:0xf bank_mask:0xf bound_ctrl:1
	v_mov_b32_dpp v98, v46 row_shr:1 row_mask:0xf bank_mask:0xf
	v_mov_b32_dpp v102, v46 row_shr:2 row_mask:0xf bank_mask:0xf
	v_mov_b32_dpp v60, v42 row_shr:1 row_mask:0xf bank_mask:0xf
	v_mov_b32_dpp v62, v42 row_shr:2 row_mask:0xf bank_mask:0xf
	v_mov_b32_dpp v54, v46 row_ror:1 row_mask:0xf bank_mask:0xf bound_ctrl:1
	v_mov_b32_dpp v48, v42 row_ror:1 row_mask:0xf bank_mask:0xf bound_ctrl:1
	v_mov_b32_dpp v58, v46 row_ror:2 row_mask:0xf bank_mask:0xf bound_ctrl:1
	v_mov_b32_dpp v50, v42 row_ror:2 row_mask:0xf bank_mask:0xf bound_ctrl:1
	v_mov_b32_dpp v99, v47 row_shr:1 row_mask:0xf bank_mask:0xf
	v_mov_b32_dpp v103, v47 row_shr:2 row_mask:0xf bank_mask:0xf
	v_mov_b32_dpp v61, v43 row_shr:1 row_mask:0xf bank_mask:0xf
	v_mov_b32_dpp v63, v43 row_shr:2 row_mask:0xf bank_mask:0xf
	v_mov_b32_dpp v55, v47 row_ror:1 row_mask:0xf bank_mask:0xf bound_ctrl:1
	v_mov_b32_dpp v49, v43 row_ror:1 row_mask:0xf bank_mask:0xf bound_ctrl:1
	v_mov_b32_dpp v59, v47 row_ror:2 row_mask:0xf bank_mask:0xf bound_ctrl:1
	v_mov_b32_dpp v51, v43 row_ror:2 row_mask:0xf bank_mask:0xf bound_ctrl:1
	s_and_saveexec_b64 s[24:25], s[74:75]
	s_cbranch_execz .LBB0_4070
	v_pk_fma_f32 v[106:107], v[80:81], v[106:107], v[92:93]
	v_pk_fma_f32 v[100:101], v[64:65], v[100:101], v[76:77]
	v_pk_fma_f32 v[104:105], v[84:85], v[104:105], v[106:107]
	v_pk_fma_f32 v[96:97], v[68:69], v[96:97], v[100:101]
	v_pk_fma_f32 v[44:45], v[44:45], v[88:89], v[104:105]
	v_pk_fma_f32 v[40:41], v[40:41], v[72:73], v[96:97]
	v_mul_f32_e32 v104, 0x3d372713, v44
	v_mul_f32_e32 v105, 0x3d372713, v45
	v_fma_f32 v104, v44, v104, 1.0
	v_fma_f32 v105, v45, v105, 1.0
	v_mul_f32_e32 v104, v44, v104
	v_mul_f32_e32 v105, v45, v105
	v_mul_f32_e32 v104, 0x40135761, v104
	v_mul_f32_e32 v105, 0x40135761, v105
	v_pk_fma_f32 v[96:97], v[82:83], v[102:103], v[94:95]
	v_exp_f32_e32 v104, v104
	v_exp_f32_e32 v105, v105
	v_pk_fma_f32 v[96:97], v[86:87], v[98:99], v[96:97]
	v_pk_fma_f32 v[62:63], v[66:67], v[62:63], v[78:79]
	v_pk_fma_f32 v[46:47], v[46:47], v[90:91], v[96:97]
	v_add_f32_e32 v104, 1.0, v104
	v_mul_f32_e32 v96, 0x3d372713, v46
	v_mul_f32_e32 v97, 0x3d372713, v47
	v_fma_f32 v96, v46, v96, 1.0
	v_fma_f32 v97, v47, v97, 1.0
	v_add_f32_e32 v105, 1.0, v105
	v_mul_f32_e32 v96, v46, v96
	v_mul_f32_e32 v97, v47, v97
	v_rcp_f32_e32 v104, v104
	v_rcp_f32_e32 v105, v105
	v_mul_f32_e32 v96, 0x40135761, v96
	v_mul_f32_e32 v97, 0x40135761, v97
	v_exp_f32_e32 v96, v96
	v_exp_f32_e32 v97, v97
	v_pk_fma_f32 v[44:45], v[44:45], v[104:105], v[44:45] neg_lo:[1,0,0] neg_hi:[1,0,0]
	v_pk_fma_f32 v[60:61], v[70:71], v[60:61], v[62:63]
	v_pk_mul_f32 v[40:41], v[40:41], v[44:45]
	v_add_f32_e32 v44, 1.0, v96
	v_add_f32_e32 v45, 1.0, v97
	v_rcp_f32_e32 v44, v44
	v_rcp_f32_e32 v45, v45
	v_pk_fma_f32 v[42:43], v[42:43], v[74:75], v[60:61]
	v_cvt_pk_bf16_f32 v40, v40, v41
	v_pk_fma_f32 v[44:45], v[46:47], v[44:45], v[46:47] neg_lo:[1,0,0] neg_hi:[1,0,0]
	s_nop 0
	v_pk_mul_f32 v[42:43], v[42:43], v[44:45]
	v_mov_b64_e32 v[44:45], s[30:31]
	v_cvt_pk_bf16_f32 v41, v42, v43
	v_lshl_add_u64 v[42:43], s[66:67], 0, v[146:147]
	v_mad_u64_u32 v[44:45], s[68:69], v42, s1, v[44:45]
	v_mad_i32_i24 v45, v43, s1, v45
	v_lshl_add_u64 v[42:43], v[192:193], 1, v[44:45]
	global_store_dwordx2 v[42:43], v[40:41], off offset:8
.LBB0_4070:
	s_or_b64 exec, exec, s[24:25]
	v_mov_b32_dpp v108, v36 row_shr:1 row_mask:0xf bank_mask:0xf
	v_mov_b32_dpp v110, v36 row_shr:2 row_mask:0xf bank_mask:0xf
	v_mov_b32_dpp v52, v32 row_shr:1 row_mask:0xf bank_mask:0xf
	v_mov_b32_dpp v56, v32 row_shr:2 row_mask:0xf bank_mask:0xf
	v_mov_b32_dpp v109, v37 row_shr:1 row_mask:0xf bank_mask:0xf
	v_mov_b32_dpp v111, v37 row_shr:2 row_mask:0xf bank_mask:0xf
	v_mov_b32_dpp v53, v33 row_shr:1 row_mask:0xf bank_mask:0xf
	v_mov_b32_dpp v57, v33 row_shr:2 row_mask:0xf bank_mask:0xf
	v_mov_b32_dpp v54, v38 row_shr:1 row_mask:0xf bank_mask:0xf
	v_mov_b32_dpp v58, v38 row_shr:2 row_mask:0xf bank_mask:0xf
	v_mov_b32_dpp v48, v34 row_shr:1 row_mask:0xf bank_mask:0xf
	v_mov_b32_dpp v50, v34 row_shr:2 row_mask:0xf bank_mask:0xf
	v_mov_b32_dpp v55, v39 row_shr:1 row_mask:0xf bank_mask:0xf
	v_mov_b32_dpp v59, v39 row_shr:2 row_mask:0xf bank_mask:0xf
	v_mov_b32_dpp v49, v35 row_shr:1 row_mask:0xf bank_mask:0xf
	v_mov_b32_dpp v51, v35 row_shr:2 row_mask:0xf bank_mask:0xf
	s_and_saveexec_b64 s[24:25], s[76:77]
	s_cbranch_execz .LBB0_4072
	v_pk_fma_f32 v[40:41], v[80:81], v[110:111], v[92:93]
	v_pk_fma_f32 v[42:43], v[64:65], v[56:57], v[76:77]
	v_pk_fma_f32 v[40:41], v[84:85], v[108:109], v[40:41]
	v_pk_fma_f32 v[42:43], v[68:69], v[52:53], v[42:43]
	v_pk_fma_f32 v[36:37], v[36:37], v[88:89], v[40:41]
	v_pk_fma_f32 v[32:33], v[32:33], v[72:73], v[42:43]
	v_mul_f32_e32 v40, 0x3d372713, v36
	v_mul_f32_e32 v41, 0x3d372713, v37
	v_fma_f32 v40, v36, v40, 1.0
	v_fma_f32 v41, v37, v41, 1.0
	v_mul_f32_e32 v40, v36, v40
	v_mul_f32_e32 v41, v37, v41
	v_mul_f32_e32 v40, 0x40135761, v40
	v_mul_f32_e32 v41, 0x40135761, v41
	v_exp_f32_e32 v40, v40
	v_exp_f32_e32 v41, v41
	v_add_f32_e32 v40, 1.0, v40
	v_add_f32_e32 v41, 1.0, v41
	v_rcp_f32_e32 v40, v40
	v_rcp_f32_e32 v41, v41
	s_nop 0
	v_pk_fma_f32 v[36:37], v[36:37], v[40:41], v[36:37] neg_lo:[1,0,0] neg_hi:[1,0,0]
	v_pk_fma_f32 v[40:41], v[82:83], v[58:59], v[94:95]
	v_pk_mul_f32 v[32:33], v[32:33], v[36:37]
	v_pk_fma_f32 v[40:41], v[86:87], v[54:55], v[40:41]
	v_cvt_pk_bf16_f32 v32, v32, v33
	v_pk_fma_f32 v[38:39], v[38:39], v[90:91], v[40:41]
	s_nop 0
	v_mul_f32_e32 v40, 0x3d372713, v38
	v_mul_f32_e32 v41, 0x3d372713, v39
	v_fma_f32 v40, v38, v40, 1.0
	v_fma_f32 v41, v39, v41, 1.0
	v_mul_f32_e32 v40, v38, v40
	v_mul_f32_e32 v41, v39, v41
	v_mul_f32_e32 v40, 0x40135761, v40
	v_mul_f32_e32 v41, 0x40135761, v41
	v_exp_f32_e32 v40, v40
	v_exp_f32_e32 v41, v41
	v_add_f32_e32 v36, 1.0, v40
	v_add_f32_e32 v37, 1.0, v41
	v_rcp_f32_e32 v36, v36
	v_rcp_f32_e32 v37, v37
	v_pk_fma_f32 v[40:41], v[66:67], v[50:51], v[78:79]
	v_pk_fma_f32 v[36:37], v[38:39], v[36:37], v[38:39] neg_lo:[1,0,0] neg_hi:[1,0,0]
	v_pk_fma_f32 v[40:41], v[70:71], v[48:49], v[40:41]
	s_nop 0
	v_pk_fma_f32 v[34:35], v[34:35], v[74:75], v[40:41]
	s_nop 0
	v_pk_mul_f32 v[34:35], v[34:35], v[36:37]
	v_mov_b64_e32 v[36:37], s[30:31]
	v_cvt_pk_bf16_f32 v33, v34, v35
	v_lshl_add_u64 v[34:35], s[66:67], 0, v[148:149]
	v_mad_u64_u32 v[36:37], s[68:69], v34, s1, v[36:37]
	v_mad_i32_i24 v37, v35, s1, v37
	v_lshl_add_u64 v[34:35], v[192:193], 1, v[36:37]
	global_store_dwordx2 v[34:35], v[32:33], off offset:8
.LBB0_4072:
	s_or_b64 exec, exec, s[24:25]
	v_add_u32_e32 v32, 0x1180, v237
	v_add_u32_e32 v36, 0x1080, v237
	ds_read2_b64 v[40:43], v32 offset1:1
	ds_read2_b64 v[44:47], v36 offset1:1
	v_add_u32_e32 v32, 0x1190, v237
	v_add_u32_e32 v36, 0x1090, v237
	ds_read2_b64 v[32:35], v32 offset1:1
	ds_read2_b64 v[36:39], v36 offset1:1
	s_waitcnt lgkmcnt(3)
	v_cndmask_b32_e64 v100, v41, v40, s[10:11]
	v_cndmask_b32_e64 v101, v43, v42, s[10:11]
	s_waitcnt lgkmcnt(2)
	v_cndmask_b32_e64 v102, v45, v44, s[10:11]
	s_waitcnt lgkmcnt(1)
	v_cndmask_b32_e64 v96, v33, v32, s[10:11]
	v_cndmask_b32_e64 v97, v35, v34, s[10:11]
	v_cndmask_b32_e64 v103, v47, v46, s[10:11]
	s_waitcnt lgkmcnt(0)
	v_cndmask_b32_e64 v98, v37, v36, s[10:11]
	v_cndmask_b32_e64 v99, v39, v38, s[10:11]
	v_mov_b32_dpp v45, v28 row_shr:1 row_mask:0xf bank_mask:0xf
	v_mov_b32_dpp v102, v28 row_shr:2 row_mask:0xf bank_mask:0xf
	v_mov_b32_dpp v41, v24 row_shr:1 row_mask:0xf bank_mask:0xf
	v_mov_b32_dpp v100, v24 row_shr:2 row_mask:0xf bank_mask:0xf
	v_mov_b32_dpp v60, v28 row_ror:1 row_mask:0xf bank_mask:0xf bound_ctrl:1
	v_mov_b32_dpp v52, v24 row_ror:1 row_mask:0xf bank_mask:0xf bound_ctrl:1
	v_mov_b32_dpp v62, v28 row_ror:2 row_mask:0xf bank_mask:0xf bound_ctrl:1
	v_mov_b32_dpp v56, v24 row_ror:2 row_mask:0xf bank_mask:0xf bound_ctrl:1
	v_mov_b32_dpp v47, v29 row_shr:1 row_mask:0xf bank_mask:0xf
	v_mov_b32_dpp v103, v29 row_shr:2 row_mask:0xf bank_mask:0xf
	v_mov_b32_dpp v43, v25 row_shr:1 row_mask:0xf bank_mask:0xf
	v_mov_b32_dpp v101, v25 row_shr:2 row_mask:0xf bank_mask:0xf
	v_mov_b32_dpp v61, v29 row_ror:1 row_mask:0xf bank_mask:0xf bound_ctrl:1
	v_mov_b32_dpp v53, v25 row_ror:1 row_mask:0xf bank_mask:0xf bound_ctrl:1
	v_mov_b32_dpp v63, v29 row_ror:2 row_mask:0xf bank_mask:0xf bound_ctrl:1
	v_mov_b32_dpp v57, v25 row_ror:2 row_mask:0xf bank_mask:0xf bound_ctrl:1
	v_mov_b32_dpp v37, v30 row_shr:1 row_mask:0xf bank_mask:0xf
	v_mov_b32_dpp v98, v30 row_shr:2 row_mask:0xf bank_mask:0xf
	v_mov_b32_dpp v33, v26 row_shr:1 row_mask:0xf bank_mask:0xf
	v_mov_b32_dpp v96, v26 row_shr:2 row_mask:0xf bank_mask:0xf
	v_mov_b32_dpp v54, v30 row_ror:1 row_mask:0xf bank_mask:0xf bound_ctrl:1
	v_mov_b32_dpp v48, v26 row_ror:1 row_mask:0xf bank_mask:0xf bound_ctrl:1
	v_mov_b32_dpp v58, v30 row_ror:2 row_mask:0xf bank_mask:0xf bound_ctrl:1
	v_mov_b32_dpp v50, v26 row_ror:2 row_mask:0xf bank_mask:0xf bound_ctrl:1
	v_mov_b32_dpp v39, v31 row_shr:1 row_mask:0xf bank_mask:0xf
	v_mov_b32_dpp v99, v31 row_shr:2 row_mask:0xf bank_mask:0xf
	v_mov_b32_dpp v35, v27 row_shr:1 row_mask:0xf bank_mask:0xf
	v_mov_b32_dpp v97, v27 row_shr:2 row_mask:0xf bank_mask:0xf
	v_mov_b32_dpp v55, v31 row_ror:1 row_mask:0xf bank_mask:0xf bound_ctrl:1
	v_mov_b32_dpp v49, v27 row_ror:1 row_mask:0xf bank_mask:0xf bound_ctrl:1
	v_mov_b32_dpp v59, v31 row_ror:2 row_mask:0xf bank_mask:0xf bound_ctrl:1
	v_mov_b32_dpp v51, v27 row_ror:2 row_mask:0xf bank_mask:0xf bound_ctrl:1
	s_and_saveexec_b64 s[24:25], s[78:79]
	s_cbranch_execz .LBB0_4074
	v_mov_b32_e32 v46, v45
	v_pk_fma_f32 v[44:45], v[80:81], v[102:103], v[92:93]
	v_mov_b32_e32 v42, v41
	v_pk_fma_f32 v[44:45], v[84:85], v[46:47], v[44:45]
	v_mov_b32_e32 v38, v37
	v_pk_fma_f32 v[28:29], v[28:29], v[88:89], v[44:45]
	v_pk_fma_f32 v[44:45], v[64:65], v[100:101], v[76:77]
	v_mul_f32_e32 v32, 0x3d372713, v28
	v_fma_f32 v32, v28, v32, 1.0
	v_mul_f32_e32 v34, 0x3d372713, v29
	v_mul_f32_e32 v32, v28, v32
	v_fma_f32 v34, v29, v34, 1.0
	v_mul_f32_e32 v32, 0x40135761, v32
	v_mul_f32_e32 v34, v29, v34
	v_exp_f32_e32 v32, v32
	v_mul_f32_e32 v34, 0x40135761, v34
	v_exp_f32_e32 v34, v34
	v_pk_fma_f32 v[42:43], v[68:69], v[42:43], v[44:45]
	v_add_f32_e32 v32, 1.0, v32
	v_rcp_f32_e32 v40, v32
	v_add_f32_e32 v32, 1.0, v34
	v_rcp_f32_e32 v41, v32
	v_pk_fma_f32 v[24:25], v[24:25], v[72:73], v[42:43]
	v_mov_b32_e32 v34, v33
	v_pk_fma_f32 v[32:33], v[66:67], v[96:97], v[78:79]
	v_pk_fma_f32 v[28:29], v[28:29], v[40:41], v[28:29] neg_lo:[1,0,0] neg_hi:[1,0,0]
	v_pk_fma_f32 v[32:33], v[70:71], v[34:35], v[32:33]
	v_pk_mul_f32 v[24:25], v[24:25], v[28:29]
	v_pk_fma_f32 v[28:29], v[82:83], v[98:99], v[94:95]
	v_pk_fma_f32 v[26:27], v[26:27], v[74:75], v[32:33]
	v_pk_fma_f32 v[28:29], v[86:87], v[38:39], v[28:29]
	v_cvt_pk_bf16_f32 v24, v24, v25
	v_pk_fma_f32 v[28:29], v[30:31], v[90:91], v[28:29]
	s_nop 0
	v_mul_f32_e32 v30, 0x3d372713, v28
	v_mul_f32_e32 v31, 0x3d372713, v29
	v_fma_f32 v30, v28, v30, 1.0
	v_fma_f32 v31, v29, v31, 1.0
	v_mul_f32_e32 v30, v28, v30
	v_mul_f32_e32 v31, v29, v31
	v_mul_f32_e32 v30, 0x40135761, v30
	v_mul_f32_e32 v31, 0x40135761, v31
	v_exp_f32_e32 v30, v30
	v_exp_f32_e32 v31, v31
	v_add_f32_e32 v30, 1.0, v30
	v_add_f32_e32 v31, 1.0, v31
	v_rcp_f32_e32 v30, v30
	v_rcp_f32_e32 v31, v31
	s_nop 0
	v_pk_fma_f32 v[28:29], v[28:29], v[30:31], v[28:29] neg_lo:[1,0,0] neg_hi:[1,0,0]
	s_nop 0
	v_pk_mul_f32 v[26:27], v[26:27], v[28:29]
	v_mov_b64_e32 v[28:29], s[30:31]
	v_cvt_pk_bf16_f32 v25, v26, v27
	v_lshl_add_u64 v[26:27], s[66:67], 0, v[144:145]
	v_mad_u64_u32 v[28:29], s[68:69], v26, s1, v[28:29]
	v_mad_i32_i24 v29, v27, s1, v29
	v_lshl_add_u64 v[26:27], v[192:193], 1, v[28:29]
	global_store_dwordx2 v[26:27], v[24:25], off offset:8
.LBB0_4074:
	s_or_b64 exec, exec, s[24:25]
	v_mov_b32_dpp v60, v20 row_shr:1 row_mask:0xf bank_mask:0xf
	v_mov_b32_dpp v62, v20 row_shr:2 row_mask:0xf bank_mask:0xf
	v_mov_b32_dpp v52, v16 row_shr:1 row_mask:0xf bank_mask:0xf
	v_mov_b32_dpp v56, v16 row_shr:2 row_mask:0xf bank_mask:0xf
	v_mov_b32_dpp v40, v20 row_ror:1 row_mask:0xf bank_mask:0xf bound_ctrl:1
	v_mov_b32_dpp v28, v16 row_ror:1 row_mask:0xf bank_mask:0xf bound_ctrl:1
	v_mov_b32_dpp v42, v20 row_ror:2 row_mask:0xf bank_mask:0xf bound_ctrl:1
	v_mov_b32_dpp v32, v16 row_ror:2 row_mask:0xf bank_mask:0xf bound_ctrl:1
	v_mov_b32_dpp v61, v21 row_shr:1 row_mask:0xf bank_mask:0xf
	v_mov_b32_dpp v63, v21 row_shr:2 row_mask:0xf bank_mask:0xf
	v_mov_b32_dpp v53, v17 row_shr:1 row_mask:0xf bank_mask:0xf
	v_mov_b32_dpp v57, v17 row_shr:2 row_mask:0xf bank_mask:0xf
	v_mov_b32_dpp v41, v21 row_ror:1 row_mask:0xf bank_mask:0xf bound_ctrl:1
	v_mov_b32_dpp v29, v17 row_ror:1 row_mask:0xf bank_mask:0xf bound_ctrl:1
	v_mov_b32_dpp v43, v21 row_ror:2 row_mask:0xf bank_mask:0xf bound_ctrl:1
	v_mov_b32_dpp v33, v17 row_ror:2 row_mask:0xf bank_mask:0xf bound_ctrl:1
	v_mov_b32_dpp v54, v22 row_shr:1 row_mask:0xf bank_mask:0xf
	v_mov_b32_dpp v58, v22 row_shr:2 row_mask:0xf bank_mask:0xf
	v_mov_b32_dpp v48, v18 row_shr:1 row_mask:0xf bank_mask:0xf
	v_mov_b32_dpp v50, v18 row_shr:2 row_mask:0xf bank_mask:0xf
	v_mov_b32_dpp v30, v22 row_ror:1 row_mask:0xf bank_mask:0xf bound_ctrl:1
	v_mov_b32_dpp v24, v18 row_ror:1 row_mask:0xf bank_mask:0xf bound_ctrl:1
	v_mov_b32_dpp v34, v22 row_ror:2 row_mask:0xf bank_mask:0xf bound_ctrl:1
	v_mov_b32_dpp v26, v18 row_ror:2 row_mask:0xf bank_mask:0xf bound_ctrl:1
	v_mov_b32_dpp v55, v23 row_shr:1 row_mask:0xf bank_mask:0xf
	v_mov_b32_dpp v59, v23 row_shr:2 row_mask:0xf bank_mask:0xf
	v_mov_b32_dpp v49, v19 row_shr:1 row_mask:0xf bank_mask:0xf
	v_mov_b32_dpp v51, v19 row_shr:2 row_mask:0xf bank_mask:0xf
	v_mov_b32_dpp v31, v23 row_ror:1 row_mask:0xf bank_mask:0xf bound_ctrl:1
	v_mov_b32_dpp v25, v19 row_ror:1 row_mask:0xf bank_mask:0xf bound_ctrl:1
	v_mov_b32_dpp v35, v23 row_ror:2 row_mask:0xf bank_mask:0xf bound_ctrl:1
	v_mov_b32_dpp v27, v19 row_ror:2 row_mask:0xf bank_mask:0xf bound_ctrl:1
	s_and_saveexec_b64 s[24:25], s[80:81]
	s_cbranch_execz .LBB0_4076
	v_pk_fma_f32 v[36:37], v[80:81], v[62:63], v[92:93]
	v_pk_fma_f32 v[38:39], v[64:65], v[56:57], v[76:77]
	v_pk_fma_f32 v[36:37], v[84:85], v[60:61], v[36:37]
	v_pk_fma_f32 v[38:39], v[68:69], v[52:53], v[38:39]
	v_pk_fma_f32 v[20:21], v[20:21], v[88:89], v[36:37]
	v_pk_fma_f32 v[16:17], v[16:17], v[72:73], v[38:39]
	v_mul_f32_e32 v36, 0x3d372713, v20
	v_mul_f32_e32 v37, 0x3d372713, v21
	v_fma_f32 v36, v20, v36, 1.0
	v_fma_f32 v37, v21, v37, 1.0
	v_mul_f32_e32 v36, v20, v36
	v_mul_f32_e32 v37, v21, v37
	v_mul_f32_e32 v36, 0x40135761, v36
	v_mul_f32_e32 v37, 0x40135761, v37
	v_exp_f32_e32 v36, v36
	v_exp_f32_e32 v37, v37
	v_add_f32_e32 v36, 1.0, v36
	v_add_f32_e32 v37, 1.0, v37
	v_rcp_f32_e32 v36, v36
	v_rcp_f32_e32 v37, v37
	s_nop 0
	v_pk_fma_f32 v[20:21], v[20:21], v[36:37], v[20:21] neg_lo:[1,0,0] neg_hi:[1,0,0]
	v_pk_fma_f32 v[36:37], v[82:83], v[58:59], v[94:95]
	v_pk_mul_f32 v[16:17], v[16:17], v[20:21]
	v_pk_fma_f32 v[36:37], v[86:87], v[54:55], v[36:37]
	v_cvt_pk_bf16_f32 v16, v16, v17
	v_pk_fma_f32 v[22:23], v[22:23], v[90:91], v[36:37]
	s_nop 0
	v_mul_f32_e32 v36, 0x3d372713, v22
	v_mul_f32_e32 v37, 0x3d372713, v23
	v_fma_f32 v36, v22, v36, 1.0
	v_fma_f32 v37, v23, v37, 1.0
	v_mul_f32_e32 v36, v22, v36
	v_mul_f32_e32 v37, v23, v37
	v_mul_f32_e32 v36, 0x40135761, v36
	v_mul_f32_e32 v37, 0x40135761, v37
	v_exp_f32_e32 v36, v36
	v_exp_f32_e32 v37, v37
	v_add_f32_e32 v20, 1.0, v36
	v_add_f32_e32 v21, 1.0, v37
	v_rcp_f32_e32 v20, v20
	v_rcp_f32_e32 v21, v21
	v_pk_fma_f32 v[36:37], v[66:67], v[50:51], v[78:79]
	v_pk_fma_f32 v[20:21], v[22:23], v[20:21], v[22:23] neg_lo:[1,0,0] neg_hi:[1,0,0]
	v_pk_fma_f32 v[36:37], v[70:71], v[48:49], v[36:37]
	s_nop 0
	v_pk_fma_f32 v[18:19], v[18:19], v[74:75], v[36:37]
	s_nop 0
	v_pk_mul_f32 v[18:19], v[18:19], v[20:21]
	v_mov_b64_e32 v[20:21], s[30:31]
	v_cvt_pk_bf16_f32 v17, v18, v19
	v_lshl_add_u64 v[18:19], s[66:67], 0, v[136:137]
	v_mad_u64_u32 v[20:21], s[68:69], v18, s1, v[20:21]
	v_mad_i32_i24 v21, v19, s1, v21
	v_lshl_add_u64 v[18:19], v[192:193], 1, v[20:21]
	global_store_dwordx2 v[18:19], v[16:17], off offset:8
.LBB0_4076:
	s_or_b64 exec, exec, s[24:25]
	v_mov_b32_dpp v40, v12 row_shr:1 row_mask:0xf bank_mask:0xf
	v_mov_b32_dpp v42, v12 row_shr:2 row_mask:0xf bank_mask:0xf
	v_mov_b32_dpp v28, v8 row_shr:1 row_mask:0xf bank_mask:0xf
	v_mov_b32_dpp v32, v8 row_shr:2 row_mask:0xf bank_mask:0xf
	v_mov_b32_dpp v44, v12 row_ror:1 row_mask:0xf bank_mask:0xf bound_ctrl:1
	v_mov_b32_dpp v20, v8 row_ror:1 row_mask:0xf bank_mask:0xf bound_ctrl:1
	v_mov_b32_dpp v46, v12 row_ror:2 row_mask:0xf bank_mask:0xf bound_ctrl:1
	v_mov_b32_dpp v36, v8 row_ror:2 row_mask:0xf bank_mask:0xf bound_ctrl:1
	v_mov_b32_dpp v41, v13 row_shr:1 row_mask:0xf bank_mask:0xf
	v_mov_b32_dpp v43, v13 row_shr:2 row_mask:0xf bank_mask:0xf
	v_mov_b32_dpp v29, v9 row_shr:1 row_mask:0xf bank_mask:0xf
	v_mov_b32_dpp v33, v9 row_shr:2 row_mask:0xf bank_mask:0xf
	v_mov_b32_dpp v45, v13 row_ror:1 row_mask:0xf bank_mask:0xf bound_ctrl:1
	v_mov_b32_dpp v21, v9 row_ror:1 row_mask:0xf bank_mask:0xf bound_ctrl:1
	v_mov_b32_dpp v47, v13 row_ror:2 row_mask:0xf bank_mask:0xf bound_ctrl:1
	v_mov_b32_dpp v37, v9 row_ror:2 row_mask:0xf bank_mask:0xf bound_ctrl:1
	v_mov_b32_dpp v30, v14 row_shr:1 row_mask:0xf bank_mask:0xf
	v_mov_b32_dpp v34, v14 row_shr:2 row_mask:0xf bank_mask:0xf
	v_mov_b32_dpp v24, v10 row_shr:1 row_mask:0xf bank_mask:0xf
	v_mov_b32_dpp v26, v10 row_shr:2 row_mask:0xf bank_mask:0xf
	v_mov_b32_dpp v22, v14 row_ror:1 row_mask:0xf bank_mask:0xf bound_ctrl:1
	v_mov_b32_dpp v16, v10 row_ror:1 row_mask:0xf bank_mask:0xf bound_ctrl:1
	v_mov_b32_dpp v38, v14 row_ror:2 row_mask:0xf bank_mask:0xf bound_ctrl:1
	v_mov_b32_dpp v18, v10 row_ror:2 row_mask:0xf bank_mask:0xf bound_ctrl:1
	v_mov_b32_dpp v31, v15 row_shr:1 row_mask:0xf bank_mask:0xf
	v_mov_b32_dpp v35, v15 row_shr:2 row_mask:0xf bank_mask:0xf
	v_mov_b32_dpp v25, v11 row_shr:1 row_mask:0xf bank_mask:0xf
	v_mov_b32_dpp v27, v11 row_shr:2 row_mask:0xf bank_mask:0xf
	v_mov_b32_dpp v23, v15 row_ror:1 row_mask:0xf bank_mask:0xf bound_ctrl:1
	v_mov_b32_dpp v17, v11 row_ror:1 row_mask:0xf bank_mask:0xf bound_ctrl:1
	v_mov_b32_dpp v39, v15 row_ror:2 row_mask:0xf bank_mask:0xf bound_ctrl:1
	v_mov_b32_dpp v19, v11 row_ror:2 row_mask:0xf bank_mask:0xf bound_ctrl:1
	s_and_saveexec_b64 s[24:25], s[82:83]
	s_cbranch_execz .LBB0_4078
	v_pk_fma_f32 v[42:43], v[80:81], v[42:43], v[92:93]
	v_pk_fma_f32 v[32:33], v[64:65], v[32:33], v[76:77]
	v_pk_fma_f32 v[40:41], v[84:85], v[40:41], v[42:43]
	v_pk_fma_f32 v[28:29], v[68:69], v[28:29], v[32:33]
	v_pk_fma_f32 v[12:13], v[12:13], v[88:89], v[40:41]
	v_pk_fma_f32 v[8:9], v[8:9], v[72:73], v[28:29]
	v_mul_f32_e32 v40, 0x3d372713, v12
	v_mul_f32_e32 v41, 0x3d372713, v13
	v_fma_f32 v40, v12, v40, 1.0
	v_fma_f32 v41, v13, v41, 1.0
	v_mul_f32_e32 v40, v12, v40
	v_mul_f32_e32 v41, v13, v41
	v_mul_f32_e32 v40, 0x40135761, v40
	v_mul_f32_e32 v41, 0x40135761, v41
	v_pk_fma_f32 v[28:29], v[82:83], v[34:35], v[94:95]
	v_exp_f32_e32 v40, v40
	v_exp_f32_e32 v41, v41
	v_pk_fma_f32 v[28:29], v[86:87], v[30:31], v[28:29]
	v_pk_fma_f32 v[26:27], v[66:67], v[26:27], v[78:79]
	v_pk_fma_f32 v[14:15], v[14:15], v[90:91], v[28:29]
	v_add_f32_e32 v40, 1.0, v40
	v_mul_f32_e32 v28, 0x3d372713, v14
	v_mul_f32_e32 v29, 0x3d372713, v15
	v_fma_f32 v28, v14, v28, 1.0
	v_fma_f32 v29, v15, v29, 1.0
	v_add_f32_e32 v41, 1.0, v41
	v_mul_f32_e32 v28, v14, v28
	v_mul_f32_e32 v29, v15, v29
	v_rcp_f32_e32 v40, v40
	v_rcp_f32_e32 v41, v41
	v_mul_f32_e32 v28, 0x40135761, v28
	v_mul_f32_e32 v29, 0x40135761, v29
	v_exp_f32_e32 v28, v28
	v_exp_f32_e32 v29, v29
	v_pk_fma_f32 v[12:13], v[12:13], v[40:41], v[12:13] neg_lo:[1,0,0] neg_hi:[1,0,0]
	v_pk_fma_f32 v[24:25], v[70:71], v[24:25], v[26:27]
	v_pk_mul_f32 v[8:9], v[8:9], v[12:13]
	v_add_f32_e32 v12, 1.0, v28
	v_add_f32_e32 v13, 1.0, v29
	v_rcp_f32_e32 v12, v12
	v_rcp_f32_e32 v13, v13
	v_pk_fma_f32 v[10:11], v[10:11], v[74:75], v[24:25]
	v_cvt_pk_bf16_f32 v8, v8, v9
	v_pk_fma_f32 v[12:13], v[14:15], v[12:13], v[14:15] neg_lo:[1,0,0] neg_hi:[1,0,0]
	s_nop 0
	v_pk_mul_f32 v[10:11], v[10:11], v[12:13]
	v_mov_b64_e32 v[12:13], s[30:31]
	v_cvt_pk_bf16_f32 v9, v10, v11
	v_lshl_add_u64 v[10:11], s[66:67], 0, v[138:139]
	v_mad_u64_u32 v[12:13], s[68:69], v10, s1, v[12:13]
	v_mad_i32_i24 v13, v11, s1, v13
	v_lshl_add_u64 v[10:11], v[192:193], 1, v[12:13]
	global_store_dwordx2 v[10:11], v[8:9], off offset:8
.LBB0_4078:
	s_or_b64 exec, exec, s[24:25]
	v_mov_b32_dpp v44, v4 row_shr:1 row_mask:0xf bank_mask:0xf
	v_mov_b32_dpp v46, v4 row_shr:2 row_mask:0xf bank_mask:0xf
	v_mov_b32_dpp v20, v0 row_shr:1 row_mask:0xf bank_mask:0xf
	v_mov_b32_dpp v36, v0 row_shr:2 row_mask:0xf bank_mask:0xf
	v_mov_b32_dpp v45, v5 row_shr:1 row_mask:0xf bank_mask:0xf
	v_mov_b32_dpp v47, v5 row_shr:2 row_mask:0xf bank_mask:0xf
	v_mov_b32_dpp v21, v1 row_shr:1 row_mask:0xf bank_mask:0xf
	v_mov_b32_dpp v37, v1 row_shr:2 row_mask:0xf bank_mask:0xf
	v_mov_b32_dpp v22, v6 row_shr:1 row_mask:0xf bank_mask:0xf
	v_mov_b32_dpp v38, v6 row_shr:2 row_mask:0xf bank_mask:0xf
	v_mov_b32_dpp v16, v2 row_shr:1 row_mask:0xf bank_mask:0xf
	v_mov_b32_dpp v18, v2 row_shr:2 row_mask:0xf bank_mask:0xf
	v_mov_b32_dpp v23, v7 row_shr:1 row_mask:0xf bank_mask:0xf
	v_mov_b32_dpp v39, v7 row_shr:2 row_mask:0xf bank_mask:0xf
	v_mov_b32_dpp v17, v3 row_shr:1 row_mask:0xf bank_mask:0xf
	v_mov_b32_dpp v19, v3 row_shr:2 row_mask:0xf bank_mask:0xf
	s_and_saveexec_b64 s[24:25], s[84:85]
	s_cbranch_execz .LBB0_4080
	v_pk_fma_f32 v[8:9], v[80:81], v[46:47], v[92:93]
	v_pk_fma_f32 v[10:11], v[64:65], v[36:37], v[76:77]
	v_pk_fma_f32 v[8:9], v[84:85], v[44:45], v[8:9]
	v_pk_fma_f32 v[10:11], v[68:69], v[20:21], v[10:11]
	v_pk_fma_f32 v[4:5], v[4:5], v[88:89], v[8:9]
	v_pk_fma_f32 v[0:1], v[0:1], v[72:73], v[10:11]
	v_mul_f32_e32 v8, 0x3d372713, v4
	v_mul_f32_e32 v9, 0x3d372713, v5
	v_fma_f32 v8, v4, v8, 1.0
	v_fma_f32 v9, v5, v9, 1.0
	v_mul_f32_e32 v8, v4, v8
	v_mul_f32_e32 v9, v5, v9
	v_mul_f32_e32 v8, 0x40135761, v8
	v_mul_f32_e32 v9, 0x40135761, v9
	v_exp_f32_e32 v8, v8
	v_exp_f32_e32 v9, v9
	v_add_f32_e32 v8, 1.0, v8
	v_add_f32_e32 v9, 1.0, v9
	v_rcp_f32_e32 v8, v8
	v_rcp_f32_e32 v9, v9
	s_nop 0
	v_pk_fma_f32 v[4:5], v[4:5], v[8:9], v[4:5] neg_lo:[1,0,0] neg_hi:[1,0,0]
	v_pk_fma_f32 v[8:9], v[82:83], v[38:39], v[94:95]
	v_pk_mul_f32 v[0:1], v[0:1], v[4:5]
	v_pk_fma_f32 v[8:9], v[86:87], v[22:23], v[8:9]
	v_cvt_pk_bf16_f32 v0, v0, v1
	v_pk_fma_f32 v[6:7], v[6:7], v[90:91], v[8:9]
	s_nop 0
	v_mul_f32_e32 v8, 0x3d372713, v6
	v_mul_f32_e32 v9, 0x3d372713, v7
	v_fma_f32 v8, v6, v8, 1.0
	v_fma_f32 v9, v7, v9, 1.0
	v_mul_f32_e32 v8, v6, v8
	v_mul_f32_e32 v9, v7, v9
	v_mul_f32_e32 v8, 0x40135761, v8
	v_mul_f32_e32 v9, 0x40135761, v9
	v_exp_f32_e32 v8, v8
	v_exp_f32_e32 v9, v9
	v_add_f32_e32 v4, 1.0, v8
	v_add_f32_e32 v5, 1.0, v9
	v_rcp_f32_e32 v4, v4
	v_rcp_f32_e32 v5, v5
	v_pk_fma_f32 v[8:9], v[66:67], v[18:19], v[78:79]
	v_pk_fma_f32 v[4:5], v[6:7], v[4:5], v[6:7] neg_lo:[1,0,0] neg_hi:[1,0,0]
	v_pk_fma_f32 v[8:9], v[70:71], v[16:17], v[8:9]
	s_nop 0
	v_pk_fma_f32 v[2:3], v[2:3], v[74:75], v[8:9]
	s_nop 0
	v_pk_mul_f32 v[2:3], v[2:3], v[4:5]
	v_mov_b64_e32 v[4:5], s[30:31]
	v_cvt_pk_bf16_f32 v1, v2, v3
	v_lshl_add_u64 v[2:3], s[66:67], 0, v[140:141]
	v_mad_u64_u32 v[4:5], s[66:67], v2, s1, v[4:5]
	v_mad_i32_i24 v5, v3, s1, v5
	v_lshl_add_u64 v[2:3], v[192:193], 1, v[4:5]
	global_store_dwordx2 v[2:3], v[0:1], off offset:8
